# K-loops: setprio off the hand-off path + single closing wait + first MFMA directly behind the phase barrier
# baseline (speedup 1.0000x reference)
; #define PG8_STAGE(bufoff, gbase, voff) do { _Pragma("unroll") for (int _i = 0; _i < 2; ++_i) \
;         __builtin_amdgcn_global_load_lds((const unsigned*)((const char*)(gbase) + (voff)[_i]), (PG8_LAS unsigned*)(lds + (bufoff) + ldsw + _i * 8192), 16, 0, 0); } while (0)
; #define PG8_LDA(dst, b, h) do { _Pragma("unroll") for (int m = 0; m < 4; ++m) _Pragma("unroll") for (int k = 0; k < 2; ++k) dst[m][k] = *(const PG8_LAS bf16x8*)(lds + PG8_SA(b, h) + aoff + m * 2048 + k * 1024); } while (0)
; #define PG8_LDB(dst, b, h) do { _Pragma("unroll") for (int n = 0; n < 2; ++n) _Pragma("unroll") for (int k = 0; k < 2; ++k) dst[n][k] = *(const PG8_LAS bf16x8*)(lds + PG8_SB(b, h) + boff + n * 2048 + k * 1024); } while (0)
; #define PG8_WAIT_V(n) asm volatile("s_waitcnt vmcnt(" #n ")" ::: "memory")
; #define PG8_WAIT_L(n) asm volatile("s_waitcnt lgkmcnt(" #n ")" ::: "memory")
; #define PG8_BAR __builtin_amdgcn_s_barrier()
; #define PG8_SCHED __builtin_amdgcn_sched_barrier(0)
; template <class Epi, class Sched, bool ALIGN_EPI = false, bool SP2 = false, bool I8 = false>
; __device__ __forceinline__ void gemm_phase(PG8_LAS unsigned char* lds, const Gemm g, const Sched& S, const Epi& E) {
;     ...
;         const bool has_next = S.next(ui + 1, nxt);
;         const char* nA = has_next ? (const char*)g.A + (size_t)nxt.pm * tstep : cA; const char* nB = has_next ? (const char*)g.Bt + (size_t)nxt.pn * tstep : cB;
;         for (int t = 0; t < nt; t += 2) {
;             const bool last = (t == nt - 2);
;             const char* a1 = cA + (size_t)(t + 1) * kstep;
;             const char* a2 = last ? nA : cA + (size_t)(t + 2) * kstep; const char* b2 = last ? nB : cB + (size_t)(t + 2) * kstep;
;             const char* a3 = a2 + kstep; const char* b3 = b2 + kstep;
;             if (last && has_next) S.a_ready(nxt);
;             if constexpr (SP2) {
;             PG8_LDB(B0, 0, 0); PG8_LDB(B1, 0, 1); PG8_SCHED; PG8_LDA(At, 0, 0); PG8_STAGE(PG8_SA(1, 1), a1 + hstep, voffA);
;             PG8_WAIT_V(8); PG8_WAIT_L(0); PG8_BAR; PG8_MMA(0, 0, At, B0); PG8_MMA(0, 1, At, B1); PG8_BAR; PG8_SCHED;
;             PG8_LDA(At, 0, 1); PG8_STAGE(PG8_SB(0, 0), b2, voffB); PG8_STAGE(PG8_SB(0, 1), b2 + hstep, voffB); PG8_STAGE(PG8_SA(0, 0), a2, voffA);
;             PG8_WAIT_V(8); PG8_WAIT_L(0); PG8_BAR; PG8_MMA(1, 0, At, B0); PG8_MMA(1, 1, At, B1); PG8_BAR; PG8_SCHED;
.LBB0_207:
	s_ashr_i32 s19, s18, 31
	s_lshl_b64 s[22:23], s[18:19], 20
	s_add_u32 s22, s28, s22
	s_addc_u32 s23, s34, s23
	s_and_b64 s[24:25], s[6:7], exec
	s_cselect_b32 s19, s23, s27
	s_cselect_b32 s64, s22, s26
	s_ashr_i32 s17, s16, 31
	s_lshl_b64 s[24:25], s[16:17], 20
	s_add_u32 s24, s35, s24
	s_addc_u32 s25, s42, s25
	s_and_b64 s[40:41], s[6:7], exec
	s_cselect_b32 s17, s25, s37
	s_cselect_b32 s65, s24, s36
	s_add_u32 s26, s26, 0x80080
	s_addc_u32 s27, s27, 0
	s_add_u32 s72, s36, 0x100
	s_addc_u32 s73, s37, 0
	s_mov_b32 s76, -2
	s_add_u32 s36, s26, 0xfff80080
	s_addc_u32 s37, s27, -1
	s_add_i32 s50, 0, 0x10000
	s_cmp_eq_u32 s76, 28
	s_cselect_b32 s41, s19, s37
	s_cselect_b32 s40, s64, s36
	s_cselect_b32 s37, s17, s73
	s_cselect_b32 s36, s65, s72
	s_add_i32 s56, 0, 0x14000
	v_add_u32_e32 v136, s50, v175
	v_add_u32_e32 v172, s56, v175
	ds_read_b128 v[116:119], v136
	ds_read_b128 v[124:127], v136 offset:1024
	ds_read_b128 v[132:135], v136 offset:2048
	ds_read_b128 v[136:139], v136 offset:3072
	ds_read_b128 v[160:163], v172
	ds_read_b128 v[164:167], v172 offset:1024
	ds_read_b128 v[168:171], v172 offset:2048
	ds_read_b128 v[178:181], v172 offset:3072
	s_add_i32 m0, s44, 0xc000
	ds_read_b128 v[182:185], v177
	ds_read_b128 v[186:189], v177 offset:1024
	ds_read_b128 v[204:207], v177 offset:2048
	ds_read_b128 v[208:211], v177 offset:3072
	ds_read_b128 v[212:215], v177 offset:4096
	ds_read_b128 v[216:219], v177 offset:5120
	ds_read_b128 v[220:223], v177 offset:6144
	ds_read_b128 v[224:227], v177 offset:7168
	global_load_lds_dwordx4 v156, s[26:27]
	s_add_i32 m0, s44, 0xe000
	s_nop 0
	global_load_lds_dwordx4 v158, s[26:27]
	s_waitcnt vmcnt(8) lgkmcnt(0)
	s_setprio 1
	s_barrier
	v_mfma_i32_16x16x64_i8 v[144:147], v[116:119], v[182:185], 0
	v_mfma_i32_16x16x64_i8 v[144:147], v[124:127], v[186:189], v[144:147]
	v_mfma_i32_16x16x64_i8 v[112:115], v[124:127], v[208:211], 0
	v_mfma_i32_16x16x64_i8 v[112:115], v[116:119], v[204:207], v[112:115]
	v_mfma_i32_16x16x64_i8 v[96:99], v[116:119], v[212:215], 0
	v_mfma_i32_16x16x64_i8 v[96:99], v[124:127], v[216:219], v[96:99]
	v_mfma_i32_16x16x64_i8 v[80:83], v[124:127], v[224:227], 0
	v_mfma_i32_16x16x64_i8 v[80:83], v[116:119], v[220:223], v[80:83]
	v_mfma_i32_16x16x64_i8 v[76:79], v[132:135], v[220:223], 0
	v_mfma_i32_16x16x64_i8 v[76:79], v[136:139], v[224:227], v[76:79]
	v_mfma_i32_16x16x64_i8 v[92:95], v[136:139], v[216:219], 0
	v_mfma_i32_16x16x64_i8 v[92:95], v[132:135], v[212:215], v[92:95]
	v_mfma_i32_16x16x64_i8 v[108:111], v[132:135], v[204:207], 0
	v_mfma_i32_16x16x64_i8 v[108:111], v[136:139], v[208:211], v[108:111]
	v_mfma_i32_16x16x64_i8 v[140:143], v[136:139], v[186:189], 0
	v_mfma_i32_16x16x64_i8 v[140:143], v[132:135], v[182:185], v[140:143]
	v_mfma_i32_16x16x64_i8 v[128:131], v[160:163], v[182:185], 0
	v_mfma_i32_16x16x64_i8 v[128:131], v[164:167], v[186:189], v[128:131]
	v_mfma_i32_16x16x64_i8 v[104:107], v[164:167], v[208:211], 0
	v_mfma_i32_16x16x64_i8 v[104:107], v[160:163], v[204:207], v[104:107]
	v_mfma_i32_16x16x64_i8 v[88:91], v[160:163], v[212:215], 0
	v_mfma_i32_16x16x64_i8 v[88:91], v[164:167], v[216:219], v[88:91]
	v_mfma_i32_16x16x64_i8 v[72:75], v[164:167], v[224:227], 0
	v_mfma_i32_16x16x64_i8 v[72:75], v[160:163], v[220:223], v[72:75]
	v_mfma_i32_16x16x64_i8 v[68:71], v[168:171], v[220:223], 0
	v_mfma_i32_16x16x64_i8 v[68:71], v[178:181], v[224:227], v[68:71]
	v_mfma_i32_16x16x64_i8 v[84:87], v[178:181], v[216:219], 0
	v_mfma_i32_16x16x64_i8 v[84:87], v[168:171], v[212:215], v[84:87]
	v_mfma_i32_16x16x64_i8 v[100:103], v[168:171], v[204:207], 0
	v_mfma_i32_16x16x64_i8 v[100:103], v[178:181], v[208:211], v[100:103]
	v_mfma_i32_16x16x64_i8 v[120:123], v[178:181], v[186:189], 0
	v_mfma_i32_16x16x64_i8 v[120:123], v[168:171], v[182:185], v[120:123]
	s_barrier
	s_setprio 0
	s_add_i32 s50, s50, s43
	v_lshl_add_u64 v[172:173], s[36:37], 0, v[2:3]
	s_mov_b32 m0, s50
	ds_read_b128 v[182:185], v177 offset:16384
	ds_read_b128 v[186:189], v177 offset:17408
	ds_read_b128 v[204:207], v177 offset:18432
	ds_read_b128 v[208:211], v177 offset:19456
	ds_read_b128 v[212:215], v177 offset:20480
	ds_read_b128 v[216:219], v177 offset:21504
	ds_read_b128 v[220:223], v177 offset:22528
	ds_read_b128 v[224:227], v177 offset:23552
	global_load_lds_dwordx4 v[172:173], off
	s_add_i32 m0, s50, 0x2000
	s_add_u32 s50, s36, 0x80000
	v_lshl_add_u64 v[190:191], s[36:37], 0, v[148:149]
	s_addc_u32 s51, s37, 0
	s_add_i32 s56, s56, s43
	global_load_lds_dwordx4 v[190:191], off
	s_mov_b32 m0, s56
	v_lshl_add_u64 v[240:241], s[40:41], 0, v[150:151]
	global_load_lds_dwordx4 v2, s[50:51]
	s_add_i32 m0, s56, 0x2000
	s_nop 0
	global_load_lds_dwordx4 v148, s[50:51]
	v_lshl_add_u64 v[228:229], s[40:41], 0, v[152:153]
	s_waitcnt vmcnt(6) lgkmcnt(0)
	s_setprio 1
	s_barrier
; #define PG8_STAGE(bufoff, gbase, voff) do { _Pragma("unroll") for (int _i = 0; _i < 2; ++_i) \
;         __builtin_amdgcn_global_load_lds((const unsigned*)((const char*)(gbase) + (voff)[_i]), (PG8_LAS unsigned*)(lds + (bufoff) + ldsw + _i * 8192), 16, 0, 0); } while (0)
; #define PG8_LDA(dst, b, h) do { _Pragma("unroll") for (int m = 0; m < 4; ++m) _Pragma("unroll") for (int k = 0; k < 2; ++k) dst[m][k] = *(const PG8_LAS bf16x8*)(lds + PG8_SA(b, h) + aoff + m * 2048 + k * 1024); } while (0)
; #define PG8_LDB(dst, b, h) do { _Pragma("unroll") for (int n = 0; n < 2; ++n) _Pragma("unroll") for (int k = 0; k < 2; ++k) dst[n][k] = *(const PG8_LAS bf16x8*)(lds + PG8_SB(b, h) + boff + n * 2048 + k * 1024); } while (0)
; #define PG8_WAIT_V(n) asm volatile("s_waitcnt vmcnt(" #n ")" ::: "memory")
; #define PG8_WAIT_L(n) asm volatile("s_waitcnt lgkmcnt(" #n ")" ::: "memory")
; #define PG8_BAR __builtin_amdgcn_s_barrier()
; #define PG8_SCHED __builtin_amdgcn_sched_barrier(0)
; template <class Epi, class Sched, bool ALIGN_EPI = false, bool SP2 = false, bool I8 = false>
; __device__ __forceinline__ void gemm_phase(PG8_LAS unsigned char* lds, const Gemm g, const Sched& S, const Epi& E) {
;     ...
;             PG8_LDB(B0, 0, 0); PG8_LDB(B1, 0, 1); PG8_SCHED; PG8_LDA(At, 0, 0); PG8_STAGE(PG8_SA(1, 1), a1 + hstep, voffA);
;             PG8_WAIT_V(8); PG8_WAIT_L(0); PG8_BAR; PG8_MMA(0, 0, At, B0); PG8_MMA(0, 1, At, B1); PG8_BAR; PG8_SCHED;
;             PG8_LDA(At, 0, 1); PG8_STAGE(PG8_SB(0, 0), b2, voffB); PG8_STAGE(PG8_SB(0, 1), b2 + hstep, voffB); PG8_STAGE(PG8_SA(0, 0), a2, voffA);
;             PG8_WAIT_V(8); PG8_WAIT_L(0); PG8_BAR; PG8_MMA(1, 0, At, B0); PG8_MMA(1, 1, At, B1); PG8_BAR; PG8_SCHED;
;             PG8_LDB(B0, 1, 0); PG8_LDB(B1, 1, 1); PG8_SCHED; PG8_LDA(At, 1, 0); PG8_STAGE(PG8_SA(0, 1), a2 + hstep, voffA);
;             PG8_WAIT_V(8); PG8_WAIT_L(0); PG8_BAR; PG8_MMA(0, 0, At, B0); PG8_MMA(0, 1, At, B1); PG8_BAR; PG8_SCHED;
;             PG8_LDA(At, 1, 1); PG8_STAGE(PG8_SB(1, 0), b3, voffB); PG8_STAGE(PG8_SB(1, 1), b3 + hstep, voffB); PG8_STAGE(PG8_SA(1, 0), a3, voffA);
;             PG8_WAIT_V(8); PG8_WAIT_L(0); PG8_BAR; PG8_MMA(1, 0, At, B0); PG8_MMA(1, 1, At, B1); PG8_BAR; PG8_SCHED;
	v_mfma_i32_16x16x64_i8 v[64:67], v[116:119], v[182:185], 0
	v_mfma_i32_16x16x64_i8 v[64:67], v[124:127], v[186:189], v[64:67]
	v_mfma_i32_16x16x64_i8 v[48:51], v[124:127], v[208:211], 0
	v_mfma_i32_16x16x64_i8 v[48:51], v[116:119], v[204:207], v[48:51]
	v_mfma_i32_16x16x64_i8 v[32:35], v[116:119], v[212:215], 0
	v_mfma_i32_16x16x64_i8 v[32:35], v[124:127], v[216:219], v[32:35]
	v_mfma_i32_16x16x64_i8 v[16:19], v[124:127], v[224:227], 0
	v_mfma_i32_16x16x64_i8 v[16:19], v[116:119], v[220:223], v[16:19]
	v_mfma_i32_16x16x64_i8 v[12:15], v[132:135], v[220:223], 0
	v_mfma_i32_16x16x64_i8 v[12:15], v[136:139], v[224:227], v[12:15]
	v_mfma_i32_16x16x64_i8 v[28:31], v[136:139], v[216:219], 0
	v_mfma_i32_16x16x64_i8 v[28:31], v[132:135], v[212:215], v[28:31]
	v_mfma_i32_16x16x64_i8 v[44:47], v[132:135], v[204:207], 0
	v_mfma_i32_16x16x64_i8 v[44:47], v[136:139], v[208:211], v[44:47]
	v_mfma_i32_16x16x64_i8 v[60:63], v[136:139], v[186:189], 0
	v_mfma_i32_16x16x64_i8 v[60:63], v[132:135], v[182:185], v[60:63]
	v_mfma_i32_16x16x64_i8 v[56:59], v[160:163], v[182:185], 0
	v_mfma_i32_16x16x64_i8 v[56:59], v[164:167], v[186:189], v[56:59]
	v_mfma_i32_16x16x64_i8 v[40:43], v[164:167], v[208:211], 0
	v_mfma_i32_16x16x64_i8 v[40:43], v[160:163], v[204:207], v[40:43]
	v_mfma_i32_16x16x64_i8 v[24:27], v[160:163], v[212:215], 0
	v_mfma_i32_16x16x64_i8 v[24:27], v[164:167], v[216:219], v[24:27]
	v_mfma_i32_16x16x64_i8 v[8:11], v[164:167], v[224:227], 0
	v_mfma_i32_16x16x64_i8 v[8:11], v[160:163], v[220:223], v[8:11]
	v_mfma_i32_16x16x64_i8 v[4:7], v[168:171], v[220:223], 0
	v_mfma_i32_16x16x64_i8 v[4:7], v[178:181], v[224:227], v[4:7]
	v_mfma_i32_16x16x64_i8 v[20:23], v[178:181], v[216:219], 0
	v_mfma_i32_16x16x64_i8 v[20:23], v[168:171], v[212:215], v[20:23]
	v_mfma_i32_16x16x64_i8 v[36:39], v[168:171], v[204:207], 0
	v_mfma_i32_16x16x64_i8 v[36:39], v[178:181], v[208:211], v[36:39]
	v_mfma_i32_16x16x64_i8 v[52:55], v[178:181], v[186:189], 0
	v_mfma_i32_16x16x64_i8 v[52:55], v[168:171], v[182:185], v[52:55]
	s_barrier
	s_setprio 0
	s_mov_b32 m0, s44
	s_nop 0
	global_load_lds_dwordx4 v[228:229], off
	s_mov_b32 m0, s45
	s_nop 0
	global_load_lds_dwordx4 v[240:241], off
	s_add_i32 s50, 0, 0x18000
	s_add_i32 s51, 0, 0x1c000
	v_add_u32_e32 v136, s50, v175
	v_add_u32_e32 v178, s51, v175
	ds_read_b128 v[116:119], v136
	ds_read_b128 v[124:127], v136 offset:1024
	ds_read_b128 v[132:135], v136 offset:2048
	ds_read_b128 v[136:139], v136 offset:3072
	ds_read_b128 v[160:163], v178
	ds_read_b128 v[164:167], v178 offset:1024
	ds_read_b128 v[168:171], v178 offset:2048
	ds_read_b128 v[178:181], v178 offset:3072
	s_add_u32 s40, s40, 0x80000
	s_addc_u32 s41, s41, 0
	s_mov_b32 m0, s46
	ds_read_b128 v[182:185], v177 offset:32768
	ds_read_b128 v[186:189], v177 offset:33792
	ds_read_b128 v[204:207], v177 offset:34816
	ds_read_b128 v[208:211], v177 offset:35840
	ds_read_b128 v[212:215], v177 offset:36864
	ds_read_b128 v[216:219], v177 offset:37888
	ds_read_b128 v[220:223], v177 offset:38912
	ds_read_b128 v[224:227], v177 offset:39936
	global_load_lds_dwordx4 v152, s[40:41]
	s_mov_b32 m0, s47
	s_nop 0
	global_load_lds_dwordx4 v150, s[40:41]
	s_waitcnt vmcnt(8) lgkmcnt(0)
	s_setprio 1
	s_barrier
	v_mfma_i32_16x16x64_i8 v[144:147], v[116:119], v[182:185], v[144:147]
	v_mfma_i32_16x16x64_i8 v[144:147], v[124:127], v[186:189], v[144:147]
	v_mfma_i32_16x16x64_i8 v[112:115], v[124:127], v[208:211], v[112:115]
	v_mfma_i32_16x16x64_i8 v[112:115], v[116:119], v[204:207], v[112:115]
	v_mfma_i32_16x16x64_i8 v[96:99], v[116:119], v[212:215], v[96:99]
	v_mfma_i32_16x16x64_i8 v[96:99], v[124:127], v[216:219], v[96:99]
	v_mfma_i32_16x16x64_i8 v[80:83], v[124:127], v[224:227], v[80:83]
	v_mfma_i32_16x16x64_i8 v[80:83], v[116:119], v[220:223], v[80:83]
	v_mfma_i32_16x16x64_i8 v[76:79], v[132:135], v[220:223], v[76:79]
	v_mfma_i32_16x16x64_i8 v[76:79], v[136:139], v[224:227], v[76:79]
	v_mfma_i32_16x16x64_i8 v[92:95], v[136:139], v[216:219], v[92:95]
	v_mfma_i32_16x16x64_i8 v[92:95], v[132:135], v[212:215], v[92:95]
	v_mfma_i32_16x16x64_i8 v[108:111], v[132:135], v[204:207], v[108:111]
	v_mfma_i32_16x16x64_i8 v[108:111], v[136:139], v[208:211], v[108:111]
	v_mfma_i32_16x16x64_i8 v[140:143], v[136:139], v[186:189], v[140:143]
	v_mfma_i32_16x16x64_i8 v[140:143], v[132:135], v[182:185], v[140:143]
	v_mfma_i32_16x16x64_i8 v[128:131], v[160:163], v[182:185], v[128:131]
	v_mfma_i32_16x16x64_i8 v[128:131], v[164:167], v[186:189], v[128:131]
	v_mfma_i32_16x16x64_i8 v[104:107], v[164:167], v[208:211], v[104:107]
	v_mfma_i32_16x16x64_i8 v[104:107], v[160:163], v[204:207], v[104:107]
	v_mfma_i32_16x16x64_i8 v[88:91], v[160:163], v[212:215], v[88:91]
	v_mfma_i32_16x16x64_i8 v[88:91], v[164:167], v[216:219], v[88:91]
	v_mfma_i32_16x16x64_i8 v[72:75], v[164:167], v[224:227], v[72:75]
	v_mfma_i32_16x16x64_i8 v[72:75], v[160:163], v[220:223], v[72:75]
	v_mfma_i32_16x16x64_i8 v[68:71], v[168:171], v[220:223], v[68:71]
	v_mfma_i32_16x16x64_i8 v[68:71], v[178:181], v[224:227], v[68:71]
	v_mfma_i32_16x16x64_i8 v[84:87], v[178:181], v[216:219], v[84:87]
	v_mfma_i32_16x16x64_i8 v[84:87], v[168:171], v[212:215], v[84:87]
	v_mfma_i32_16x16x64_i8 v[100:103], v[168:171], v[204:207], v[100:103]
	v_mfma_i32_16x16x64_i8 v[100:103], v[178:181], v[208:211], v[100:103]
	v_mfma_i32_16x16x64_i8 v[120:123], v[178:181], v[186:189], v[120:123]
	v_mfma_i32_16x16x64_i8 v[120:123], v[168:171], v[182:185], v[120:123]
	s_barrier
	s_setprio 0
	s_add_i32 s40, s50, s43
	v_lshl_add_u64 v[172:173], v[172:173], 0, s[84:85]
	s_mov_b32 m0, s40
	ds_read_b128 v[182:185], v177 offset:49152
	ds_read_b128 v[186:189], v177 offset:50176
	ds_read_b128 v[204:207], v177 offset:51200
	ds_read_b128 v[208:211], v177 offset:52224
	ds_read_b128 v[212:215], v177 offset:53248
	ds_read_b128 v[216:219], v177 offset:54272
	ds_read_b128 v[220:223], v177 offset:55296
	ds_read_b128 v[224:227], v177 offset:56320
	global_load_lds_dwordx4 v[172:173], off
	s_add_i32 m0, s40, 0x2000
	s_add_u32 s36, s36, 0x80080
	v_lshl_add_u64 v[172:173], v[190:191], 0, s[84:85]
	s_addc_u32 s37, s37, 0
	s_add_i32 s40, s51, s43
	global_load_lds_dwordx4 v[172:173], off
	s_mov_b32 m0, s40
	s_nop 0
	global_load_lds_dwordx4 v2, s[36:37]
	s_add_i32 m0, s40, 0x2000
	s_nop 0
	global_load_lds_dwordx4 v148, s[36:37]
	s_cmp_eq_u32 s76, 28
	s_cbranch_scc0 .Ldefer_208_peel
	v_lshl_add_u64 v[172:173], v[228:229], 0, s[84:85]
	s_mov_b32 m0, s52
	s_nop 0
	global_load_lds_dwordx4 v[172:173], off
	v_lshl_add_u64 v[172:173], v[240:241], 0, s[84:85]
	s_mov_b32 m0, s53
	s_nop 0
	global_load_lds_dwordx4 v[172:173], off
; #define PG8_STAGE(bufoff, gbase, voff) do { _Pragma("unroll") for (int _i = 0; _i < 2; ++_i) \
;         __builtin_amdgcn_global_load_lds((const unsigned*)((const char*)(gbase) + (voff)[_i]), (PG8_LAS unsigned*)(lds + (bufoff) + ldsw + _i * 8192), 16, 0, 0); } while (0)
; #define PG8_LDA(dst, b, h) do { _Pragma("unroll") for (int m = 0; m < 4; ++m) _Pragma("unroll") for (int k = 0; k < 2; ++k) dst[m][k] = *(const PG8_LAS bf16x8*)(lds + PG8_SA(b, h) + aoff + m * 2048 + k * 1024); } while (0)
; #define PG8_WAIT_V(n) asm volatile("s_waitcnt vmcnt(" #n ")" ::: "memory")
; #define PG8_WAIT_L(n) asm volatile("s_waitcnt lgkmcnt(" #n ")" ::: "memory")
; #define PG8_BAR __builtin_amdgcn_s_barrier()
; template <class Epi, class Sched, bool ALIGN_EPI = false, bool SP2 = false, bool I8 = false>
; __device__ __forceinline__ void gemm_phase(PG8_LAS unsigned char* lds, const Gemm g, const Sched& S, const Epi& E) {
;     ...
;         for (int t = 0; t < nt; t += 2) {
;             const bool last = (t == nt - 2);
;             const char* a1 = cA + (size_t)(t + 1) * kstep;
;             const char* a2 = last ? nA : cA + (size_t)(t + 2) * kstep; const char* b2 = last ? nB : cB + (size_t)(t + 2) * kstep;
;             const char* a3 = a2 + kstep; const char* b3 = b2 + kstep;
;             if (last && has_next) S.a_ready(nxt);
;             if constexpr (SP2) {
;             PG8_LDB(B0, 0, 0); PG8_LDB(B1, 0, 1); PG8_SCHED; PG8_LDA(At, 0, 0); PG8_STAGE(PG8_SA(1, 1), a1 + hstep, voffA);
;             PG8_WAIT_V(8); PG8_WAIT_L(0); PG8_BAR; PG8_MMA(0, 0, At, B0); PG8_MMA(0, 1, At, B1); PG8_BAR; PG8_SCHED;
;             PG8_LDA(At, 0, 1); PG8_STAGE(PG8_SB(0, 0), b2, voffB); PG8_STAGE(PG8_SB(0, 1), b2 + hstep, voffB); PG8_STAGE(PG8_SA(0, 0), a2, voffA);
;             PG8_WAIT_V(8); PG8_WAIT_L(0); PG8_BAR; PG8_MMA(1, 0, At, B0); PG8_MMA(1, 1, At, B1); PG8_BAR; PG8_SCHED;
;             PG8_LDB(B0, 1, 0); PG8_LDB(B1, 1, 1); PG8_SCHED; PG8_LDA(At, 1, 0); PG8_STAGE(PG8_SA(0, 1), a2 + hstep, voffA);
;             PG8_WAIT_V(8); PG8_WAIT_L(0); PG8_BAR; PG8_MMA(0, 0, At, B0); PG8_MMA(0, 1, At, B1); PG8_BAR; PG8_SCHED;
;             PG8_LDA(At, 1, 1); PG8_STAGE(PG8_SB(1, 0), b3, voffB); PG8_STAGE(PG8_SB(1, 1), b3 + hstep, voffB); PG8_STAGE(PG8_SA(1, 0), a3, voffA);
;             PG8_WAIT_V(8); PG8_WAIT_L(0); PG8_BAR; PG8_MMA(1, 0, At, B0); PG8_MMA(1, 1, At, B1); PG8_BAR; PG8_SCHED;
.Ldefer_208_peel:
	s_waitcnt vmcnt(6) lgkmcnt(0)
	s_setprio 1
	s_barrier
	v_mfma_i32_16x16x64_i8 v[64:67], v[116:119], v[182:185], v[64:67]
	v_mfma_i32_16x16x64_i8 v[64:67], v[124:127], v[186:189], v[64:67]
	v_mfma_i32_16x16x64_i8 v[48:51], v[124:127], v[208:211], v[48:51]
	v_mfma_i32_16x16x64_i8 v[48:51], v[116:119], v[204:207], v[48:51]
	v_mfma_i32_16x16x64_i8 v[32:35], v[116:119], v[212:215], v[32:35]
	v_mfma_i32_16x16x64_i8 v[32:35], v[124:127], v[216:219], v[32:35]
	v_mfma_i32_16x16x64_i8 v[16:19], v[124:127], v[224:227], v[16:19]
	v_mfma_i32_16x16x64_i8 v[16:19], v[116:119], v[220:223], v[16:19]
	v_mfma_i32_16x16x64_i8 v[12:15], v[132:135], v[220:223], v[12:15]
	v_mfma_i32_16x16x64_i8 v[12:15], v[136:139], v[224:227], v[12:15]
	v_mfma_i32_16x16x64_i8 v[28:31], v[136:139], v[216:219], v[28:31]
	v_mfma_i32_16x16x64_i8 v[28:31], v[132:135], v[212:215], v[28:31]
	v_mfma_i32_16x16x64_i8 v[44:47], v[132:135], v[204:207], v[44:47]
	v_mfma_i32_16x16x64_i8 v[44:47], v[136:139], v[208:211], v[44:47]
	v_mfma_i32_16x16x64_i8 v[60:63], v[136:139], v[186:189], v[60:63]
	v_mfma_i32_16x16x64_i8 v[60:63], v[132:135], v[182:185], v[60:63]
	v_mfma_i32_16x16x64_i8 v[56:59], v[160:163], v[182:185], v[56:59]
	v_mfma_i32_16x16x64_i8 v[56:59], v[164:167], v[186:189], v[56:59]
	v_mfma_i32_16x16x64_i8 v[40:43], v[164:167], v[208:211], v[40:43]
	v_mfma_i32_16x16x64_i8 v[40:43], v[160:163], v[204:207], v[40:43]
	v_mfma_i32_16x16x64_i8 v[24:27], v[160:163], v[212:215], v[24:27]
	v_mfma_i32_16x16x64_i8 v[24:27], v[164:167], v[216:219], v[24:27]
	v_mfma_i32_16x16x64_i8 v[8:11], v[164:167], v[224:227], v[8:11]
	v_mfma_i32_16x16x64_i8 v[8:11], v[160:163], v[220:223], v[8:11]
	v_mfma_i32_16x16x64_i8 v[4:7], v[168:171], v[220:223], v[4:7]
	v_mfma_i32_16x16x64_i8 v[4:7], v[178:181], v[224:227], v[4:7]
	v_mfma_i32_16x16x64_i8 v[20:23], v[178:181], v[216:219], v[20:23]
	v_mfma_i32_16x16x64_i8 v[20:23], v[168:171], v[212:215], v[20:23]
	v_mfma_i32_16x16x64_i8 v[36:39], v[168:171], v[204:207], v[36:39]
	v_mfma_i32_16x16x64_i8 v[36:39], v[178:181], v[208:211], v[36:39]
	v_mfma_i32_16x16x64_i8 v[52:55], v[178:181], v[186:189], v[52:55]
	v_mfma_i32_16x16x64_i8 v[52:55], v[168:171], v[182:185], v[52:55]
	s_barrier
	s_setprio 0
	s_add_i32 s76, s76, 2
	s_add_u32 s26, s26, 0x100
	s_addc_u32 s27, s27, 0
	s_add_u32 s72, s72, 0x100
	s_addc_u32 s73, s73, 0
	s_cmp_gt_u32 s76, 29
	s_cbranch_scc1 .Lkloop_exit_0
.LBB0_208:
	s_add_u32 s36, s26, 0xfff80080
	s_addc_u32 s37, s27, -1
	s_add_i32 s50, 0, 0x10000
	s_cmp_eq_u32 s76, 28
	s_cselect_b32 s41, s19, s37
	s_cselect_b32 s40, s64, s36
	s_cselect_b32 s37, s17, s73
	s_cselect_b32 s36, s65, s72
	s_add_i32 s56, 0, 0x14000
	v_add_u32_e32 v136, s50, v175
	v_add_u32_e32 v172, s56, v175
	ds_read_b128 v[116:119], v136
	ds_read_b128 v[124:127], v136 offset:1024
	ds_read_b128 v[132:135], v136 offset:2048
	ds_read_b128 v[136:139], v136 offset:3072
	ds_read_b128 v[160:163], v172
	ds_read_b128 v[164:167], v172 offset:1024
	ds_read_b128 v[168:171], v172 offset:2048
	ds_read_b128 v[178:181], v172 offset:3072
	v_lshl_add_u64 v[172:173], v[228:229], 0, s[84:85]
	s_mov_b32 m0, s52
	s_nop 0
	global_load_lds_dwordx4 v[172:173], off
	v_lshl_add_u64 v[172:173], v[240:241], 0, s[84:85]
	s_mov_b32 m0, s53
	s_nop 0
	global_load_lds_dwordx4 v[172:173], off
	s_add_i32 m0, s44, 0xc000
	ds_read_b128 v[182:185], v177
	ds_read_b128 v[186:189], v177 offset:1024
	ds_read_b128 v[204:207], v177 offset:2048
	ds_read_b128 v[208:211], v177 offset:3072
	ds_read_b128 v[212:215], v177 offset:4096
	ds_read_b128 v[216:219], v177 offset:5120
	ds_read_b128 v[220:223], v177 offset:6144
	ds_read_b128 v[224:227], v177 offset:7168
	global_load_lds_dwordx4 v156, s[26:27]
	s_add_i32 m0, s44, 0xe000
	s_nop 0
	global_load_lds_dwordx4 v158, s[26:27]
	s_waitcnt vmcnt(8) lgkmcnt(0)
	s_setprio 1
	s_barrier
	v_mfma_i32_16x16x64_i8 v[144:147], v[116:119], v[182:185], v[144:147]
	v_mfma_i32_16x16x64_i8 v[144:147], v[124:127], v[186:189], v[144:147]
	v_mfma_i32_16x16x64_i8 v[112:115], v[124:127], v[208:211], v[112:115]
	v_mfma_i32_16x16x64_i8 v[112:115], v[116:119], v[204:207], v[112:115]
	v_mfma_i32_16x16x64_i8 v[96:99], v[116:119], v[212:215], v[96:99]
	v_mfma_i32_16x16x64_i8 v[96:99], v[124:127], v[216:219], v[96:99]
	v_mfma_i32_16x16x64_i8 v[80:83], v[124:127], v[224:227], v[80:83]
	v_mfma_i32_16x16x64_i8 v[80:83], v[116:119], v[220:223], v[80:83]
	v_mfma_i32_16x16x64_i8 v[76:79], v[132:135], v[220:223], v[76:79]
	v_mfma_i32_16x16x64_i8 v[76:79], v[136:139], v[224:227], v[76:79]
	v_mfma_i32_16x16x64_i8 v[92:95], v[136:139], v[216:219], v[92:95]
	v_mfma_i32_16x16x64_i8 v[92:95], v[132:135], v[212:215], v[92:95]
	v_mfma_i32_16x16x64_i8 v[108:111], v[132:135], v[204:207], v[108:111]
	v_mfma_i32_16x16x64_i8 v[108:111], v[136:139], v[208:211], v[108:111]
	v_mfma_i32_16x16x64_i8 v[140:143], v[136:139], v[186:189], v[140:143]
	v_mfma_i32_16x16x64_i8 v[140:143], v[132:135], v[182:185], v[140:143]
	v_mfma_i32_16x16x64_i8 v[128:131], v[160:163], v[182:185], v[128:131]
	v_mfma_i32_16x16x64_i8 v[128:131], v[164:167], v[186:189], v[128:131]
	v_mfma_i32_16x16x64_i8 v[104:107], v[164:167], v[208:211], v[104:107]
	v_mfma_i32_16x16x64_i8 v[104:107], v[160:163], v[204:207], v[104:107]
	v_mfma_i32_16x16x64_i8 v[88:91], v[160:163], v[212:215], v[88:91]
	v_mfma_i32_16x16x64_i8 v[88:91], v[164:167], v[216:219], v[88:91]
	v_mfma_i32_16x16x64_i8 v[72:75], v[164:167], v[224:227], v[72:75]
	v_mfma_i32_16x16x64_i8 v[72:75], v[160:163], v[220:223], v[72:75]
	v_mfma_i32_16x16x64_i8 v[68:71], v[168:171], v[220:223], v[68:71]
	v_mfma_i32_16x16x64_i8 v[68:71], v[178:181], v[224:227], v[68:71]
	v_mfma_i32_16x16x64_i8 v[84:87], v[178:181], v[216:219], v[84:87]
	v_mfma_i32_16x16x64_i8 v[84:87], v[168:171], v[212:215], v[84:87]
	v_mfma_i32_16x16x64_i8 v[100:103], v[168:171], v[204:207], v[100:103]
	v_mfma_i32_16x16x64_i8 v[100:103], v[178:181], v[208:211], v[100:103]
	v_mfma_i32_16x16x64_i8 v[120:123], v[178:181], v[186:189], v[120:123]
	v_mfma_i32_16x16x64_i8 v[120:123], v[168:171], v[182:185], v[120:123]
	s_barrier
; #define PG8_STAGE(bufoff, gbase, voff) do { _Pragma("unroll") for (int _i = 0; _i < 2; ++_i) \
;         __builtin_amdgcn_global_load_lds((const unsigned*)((const char*)(gbase) + (voff)[_i]), (PG8_LAS unsigned*)(lds + (bufoff) + ldsw + _i * 8192), 16, 0, 0); } while (0)
; #define PG8_LDA(dst, b, h) do { _Pragma("unroll") for (int m = 0; m < 4; ++m) _Pragma("unroll") for (int k = 0; k < 2; ++k) dst[m][k] = *(const PG8_LAS bf16x8*)(lds + PG8_SA(b, h) + aoff + m * 2048 + k * 1024); } while (0)
; #define PG8_LDB(dst, b, h) do { _Pragma("unroll") for (int n = 0; n < 2; ++n) _Pragma("unroll") for (int k = 0; k < 2; ++k) dst[n][k] = *(const PG8_LAS bf16x8*)(lds + PG8_SB(b, h) + boff + n * 2048 + k * 1024); } while (0)
; #define PG8_WAIT_V(n) asm volatile("s_waitcnt vmcnt(" #n ")" ::: "memory")
; #define PG8_WAIT_L(n) asm volatile("s_waitcnt lgkmcnt(" #n ")" ::: "memory")
; #define PG8_BAR __builtin_amdgcn_s_barrier()
; #define PG8_SCHED __builtin_amdgcn_sched_barrier(0)
; template <class Epi, class Sched, bool ALIGN_EPI = false, bool SP2 = false, bool I8 = false>
; __device__ __forceinline__ void gemm_phase(PG8_LAS unsigned char* lds, const Gemm g, const Sched& S, const Epi& E) {
;     ...
;             PG8_LDB(B0, 0, 0); PG8_LDB(B1, 0, 1); PG8_SCHED; PG8_LDA(At, 0, 0); PG8_STAGE(PG8_SA(1, 1), a1 + hstep, voffA);
;             PG8_WAIT_V(8); PG8_WAIT_L(0); PG8_BAR; PG8_MMA(0, 0, At, B0); PG8_MMA(0, 1, At, B1); PG8_BAR; PG8_SCHED;
;             PG8_LDA(At, 0, 1); PG8_STAGE(PG8_SB(0, 0), b2, voffB); PG8_STAGE(PG8_SB(0, 1), b2 + hstep, voffB); PG8_STAGE(PG8_SA(0, 0), a2, voffA);
;             PG8_WAIT_V(8); PG8_WAIT_L(0); PG8_BAR; PG8_MMA(1, 0, At, B0); PG8_MMA(1, 1, At, B1); PG8_BAR; PG8_SCHED;
;             PG8_LDB(B0, 1, 0); PG8_LDB(B1, 1, 1); PG8_SCHED; PG8_LDA(At, 1, 0); PG8_STAGE(PG8_SA(0, 1), a2 + hstep, voffA);
;             PG8_WAIT_V(8); PG8_WAIT_L(0); PG8_BAR; PG8_MMA(0, 0, At, B0); PG8_MMA(0, 1, At, B1); PG8_BAR; PG8_SCHED;
;             PG8_LDA(At, 1, 1); PG8_STAGE(PG8_SB(1, 0), b3, voffB); PG8_STAGE(PG8_SB(1, 1), b3 + hstep, voffB); PG8_STAGE(PG8_SA(1, 0), a3, voffA);
;             PG8_WAIT_V(8); PG8_WAIT_L(0); PG8_BAR; PG8_MMA(1, 0, At, B0); PG8_MMA(1, 1, At, B1); PG8_BAR; PG8_SCHED;
	s_setprio 0
	s_add_i32 s50, s50, s43
	v_lshl_add_u64 v[172:173], s[36:37], 0, v[2:3]
	s_mov_b32 m0, s50
	ds_read_b128 v[182:185], v177 offset:16384
	ds_read_b128 v[186:189], v177 offset:17408
	ds_read_b128 v[204:207], v177 offset:18432
	ds_read_b128 v[208:211], v177 offset:19456
	ds_read_b128 v[212:215], v177 offset:20480
	ds_read_b128 v[216:219], v177 offset:21504
	ds_read_b128 v[220:223], v177 offset:22528
	ds_read_b128 v[224:227], v177 offset:23552
	global_load_lds_dwordx4 v[172:173], off
	s_add_i32 m0, s50, 0x2000
	s_add_u32 s50, s36, 0x80000
	v_lshl_add_u64 v[190:191], s[36:37], 0, v[148:149]
	s_addc_u32 s51, s37, 0
	s_add_i32 s56, s56, s43
	global_load_lds_dwordx4 v[190:191], off
	s_mov_b32 m0, s56
	v_lshl_add_u64 v[240:241], s[40:41], 0, v[150:151]
	global_load_lds_dwordx4 v2, s[50:51]
	s_add_i32 m0, s56, 0x2000
	s_nop 0
	global_load_lds_dwordx4 v148, s[50:51]
	v_lshl_add_u64 v[228:229], s[40:41], 0, v[152:153]
	s_waitcnt vmcnt(6) lgkmcnt(0)
	s_setprio 1
	s_barrier
	v_mfma_i32_16x16x64_i8 v[64:67], v[116:119], v[182:185], v[64:67]
	v_mfma_i32_16x16x64_i8 v[64:67], v[124:127], v[186:189], v[64:67]
	v_mfma_i32_16x16x64_i8 v[48:51], v[124:127], v[208:211], v[48:51]
	v_mfma_i32_16x16x64_i8 v[48:51], v[116:119], v[204:207], v[48:51]
	v_mfma_i32_16x16x64_i8 v[32:35], v[116:119], v[212:215], v[32:35]
	v_mfma_i32_16x16x64_i8 v[32:35], v[124:127], v[216:219], v[32:35]
	v_mfma_i32_16x16x64_i8 v[16:19], v[124:127], v[224:227], v[16:19]
	v_mfma_i32_16x16x64_i8 v[16:19], v[116:119], v[220:223], v[16:19]
	v_mfma_i32_16x16x64_i8 v[12:15], v[132:135], v[220:223], v[12:15]
	v_mfma_i32_16x16x64_i8 v[12:15], v[136:139], v[224:227], v[12:15]
	v_mfma_i32_16x16x64_i8 v[28:31], v[136:139], v[216:219], v[28:31]
	v_mfma_i32_16x16x64_i8 v[28:31], v[132:135], v[212:215], v[28:31]
	v_mfma_i32_16x16x64_i8 v[44:47], v[132:135], v[204:207], v[44:47]
	v_mfma_i32_16x16x64_i8 v[44:47], v[136:139], v[208:211], v[44:47]
	v_mfma_i32_16x16x64_i8 v[60:63], v[136:139], v[186:189], v[60:63]
	v_mfma_i32_16x16x64_i8 v[60:63], v[132:135], v[182:185], v[60:63]
	v_mfma_i32_16x16x64_i8 v[56:59], v[160:163], v[182:185], v[56:59]
	v_mfma_i32_16x16x64_i8 v[56:59], v[164:167], v[186:189], v[56:59]
	v_mfma_i32_16x16x64_i8 v[40:43], v[164:167], v[208:211], v[40:43]
	v_mfma_i32_16x16x64_i8 v[40:43], v[160:163], v[204:207], v[40:43]
	v_mfma_i32_16x16x64_i8 v[24:27], v[160:163], v[212:215], v[24:27]
	v_mfma_i32_16x16x64_i8 v[24:27], v[164:167], v[216:219], v[24:27]
	v_mfma_i32_16x16x64_i8 v[8:11], v[164:167], v[224:227], v[8:11]
	v_mfma_i32_16x16x64_i8 v[8:11], v[160:163], v[220:223], v[8:11]
	v_mfma_i32_16x16x64_i8 v[4:7], v[168:171], v[220:223], v[4:7]
	v_mfma_i32_16x16x64_i8 v[4:7], v[178:181], v[224:227], v[4:7]
	v_mfma_i32_16x16x64_i8 v[20:23], v[178:181], v[216:219], v[20:23]
	v_mfma_i32_16x16x64_i8 v[20:23], v[168:171], v[212:215], v[20:23]
	v_mfma_i32_16x16x64_i8 v[36:39], v[168:171], v[204:207], v[36:39]
	v_mfma_i32_16x16x64_i8 v[36:39], v[178:181], v[208:211], v[36:39]
	v_mfma_i32_16x16x64_i8 v[52:55], v[178:181], v[186:189], v[52:55]
	v_mfma_i32_16x16x64_i8 v[52:55], v[168:171], v[182:185], v[52:55]
	s_barrier
	s_setprio 0
	s_mov_b32 m0, s44
	s_nop 0
	global_load_lds_dwordx4 v[228:229], off
	s_mov_b32 m0, s45
	s_nop 0
	global_load_lds_dwordx4 v[240:241], off
	s_add_i32 s50, 0, 0x18000
	s_add_i32 s51, 0, 0x1c000
	v_add_u32_e32 v136, s50, v175
	v_add_u32_e32 v178, s51, v175
	ds_read_b128 v[116:119], v136
	ds_read_b128 v[124:127], v136 offset:1024
	ds_read_b128 v[132:135], v136 offset:2048
	ds_read_b128 v[136:139], v136 offset:3072
	ds_read_b128 v[160:163], v178
	ds_read_b128 v[164:167], v178 offset:1024
	ds_read_b128 v[168:171], v178 offset:2048
	ds_read_b128 v[178:181], v178 offset:3072
	s_add_u32 s40, s40, 0x80000
	s_addc_u32 s41, s41, 0
	s_mov_b32 m0, s46
	ds_read_b128 v[182:185], v177 offset:32768
	ds_read_b128 v[186:189], v177 offset:33792
	ds_read_b128 v[204:207], v177 offset:34816
	ds_read_b128 v[208:211], v177 offset:35840
	ds_read_b128 v[212:215], v177 offset:36864
	ds_read_b128 v[216:219], v177 offset:37888
	ds_read_b128 v[220:223], v177 offset:38912
	ds_read_b128 v[224:227], v177 offset:39936
	global_load_lds_dwordx4 v152, s[40:41]
	s_mov_b32 m0, s47
	s_nop 0
	global_load_lds_dwordx4 v150, s[40:41]
	s_waitcnt vmcnt(8) lgkmcnt(0)
	s_setprio 1
	s_barrier
; #define PG8_STAGE(bufoff, gbase, voff) do { _Pragma("unroll") for (int _i = 0; _i < 2; ++_i) \
;         __builtin_amdgcn_global_load_lds((const unsigned*)((const char*)(gbase) + (voff)[_i]), (PG8_LAS unsigned*)(lds + (bufoff) + ldsw + _i * 8192), 16, 0, 0); } while (0)
; #define PG8_LDA(dst, b, h) do { _Pragma("unroll") for (int m = 0; m < 4; ++m) _Pragma("unroll") for (int k = 0; k < 2; ++k) dst[m][k] = *(const PG8_LAS bf16x8*)(lds + PG8_SA(b, h) + aoff + m * 2048 + k * 1024); } while (0)
; #define PG8_LDB(dst, b, h) do { _Pragma("unroll") for (int n = 0; n < 2; ++n) _Pragma("unroll") for (int k = 0; k < 2; ++k) dst[n][k] = *(const PG8_LAS bf16x8*)(lds + PG8_SB(b, h) + boff + n * 2048 + k * 1024); } while (0)
; #define PG8_WAIT_V(n) asm volatile("s_waitcnt vmcnt(" #n ")" ::: "memory")
; #define PG8_WAIT_L(n) asm volatile("s_waitcnt lgkmcnt(" #n ")" ::: "memory")
; #define PG8_BAR __builtin_amdgcn_s_barrier()
; #define PG8_SCHED __builtin_amdgcn_sched_barrier(0)
; template <class Epi, class Sched, bool ALIGN_EPI = false, bool SP2 = false, bool I8 = false>
; __device__ __forceinline__ void gemm_phase(PG8_LAS unsigned char* lds, const Gemm g, const Sched& S, const Epi& E) {
;     ...
;             PG8_LDB(B0, 0, 0); PG8_LDB(B1, 0, 1); PG8_SCHED; PG8_LDA(At, 0, 0); PG8_STAGE(PG8_SA(1, 1), a1 + hstep, voffA);
;             PG8_WAIT_V(8); PG8_WAIT_L(0); PG8_BAR; PG8_MMA(0, 0, At, B0); PG8_MMA(0, 1, At, B1); PG8_BAR; PG8_SCHED;
;             PG8_LDA(At, 0, 1); PG8_STAGE(PG8_SB(0, 0), b2, voffB); PG8_STAGE(PG8_SB(0, 1), b2 + hstep, voffB); PG8_STAGE(PG8_SA(0, 0), a2, voffA);
;             PG8_WAIT_V(8); PG8_WAIT_L(0); PG8_BAR; PG8_MMA(1, 0, At, B0); PG8_MMA(1, 1, At, B1); PG8_BAR; PG8_SCHED;
;             PG8_LDB(B0, 1, 0); PG8_LDB(B1, 1, 1); PG8_SCHED; PG8_LDA(At, 1, 0); PG8_STAGE(PG8_SA(0, 1), a2 + hstep, voffA);
;             PG8_WAIT_V(8); PG8_WAIT_L(0); PG8_BAR; PG8_MMA(0, 0, At, B0); PG8_MMA(0, 1, At, B1); PG8_BAR; PG8_SCHED;
;             PG8_LDA(At, 1, 1); PG8_STAGE(PG8_SB(1, 0), b3, voffB); PG8_STAGE(PG8_SB(1, 1), b3 + hstep, voffB); PG8_STAGE(PG8_SA(1, 0), a3, voffA);
;             PG8_WAIT_V(8); PG8_WAIT_L(0); PG8_BAR; PG8_MMA(1, 0, At, B0); PG8_MMA(1, 1, At, B1); PG8_BAR; PG8_SCHED;
	v_mfma_i32_16x16x64_i8 v[144:147], v[116:119], v[182:185], v[144:147]
	v_mfma_i32_16x16x64_i8 v[144:147], v[124:127], v[186:189], v[144:147]
	v_mfma_i32_16x16x64_i8 v[112:115], v[124:127], v[208:211], v[112:115]
	v_mfma_i32_16x16x64_i8 v[112:115], v[116:119], v[204:207], v[112:115]
	v_mfma_i32_16x16x64_i8 v[96:99], v[116:119], v[212:215], v[96:99]
	v_mfma_i32_16x16x64_i8 v[96:99], v[124:127], v[216:219], v[96:99]
	v_mfma_i32_16x16x64_i8 v[80:83], v[124:127], v[224:227], v[80:83]
	v_mfma_i32_16x16x64_i8 v[80:83], v[116:119], v[220:223], v[80:83]
	v_mfma_i32_16x16x64_i8 v[76:79], v[132:135], v[220:223], v[76:79]
	v_mfma_i32_16x16x64_i8 v[76:79], v[136:139], v[224:227], v[76:79]
	v_mfma_i32_16x16x64_i8 v[92:95], v[136:139], v[216:219], v[92:95]
	v_mfma_i32_16x16x64_i8 v[92:95], v[132:135], v[212:215], v[92:95]
	v_mfma_i32_16x16x64_i8 v[108:111], v[132:135], v[204:207], v[108:111]
	v_mfma_i32_16x16x64_i8 v[108:111], v[136:139], v[208:211], v[108:111]
	v_mfma_i32_16x16x64_i8 v[140:143], v[136:139], v[186:189], v[140:143]
	v_mfma_i32_16x16x64_i8 v[140:143], v[132:135], v[182:185], v[140:143]
	v_mfma_i32_16x16x64_i8 v[128:131], v[160:163], v[182:185], v[128:131]
	v_mfma_i32_16x16x64_i8 v[128:131], v[164:167], v[186:189], v[128:131]
	v_mfma_i32_16x16x64_i8 v[104:107], v[164:167], v[208:211], v[104:107]
	v_mfma_i32_16x16x64_i8 v[104:107], v[160:163], v[204:207], v[104:107]
	v_mfma_i32_16x16x64_i8 v[88:91], v[160:163], v[212:215], v[88:91]
	v_mfma_i32_16x16x64_i8 v[88:91], v[164:167], v[216:219], v[88:91]
	v_mfma_i32_16x16x64_i8 v[72:75], v[164:167], v[224:227], v[72:75]
	v_mfma_i32_16x16x64_i8 v[72:75], v[160:163], v[220:223], v[72:75]
	v_mfma_i32_16x16x64_i8 v[68:71], v[168:171], v[220:223], v[68:71]
	v_mfma_i32_16x16x64_i8 v[68:71], v[178:181], v[224:227], v[68:71]
	v_mfma_i32_16x16x64_i8 v[84:87], v[178:181], v[216:219], v[84:87]
	v_mfma_i32_16x16x64_i8 v[84:87], v[168:171], v[212:215], v[84:87]
	v_mfma_i32_16x16x64_i8 v[100:103], v[168:171], v[204:207], v[100:103]
	v_mfma_i32_16x16x64_i8 v[100:103], v[178:181], v[208:211], v[100:103]
	v_mfma_i32_16x16x64_i8 v[120:123], v[178:181], v[186:189], v[120:123]
	v_mfma_i32_16x16x64_i8 v[120:123], v[168:171], v[182:185], v[120:123]
	s_barrier
	s_setprio 0
	s_add_i32 s40, s50, s43
	v_lshl_add_u64 v[172:173], v[172:173], 0, s[84:85]
	s_mov_b32 m0, s40
	ds_read_b128 v[182:185], v177 offset:49152
	ds_read_b128 v[186:189], v177 offset:50176
	ds_read_b128 v[204:207], v177 offset:51200
	ds_read_b128 v[208:211], v177 offset:52224
	ds_read_b128 v[212:215], v177 offset:53248
	ds_read_b128 v[216:219], v177 offset:54272
	ds_read_b128 v[220:223], v177 offset:55296
	ds_read_b128 v[224:227], v177 offset:56320
	global_load_lds_dwordx4 v[172:173], off
	s_add_i32 m0, s40, 0x2000
	s_add_u32 s36, s36, 0x80080
	v_lshl_add_u64 v[172:173], v[190:191], 0, s[84:85]
	s_addc_u32 s37, s37, 0
	s_add_i32 s40, s51, s43
	global_load_lds_dwordx4 v[172:173], off
	s_mov_b32 m0, s40
	s_nop 0
	global_load_lds_dwordx4 v2, s[36:37]
	s_add_i32 m0, s40, 0x2000
	s_nop 0
	global_load_lds_dwordx4 v148, s[36:37]
	s_cmp_eq_u32 s76, 28
	s_cbranch_scc0 .Ldefer_208_body
	v_lshl_add_u64 v[172:173], v[228:229], 0, s[84:85]
	s_mov_b32 m0, s52
	s_nop 0
	global_load_lds_dwordx4 v[172:173], off
	v_lshl_add_u64 v[172:173], v[240:241], 0, s[84:85]
	s_mov_b32 m0, s53
	s_nop 0
	global_load_lds_dwordx4 v[172:173], off
.Ldefer_208_body:
	s_waitcnt vmcnt(6) lgkmcnt(0)
	s_setprio 1
	s_barrier
	v_mfma_i32_16x16x64_i8 v[64:67], v[116:119], v[182:185], v[64:67]
	v_mfma_i32_16x16x64_i8 v[64:67], v[124:127], v[186:189], v[64:67]
	v_mfma_i32_16x16x64_i8 v[48:51], v[124:127], v[208:211], v[48:51]
	v_mfma_i32_16x16x64_i8 v[48:51], v[116:119], v[204:207], v[48:51]
	v_mfma_i32_16x16x64_i8 v[32:35], v[116:119], v[212:215], v[32:35]
	v_mfma_i32_16x16x64_i8 v[32:35], v[124:127], v[216:219], v[32:35]
	v_mfma_i32_16x16x64_i8 v[16:19], v[124:127], v[224:227], v[16:19]
	v_mfma_i32_16x16x64_i8 v[16:19], v[116:119], v[220:223], v[16:19]
	v_mfma_i32_16x16x64_i8 v[12:15], v[132:135], v[220:223], v[12:15]
	v_mfma_i32_16x16x64_i8 v[12:15], v[136:139], v[224:227], v[12:15]
	v_mfma_i32_16x16x64_i8 v[28:31], v[136:139], v[216:219], v[28:31]
	v_mfma_i32_16x16x64_i8 v[28:31], v[132:135], v[212:215], v[28:31]
	v_mfma_i32_16x16x64_i8 v[44:47], v[132:135], v[204:207], v[44:47]
	v_mfma_i32_16x16x64_i8 v[44:47], v[136:139], v[208:211], v[44:47]
	v_mfma_i32_16x16x64_i8 v[60:63], v[136:139], v[186:189], v[60:63]
	v_mfma_i32_16x16x64_i8 v[60:63], v[132:135], v[182:185], v[60:63]
	v_mfma_i32_16x16x64_i8 v[56:59], v[160:163], v[182:185], v[56:59]
	v_mfma_i32_16x16x64_i8 v[56:59], v[164:167], v[186:189], v[56:59]
	v_mfma_i32_16x16x64_i8 v[40:43], v[164:167], v[208:211], v[40:43]
	v_mfma_i32_16x16x64_i8 v[40:43], v[160:163], v[204:207], v[40:43]
	v_mfma_i32_16x16x64_i8 v[24:27], v[160:163], v[212:215], v[24:27]
	v_mfma_i32_16x16x64_i8 v[24:27], v[164:167], v[216:219], v[24:27]
	v_mfma_i32_16x16x64_i8 v[8:11], v[164:167], v[224:227], v[8:11]
	v_mfma_i32_16x16x64_i8 v[8:11], v[160:163], v[220:223], v[8:11]
	v_mfma_i32_16x16x64_i8 v[4:7], v[168:171], v[220:223], v[4:7]
	v_mfma_i32_16x16x64_i8 v[4:7], v[178:181], v[224:227], v[4:7]
	v_mfma_i32_16x16x64_i8 v[20:23], v[178:181], v[216:219], v[20:23]
	v_mfma_i32_16x16x64_i8 v[20:23], v[168:171], v[212:215], v[20:23]
	v_mfma_i32_16x16x64_i8 v[36:39], v[168:171], v[204:207], v[36:39]
	v_mfma_i32_16x16x64_i8 v[36:39], v[178:181], v[208:211], v[36:39]
	v_mfma_i32_16x16x64_i8 v[52:55], v[178:181], v[186:189], v[52:55]
	v_mfma_i32_16x16x64_i8 v[52:55], v[168:171], v[182:185], v[52:55]
	s_barrier
	s_setprio 0
	s_add_i32 s76, s76, 2
	s_add_u32 s26, s26, 0x100
	s_addc_u32 s27, s27, 0
	s_add_u32 s72, s72, 0x100
	s_addc_u32 s73, s73, 0
	s_cmp_gt_u32 s76, 29
	s_cbranch_scc0 .LBB0_208

; #define PG8_STAGE(bufoff, gbase, voff) do { _Pragma("unroll") for (int _i = 0; _i < 2; ++_i) \
;         __builtin_amdgcn_global_load_lds((const unsigned*)((const char*)(gbase) + (voff)[_i]), (PG8_LAS unsigned*)(lds + (bufoff) + ldsw + _i * 8192), 16, 0, 0); } while (0)
; #define PG8_LDA(dst, b, h) do { _Pragma("unroll") for (int m = 0; m < 4; ++m) _Pragma("unroll") for (int k = 0; k < 2; ++k) dst[m][k] = *(const PG8_LAS bf16x8*)(lds + PG8_SA(b, h) + aoff + m * 2048 + k * 1024); } while (0)
; #define PG8_LDB(dst, b, h) do { _Pragma("unroll") for (int n = 0; n < 2; ++n) _Pragma("unroll") for (int k = 0; k < 2; ++k) dst[n][k] = *(const PG8_LAS bf16x8*)(lds + PG8_SB(b, h) + boff + n * 2048 + k * 1024); } while (0)
; #define PG8_WAIT_V(n) asm volatile("s_waitcnt vmcnt(" #n ")" ::: "memory")
; #define PG8_WAIT_L(n) asm volatile("s_waitcnt lgkmcnt(" #n ")" ::: "memory")
; #define PG8_BAR __builtin_amdgcn_s_barrier()
; #define PG8_SCHED __builtin_amdgcn_sched_barrier(0)
; template <class Epi, class Sched, bool ALIGN_EPI = false, bool SP2 = false, bool I8 = false>
; __device__ __forceinline__ void gemm_phase(PG8_LAS unsigned char* lds, const Gemm g, const Sched& S, const Epi& E) {
;     ...
;         const bool has_next = S.next(ui + 1, nxt);
;         const char* nA = has_next ? (const char*)g.A + (size_t)nxt.pm * tstep : cA; const char* nB = has_next ? (const char*)g.Bt + (size_t)nxt.pn * tstep : cB;
;         for (int t = 0; t < nt; t += 2) {
;             const bool last = (t == nt - 2);
;             const char* a1 = cA + (size_t)(t + 1) * kstep;
;             const char* a2 = last ? nA : cA + (size_t)(t + 2) * kstep; const char* b2 = last ? nB : cB + (size_t)(t + 2) * kstep;
;             const char* a3 = a2 + kstep; const char* b3 = b2 + kstep;
;             if (last && has_next) S.a_ready(nxt);
;             if constexpr (SP2) {
;             PG8_LDB(B0, 0, 0); PG8_LDB(B1, 0, 1); PG8_SCHED; PG8_LDA(At, 0, 0); PG8_STAGE(PG8_SA(1, 1), a1 + hstep, voffA);
;             PG8_WAIT_V(8); PG8_WAIT_L(0); PG8_BAR; PG8_MMA(0, 0, At, B0); PG8_MMA(0, 1, At, B1); PG8_BAR; PG8_SCHED;
;             PG8_LDA(At, 0, 1); PG8_STAGE(PG8_SB(0, 0), b2, voffB); PG8_STAGE(PG8_SB(0, 1), b2 + hstep, voffB); PG8_STAGE(PG8_SA(0, 0), a2, voffA);
;             PG8_WAIT_V(8); PG8_WAIT_L(0); PG8_BAR; PG8_MMA(1, 0, At, B0); PG8_MMA(1, 1, At, B1); PG8_BAR; PG8_SCHED;
.LBB0_229:
	s_ashr_i32 s37, s36, 31
	s_lshl_b64 s[34:35], s[36:37], 21
	s_add_u32 s40, s42, s34
	s_addc_u32 s41, s43, s35
	s_and_b64 s[34:35], s[8:9], exec
	s_cselect_b32 s11, s41, s13
	s_cselect_b32 s34, s40, s12
	s_ashr_i32 s27, s26, 31
	s_lshl_b64 s[50:51], s[26:27], 21
	s_add_u32 s54, s44, s50
	s_addc_u32 s55, s45, s51
	s_and_b64 s[50:51], s[8:9], exec
	s_cselect_b32 s27, s55, s73
	s_cselect_b32 s35, s54, s72
	s_add_u32 s12, s12, 0x100080
	s_addc_u32 s13, s13, 0
	s_add_u32 s37, s72, 0x100
	s_addc_u32 s61, s73, 0
	s_mov_b32 s97, -2
	s_add_u32 s50, s12, 0xfff00080
	s_addc_u32 s51, s13, -1
	s_add_i32 s56, 0, 0x10000
	s_cmp_eq_u32 s97, 60
	s_cselect_b32 s77, s11, s51
	s_cselect_b32 s76, s34, s50
	s_cselect_b32 s73, s27, s61
	s_cselect_b32 s72, s35, s37
	s_add_i32 s57, 0, 0x14000
	v_add_u32_e32 v156, s56, v171
	v_add_u32_e32 v168, s57, v171
	s_waitcnt vmcnt(0)
	ds_read_b128 v[112:115], v156
	ds_read_b128 v[120:123], v156 offset:1024
	ds_read_b128 v[152:155], v156 offset:2048
	ds_read_b128 v[156:159], v156 offset:3072
	ds_read_b128 v[160:163], v168
	ds_read_b128 v[164:167], v168 offset:1024
	s_waitcnt lgkmcnt(0)
	ds_read_b128 v[176:179], v168 offset:2048
	ds_read_b128 v[180:183], v168 offset:3072
	s_add_i32 m0, s47, 0xc000
	ds_read_b128 v[184:187], v173
	ds_read_b128 v[188:191], v173 offset:1024
	ds_read_b128 v[204:207], v173 offset:2048
	ds_read_b128 v[208:211], v173 offset:3072
	ds_read_b128 v[212:215], v173 offset:4096
	ds_read_b128 v[216:219], v173 offset:5120
	ds_read_b128 v[220:223], v173 offset:6144
	ds_read_b128 v[224:227], v173 offset:7168
	global_load_lds_dwordx4 v148, s[12:13]
	s_add_i32 m0, s47, 0xe000
	s_nop 0
	global_load_lds_dwordx4 v150, s[12:13]
	s_waitcnt vmcnt(8) lgkmcnt(0)
	s_setprio 1
	s_barrier
	v_mfma_f32_16x16x32_bf16 v[136:139], v[112:115], v[184:187], 0
	v_mfma_f32_16x16x32_bf16 v[136:139], v[120:123], v[188:191], v[136:139]
	v_mfma_f32_16x16x32_bf16 v[116:119], v[120:123], v[208:211], 0
	v_mfma_f32_16x16x32_bf16 v[116:119], v[112:115], v[204:207], v[116:119]
	v_mfma_f32_16x16x32_bf16 v[96:99], v[112:115], v[212:215], 0
	v_mfma_f32_16x16x32_bf16 v[96:99], v[120:123], v[216:219], v[96:99]
	v_mfma_f32_16x16x32_bf16 v[80:83], v[120:123], v[224:227], 0
	v_mfma_f32_16x16x32_bf16 v[80:83], v[112:115], v[220:223], v[80:83]
	v_mfma_f32_16x16x32_bf16 v[76:79], v[152:155], v[220:223], 0
	v_mfma_f32_16x16x32_bf16 v[76:79], v[156:159], v[224:227], v[76:79]
	v_mfma_f32_16x16x32_bf16 v[92:95], v[156:159], v[216:219], 0
	v_mfma_f32_16x16x32_bf16 v[92:95], v[152:155], v[212:215], v[92:95]
	v_mfma_f32_16x16x32_bf16 v[108:111], v[152:155], v[204:207], 0
	v_mfma_f32_16x16x32_bf16 v[108:111], v[156:159], v[208:211], v[108:111]
	v_mfma_f32_16x16x32_bf16 v[132:135], v[156:159], v[188:191], 0
	v_mfma_f32_16x16x32_bf16 v[132:135], v[152:155], v[184:187], v[132:135]
	v_mfma_f32_16x16x32_bf16 v[128:131], v[160:163], v[184:187], 0
	v_mfma_f32_16x16x32_bf16 v[128:131], v[164:167], v[188:191], v[128:131]
	v_mfma_f32_16x16x32_bf16 v[104:107], v[164:167], v[208:211], 0
	v_mfma_f32_16x16x32_bf16 v[104:107], v[160:163], v[204:207], v[104:107]
	v_mfma_f32_16x16x32_bf16 v[88:91], v[160:163], v[212:215], 0
	v_mfma_f32_16x16x32_bf16 v[88:91], v[164:167], v[216:219], v[88:91]
	v_mfma_f32_16x16x32_bf16 v[72:75], v[164:167], v[224:227], 0
	v_mfma_f32_16x16x32_bf16 v[72:75], v[160:163], v[220:223], v[72:75]
	v_mfma_f32_16x16x32_bf16 v[68:71], v[176:179], v[220:223], 0
	v_mfma_f32_16x16x32_bf16 v[68:71], v[180:183], v[224:227], v[68:71]
	v_mfma_f32_16x16x32_bf16 v[84:87], v[180:183], v[216:219], 0
	v_mfma_f32_16x16x32_bf16 v[84:87], v[176:179], v[212:215], v[84:87]
	v_mfma_f32_16x16x32_bf16 v[100:103], v[176:179], v[204:207], 0
	v_mfma_f32_16x16x32_bf16 v[100:103], v[180:183], v[208:211], v[100:103]
	v_mfma_f32_16x16x32_bf16 v[124:127], v[180:183], v[188:191], 0
	v_mfma_f32_16x16x32_bf16 v[124:127], v[176:179], v[184:187], v[124:127]
	s_barrier
	s_setprio 0
	s_add_i32 s50, s56, s46
	v_lshl_add_u64 v[168:169], s[72:73], 0, v[2:3]
	s_mov_b32 m0, s50
	ds_read_b128 v[184:187], v173 offset:16384
	ds_read_b128 v[188:191], v173 offset:17408
	ds_read_b128 v[204:207], v173 offset:18432
	ds_read_b128 v[208:211], v173 offset:19456
	ds_read_b128 v[212:215], v173 offset:20480
	ds_read_b128 v[216:219], v173 offset:21504
	ds_read_b128 v[220:223], v173 offset:22528
	ds_read_b128 v[224:227], v173 offset:23552
	global_load_lds_dwordx4 v[168:169], off
	s_add_i32 m0, s50, 0x2000
	s_add_u32 s50, s72, 0x100000
	v_lshl_add_u64 v[228:229], s[72:73], 0, v[144:145]
	s_addc_u32 s51, s73, 0
	s_add_i32 s56, s57, s46
	global_load_lds_dwordx4 v[228:229], off
	s_mov_b32 m0, s56
	v_lshl_add_u64 v[242:243], s[76:77], 0, v[142:143]
	global_load_lds_dwordx4 v2, s[50:51]
	s_add_i32 m0, s56, 0x2000
	s_nop 0
	global_load_lds_dwordx4 v144, s[50:51]
	v_lshl_add_u64 v[240:241], s[76:77], 0, v[140:141]
	s_waitcnt vmcnt(6) lgkmcnt(0)
	s_setprio 1
	s_barrier
; #define PG8_STAGE(bufoff, gbase, voff) do { _Pragma("unroll") for (int _i = 0; _i < 2; ++_i) \
;         __builtin_amdgcn_global_load_lds((const unsigned*)((const char*)(gbase) + (voff)[_i]), (PG8_LAS unsigned*)(lds + (bufoff) + ldsw + _i * 8192), 16, 0, 0); } while (0)
; #define PG8_LDA(dst, b, h) do { _Pragma("unroll") for (int m = 0; m < 4; ++m) _Pragma("unroll") for (int k = 0; k < 2; ++k) dst[m][k] = *(const PG8_LAS bf16x8*)(lds + PG8_SA(b, h) + aoff + m * 2048 + k * 1024); } while (0)
; #define PG8_LDB(dst, b, h) do { _Pragma("unroll") for (int n = 0; n < 2; ++n) _Pragma("unroll") for (int k = 0; k < 2; ++k) dst[n][k] = *(const PG8_LAS bf16x8*)(lds + PG8_SB(b, h) + boff + n * 2048 + k * 1024); } while (0)
; #define PG8_WAIT_V(n) asm volatile("s_waitcnt vmcnt(" #n ")" ::: "memory")
; #define PG8_WAIT_L(n) asm volatile("s_waitcnt lgkmcnt(" #n ")" ::: "memory")
; #define PG8_BAR __builtin_amdgcn_s_barrier()
; #define PG8_SCHED __builtin_amdgcn_sched_barrier(0)
; template <class Epi, class Sched, bool ALIGN_EPI = false, bool SP2 = false, bool I8 = false>
; __device__ __forceinline__ void gemm_phase(PG8_LAS unsigned char* lds, const Gemm g, const Sched& S, const Epi& E) {
;     ...
;             PG8_LDB(B0, 0, 0); PG8_LDB(B1, 0, 1); PG8_SCHED; PG8_LDA(At, 0, 0); PG8_STAGE(PG8_SA(1, 1), a1 + hstep, voffA);
;             PG8_WAIT_V(8); PG8_WAIT_L(0); PG8_BAR; PG8_MMA(0, 0, At, B0); PG8_MMA(0, 1, At, B1); PG8_BAR; PG8_SCHED;
;             PG8_LDA(At, 0, 1); PG8_STAGE(PG8_SB(0, 0), b2, voffB); PG8_STAGE(PG8_SB(0, 1), b2 + hstep, voffB); PG8_STAGE(PG8_SA(0, 0), a2, voffA);
;             PG8_WAIT_V(8); PG8_WAIT_L(0); PG8_BAR; PG8_MMA(1, 0, At, B0); PG8_MMA(1, 1, At, B1); PG8_BAR; PG8_SCHED;
;             PG8_LDB(B0, 1, 0); PG8_LDB(B1, 1, 1); PG8_SCHED; PG8_LDA(At, 1, 0); PG8_STAGE(PG8_SA(0, 1), a2 + hstep, voffA);
;             PG8_WAIT_V(8); PG8_WAIT_L(0); PG8_BAR; PG8_MMA(0, 0, At, B0); PG8_MMA(0, 1, At, B1); PG8_BAR; PG8_SCHED;
;             PG8_LDA(At, 1, 1); PG8_STAGE(PG8_SB(1, 0), b3, voffB); PG8_STAGE(PG8_SB(1, 1), b3 + hstep, voffB); PG8_STAGE(PG8_SA(1, 0), a3, voffA);
;             PG8_WAIT_V(8); PG8_WAIT_L(0); PG8_BAR; PG8_MMA(1, 0, At, B0); PG8_MMA(1, 1, At, B1); PG8_BAR; PG8_SCHED;
	v_mfma_f32_16x16x32_bf16 v[64:67], v[112:115], v[184:187], 0
	v_mfma_f32_16x16x32_bf16 v[64:67], v[120:123], v[188:191], v[64:67]
	v_mfma_f32_16x16x32_bf16 v[48:51], v[120:123], v[208:211], 0
	v_mfma_f32_16x16x32_bf16 v[48:51], v[112:115], v[204:207], v[48:51]
	v_mfma_f32_16x16x32_bf16 v[32:35], v[112:115], v[212:215], 0
	v_mfma_f32_16x16x32_bf16 v[32:35], v[120:123], v[216:219], v[32:35]
	v_mfma_f32_16x16x32_bf16 v[16:19], v[120:123], v[224:227], 0
	v_mfma_f32_16x16x32_bf16 v[16:19], v[112:115], v[220:223], v[16:19]
	v_mfma_f32_16x16x32_bf16 v[12:15], v[152:155], v[220:223], 0
	v_mfma_f32_16x16x32_bf16 v[12:15], v[156:159], v[224:227], v[12:15]
	v_mfma_f32_16x16x32_bf16 v[28:31], v[156:159], v[216:219], 0
	v_mfma_f32_16x16x32_bf16 v[28:31], v[152:155], v[212:215], v[28:31]
	v_mfma_f32_16x16x32_bf16 v[44:47], v[152:155], v[204:207], 0
	v_mfma_f32_16x16x32_bf16 v[44:47], v[156:159], v[208:211], v[44:47]
	v_mfma_f32_16x16x32_bf16 v[60:63], v[156:159], v[188:191], 0
	v_mfma_f32_16x16x32_bf16 v[60:63], v[152:155], v[184:187], v[60:63]
	v_mfma_f32_16x16x32_bf16 v[56:59], v[160:163], v[184:187], 0
	v_mfma_f32_16x16x32_bf16 v[56:59], v[164:167], v[188:191], v[56:59]
	v_mfma_f32_16x16x32_bf16 v[40:43], v[164:167], v[208:211], 0
	v_mfma_f32_16x16x32_bf16 v[40:43], v[160:163], v[204:207], v[40:43]
	v_mfma_f32_16x16x32_bf16 v[24:27], v[160:163], v[212:215], 0
	v_mfma_f32_16x16x32_bf16 v[24:27], v[164:167], v[216:219], v[24:27]
	v_mfma_f32_16x16x32_bf16 v[8:11], v[164:167], v[224:227], 0
	v_mfma_f32_16x16x32_bf16 v[8:11], v[160:163], v[220:223], v[8:11]
	v_mfma_f32_16x16x32_bf16 v[4:7], v[176:179], v[220:223], 0
	v_mfma_f32_16x16x32_bf16 v[4:7], v[180:183], v[224:227], v[4:7]
	v_mfma_f32_16x16x32_bf16 v[20:23], v[180:183], v[216:219], 0
	v_mfma_f32_16x16x32_bf16 v[20:23], v[176:179], v[212:215], v[20:23]
	v_mfma_f32_16x16x32_bf16 v[36:39], v[176:179], v[204:207], 0
	v_mfma_f32_16x16x32_bf16 v[36:39], v[180:183], v[208:211], v[36:39]
	v_mfma_f32_16x16x32_bf16 v[52:55], v[180:183], v[188:191], 0
	v_mfma_f32_16x16x32_bf16 v[52:55], v[176:179], v[184:187], v[52:55]
	s_barrier
	s_setprio 0
	s_mov_b32 m0, s47
	s_nop 0
	global_load_lds_dwordx4 v[240:241], off
	s_mov_b32 m0, s52
	s_nop 0
	global_load_lds_dwordx4 v[242:243], off
	s_add_i32 s56, 0, 0x18000
	s_add_i32 s57, 0, 0x1c000
	v_add_u32_e32 v156, s56, v171
	v_add_u32_e32 v175, s57, v171
	ds_read_b128 v[112:115], v156
	ds_read_b128 v[120:123], v156 offset:1024
	ds_read_b128 v[152:155], v156 offset:2048
	ds_read_b128 v[156:159], v156 offset:3072
	ds_read_b128 v[160:163], v175
	ds_read_b128 v[164:167], v175 offset:1024
	ds_read_b128 v[176:179], v175 offset:2048
	ds_read_b128 v[180:183], v175 offset:3072
	s_add_u32 s50, s76, 0x100000
	s_addc_u32 s51, s77, 0
	s_mov_b32 m0, s53
	ds_read_b128 v[184:187], v173 offset:32768
	ds_read_b128 v[188:191], v173 offset:33792
	ds_read_b128 v[204:207], v173 offset:34816
	ds_read_b128 v[208:211], v173 offset:35840
	ds_read_b128 v[212:215], v173 offset:36864
	ds_read_b128 v[216:219], v173 offset:37888
	ds_read_b128 v[220:223], v173 offset:38912
	ds_read_b128 v[224:227], v173 offset:39936
	global_load_lds_dwordx4 v140, s[50:51]
	s_mov_b32 m0, s64
	s_nop 0
	global_load_lds_dwordx4 v142, s[50:51]
	s_waitcnt vmcnt(8) lgkmcnt(0)
	s_setprio 1
	s_barrier
	v_mfma_f32_16x16x32_bf16 v[136:139], v[112:115], v[184:187], v[136:139]
	v_mfma_f32_16x16x32_bf16 v[136:139], v[120:123], v[188:191], v[136:139]
	v_mfma_f32_16x16x32_bf16 v[116:119], v[120:123], v[208:211], v[116:119]
	v_mfma_f32_16x16x32_bf16 v[116:119], v[112:115], v[204:207], v[116:119]
	v_mfma_f32_16x16x32_bf16 v[96:99], v[112:115], v[212:215], v[96:99]
	v_mfma_f32_16x16x32_bf16 v[96:99], v[120:123], v[216:219], v[96:99]
	v_mfma_f32_16x16x32_bf16 v[80:83], v[120:123], v[224:227], v[80:83]
	v_mfma_f32_16x16x32_bf16 v[80:83], v[112:115], v[220:223], v[80:83]
	v_mfma_f32_16x16x32_bf16 v[76:79], v[152:155], v[220:223], v[76:79]
	v_mfma_f32_16x16x32_bf16 v[76:79], v[156:159], v[224:227], v[76:79]
	v_mfma_f32_16x16x32_bf16 v[92:95], v[156:159], v[216:219], v[92:95]
	v_mfma_f32_16x16x32_bf16 v[92:95], v[152:155], v[212:215], v[92:95]
	v_mfma_f32_16x16x32_bf16 v[108:111], v[152:155], v[204:207], v[108:111]
	v_mfma_f32_16x16x32_bf16 v[108:111], v[156:159], v[208:211], v[108:111]
	v_mfma_f32_16x16x32_bf16 v[132:135], v[156:159], v[188:191], v[132:135]
	v_mfma_f32_16x16x32_bf16 v[132:135], v[152:155], v[184:187], v[132:135]
	v_mfma_f32_16x16x32_bf16 v[128:131], v[160:163], v[184:187], v[128:131]
	v_mfma_f32_16x16x32_bf16 v[128:131], v[164:167], v[188:191], v[128:131]
	v_mfma_f32_16x16x32_bf16 v[104:107], v[164:167], v[208:211], v[104:107]
	v_mfma_f32_16x16x32_bf16 v[104:107], v[160:163], v[204:207], v[104:107]
	v_mfma_f32_16x16x32_bf16 v[88:91], v[160:163], v[212:215], v[88:91]
	v_mfma_f32_16x16x32_bf16 v[88:91], v[164:167], v[216:219], v[88:91]
	v_mfma_f32_16x16x32_bf16 v[72:75], v[164:167], v[224:227], v[72:75]
	v_mfma_f32_16x16x32_bf16 v[72:75], v[160:163], v[220:223], v[72:75]
	v_mfma_f32_16x16x32_bf16 v[68:71], v[176:179], v[220:223], v[68:71]
	v_mfma_f32_16x16x32_bf16 v[68:71], v[180:183], v[224:227], v[68:71]
	v_mfma_f32_16x16x32_bf16 v[84:87], v[180:183], v[216:219], v[84:87]
	v_mfma_f32_16x16x32_bf16 v[84:87], v[176:179], v[212:215], v[84:87]
	v_mfma_f32_16x16x32_bf16 v[100:103], v[176:179], v[204:207], v[100:103]
	v_mfma_f32_16x16x32_bf16 v[100:103], v[180:183], v[208:211], v[100:103]
	v_mfma_f32_16x16x32_bf16 v[124:127], v[180:183], v[188:191], v[124:127]
	v_mfma_f32_16x16x32_bf16 v[124:127], v[176:179], v[184:187], v[124:127]
	s_barrier
	s_setprio 0
	s_add_i32 s50, s56, s46
	v_lshl_add_u64 v[168:169], v[168:169], 0, s[84:85]
	s_mov_b32 m0, s50
	ds_read_b128 v[184:187], v173 offset:49152
	ds_read_b128 v[188:191], v173 offset:50176
	ds_read_b128 v[204:207], v173 offset:51200
	ds_read_b128 v[208:211], v173 offset:52224
	ds_read_b128 v[212:215], v173 offset:53248
	ds_read_b128 v[216:219], v173 offset:54272
	ds_read_b128 v[220:223], v173 offset:55296
	ds_read_b128 v[224:227], v173 offset:56320
	global_load_lds_dwordx4 v[168:169], off
	s_add_i32 m0, s50, 0x2000
	s_add_u32 s50, s72, 0x100080
	v_lshl_add_u64 v[168:169], v[228:229], 0, s[84:85]
	s_addc_u32 s51, s73, 0
	s_add_i32 s56, s57, s46
	global_load_lds_dwordx4 v[168:169], off
	s_mov_b32 m0, s56
	s_nop 0
	global_load_lds_dwordx4 v2, s[50:51]
	s_add_i32 m0, s56, 0x2000
	s_nop 0
	global_load_lds_dwordx4 v144, s[50:51]
	s_cmp_eq_u32 s97, 60
	s_cbranch_scc0 .Ldefer_230_peel
	v_lshl_add_u64 v[168:169], v[240:241], 0, s[84:85]
	s_mov_b32 m0, s28
	s_nop 0
	global_load_lds_dwordx4 v[168:169], off
	v_lshl_add_u64 v[168:169], v[242:243], 0, s[84:85]
	s_mov_b32 m0, s65
	s_nop 0
	global_load_lds_dwordx4 v[168:169], off
; #define PG8_STAGE(bufoff, gbase, voff) do { _Pragma("unroll") for (int _i = 0; _i < 2; ++_i) \
;         __builtin_amdgcn_global_load_lds((const unsigned*)((const char*)(gbase) + (voff)[_i]), (PG8_LAS unsigned*)(lds + (bufoff) + ldsw + _i * 8192), 16, 0, 0); } while (0)
; #define PG8_LDA(dst, b, h) do { _Pragma("unroll") for (int m = 0; m < 4; ++m) _Pragma("unroll") for (int k = 0; k < 2; ++k) dst[m][k] = *(const PG8_LAS bf16x8*)(lds + PG8_SA(b, h) + aoff + m * 2048 + k * 1024); } while (0)
; #define PG8_WAIT_V(n) asm volatile("s_waitcnt vmcnt(" #n ")" ::: "memory")
; #define PG8_WAIT_L(n) asm volatile("s_waitcnt lgkmcnt(" #n ")" ::: "memory")
; #define PG8_BAR __builtin_amdgcn_s_barrier()
; template <class Epi, class Sched, bool ALIGN_EPI = false, bool SP2 = false, bool I8 = false>
; __device__ __forceinline__ void gemm_phase(PG8_LAS unsigned char* lds, const Gemm g, const Sched& S, const Epi& E) {
;     ...
;         for (int t = 0; t < nt; t += 2) {
;             const bool last = (t == nt - 2);
;             const char* a1 = cA + (size_t)(t + 1) * kstep;
;             const char* a2 = last ? nA : cA + (size_t)(t + 2) * kstep; const char* b2 = last ? nB : cB + (size_t)(t + 2) * kstep;
;             const char* a3 = a2 + kstep; const char* b3 = b2 + kstep;
;             if (last && has_next) S.a_ready(nxt);
;             if constexpr (SP2) {
;             PG8_LDB(B0, 0, 0); PG8_LDB(B1, 0, 1); PG8_SCHED; PG8_LDA(At, 0, 0); PG8_STAGE(PG8_SA(1, 1), a1 + hstep, voffA);
;             PG8_WAIT_V(8); PG8_WAIT_L(0); PG8_BAR; PG8_MMA(0, 0, At, B0); PG8_MMA(0, 1, At, B1); PG8_BAR; PG8_SCHED;
;             PG8_LDA(At, 0, 1); PG8_STAGE(PG8_SB(0, 0), b2, voffB); PG8_STAGE(PG8_SB(0, 1), b2 + hstep, voffB); PG8_STAGE(PG8_SA(0, 0), a2, voffA);
;             PG8_WAIT_V(8); PG8_WAIT_L(0); PG8_BAR; PG8_MMA(1, 0, At, B0); PG8_MMA(1, 1, At, B1); PG8_BAR; PG8_SCHED;
;             PG8_LDB(B0, 1, 0); PG8_LDB(B1, 1, 1); PG8_SCHED; PG8_LDA(At, 1, 0); PG8_STAGE(PG8_SA(0, 1), a2 + hstep, voffA);
;             PG8_WAIT_V(8); PG8_WAIT_L(0); PG8_BAR; PG8_MMA(0, 0, At, B0); PG8_MMA(0, 1, At, B1); PG8_BAR; PG8_SCHED;
;             PG8_LDA(At, 1, 1); PG8_STAGE(PG8_SB(1, 0), b3, voffB); PG8_STAGE(PG8_SB(1, 1), b3 + hstep, voffB); PG8_STAGE(PG8_SA(1, 0), a3, voffA);
;             PG8_WAIT_V(8); PG8_WAIT_L(0); PG8_BAR; PG8_MMA(1, 0, At, B0); PG8_MMA(1, 1, At, B1); PG8_BAR; PG8_SCHED;
.Ldefer_230_peel:
	s_waitcnt vmcnt(6) lgkmcnt(0)
	s_setprio 1
	s_barrier
	v_mfma_f32_16x16x32_bf16 v[64:67], v[112:115], v[184:187], v[64:67]
	v_mfma_f32_16x16x32_bf16 v[64:67], v[120:123], v[188:191], v[64:67]
	v_mfma_f32_16x16x32_bf16 v[48:51], v[120:123], v[208:211], v[48:51]
	v_mfma_f32_16x16x32_bf16 v[48:51], v[112:115], v[204:207], v[48:51]
	v_mfma_f32_16x16x32_bf16 v[32:35], v[112:115], v[212:215], v[32:35]
	v_mfma_f32_16x16x32_bf16 v[32:35], v[120:123], v[216:219], v[32:35]
	v_mfma_f32_16x16x32_bf16 v[16:19], v[120:123], v[224:227], v[16:19]
	v_mfma_f32_16x16x32_bf16 v[16:19], v[112:115], v[220:223], v[16:19]
	v_mfma_f32_16x16x32_bf16 v[12:15], v[152:155], v[220:223], v[12:15]
	v_mfma_f32_16x16x32_bf16 v[12:15], v[156:159], v[224:227], v[12:15]
	v_mfma_f32_16x16x32_bf16 v[28:31], v[156:159], v[216:219], v[28:31]
	v_mfma_f32_16x16x32_bf16 v[28:31], v[152:155], v[212:215], v[28:31]
	v_mfma_f32_16x16x32_bf16 v[44:47], v[152:155], v[204:207], v[44:47]
	v_mfma_f32_16x16x32_bf16 v[44:47], v[156:159], v[208:211], v[44:47]
	v_mfma_f32_16x16x32_bf16 v[60:63], v[156:159], v[188:191], v[60:63]
	v_mfma_f32_16x16x32_bf16 v[60:63], v[152:155], v[184:187], v[60:63]
	v_mfma_f32_16x16x32_bf16 v[56:59], v[160:163], v[184:187], v[56:59]
	v_mfma_f32_16x16x32_bf16 v[56:59], v[164:167], v[188:191], v[56:59]
	v_mfma_f32_16x16x32_bf16 v[40:43], v[164:167], v[208:211], v[40:43]
	v_mfma_f32_16x16x32_bf16 v[40:43], v[160:163], v[204:207], v[40:43]
	v_mfma_f32_16x16x32_bf16 v[24:27], v[160:163], v[212:215], v[24:27]
	v_mfma_f32_16x16x32_bf16 v[24:27], v[164:167], v[216:219], v[24:27]
	v_mfma_f32_16x16x32_bf16 v[8:11], v[164:167], v[224:227], v[8:11]
	v_mfma_f32_16x16x32_bf16 v[8:11], v[160:163], v[220:223], v[8:11]
	v_mfma_f32_16x16x32_bf16 v[4:7], v[176:179], v[220:223], v[4:7]
	v_mfma_f32_16x16x32_bf16 v[4:7], v[180:183], v[224:227], v[4:7]
	v_mfma_f32_16x16x32_bf16 v[20:23], v[180:183], v[216:219], v[20:23]
	v_mfma_f32_16x16x32_bf16 v[20:23], v[176:179], v[212:215], v[20:23]
	v_mfma_f32_16x16x32_bf16 v[36:39], v[176:179], v[204:207], v[36:39]
	v_mfma_f32_16x16x32_bf16 v[36:39], v[180:183], v[208:211], v[36:39]
	v_mfma_f32_16x16x32_bf16 v[52:55], v[180:183], v[188:191], v[52:55]
	v_mfma_f32_16x16x32_bf16 v[52:55], v[176:179], v[184:187], v[52:55]
	s_barrier
	s_setprio 0
	s_add_i32 s97, s97, 2
	s_add_u32 s12, s12, 0x100
	s_addc_u32 s13, s13, 0
	s_add_u32 s37, s37, 0x100
	s_addc_u32 s61, s61, 0
	s_cmp_gt_u32 s97, 61
	s_cbranch_scc1 .Lkloop_exit_1
.LBB0_230:
	s_add_u32 s50, s12, 0xfff00080
	s_addc_u32 s51, s13, -1
	s_add_i32 s56, 0, 0x10000
	s_cmp_eq_u32 s97, 60
	s_cselect_b32 s77, s11, s51
	s_cselect_b32 s76, s34, s50
	s_cselect_b32 s73, s27, s61
	s_cselect_b32 s72, s35, s37
	s_add_i32 s57, 0, 0x14000
	v_add_u32_e32 v156, s56, v171
	v_add_u32_e32 v168, s57, v171
	ds_read_b128 v[112:115], v156
	ds_read_b128 v[120:123], v156 offset:1024
	ds_read_b128 v[152:155], v156 offset:2048
	ds_read_b128 v[156:159], v156 offset:3072
	ds_read_b128 v[160:163], v168
	ds_read_b128 v[164:167], v168 offset:1024
	ds_read_b128 v[176:179], v168 offset:2048
	ds_read_b128 v[180:183], v168 offset:3072
	v_lshl_add_u64 v[168:169], v[240:241], 0, s[84:85]
	s_mov_b32 m0, s28
	s_nop 0
	global_load_lds_dwordx4 v[168:169], off
	v_lshl_add_u64 v[168:169], v[242:243], 0, s[84:85]
	s_mov_b32 m0, s65
	s_nop 0
	global_load_lds_dwordx4 v[168:169], off
	s_add_i32 m0, s47, 0xc000
	ds_read_b128 v[184:187], v173
	ds_read_b128 v[188:191], v173 offset:1024
	ds_read_b128 v[204:207], v173 offset:2048
	ds_read_b128 v[208:211], v173 offset:3072
	ds_read_b128 v[212:215], v173 offset:4096
	ds_read_b128 v[216:219], v173 offset:5120
	ds_read_b128 v[220:223], v173 offset:6144
	ds_read_b128 v[224:227], v173 offset:7168
	global_load_lds_dwordx4 v148, s[12:13]
	s_add_i32 m0, s47, 0xe000
	s_nop 0
	global_load_lds_dwordx4 v150, s[12:13]
	s_waitcnt vmcnt(8) lgkmcnt(0)
	s_setprio 1
	s_barrier
	v_mfma_f32_16x16x32_bf16 v[136:139], v[112:115], v[184:187], v[136:139]
	v_mfma_f32_16x16x32_bf16 v[136:139], v[120:123], v[188:191], v[136:139]
	v_mfma_f32_16x16x32_bf16 v[116:119], v[120:123], v[208:211], v[116:119]
	v_mfma_f32_16x16x32_bf16 v[116:119], v[112:115], v[204:207], v[116:119]
	v_mfma_f32_16x16x32_bf16 v[96:99], v[112:115], v[212:215], v[96:99]
	v_mfma_f32_16x16x32_bf16 v[96:99], v[120:123], v[216:219], v[96:99]
	v_mfma_f32_16x16x32_bf16 v[80:83], v[120:123], v[224:227], v[80:83]
	v_mfma_f32_16x16x32_bf16 v[80:83], v[112:115], v[220:223], v[80:83]
	v_mfma_f32_16x16x32_bf16 v[76:79], v[152:155], v[220:223], v[76:79]
	v_mfma_f32_16x16x32_bf16 v[76:79], v[156:159], v[224:227], v[76:79]
	v_mfma_f32_16x16x32_bf16 v[92:95], v[156:159], v[216:219], v[92:95]
	v_mfma_f32_16x16x32_bf16 v[92:95], v[152:155], v[212:215], v[92:95]
	v_mfma_f32_16x16x32_bf16 v[108:111], v[152:155], v[204:207], v[108:111]
	v_mfma_f32_16x16x32_bf16 v[108:111], v[156:159], v[208:211], v[108:111]
	v_mfma_f32_16x16x32_bf16 v[132:135], v[156:159], v[188:191], v[132:135]
	v_mfma_f32_16x16x32_bf16 v[132:135], v[152:155], v[184:187], v[132:135]
	v_mfma_f32_16x16x32_bf16 v[128:131], v[160:163], v[184:187], v[128:131]
	v_mfma_f32_16x16x32_bf16 v[128:131], v[164:167], v[188:191], v[128:131]
	v_mfma_f32_16x16x32_bf16 v[104:107], v[164:167], v[208:211], v[104:107]
	v_mfma_f32_16x16x32_bf16 v[104:107], v[160:163], v[204:207], v[104:107]
	v_mfma_f32_16x16x32_bf16 v[88:91], v[160:163], v[212:215], v[88:91]
	v_mfma_f32_16x16x32_bf16 v[88:91], v[164:167], v[216:219], v[88:91]
	v_mfma_f32_16x16x32_bf16 v[72:75], v[164:167], v[224:227], v[72:75]
	v_mfma_f32_16x16x32_bf16 v[72:75], v[160:163], v[220:223], v[72:75]
	v_mfma_f32_16x16x32_bf16 v[68:71], v[176:179], v[220:223], v[68:71]
	v_mfma_f32_16x16x32_bf16 v[68:71], v[180:183], v[224:227], v[68:71]
	v_mfma_f32_16x16x32_bf16 v[84:87], v[180:183], v[216:219], v[84:87]
	v_mfma_f32_16x16x32_bf16 v[84:87], v[176:179], v[212:215], v[84:87]
	v_mfma_f32_16x16x32_bf16 v[100:103], v[176:179], v[204:207], v[100:103]
	v_mfma_f32_16x16x32_bf16 v[100:103], v[180:183], v[208:211], v[100:103]
	v_mfma_f32_16x16x32_bf16 v[124:127], v[180:183], v[188:191], v[124:127]
	v_mfma_f32_16x16x32_bf16 v[124:127], v[176:179], v[184:187], v[124:127]
	s_barrier
; #define PG8_STAGE(bufoff, gbase, voff) do { _Pragma("unroll") for (int _i = 0; _i < 2; ++_i) \
;         __builtin_amdgcn_global_load_lds((const unsigned*)((const char*)(gbase) + (voff)[_i]), (PG8_LAS unsigned*)(lds + (bufoff) + ldsw + _i * 8192), 16, 0, 0); } while (0)
; #define PG8_LDA(dst, b, h) do { _Pragma("unroll") for (int m = 0; m < 4; ++m) _Pragma("unroll") for (int k = 0; k < 2; ++k) dst[m][k] = *(const PG8_LAS bf16x8*)(lds + PG8_SA(b, h) + aoff + m * 2048 + k * 1024); } while (0)
; #define PG8_LDB(dst, b, h) do { _Pragma("unroll") for (int n = 0; n < 2; ++n) _Pragma("unroll") for (int k = 0; k < 2; ++k) dst[n][k] = *(const PG8_LAS bf16x8*)(lds + PG8_SB(b, h) + boff + n * 2048 + k * 1024); } while (0)
; #define PG8_WAIT_V(n) asm volatile("s_waitcnt vmcnt(" #n ")" ::: "memory")
; #define PG8_WAIT_L(n) asm volatile("s_waitcnt lgkmcnt(" #n ")" ::: "memory")
; #define PG8_BAR __builtin_amdgcn_s_barrier()
; #define PG8_SCHED __builtin_amdgcn_sched_barrier(0)
; template <class Epi, class Sched, bool ALIGN_EPI = false, bool SP2 = false, bool I8 = false>
; __device__ __forceinline__ void gemm_phase(PG8_LAS unsigned char* lds, const Gemm g, const Sched& S, const Epi& E) {
;     ...
;             PG8_LDB(B0, 0, 0); PG8_LDB(B1, 0, 1); PG8_SCHED; PG8_LDA(At, 0, 0); PG8_STAGE(PG8_SA(1, 1), a1 + hstep, voffA);
;             PG8_WAIT_V(8); PG8_WAIT_L(0); PG8_BAR; PG8_MMA(0, 0, At, B0); PG8_MMA(0, 1, At, B1); PG8_BAR; PG8_SCHED;
;             PG8_LDA(At, 0, 1); PG8_STAGE(PG8_SB(0, 0), b2, voffB); PG8_STAGE(PG8_SB(0, 1), b2 + hstep, voffB); PG8_STAGE(PG8_SA(0, 0), a2, voffA);
;             PG8_WAIT_V(8); PG8_WAIT_L(0); PG8_BAR; PG8_MMA(1, 0, At, B0); PG8_MMA(1, 1, At, B1); PG8_BAR; PG8_SCHED;
;             PG8_LDB(B0, 1, 0); PG8_LDB(B1, 1, 1); PG8_SCHED; PG8_LDA(At, 1, 0); PG8_STAGE(PG8_SA(0, 1), a2 + hstep, voffA);
;             PG8_WAIT_V(8); PG8_WAIT_L(0); PG8_BAR; PG8_MMA(0, 0, At, B0); PG8_MMA(0, 1, At, B1); PG8_BAR; PG8_SCHED;
;             PG8_LDA(At, 1, 1); PG8_STAGE(PG8_SB(1, 0), b3, voffB); PG8_STAGE(PG8_SB(1, 1), b3 + hstep, voffB); PG8_STAGE(PG8_SA(1, 0), a3, voffA);
;             PG8_WAIT_V(8); PG8_WAIT_L(0); PG8_BAR; PG8_MMA(1, 0, At, B0); PG8_MMA(1, 1, At, B1); PG8_BAR; PG8_SCHED;
	s_setprio 0
	s_add_i32 s50, s56, s46
	v_lshl_add_u64 v[168:169], s[72:73], 0, v[2:3]
	s_mov_b32 m0, s50
	ds_read_b128 v[184:187], v173 offset:16384
	ds_read_b128 v[188:191], v173 offset:17408
	ds_read_b128 v[204:207], v173 offset:18432
	ds_read_b128 v[208:211], v173 offset:19456
	ds_read_b128 v[212:215], v173 offset:20480
	ds_read_b128 v[216:219], v173 offset:21504
	ds_read_b128 v[220:223], v173 offset:22528
	ds_read_b128 v[224:227], v173 offset:23552
	global_load_lds_dwordx4 v[168:169], off
	s_add_i32 m0, s50, 0x2000
	s_add_u32 s50, s72, 0x100000
	v_lshl_add_u64 v[228:229], s[72:73], 0, v[144:145]
	s_addc_u32 s51, s73, 0
	s_add_i32 s56, s57, s46
	global_load_lds_dwordx4 v[228:229], off
	s_mov_b32 m0, s56
	v_lshl_add_u64 v[242:243], s[76:77], 0, v[142:143]
	global_load_lds_dwordx4 v2, s[50:51]
	s_add_i32 m0, s56, 0x2000
	s_nop 0
	global_load_lds_dwordx4 v144, s[50:51]
	v_lshl_add_u64 v[240:241], s[76:77], 0, v[140:141]
	s_waitcnt vmcnt(6) lgkmcnt(0)
	s_setprio 1
	s_barrier
	v_mfma_f32_16x16x32_bf16 v[64:67], v[112:115], v[184:187], v[64:67]
	v_mfma_f32_16x16x32_bf16 v[64:67], v[120:123], v[188:191], v[64:67]
	v_mfma_f32_16x16x32_bf16 v[48:51], v[120:123], v[208:211], v[48:51]
	v_mfma_f32_16x16x32_bf16 v[48:51], v[112:115], v[204:207], v[48:51]
	v_mfma_f32_16x16x32_bf16 v[32:35], v[112:115], v[212:215], v[32:35]
	v_mfma_f32_16x16x32_bf16 v[32:35], v[120:123], v[216:219], v[32:35]
	v_mfma_f32_16x16x32_bf16 v[16:19], v[120:123], v[224:227], v[16:19]
	v_mfma_f32_16x16x32_bf16 v[16:19], v[112:115], v[220:223], v[16:19]
	v_mfma_f32_16x16x32_bf16 v[12:15], v[152:155], v[220:223], v[12:15]
	v_mfma_f32_16x16x32_bf16 v[12:15], v[156:159], v[224:227], v[12:15]
	v_mfma_f32_16x16x32_bf16 v[28:31], v[156:159], v[216:219], v[28:31]
	v_mfma_f32_16x16x32_bf16 v[28:31], v[152:155], v[212:215], v[28:31]
	v_mfma_f32_16x16x32_bf16 v[44:47], v[152:155], v[204:207], v[44:47]
	v_mfma_f32_16x16x32_bf16 v[44:47], v[156:159], v[208:211], v[44:47]
	v_mfma_f32_16x16x32_bf16 v[60:63], v[156:159], v[188:191], v[60:63]
	v_mfma_f32_16x16x32_bf16 v[60:63], v[152:155], v[184:187], v[60:63]
	v_mfma_f32_16x16x32_bf16 v[56:59], v[160:163], v[184:187], v[56:59]
	v_mfma_f32_16x16x32_bf16 v[56:59], v[164:167], v[188:191], v[56:59]
	v_mfma_f32_16x16x32_bf16 v[40:43], v[164:167], v[208:211], v[40:43]
	v_mfma_f32_16x16x32_bf16 v[40:43], v[160:163], v[204:207], v[40:43]
	v_mfma_f32_16x16x32_bf16 v[24:27], v[160:163], v[212:215], v[24:27]
	v_mfma_f32_16x16x32_bf16 v[24:27], v[164:167], v[216:219], v[24:27]
	v_mfma_f32_16x16x32_bf16 v[8:11], v[164:167], v[224:227], v[8:11]
	v_mfma_f32_16x16x32_bf16 v[8:11], v[160:163], v[220:223], v[8:11]
	v_mfma_f32_16x16x32_bf16 v[4:7], v[176:179], v[220:223], v[4:7]
	v_mfma_f32_16x16x32_bf16 v[4:7], v[180:183], v[224:227], v[4:7]
	v_mfma_f32_16x16x32_bf16 v[20:23], v[180:183], v[216:219], v[20:23]
	v_mfma_f32_16x16x32_bf16 v[20:23], v[176:179], v[212:215], v[20:23]
	v_mfma_f32_16x16x32_bf16 v[36:39], v[176:179], v[204:207], v[36:39]
	v_mfma_f32_16x16x32_bf16 v[36:39], v[180:183], v[208:211], v[36:39]
	v_mfma_f32_16x16x32_bf16 v[52:55], v[180:183], v[188:191], v[52:55]
	v_mfma_f32_16x16x32_bf16 v[52:55], v[176:179], v[184:187], v[52:55]
	s_barrier
	s_setprio 0
	s_mov_b32 m0, s47
	s_nop 0
	global_load_lds_dwordx4 v[240:241], off
	s_mov_b32 m0, s52
	s_nop 0
	global_load_lds_dwordx4 v[242:243], off
	s_add_i32 s56, 0, 0x18000
	s_add_i32 s57, 0, 0x1c000
	v_add_u32_e32 v156, s56, v171
	v_add_u32_e32 v175, s57, v171
	ds_read_b128 v[112:115], v156
	ds_read_b128 v[120:123], v156 offset:1024
	ds_read_b128 v[152:155], v156 offset:2048
	ds_read_b128 v[156:159], v156 offset:3072
	ds_read_b128 v[160:163], v175
	ds_read_b128 v[164:167], v175 offset:1024
	ds_read_b128 v[176:179], v175 offset:2048
	ds_read_b128 v[180:183], v175 offset:3072
	s_add_u32 s50, s76, 0x100000
	s_addc_u32 s51, s77, 0
	s_mov_b32 m0, s53
	ds_read_b128 v[184:187], v173 offset:32768
	ds_read_b128 v[188:191], v173 offset:33792
	ds_read_b128 v[204:207], v173 offset:34816
	ds_read_b128 v[208:211], v173 offset:35840
	ds_read_b128 v[212:215], v173 offset:36864
	ds_read_b128 v[216:219], v173 offset:37888
	ds_read_b128 v[220:223], v173 offset:38912
	ds_read_b128 v[224:227], v173 offset:39936
	global_load_lds_dwordx4 v140, s[50:51]
	s_mov_b32 m0, s64
	s_nop 0
	global_load_lds_dwordx4 v142, s[50:51]
	s_waitcnt vmcnt(8) lgkmcnt(0)
	s_setprio 1
	s_barrier
; #define PG8_STAGE(bufoff, gbase, voff) do { _Pragma("unroll") for (int _i = 0; _i < 2; ++_i) \
;         __builtin_amdgcn_global_load_lds((const unsigned*)((const char*)(gbase) + (voff)[_i]), (PG8_LAS unsigned*)(lds + (bufoff) + ldsw + _i * 8192), 16, 0, 0); } while (0)
; #define PG8_LDA(dst, b, h) do { _Pragma("unroll") for (int m = 0; m < 4; ++m) _Pragma("unroll") for (int k = 0; k < 2; ++k) dst[m][k] = *(const PG8_LAS bf16x8*)(lds + PG8_SA(b, h) + aoff + m * 2048 + k * 1024); } while (0)
; #define PG8_LDB(dst, b, h) do { _Pragma("unroll") for (int n = 0; n < 2; ++n) _Pragma("unroll") for (int k = 0; k < 2; ++k) dst[n][k] = *(const PG8_LAS bf16x8*)(lds + PG8_SB(b, h) + boff + n * 2048 + k * 1024); } while (0)
; #define PG8_WAIT_V(n) asm volatile("s_waitcnt vmcnt(" #n ")" ::: "memory")
; #define PG8_WAIT_L(n) asm volatile("s_waitcnt lgkmcnt(" #n ")" ::: "memory")
; #define PG8_BAR __builtin_amdgcn_s_barrier()
; #define PG8_SCHED __builtin_amdgcn_sched_barrier(0)
; template <class Epi, class Sched, bool ALIGN_EPI = false, bool SP2 = false, bool I8 = false>
; __device__ __forceinline__ void gemm_phase(PG8_LAS unsigned char* lds, const Gemm g, const Sched& S, const Epi& E) {
;     ...
;             PG8_LDB(B0, 0, 0); PG8_LDB(B1, 0, 1); PG8_SCHED; PG8_LDA(At, 0, 0); PG8_STAGE(PG8_SA(1, 1), a1 + hstep, voffA);
;             PG8_WAIT_V(8); PG8_WAIT_L(0); PG8_BAR; PG8_MMA(0, 0, At, B0); PG8_MMA(0, 1, At, B1); PG8_BAR; PG8_SCHED;
;             PG8_LDA(At, 0, 1); PG8_STAGE(PG8_SB(0, 0), b2, voffB); PG8_STAGE(PG8_SB(0, 1), b2 + hstep, voffB); PG8_STAGE(PG8_SA(0, 0), a2, voffA);
;             PG8_WAIT_V(8); PG8_WAIT_L(0); PG8_BAR; PG8_MMA(1, 0, At, B0); PG8_MMA(1, 1, At, B1); PG8_BAR; PG8_SCHED;
;             PG8_LDB(B0, 1, 0); PG8_LDB(B1, 1, 1); PG8_SCHED; PG8_LDA(At, 1, 0); PG8_STAGE(PG8_SA(0, 1), a2 + hstep, voffA);
;             PG8_WAIT_V(8); PG8_WAIT_L(0); PG8_BAR; PG8_MMA(0, 0, At, B0); PG8_MMA(0, 1, At, B1); PG8_BAR; PG8_SCHED;
;             PG8_LDA(At, 1, 1); PG8_STAGE(PG8_SB(1, 0), b3, voffB); PG8_STAGE(PG8_SB(1, 1), b3 + hstep, voffB); PG8_STAGE(PG8_SA(1, 0), a3, voffA);
;             PG8_WAIT_V(8); PG8_WAIT_L(0); PG8_BAR; PG8_MMA(1, 0, At, B0); PG8_MMA(1, 1, At, B1); PG8_BAR; PG8_SCHED;
	v_mfma_f32_16x16x32_bf16 v[136:139], v[112:115], v[184:187], v[136:139]
	v_mfma_f32_16x16x32_bf16 v[136:139], v[120:123], v[188:191], v[136:139]
	v_mfma_f32_16x16x32_bf16 v[116:119], v[120:123], v[208:211], v[116:119]
	v_mfma_f32_16x16x32_bf16 v[116:119], v[112:115], v[204:207], v[116:119]
	v_mfma_f32_16x16x32_bf16 v[96:99], v[112:115], v[212:215], v[96:99]
	v_mfma_f32_16x16x32_bf16 v[96:99], v[120:123], v[216:219], v[96:99]
	v_mfma_f32_16x16x32_bf16 v[80:83], v[120:123], v[224:227], v[80:83]
	v_mfma_f32_16x16x32_bf16 v[80:83], v[112:115], v[220:223], v[80:83]
	v_mfma_f32_16x16x32_bf16 v[76:79], v[152:155], v[220:223], v[76:79]
	v_mfma_f32_16x16x32_bf16 v[76:79], v[156:159], v[224:227], v[76:79]
	v_mfma_f32_16x16x32_bf16 v[92:95], v[156:159], v[216:219], v[92:95]
	v_mfma_f32_16x16x32_bf16 v[92:95], v[152:155], v[212:215], v[92:95]
	v_mfma_f32_16x16x32_bf16 v[108:111], v[152:155], v[204:207], v[108:111]
	v_mfma_f32_16x16x32_bf16 v[108:111], v[156:159], v[208:211], v[108:111]
	v_mfma_f32_16x16x32_bf16 v[132:135], v[156:159], v[188:191], v[132:135]
	v_mfma_f32_16x16x32_bf16 v[132:135], v[152:155], v[184:187], v[132:135]
	v_mfma_f32_16x16x32_bf16 v[128:131], v[160:163], v[184:187], v[128:131]
	v_mfma_f32_16x16x32_bf16 v[128:131], v[164:167], v[188:191], v[128:131]
	v_mfma_f32_16x16x32_bf16 v[104:107], v[164:167], v[208:211], v[104:107]
	v_mfma_f32_16x16x32_bf16 v[104:107], v[160:163], v[204:207], v[104:107]
	v_mfma_f32_16x16x32_bf16 v[88:91], v[160:163], v[212:215], v[88:91]
	v_mfma_f32_16x16x32_bf16 v[88:91], v[164:167], v[216:219], v[88:91]
	v_mfma_f32_16x16x32_bf16 v[72:75], v[164:167], v[224:227], v[72:75]
	v_mfma_f32_16x16x32_bf16 v[72:75], v[160:163], v[220:223], v[72:75]
	v_mfma_f32_16x16x32_bf16 v[68:71], v[176:179], v[220:223], v[68:71]
	v_mfma_f32_16x16x32_bf16 v[68:71], v[180:183], v[224:227], v[68:71]
	v_mfma_f32_16x16x32_bf16 v[84:87], v[180:183], v[216:219], v[84:87]
	v_mfma_f32_16x16x32_bf16 v[84:87], v[176:179], v[212:215], v[84:87]
	v_mfma_f32_16x16x32_bf16 v[100:103], v[176:179], v[204:207], v[100:103]
	v_mfma_f32_16x16x32_bf16 v[100:103], v[180:183], v[208:211], v[100:103]
	v_mfma_f32_16x16x32_bf16 v[124:127], v[180:183], v[188:191], v[124:127]
	v_mfma_f32_16x16x32_bf16 v[124:127], v[176:179], v[184:187], v[124:127]
	s_barrier
	s_setprio 0
	s_add_i32 s50, s56, s46
	v_lshl_add_u64 v[168:169], v[168:169], 0, s[84:85]
	s_mov_b32 m0, s50
	ds_read_b128 v[184:187], v173 offset:49152
	ds_read_b128 v[188:191], v173 offset:50176
	ds_read_b128 v[204:207], v173 offset:51200
	ds_read_b128 v[208:211], v173 offset:52224
	ds_read_b128 v[212:215], v173 offset:53248
	ds_read_b128 v[216:219], v173 offset:54272
	ds_read_b128 v[220:223], v173 offset:55296
	ds_read_b128 v[224:227], v173 offset:56320
	global_load_lds_dwordx4 v[168:169], off
	s_add_i32 m0, s50, 0x2000
	s_add_u32 s50, s72, 0x100080
	v_lshl_add_u64 v[168:169], v[228:229], 0, s[84:85]
	s_addc_u32 s51, s73, 0
	s_add_i32 s56, s57, s46
	global_load_lds_dwordx4 v[168:169], off
	s_mov_b32 m0, s56
	s_nop 0
	global_load_lds_dwordx4 v2, s[50:51]
	s_add_i32 m0, s56, 0x2000
	s_nop 0
	global_load_lds_dwordx4 v144, s[50:51]
	s_cmp_eq_u32 s97, 60
	s_cbranch_scc0 .Ldefer_230_body
	v_lshl_add_u64 v[168:169], v[240:241], 0, s[84:85]
	s_mov_b32 m0, s28
	s_nop 0
	global_load_lds_dwordx4 v[168:169], off
	v_lshl_add_u64 v[168:169], v[242:243], 0, s[84:85]
	s_mov_b32 m0, s65
	s_nop 0
	global_load_lds_dwordx4 v[168:169], off
.Ldefer_230_body:
	s_waitcnt vmcnt(6) lgkmcnt(0)
	s_setprio 1
	s_barrier
	v_mfma_f32_16x16x32_bf16 v[64:67], v[112:115], v[184:187], v[64:67]
	v_mfma_f32_16x16x32_bf16 v[64:67], v[120:123], v[188:191], v[64:67]
	v_mfma_f32_16x16x32_bf16 v[48:51], v[120:123], v[208:211], v[48:51]
	v_mfma_f32_16x16x32_bf16 v[48:51], v[112:115], v[204:207], v[48:51]
	v_mfma_f32_16x16x32_bf16 v[32:35], v[112:115], v[212:215], v[32:35]
	v_mfma_f32_16x16x32_bf16 v[32:35], v[120:123], v[216:219], v[32:35]
	v_mfma_f32_16x16x32_bf16 v[16:19], v[120:123], v[224:227], v[16:19]
	v_mfma_f32_16x16x32_bf16 v[16:19], v[112:115], v[220:223], v[16:19]
	v_mfma_f32_16x16x32_bf16 v[12:15], v[152:155], v[220:223], v[12:15]
	v_mfma_f32_16x16x32_bf16 v[12:15], v[156:159], v[224:227], v[12:15]
	v_mfma_f32_16x16x32_bf16 v[28:31], v[156:159], v[216:219], v[28:31]
	v_mfma_f32_16x16x32_bf16 v[28:31], v[152:155], v[212:215], v[28:31]
	v_mfma_f32_16x16x32_bf16 v[44:47], v[152:155], v[204:207], v[44:47]
	v_mfma_f32_16x16x32_bf16 v[44:47], v[156:159], v[208:211], v[44:47]
	v_mfma_f32_16x16x32_bf16 v[60:63], v[156:159], v[188:191], v[60:63]
	v_mfma_f32_16x16x32_bf16 v[60:63], v[152:155], v[184:187], v[60:63]
	v_mfma_f32_16x16x32_bf16 v[56:59], v[160:163], v[184:187], v[56:59]
	v_mfma_f32_16x16x32_bf16 v[56:59], v[164:167], v[188:191], v[56:59]
	v_mfma_f32_16x16x32_bf16 v[40:43], v[164:167], v[208:211], v[40:43]
	v_mfma_f32_16x16x32_bf16 v[40:43], v[160:163], v[204:207], v[40:43]
	v_mfma_f32_16x16x32_bf16 v[24:27], v[160:163], v[212:215], v[24:27]
	v_mfma_f32_16x16x32_bf16 v[24:27], v[164:167], v[216:219], v[24:27]
	v_mfma_f32_16x16x32_bf16 v[8:11], v[164:167], v[224:227], v[8:11]
	v_mfma_f32_16x16x32_bf16 v[8:11], v[160:163], v[220:223], v[8:11]
	v_mfma_f32_16x16x32_bf16 v[4:7], v[176:179], v[220:223], v[4:7]
	v_mfma_f32_16x16x32_bf16 v[4:7], v[180:183], v[224:227], v[4:7]
	v_mfma_f32_16x16x32_bf16 v[20:23], v[180:183], v[216:219], v[20:23]
	v_mfma_f32_16x16x32_bf16 v[20:23], v[176:179], v[212:215], v[20:23]
	v_mfma_f32_16x16x32_bf16 v[36:39], v[176:179], v[204:207], v[36:39]
	v_mfma_f32_16x16x32_bf16 v[36:39], v[180:183], v[208:211], v[36:39]
	v_mfma_f32_16x16x32_bf16 v[52:55], v[180:183], v[188:191], v[52:55]
	v_mfma_f32_16x16x32_bf16 v[52:55], v[176:179], v[184:187], v[52:55]
	s_barrier
	s_setprio 0
	s_add_i32 s97, s97, 2
	s_add_u32 s12, s12, 0x100
	s_addc_u32 s13, s13, 0
	s_add_u32 s37, s37, 0x100
	s_addc_u32 s61, s61, 0
	s_cmp_gt_u32 s97, 61
	s_cbranch_scc0 .LBB0_230

; #define PG8_STAGE(bufoff, gbase, voff) do { _Pragma("unroll") for (int _i = 0; _i < 2; ++_i) \
;         __builtin_amdgcn_global_load_lds((const unsigned*)((const char*)(gbase) + (voff)[_i]), (PG8_LAS unsigned*)(lds + (bufoff) + ldsw + _i * 8192), 16, 0, 0); } while (0)
; #define PG8_LDA(dst, b, h) do { _Pragma("unroll") for (int m = 0; m < 4; ++m) _Pragma("unroll") for (int k = 0; k < 2; ++k) dst[m][k] = *(const PG8_LAS bf16x8*)(lds + PG8_SA(b, h) + aoff + m * 2048 + k * 1024); } while (0)
; #define PG8_LDB(dst, b, h) do { _Pragma("unroll") for (int n = 0; n < 2; ++n) _Pragma("unroll") for (int k = 0; k < 2; ++k) dst[n][k] = *(const PG8_LAS bf16x8*)(lds + PG8_SB(b, h) + boff + n * 2048 + k * 1024); } while (0)
; #define PG8_WAIT_V(n) asm volatile("s_waitcnt vmcnt(" #n ")" ::: "memory")
; #define PG8_WAIT_L(n) asm volatile("s_waitcnt lgkmcnt(" #n ")" ::: "memory")
; #define PG8_BAR __builtin_amdgcn_s_barrier()
; #define PG8_SCHED __builtin_amdgcn_sched_barrier(0)
; template <class Epi, class Sched, bool ALIGN_EPI = false, bool SP2 = false, bool I8 = false>
; __device__ __forceinline__ void gemm_phase(PG8_LAS unsigned char* lds, const Gemm g, const Sched& S, const Epi& E) {
;     ...
;         const bool has_next = S.next(ui + 1, nxt);
;         const char* nA = has_next ? (const char*)g.A + (size_t)nxt.pm * tstep : cA; const char* nB = has_next ? (const char*)g.Bt + (size_t)nxt.pn * tstep : cB;
;         for (int t = 0; t < nt; t += 2) {
;             const bool last = (t == nt - 2);
;             const char* a1 = cA + (size_t)(t + 1) * kstep;
;             const char* a2 = last ? nA : cA + (size_t)(t + 2) * kstep; const char* b2 = last ? nB : cB + (size_t)(t + 2) * kstep;
;             const char* a3 = a2 + kstep; const char* b3 = b2 + kstep;
;             if (last && has_next) S.a_ready(nxt);
;             if constexpr (SP2) {
;             PG8_LDB(B0, 0, 0); PG8_LDB(B1, 0, 1); PG8_SCHED; PG8_LDA(At, 0, 0); PG8_STAGE(PG8_SA(1, 1), a1 + hstep, voffA);
;             PG8_WAIT_V(8); PG8_WAIT_L(0); PG8_BAR; PG8_MMA(0, 0, At, B0); PG8_MMA(0, 1, At, B1); PG8_BAR; PG8_SCHED;
;             PG8_LDA(At, 0, 1); PG8_STAGE(PG8_SB(0, 0), b2, voffB); PG8_STAGE(PG8_SB(0, 1), b2 + hstep, voffB); PG8_STAGE(PG8_SA(0, 0), a2, voffA);
;             PG8_WAIT_V(8); PG8_WAIT_L(0); PG8_BAR; PG8_MMA(1, 0, At, B0); PG8_MMA(1, 1, At, B1); PG8_BAR; PG8_SCHED;
.LBB0_1455:
	s_ashr_i32 s17, s16, 31
	s_lshl_b64 s[20:21], s[16:17], 21
	s_add_u32 s20, s28, s20
	s_addc_u32 s21, s34, s21
	s_and_b64 s[22:23], s[8:9], exec
	s_cselect_b32 s17, s21, s25
	s_cselect_b32 s51, s20, s24
	s_ashr_i32 s19, s18, 31
	s_lshl_b64 s[22:23], s[18:19], 21
	s_add_u32 s22, s35, s22
	s_addc_u32 s23, s39, s23
	s_and_b64 s[36:37], s[8:9], exec
	s_cselect_b32 s19, s23, s27
	s_cselect_b32 s52, s22, s26
	s_add_u32 s24, s24, 0x100080
	s_addc_u32 s25, s25, 0
	s_add_u32 s53, s26, 0x100
	s_addc_u32 s54, s27, 0
	s_mov_b32 s55, -2
	s_waitcnt vmcnt(0)
	s_add_u32 s26, s24, 0xfff00080
	s_addc_u32 s27, s25, -1
	s_add_i32 s56, 0, 0x10000
	s_cmp_eq_u32 s55, 60
	s_cselect_b32 s37, s17, s27
	s_cselect_b32 s36, s51, s26
	s_cselect_b32 s27, s19, s54
	s_cselect_b32 s26, s52, s53
	s_add_i32 s58, 0, 0x14000
	v_add_u32_e32 v144, s56, v240
	v_add_u32_e32 v160, s58, v240
	ds_read_b128 v[124:127], v144
	ds_read_b128 v[128:131], v144 offset:1024
	ds_read_b128 v[132:135], v144 offset:2048
	ds_read_b128 v[144:147], v144 offset:3072
	ds_read_b128 v[148:151], v160
	ds_read_b128 v[152:155], v160 offset:1024
	ds_read_b128 v[156:159], v160 offset:2048
	ds_read_b128 v[160:163], v160 offset:3072
	s_add_i32 m0, s41, 0xc000
	ds_read_b128 v[164:167], v242
	ds_read_b128 v[168:171], v242 offset:1024
	ds_read_b128 v[172:175], v242 offset:2048
	ds_read_b128 v[176:179], v242 offset:3072
	ds_read_b128 v[180:183], v242 offset:4096
	ds_read_b128 v[184:187], v242 offset:5120
	ds_read_b128 v[188:191], v242 offset:6144
	ds_read_b128 v[214:217], v242 offset:7168
	global_load_lds_dwordx4 v210, s[24:25]
	s_add_i32 m0, s41, 0xe000
	s_nop 0
	global_load_lds_dwordx4 v212, s[24:25]
	s_waitcnt vmcnt(8) lgkmcnt(0)
	s_setprio 1
	s_barrier
	v_mfma_f32_16x16x32_bf16 v[140:143], v[124:127], v[164:167], 0
	v_mfma_f32_16x16x32_bf16 v[140:143], v[128:131], v[168:171], v[140:143]
	v_mfma_f32_16x16x32_bf16 v[112:115], v[128:131], v[176:179], 0
	v_mfma_f32_16x16x32_bf16 v[112:115], v[124:127], v[172:175], v[112:115]
	v_mfma_f32_16x16x32_bf16 v[96:99], v[124:127], v[180:183], 0
	v_mfma_f32_16x16x32_bf16 v[96:99], v[128:131], v[184:187], v[96:99]
	v_mfma_f32_16x16x32_bf16 v[80:83], v[128:131], v[214:217], 0
	v_mfma_f32_16x16x32_bf16 v[80:83], v[124:127], v[188:191], v[80:83]
	v_mfma_f32_16x16x32_bf16 v[76:79], v[132:135], v[188:191], 0
	v_mfma_f32_16x16x32_bf16 v[76:79], v[144:147], v[214:217], v[76:79]
	v_mfma_f32_16x16x32_bf16 v[92:95], v[144:147], v[184:187], 0
	v_mfma_f32_16x16x32_bf16 v[92:95], v[132:135], v[180:183], v[92:95]
	v_mfma_f32_16x16x32_bf16 v[108:111], v[132:135], v[172:175], 0
	v_mfma_f32_16x16x32_bf16 v[108:111], v[144:147], v[176:179], v[108:111]
	v_mfma_f32_16x16x32_bf16 v[136:139], v[144:147], v[168:171], 0
	v_mfma_f32_16x16x32_bf16 v[136:139], v[132:135], v[164:167], v[136:139]
	v_mfma_f32_16x16x32_bf16 v[120:123], v[148:151], v[164:167], 0
	v_mfma_f32_16x16x32_bf16 v[120:123], v[152:155], v[168:171], v[120:123]
	v_mfma_f32_16x16x32_bf16 v[104:107], v[152:155], v[176:179], 0
	v_mfma_f32_16x16x32_bf16 v[104:107], v[148:151], v[172:175], v[104:107]
	v_mfma_f32_16x16x32_bf16 v[88:91], v[148:151], v[180:183], 0
	v_mfma_f32_16x16x32_bf16 v[88:91], v[152:155], v[184:187], v[88:91]
	v_mfma_f32_16x16x32_bf16 v[72:75], v[152:155], v[214:217], 0
	v_mfma_f32_16x16x32_bf16 v[72:75], v[148:151], v[188:191], v[72:75]
	v_mfma_f32_16x16x32_bf16 v[68:71], v[156:159], v[188:191], 0
	v_mfma_f32_16x16x32_bf16 v[68:71], v[160:163], v[214:217], v[68:71]
	v_mfma_f32_16x16x32_bf16 v[84:87], v[160:163], v[184:187], 0
	v_mfma_f32_16x16x32_bf16 v[84:87], v[156:159], v[180:183], v[84:87]
	v_mfma_f32_16x16x32_bf16 v[100:103], v[156:159], v[172:175], 0
	v_mfma_f32_16x16x32_bf16 v[100:103], v[160:163], v[176:179], v[100:103]
	v_mfma_f32_16x16x32_bf16 v[116:119], v[160:163], v[168:171], 0
	v_mfma_f32_16x16x32_bf16 v[116:119], v[156:159], v[164:167], v[116:119]
	s_barrier
	s_setprio 0
	s_add_i32 s56, s56, s40
	v_lshl_add_u64 v[218:219], s[26:27], 0, v[2:3]
	s_mov_b32 m0, s56
	ds_read_b128 v[164:167], v242 offset:16384
	ds_read_b128 v[168:171], v242 offset:17408
	ds_read_b128 v[172:175], v242 offset:18432
	ds_read_b128 v[176:179], v242 offset:19456
	ds_read_b128 v[180:183], v242 offset:20480
	ds_read_b128 v[184:187], v242 offset:21504
	ds_read_b128 v[188:191], v242 offset:22528
	ds_read_b128 v[214:217], v242 offset:23552
	global_load_lds_dwordx4 v[218:219], off
	s_add_i32 m0, s56, 0x2000
	s_add_u32 s56, s26, 0x100000
	v_lshl_add_u64 v[220:221], s[26:27], 0, v[204:205]
	s_addc_u32 s57, s27, 0
	s_add_i32 s58, s58, s40
	global_load_lds_dwordx4 v[220:221], off
	s_mov_b32 m0, s58
	v_lshl_add_u64 v[224:225], s[36:37], 0, v[206:207]
	global_load_lds_dwordx4 v2, s[56:57]
	s_add_i32 m0, s58, 0x2000
	s_nop 0
	global_load_lds_dwordx4 v204, s[56:57]
	v_lshl_add_u64 v[222:223], s[36:37], 0, v[208:209]
	s_waitcnt vmcnt(6) lgkmcnt(0)
	s_setprio 1
	s_barrier
; #define PG8_STAGE(bufoff, gbase, voff) do { _Pragma("unroll") for (int _i = 0; _i < 2; ++_i) \
;         __builtin_amdgcn_global_load_lds((const unsigned*)((const char*)(gbase) + (voff)[_i]), (PG8_LAS unsigned*)(lds + (bufoff) + ldsw + _i * 8192), 16, 0, 0); } while (0)
; #define PG8_LDA(dst, b, h) do { _Pragma("unroll") for (int m = 0; m < 4; ++m) _Pragma("unroll") for (int k = 0; k < 2; ++k) dst[m][k] = *(const PG8_LAS bf16x8*)(lds + PG8_SA(b, h) + aoff + m * 2048 + k * 1024); } while (0)
; #define PG8_LDB(dst, b, h) do { _Pragma("unroll") for (int n = 0; n < 2; ++n) _Pragma("unroll") for (int k = 0; k < 2; ++k) dst[n][k] = *(const PG8_LAS bf16x8*)(lds + PG8_SB(b, h) + boff + n * 2048 + k * 1024); } while (0)
; #define PG8_WAIT_V(n) asm volatile("s_waitcnt vmcnt(" #n ")" ::: "memory")
; #define PG8_WAIT_L(n) asm volatile("s_waitcnt lgkmcnt(" #n ")" ::: "memory")
; #define PG8_BAR __builtin_amdgcn_s_barrier()
; #define PG8_SCHED __builtin_amdgcn_sched_barrier(0)
; template <class Epi, class Sched, bool ALIGN_EPI = false, bool SP2 = false, bool I8 = false>
; __device__ __forceinline__ void gemm_phase(PG8_LAS unsigned char* lds, const Gemm g, const Sched& S, const Epi& E) {
;     ...
;             PG8_LDB(B0, 0, 0); PG8_LDB(B1, 0, 1); PG8_SCHED; PG8_LDA(At, 0, 0); PG8_STAGE(PG8_SA(1, 1), a1 + hstep, voffA);
;             PG8_WAIT_V(8); PG8_WAIT_L(0); PG8_BAR; PG8_MMA(0, 0, At, B0); PG8_MMA(0, 1, At, B1); PG8_BAR; PG8_SCHED;
;             PG8_LDA(At, 0, 1); PG8_STAGE(PG8_SB(0, 0), b2, voffB); PG8_STAGE(PG8_SB(0, 1), b2 + hstep, voffB); PG8_STAGE(PG8_SA(0, 0), a2, voffA);
;             PG8_WAIT_V(8); PG8_WAIT_L(0); PG8_BAR; PG8_MMA(1, 0, At, B0); PG8_MMA(1, 1, At, B1); PG8_BAR; PG8_SCHED;
;             PG8_LDB(B0, 1, 0); PG8_LDB(B1, 1, 1); PG8_SCHED; PG8_LDA(At, 1, 0); PG8_STAGE(PG8_SA(0, 1), a2 + hstep, voffA);
;             PG8_WAIT_V(8); PG8_WAIT_L(0); PG8_BAR; PG8_MMA(0, 0, At, B0); PG8_MMA(0, 1, At, B1); PG8_BAR; PG8_SCHED;
;             PG8_LDA(At, 1, 1); PG8_STAGE(PG8_SB(1, 0), b3, voffB); PG8_STAGE(PG8_SB(1, 1), b3 + hstep, voffB); PG8_STAGE(PG8_SA(1, 0), a3, voffA);
;             PG8_WAIT_V(8); PG8_WAIT_L(0); PG8_BAR; PG8_MMA(1, 0, At, B0); PG8_MMA(1, 1, At, B1); PG8_BAR; PG8_SCHED;
	v_mfma_f32_16x16x32_bf16 v[64:67], v[124:127], v[164:167], 0
	v_mfma_f32_16x16x32_bf16 v[64:67], v[128:131], v[168:171], v[64:67]
	v_mfma_f32_16x16x32_bf16 v[48:51], v[128:131], v[176:179], 0
	v_mfma_f32_16x16x32_bf16 v[48:51], v[124:127], v[172:175], v[48:51]
	v_mfma_f32_16x16x32_bf16 v[32:35], v[124:127], v[180:183], 0
	v_mfma_f32_16x16x32_bf16 v[32:35], v[128:131], v[184:187], v[32:35]
	v_mfma_f32_16x16x32_bf16 v[16:19], v[128:131], v[214:217], 0
	v_mfma_f32_16x16x32_bf16 v[16:19], v[124:127], v[188:191], v[16:19]
	v_mfma_f32_16x16x32_bf16 v[12:15], v[132:135], v[188:191], 0
	v_mfma_f32_16x16x32_bf16 v[12:15], v[144:147], v[214:217], v[12:15]
	v_mfma_f32_16x16x32_bf16 v[28:31], v[144:147], v[184:187], 0
	v_mfma_f32_16x16x32_bf16 v[28:31], v[132:135], v[180:183], v[28:31]
	v_mfma_f32_16x16x32_bf16 v[44:47], v[132:135], v[172:175], 0
	v_mfma_f32_16x16x32_bf16 v[44:47], v[144:147], v[176:179], v[44:47]
	v_mfma_f32_16x16x32_bf16 v[60:63], v[144:147], v[168:171], 0
	v_mfma_f32_16x16x32_bf16 v[60:63], v[132:135], v[164:167], v[60:63]
	v_mfma_f32_16x16x32_bf16 v[56:59], v[148:151], v[164:167], 0
	v_mfma_f32_16x16x32_bf16 v[56:59], v[152:155], v[168:171], v[56:59]
	v_mfma_f32_16x16x32_bf16 v[40:43], v[152:155], v[176:179], 0
	v_mfma_f32_16x16x32_bf16 v[40:43], v[148:151], v[172:175], v[40:43]
	v_mfma_f32_16x16x32_bf16 v[24:27], v[148:151], v[180:183], 0
	v_mfma_f32_16x16x32_bf16 v[24:27], v[152:155], v[184:187], v[24:27]
	v_mfma_f32_16x16x32_bf16 v[8:11], v[152:155], v[214:217], 0
	v_mfma_f32_16x16x32_bf16 v[8:11], v[148:151], v[188:191], v[8:11]
	v_mfma_f32_16x16x32_bf16 v[4:7], v[156:159], v[188:191], 0
	v_mfma_f32_16x16x32_bf16 v[4:7], v[160:163], v[214:217], v[4:7]
	v_mfma_f32_16x16x32_bf16 v[20:23], v[160:163], v[184:187], 0
	v_mfma_f32_16x16x32_bf16 v[20:23], v[156:159], v[180:183], v[20:23]
	v_mfma_f32_16x16x32_bf16 v[36:39], v[156:159], v[172:175], 0
	v_mfma_f32_16x16x32_bf16 v[36:39], v[160:163], v[176:179], v[36:39]
	v_mfma_f32_16x16x32_bf16 v[52:55], v[160:163], v[168:171], 0
	v_mfma_f32_16x16x32_bf16 v[52:55], v[156:159], v[164:167], v[52:55]
	s_barrier
	s_setprio 0
	s_mov_b32 m0, s41
	s_nop 0
	global_load_lds_dwordx4 v[222:223], off
	s_mov_b32 m0, s42
	s_nop 0
	global_load_lds_dwordx4 v[224:225], off
	s_add_i32 s56, 0, 0x18000
	s_add_i32 s57, 0, 0x1c000
	v_add_u32_e32 v144, s56, v240
	v_add_u32_e32 v160, s57, v240
	ds_read_b128 v[124:127], v144
	ds_read_b128 v[128:131], v144 offset:1024
	ds_read_b128 v[132:135], v144 offset:2048
	ds_read_b128 v[144:147], v144 offset:3072
	ds_read_b128 v[148:151], v160
	ds_read_b128 v[152:155], v160 offset:1024
	ds_read_b128 v[156:159], v160 offset:2048
	ds_read_b128 v[160:163], v160 offset:3072
	s_add_u32 s36, s36, 0x100000
	s_addc_u32 s37, s37, 0
	s_mov_b32 m0, s43
	ds_read_b128 v[164:167], v242 offset:32768
	ds_read_b128 v[168:171], v242 offset:33792
	ds_read_b128 v[172:175], v242 offset:34816
	ds_read_b128 v[176:179], v242 offset:35840
	ds_read_b128 v[180:183], v242 offset:36864
	ds_read_b128 v[184:187], v242 offset:37888
	ds_read_b128 v[188:191], v242 offset:38912
	ds_read_b128 v[214:217], v242 offset:39936
	global_load_lds_dwordx4 v208, s[36:37]
	s_mov_b32 m0, s44
	s_nop 0
	global_load_lds_dwordx4 v206, s[36:37]
	s_waitcnt vmcnt(8) lgkmcnt(0)
	s_setprio 1
	s_barrier
	v_mfma_f32_16x16x32_bf16 v[140:143], v[124:127], v[164:167], v[140:143]
	v_mfma_f32_16x16x32_bf16 v[140:143], v[128:131], v[168:171], v[140:143]
	v_mfma_f32_16x16x32_bf16 v[112:115], v[128:131], v[176:179], v[112:115]
	v_mfma_f32_16x16x32_bf16 v[112:115], v[124:127], v[172:175], v[112:115]
	v_mfma_f32_16x16x32_bf16 v[96:99], v[124:127], v[180:183], v[96:99]
	v_mfma_f32_16x16x32_bf16 v[96:99], v[128:131], v[184:187], v[96:99]
	v_mfma_f32_16x16x32_bf16 v[80:83], v[128:131], v[214:217], v[80:83]
	v_mfma_f32_16x16x32_bf16 v[80:83], v[124:127], v[188:191], v[80:83]
	v_mfma_f32_16x16x32_bf16 v[76:79], v[132:135], v[188:191], v[76:79]
	v_mfma_f32_16x16x32_bf16 v[76:79], v[144:147], v[214:217], v[76:79]
	v_mfma_f32_16x16x32_bf16 v[92:95], v[144:147], v[184:187], v[92:95]
	v_mfma_f32_16x16x32_bf16 v[92:95], v[132:135], v[180:183], v[92:95]
	v_mfma_f32_16x16x32_bf16 v[108:111], v[132:135], v[172:175], v[108:111]
	v_mfma_f32_16x16x32_bf16 v[108:111], v[144:147], v[176:179], v[108:111]
	v_mfma_f32_16x16x32_bf16 v[136:139], v[144:147], v[168:171], v[136:139]
	v_mfma_f32_16x16x32_bf16 v[136:139], v[132:135], v[164:167], v[136:139]
	v_mfma_f32_16x16x32_bf16 v[120:123], v[148:151], v[164:167], v[120:123]
	v_mfma_f32_16x16x32_bf16 v[120:123], v[152:155], v[168:171], v[120:123]
	v_mfma_f32_16x16x32_bf16 v[104:107], v[152:155], v[176:179], v[104:107]
	v_mfma_f32_16x16x32_bf16 v[104:107], v[148:151], v[172:175], v[104:107]
	v_mfma_f32_16x16x32_bf16 v[88:91], v[148:151], v[180:183], v[88:91]
	v_mfma_f32_16x16x32_bf16 v[88:91], v[152:155], v[184:187], v[88:91]
	v_mfma_f32_16x16x32_bf16 v[72:75], v[152:155], v[214:217], v[72:75]
	v_mfma_f32_16x16x32_bf16 v[72:75], v[148:151], v[188:191], v[72:75]
	v_mfma_f32_16x16x32_bf16 v[68:71], v[156:159], v[188:191], v[68:71]
	v_mfma_f32_16x16x32_bf16 v[68:71], v[160:163], v[214:217], v[68:71]
	v_mfma_f32_16x16x32_bf16 v[84:87], v[160:163], v[184:187], v[84:87]
	v_mfma_f32_16x16x32_bf16 v[84:87], v[156:159], v[180:183], v[84:87]
	v_mfma_f32_16x16x32_bf16 v[100:103], v[156:159], v[172:175], v[100:103]
	v_mfma_f32_16x16x32_bf16 v[100:103], v[160:163], v[176:179], v[100:103]
	v_mfma_f32_16x16x32_bf16 v[116:119], v[160:163], v[168:171], v[116:119]
	v_mfma_f32_16x16x32_bf16 v[116:119], v[156:159], v[164:167], v[116:119]
	s_barrier
	s_setprio 0
	s_add_i32 s36, s56, s40
	v_lshl_add_u64 v[218:219], v[218:219], 0, s[84:85]
	s_mov_b32 m0, s36
	ds_read_b128 v[164:167], v242 offset:49152
	ds_read_b128 v[168:171], v242 offset:50176
	ds_read_b128 v[172:175], v242 offset:51200
	ds_read_b128 v[176:179], v242 offset:52224
	ds_read_b128 v[180:183], v242 offset:53248
	ds_read_b128 v[184:187], v242 offset:54272
	ds_read_b128 v[188:191], v242 offset:55296
	ds_read_b128 v[214:217], v242 offset:56320
	global_load_lds_dwordx4 v[218:219], off
	s_add_i32 m0, s36, 0x2000
	s_add_u32 s26, s26, 0x100080
	v_lshl_add_u64 v[218:219], v[220:221], 0, s[84:85]
	s_addc_u32 s27, s27, 0
	s_add_i32 s36, s57, s40
	global_load_lds_dwordx4 v[218:219], off
	s_mov_b32 m0, s36
	s_nop 0
	global_load_lds_dwordx4 v2, s[26:27]
	s_add_i32 m0, s36, 0x2000
	s_nop 0
	global_load_lds_dwordx4 v204, s[26:27]
	s_cmp_eq_u32 s55, 60
	s_cbranch_scc0 .Ldefer_1456_peel
	v_lshl_add_u64 v[218:219], v[222:223], 0, s[84:85]
	s_mov_b32 m0, s45
	s_nop 0
	global_load_lds_dwordx4 v[218:219], off
	v_lshl_add_u64 v[218:219], v[224:225], 0, s[84:85]
	s_mov_b32 m0, s46
	s_nop 0
	global_load_lds_dwordx4 v[218:219], off
; #define PG8_STAGE(bufoff, gbase, voff) do { _Pragma("unroll") for (int _i = 0; _i < 2; ++_i) \
;         __builtin_amdgcn_global_load_lds((const unsigned*)((const char*)(gbase) + (voff)[_i]), (PG8_LAS unsigned*)(lds + (bufoff) + ldsw + _i * 8192), 16, 0, 0); } while (0)
; #define PG8_LDA(dst, b, h) do { _Pragma("unroll") for (int m = 0; m < 4; ++m) _Pragma("unroll") for (int k = 0; k < 2; ++k) dst[m][k] = *(const PG8_LAS bf16x8*)(lds + PG8_SA(b, h) + aoff + m * 2048 + k * 1024); } while (0)
; #define PG8_WAIT_V(n) asm volatile("s_waitcnt vmcnt(" #n ")" ::: "memory")
; #define PG8_WAIT_L(n) asm volatile("s_waitcnt lgkmcnt(" #n ")" ::: "memory")
; #define PG8_BAR __builtin_amdgcn_s_barrier()
; template <class Epi, class Sched, bool ALIGN_EPI = false, bool SP2 = false, bool I8 = false>
; __device__ __forceinline__ void gemm_phase(PG8_LAS unsigned char* lds, const Gemm g, const Sched& S, const Epi& E) {
;     ...
;         for (int t = 0; t < nt; t += 2) {
;             const bool last = (t == nt - 2);
;             const char* a1 = cA + (size_t)(t + 1) * kstep;
;             const char* a2 = last ? nA : cA + (size_t)(t + 2) * kstep; const char* b2 = last ? nB : cB + (size_t)(t + 2) * kstep;
;             const char* a3 = a2 + kstep; const char* b3 = b2 + kstep;
;             if (last && has_next) S.a_ready(nxt);
;             if constexpr (SP2) {
;             PG8_LDB(B0, 0, 0); PG8_LDB(B1, 0, 1); PG8_SCHED; PG8_LDA(At, 0, 0); PG8_STAGE(PG8_SA(1, 1), a1 + hstep, voffA);
;             PG8_WAIT_V(8); PG8_WAIT_L(0); PG8_BAR; PG8_MMA(0, 0, At, B0); PG8_MMA(0, 1, At, B1); PG8_BAR; PG8_SCHED;
;             PG8_LDA(At, 0, 1); PG8_STAGE(PG8_SB(0, 0), b2, voffB); PG8_STAGE(PG8_SB(0, 1), b2 + hstep, voffB); PG8_STAGE(PG8_SA(0, 0), a2, voffA);
;             PG8_WAIT_V(8); PG8_WAIT_L(0); PG8_BAR; PG8_MMA(1, 0, At, B0); PG8_MMA(1, 1, At, B1); PG8_BAR; PG8_SCHED;
;             PG8_LDB(B0, 1, 0); PG8_LDB(B1, 1, 1); PG8_SCHED; PG8_LDA(At, 1, 0); PG8_STAGE(PG8_SA(0, 1), a2 + hstep, voffA);
;             PG8_WAIT_V(8); PG8_WAIT_L(0); PG8_BAR; PG8_MMA(0, 0, At, B0); PG8_MMA(0, 1, At, B1); PG8_BAR; PG8_SCHED;
;             PG8_LDA(At, 1, 1); PG8_STAGE(PG8_SB(1, 0), b3, voffB); PG8_STAGE(PG8_SB(1, 1), b3 + hstep, voffB); PG8_STAGE(PG8_SA(1, 0), a3, voffA);
;             PG8_WAIT_V(8); PG8_WAIT_L(0); PG8_BAR; PG8_MMA(1, 0, At, B0); PG8_MMA(1, 1, At, B1); PG8_BAR; PG8_SCHED;
.Ldefer_1456_peel:
	s_waitcnt vmcnt(6) lgkmcnt(0)
	s_setprio 1
	s_barrier
	v_mfma_f32_16x16x32_bf16 v[64:67], v[124:127], v[164:167], v[64:67]
	v_mfma_f32_16x16x32_bf16 v[64:67], v[128:131], v[168:171], v[64:67]
	v_mfma_f32_16x16x32_bf16 v[48:51], v[128:131], v[176:179], v[48:51]
	v_mfma_f32_16x16x32_bf16 v[48:51], v[124:127], v[172:175], v[48:51]
	v_mfma_f32_16x16x32_bf16 v[32:35], v[124:127], v[180:183], v[32:35]
	v_mfma_f32_16x16x32_bf16 v[32:35], v[128:131], v[184:187], v[32:35]
	v_mfma_f32_16x16x32_bf16 v[16:19], v[128:131], v[214:217], v[16:19]
	v_mfma_f32_16x16x32_bf16 v[16:19], v[124:127], v[188:191], v[16:19]
	v_mfma_f32_16x16x32_bf16 v[12:15], v[132:135], v[188:191], v[12:15]
	v_mfma_f32_16x16x32_bf16 v[12:15], v[144:147], v[214:217], v[12:15]
	v_mfma_f32_16x16x32_bf16 v[28:31], v[144:147], v[184:187], v[28:31]
	v_mfma_f32_16x16x32_bf16 v[28:31], v[132:135], v[180:183], v[28:31]
	v_mfma_f32_16x16x32_bf16 v[44:47], v[132:135], v[172:175], v[44:47]
	v_mfma_f32_16x16x32_bf16 v[44:47], v[144:147], v[176:179], v[44:47]
	v_mfma_f32_16x16x32_bf16 v[60:63], v[144:147], v[168:171], v[60:63]
	v_mfma_f32_16x16x32_bf16 v[60:63], v[132:135], v[164:167], v[60:63]
	v_mfma_f32_16x16x32_bf16 v[56:59], v[148:151], v[164:167], v[56:59]
	v_mfma_f32_16x16x32_bf16 v[56:59], v[152:155], v[168:171], v[56:59]
	v_mfma_f32_16x16x32_bf16 v[40:43], v[152:155], v[176:179], v[40:43]
	v_mfma_f32_16x16x32_bf16 v[40:43], v[148:151], v[172:175], v[40:43]
	v_mfma_f32_16x16x32_bf16 v[24:27], v[148:151], v[180:183], v[24:27]
	v_mfma_f32_16x16x32_bf16 v[24:27], v[152:155], v[184:187], v[24:27]
	v_mfma_f32_16x16x32_bf16 v[8:11], v[152:155], v[214:217], v[8:11]
	v_mfma_f32_16x16x32_bf16 v[8:11], v[148:151], v[188:191], v[8:11]
	v_mfma_f32_16x16x32_bf16 v[4:7], v[156:159], v[188:191], v[4:7]
	v_mfma_f32_16x16x32_bf16 v[4:7], v[160:163], v[214:217], v[4:7]
	v_mfma_f32_16x16x32_bf16 v[20:23], v[160:163], v[184:187], v[20:23]
	v_mfma_f32_16x16x32_bf16 v[20:23], v[156:159], v[180:183], v[20:23]
	v_mfma_f32_16x16x32_bf16 v[36:39], v[156:159], v[172:175], v[36:39]
	v_mfma_f32_16x16x32_bf16 v[36:39], v[160:163], v[176:179], v[36:39]
	v_mfma_f32_16x16x32_bf16 v[52:55], v[160:163], v[168:171], v[52:55]
	v_mfma_f32_16x16x32_bf16 v[52:55], v[156:159], v[164:167], v[52:55]
	s_barrier
	s_setprio 0
	s_add_i32 s55, s55, 2
	s_add_u32 s24, s24, 0x100
	s_addc_u32 s25, s25, 0
	s_add_u32 s53, s53, 0x100
	s_addc_u32 s54, s54, 0
	s_cmp_gt_u32 s55, 61
	s_cbranch_scc1 .Lkloop_exit_2
.LBB0_1456:
	s_add_u32 s26, s24, 0xfff00080
	s_addc_u32 s27, s25, -1
	s_add_i32 s56, 0, 0x10000
	s_cmp_eq_u32 s55, 60
	s_cselect_b32 s37, s17, s27
	s_cselect_b32 s36, s51, s26
	s_cselect_b32 s27, s19, s54
	s_cselect_b32 s26, s52, s53
	s_add_i32 s58, 0, 0x14000
	v_add_u32_e32 v144, s56, v240
	v_add_u32_e32 v160, s58, v240
	ds_read_b128 v[124:127], v144
	ds_read_b128 v[128:131], v144 offset:1024
	ds_read_b128 v[132:135], v144 offset:2048
	ds_read_b128 v[144:147], v144 offset:3072
	ds_read_b128 v[148:151], v160
	ds_read_b128 v[152:155], v160 offset:1024
	ds_read_b128 v[156:159], v160 offset:2048
	ds_read_b128 v[160:163], v160 offset:3072
	v_lshl_add_u64 v[218:219], v[222:223], 0, s[84:85]
	s_mov_b32 m0, s45
	s_nop 0
	global_load_lds_dwordx4 v[218:219], off
	v_lshl_add_u64 v[218:219], v[224:225], 0, s[84:85]
	s_mov_b32 m0, s46
	s_nop 0
	global_load_lds_dwordx4 v[218:219], off
	s_add_i32 m0, s41, 0xc000
	ds_read_b128 v[164:167], v242
	ds_read_b128 v[168:171], v242 offset:1024
	ds_read_b128 v[172:175], v242 offset:2048
	ds_read_b128 v[176:179], v242 offset:3072
	ds_read_b128 v[180:183], v242 offset:4096
	ds_read_b128 v[184:187], v242 offset:5120
	ds_read_b128 v[188:191], v242 offset:6144
	ds_read_b128 v[214:217], v242 offset:7168
	global_load_lds_dwordx4 v210, s[24:25]
	s_add_i32 m0, s41, 0xe000
	s_nop 0
	global_load_lds_dwordx4 v212, s[24:25]
	s_waitcnt vmcnt(8) lgkmcnt(0)
	s_setprio 1
	s_barrier
	v_mfma_f32_16x16x32_bf16 v[140:143], v[124:127], v[164:167], v[140:143]
	v_mfma_f32_16x16x32_bf16 v[140:143], v[128:131], v[168:171], v[140:143]
	v_mfma_f32_16x16x32_bf16 v[112:115], v[128:131], v[176:179], v[112:115]
	v_mfma_f32_16x16x32_bf16 v[112:115], v[124:127], v[172:175], v[112:115]
	v_mfma_f32_16x16x32_bf16 v[96:99], v[124:127], v[180:183], v[96:99]
	v_mfma_f32_16x16x32_bf16 v[96:99], v[128:131], v[184:187], v[96:99]
	v_mfma_f32_16x16x32_bf16 v[80:83], v[128:131], v[214:217], v[80:83]
	v_mfma_f32_16x16x32_bf16 v[80:83], v[124:127], v[188:191], v[80:83]
	v_mfma_f32_16x16x32_bf16 v[76:79], v[132:135], v[188:191], v[76:79]
	v_mfma_f32_16x16x32_bf16 v[76:79], v[144:147], v[214:217], v[76:79]
	v_mfma_f32_16x16x32_bf16 v[92:95], v[144:147], v[184:187], v[92:95]
	v_mfma_f32_16x16x32_bf16 v[92:95], v[132:135], v[180:183], v[92:95]
	v_mfma_f32_16x16x32_bf16 v[108:111], v[132:135], v[172:175], v[108:111]
	v_mfma_f32_16x16x32_bf16 v[108:111], v[144:147], v[176:179], v[108:111]
	v_mfma_f32_16x16x32_bf16 v[136:139], v[144:147], v[168:171], v[136:139]
	v_mfma_f32_16x16x32_bf16 v[136:139], v[132:135], v[164:167], v[136:139]
	v_mfma_f32_16x16x32_bf16 v[120:123], v[148:151], v[164:167], v[120:123]
	v_mfma_f32_16x16x32_bf16 v[120:123], v[152:155], v[168:171], v[120:123]
	v_mfma_f32_16x16x32_bf16 v[104:107], v[152:155], v[176:179], v[104:107]
	v_mfma_f32_16x16x32_bf16 v[104:107], v[148:151], v[172:175], v[104:107]
	v_mfma_f32_16x16x32_bf16 v[88:91], v[148:151], v[180:183], v[88:91]
	v_mfma_f32_16x16x32_bf16 v[88:91], v[152:155], v[184:187], v[88:91]
	v_mfma_f32_16x16x32_bf16 v[72:75], v[152:155], v[214:217], v[72:75]
	v_mfma_f32_16x16x32_bf16 v[72:75], v[148:151], v[188:191], v[72:75]
	v_mfma_f32_16x16x32_bf16 v[68:71], v[156:159], v[188:191], v[68:71]
	v_mfma_f32_16x16x32_bf16 v[68:71], v[160:163], v[214:217], v[68:71]
	v_mfma_f32_16x16x32_bf16 v[84:87], v[160:163], v[184:187], v[84:87]
	v_mfma_f32_16x16x32_bf16 v[84:87], v[156:159], v[180:183], v[84:87]
	v_mfma_f32_16x16x32_bf16 v[100:103], v[156:159], v[172:175], v[100:103]
	v_mfma_f32_16x16x32_bf16 v[100:103], v[160:163], v[176:179], v[100:103]
	v_mfma_f32_16x16x32_bf16 v[116:119], v[160:163], v[168:171], v[116:119]
	v_mfma_f32_16x16x32_bf16 v[116:119], v[156:159], v[164:167], v[116:119]
	s_barrier
; #define PG8_STAGE(bufoff, gbase, voff) do { _Pragma("unroll") for (int _i = 0; _i < 2; ++_i) \
;         __builtin_amdgcn_global_load_lds((const unsigned*)((const char*)(gbase) + (voff)[_i]), (PG8_LAS unsigned*)(lds + (bufoff) + ldsw + _i * 8192), 16, 0, 0); } while (0)
; #define PG8_LDA(dst, b, h) do { _Pragma("unroll") for (int m = 0; m < 4; ++m) _Pragma("unroll") for (int k = 0; k < 2; ++k) dst[m][k] = *(const PG8_LAS bf16x8*)(lds + PG8_SA(b, h) + aoff + m * 2048 + k * 1024); } while (0)
; #define PG8_LDB(dst, b, h) do { _Pragma("unroll") for (int n = 0; n < 2; ++n) _Pragma("unroll") for (int k = 0; k < 2; ++k) dst[n][k] = *(const PG8_LAS bf16x8*)(lds + PG8_SB(b, h) + boff + n * 2048 + k * 1024); } while (0)
; #define PG8_WAIT_V(n) asm volatile("s_waitcnt vmcnt(" #n ")" ::: "memory")
; #define PG8_WAIT_L(n) asm volatile("s_waitcnt lgkmcnt(" #n ")" ::: "memory")
; #define PG8_BAR __builtin_amdgcn_s_barrier()
; #define PG8_SCHED __builtin_amdgcn_sched_barrier(0)
; template <class Epi, class Sched, bool ALIGN_EPI = false, bool SP2 = false, bool I8 = false>
; __device__ __forceinline__ void gemm_phase(PG8_LAS unsigned char* lds, const Gemm g, const Sched& S, const Epi& E) {
;     ...
;             PG8_LDB(B0, 0, 0); PG8_LDB(B1, 0, 1); PG8_SCHED; PG8_LDA(At, 0, 0); PG8_STAGE(PG8_SA(1, 1), a1 + hstep, voffA);
;             PG8_WAIT_V(8); PG8_WAIT_L(0); PG8_BAR; PG8_MMA(0, 0, At, B0); PG8_MMA(0, 1, At, B1); PG8_BAR; PG8_SCHED;
;             PG8_LDA(At, 0, 1); PG8_STAGE(PG8_SB(0, 0), b2, voffB); PG8_STAGE(PG8_SB(0, 1), b2 + hstep, voffB); PG8_STAGE(PG8_SA(0, 0), a2, voffA);
;             PG8_WAIT_V(8); PG8_WAIT_L(0); PG8_BAR; PG8_MMA(1, 0, At, B0); PG8_MMA(1, 1, At, B1); PG8_BAR; PG8_SCHED;
;             PG8_LDB(B0, 1, 0); PG8_LDB(B1, 1, 1); PG8_SCHED; PG8_LDA(At, 1, 0); PG8_STAGE(PG8_SA(0, 1), a2 + hstep, voffA);
;             PG8_WAIT_V(8); PG8_WAIT_L(0); PG8_BAR; PG8_MMA(0, 0, At, B0); PG8_MMA(0, 1, At, B1); PG8_BAR; PG8_SCHED;
;             PG8_LDA(At, 1, 1); PG8_STAGE(PG8_SB(1, 0), b3, voffB); PG8_STAGE(PG8_SB(1, 1), b3 + hstep, voffB); PG8_STAGE(PG8_SA(1, 0), a3, voffA);
;             PG8_WAIT_V(8); PG8_WAIT_L(0); PG8_BAR; PG8_MMA(1, 0, At, B0); PG8_MMA(1, 1, At, B1); PG8_BAR; PG8_SCHED;
	s_setprio 0
	s_add_i32 s56, s56, s40
	v_lshl_add_u64 v[218:219], s[26:27], 0, v[2:3]
	s_mov_b32 m0, s56
	ds_read_b128 v[164:167], v242 offset:16384
	ds_read_b128 v[168:171], v242 offset:17408
	ds_read_b128 v[172:175], v242 offset:18432
	ds_read_b128 v[176:179], v242 offset:19456
	ds_read_b128 v[180:183], v242 offset:20480
	ds_read_b128 v[184:187], v242 offset:21504
	ds_read_b128 v[188:191], v242 offset:22528
	ds_read_b128 v[214:217], v242 offset:23552
	global_load_lds_dwordx4 v[218:219], off
	s_add_i32 m0, s56, 0x2000
	s_add_u32 s56, s26, 0x100000
	v_lshl_add_u64 v[220:221], s[26:27], 0, v[204:205]
	s_addc_u32 s57, s27, 0
	s_add_i32 s58, s58, s40
	global_load_lds_dwordx4 v[220:221], off
	s_mov_b32 m0, s58
	v_lshl_add_u64 v[224:225], s[36:37], 0, v[206:207]
	global_load_lds_dwordx4 v2, s[56:57]
	s_add_i32 m0, s58, 0x2000
	s_nop 0
	global_load_lds_dwordx4 v204, s[56:57]
	v_lshl_add_u64 v[222:223], s[36:37], 0, v[208:209]
	s_waitcnt vmcnt(6) lgkmcnt(0)
	s_setprio 1
	s_barrier
	v_mfma_f32_16x16x32_bf16 v[64:67], v[124:127], v[164:167], v[64:67]
	v_mfma_f32_16x16x32_bf16 v[64:67], v[128:131], v[168:171], v[64:67]
	v_mfma_f32_16x16x32_bf16 v[48:51], v[128:131], v[176:179], v[48:51]
	v_mfma_f32_16x16x32_bf16 v[48:51], v[124:127], v[172:175], v[48:51]
	v_mfma_f32_16x16x32_bf16 v[32:35], v[124:127], v[180:183], v[32:35]
	v_mfma_f32_16x16x32_bf16 v[32:35], v[128:131], v[184:187], v[32:35]
	v_mfma_f32_16x16x32_bf16 v[16:19], v[128:131], v[214:217], v[16:19]
	v_mfma_f32_16x16x32_bf16 v[16:19], v[124:127], v[188:191], v[16:19]
	v_mfma_f32_16x16x32_bf16 v[12:15], v[132:135], v[188:191], v[12:15]
	v_mfma_f32_16x16x32_bf16 v[12:15], v[144:147], v[214:217], v[12:15]
	v_mfma_f32_16x16x32_bf16 v[28:31], v[144:147], v[184:187], v[28:31]
	v_mfma_f32_16x16x32_bf16 v[28:31], v[132:135], v[180:183], v[28:31]
	v_mfma_f32_16x16x32_bf16 v[44:47], v[132:135], v[172:175], v[44:47]
	v_mfma_f32_16x16x32_bf16 v[44:47], v[144:147], v[176:179], v[44:47]
	v_mfma_f32_16x16x32_bf16 v[60:63], v[144:147], v[168:171], v[60:63]
	v_mfma_f32_16x16x32_bf16 v[60:63], v[132:135], v[164:167], v[60:63]
	v_mfma_f32_16x16x32_bf16 v[56:59], v[148:151], v[164:167], v[56:59]
	v_mfma_f32_16x16x32_bf16 v[56:59], v[152:155], v[168:171], v[56:59]
	v_mfma_f32_16x16x32_bf16 v[40:43], v[152:155], v[176:179], v[40:43]
	v_mfma_f32_16x16x32_bf16 v[40:43], v[148:151], v[172:175], v[40:43]
	v_mfma_f32_16x16x32_bf16 v[24:27], v[148:151], v[180:183], v[24:27]
	v_mfma_f32_16x16x32_bf16 v[24:27], v[152:155], v[184:187], v[24:27]
	v_mfma_f32_16x16x32_bf16 v[8:11], v[152:155], v[214:217], v[8:11]
	v_mfma_f32_16x16x32_bf16 v[8:11], v[148:151], v[188:191], v[8:11]
	v_mfma_f32_16x16x32_bf16 v[4:7], v[156:159], v[188:191], v[4:7]
	v_mfma_f32_16x16x32_bf16 v[4:7], v[160:163], v[214:217], v[4:7]
	v_mfma_f32_16x16x32_bf16 v[20:23], v[160:163], v[184:187], v[20:23]
	v_mfma_f32_16x16x32_bf16 v[20:23], v[156:159], v[180:183], v[20:23]
	v_mfma_f32_16x16x32_bf16 v[36:39], v[156:159], v[172:175], v[36:39]
	v_mfma_f32_16x16x32_bf16 v[36:39], v[160:163], v[176:179], v[36:39]
	v_mfma_f32_16x16x32_bf16 v[52:55], v[160:163], v[168:171], v[52:55]
	v_mfma_f32_16x16x32_bf16 v[52:55], v[156:159], v[164:167], v[52:55]
	s_barrier
	s_setprio 0
	s_mov_b32 m0, s41
	s_nop 0
	global_load_lds_dwordx4 v[222:223], off
	s_mov_b32 m0, s42
	s_nop 0
	global_load_lds_dwordx4 v[224:225], off
	s_add_i32 s56, 0, 0x18000
	s_add_i32 s57, 0, 0x1c000
	v_add_u32_e32 v144, s56, v240
	v_add_u32_e32 v160, s57, v240
	ds_read_b128 v[124:127], v144
	ds_read_b128 v[128:131], v144 offset:1024
	ds_read_b128 v[132:135], v144 offset:2048
	ds_read_b128 v[144:147], v144 offset:3072
	ds_read_b128 v[148:151], v160
	ds_read_b128 v[152:155], v160 offset:1024
	ds_read_b128 v[156:159], v160 offset:2048
	ds_read_b128 v[160:163], v160 offset:3072
	s_add_u32 s36, s36, 0x100000
	s_addc_u32 s37, s37, 0
	s_mov_b32 m0, s43
	ds_read_b128 v[164:167], v242 offset:32768
	ds_read_b128 v[168:171], v242 offset:33792
	ds_read_b128 v[172:175], v242 offset:34816
	ds_read_b128 v[176:179], v242 offset:35840
	ds_read_b128 v[180:183], v242 offset:36864
	ds_read_b128 v[184:187], v242 offset:37888
	ds_read_b128 v[188:191], v242 offset:38912
	ds_read_b128 v[214:217], v242 offset:39936
	global_load_lds_dwordx4 v208, s[36:37]
	s_mov_b32 m0, s44
	s_nop 0
	global_load_lds_dwordx4 v206, s[36:37]
	s_waitcnt vmcnt(8) lgkmcnt(0)
	s_setprio 1
	s_barrier
; #define PG8_STAGE(bufoff, gbase, voff) do { _Pragma("unroll") for (int _i = 0; _i < 2; ++_i) \
;         __builtin_amdgcn_global_load_lds((const unsigned*)((const char*)(gbase) + (voff)[_i]), (PG8_LAS unsigned*)(lds + (bufoff) + ldsw + _i * 8192), 16, 0, 0); } while (0)
; #define PG8_LDA(dst, b, h) do { _Pragma("unroll") for (int m = 0; m < 4; ++m) _Pragma("unroll") for (int k = 0; k < 2; ++k) dst[m][k] = *(const PG8_LAS bf16x8*)(lds + PG8_SA(b, h) + aoff + m * 2048 + k * 1024); } while (0)
; #define PG8_LDB(dst, b, h) do { _Pragma("unroll") for (int n = 0; n < 2; ++n) _Pragma("unroll") for (int k = 0; k < 2; ++k) dst[n][k] = *(const PG8_LAS bf16x8*)(lds + PG8_SB(b, h) + boff + n * 2048 + k * 1024); } while (0)
; #define PG8_WAIT_V(n) asm volatile("s_waitcnt vmcnt(" #n ")" ::: "memory")
; #define PG8_WAIT_L(n) asm volatile("s_waitcnt lgkmcnt(" #n ")" ::: "memory")
; #define PG8_BAR __builtin_amdgcn_s_barrier()
; #define PG8_SCHED __builtin_amdgcn_sched_barrier(0)
; template <class Epi, class Sched, bool ALIGN_EPI = false, bool SP2 = false, bool I8 = false>
; __device__ __forceinline__ void gemm_phase(PG8_LAS unsigned char* lds, const Gemm g, const Sched& S, const Epi& E) {
;     ...
;             PG8_LDB(B0, 0, 0); PG8_LDB(B1, 0, 1); PG8_SCHED; PG8_LDA(At, 0, 0); PG8_STAGE(PG8_SA(1, 1), a1 + hstep, voffA);
;             PG8_WAIT_V(8); PG8_WAIT_L(0); PG8_BAR; PG8_MMA(0, 0, At, B0); PG8_MMA(0, 1, At, B1); PG8_BAR; PG8_SCHED;
;             PG8_LDA(At, 0, 1); PG8_STAGE(PG8_SB(0, 0), b2, voffB); PG8_STAGE(PG8_SB(0, 1), b2 + hstep, voffB); PG8_STAGE(PG8_SA(0, 0), a2, voffA);
;             PG8_WAIT_V(8); PG8_WAIT_L(0); PG8_BAR; PG8_MMA(1, 0, At, B0); PG8_MMA(1, 1, At, B1); PG8_BAR; PG8_SCHED;
;             PG8_LDB(B0, 1, 0); PG8_LDB(B1, 1, 1); PG8_SCHED; PG8_LDA(At, 1, 0); PG8_STAGE(PG8_SA(0, 1), a2 + hstep, voffA);
;             PG8_WAIT_V(8); PG8_WAIT_L(0); PG8_BAR; PG8_MMA(0, 0, At, B0); PG8_MMA(0, 1, At, B1); PG8_BAR; PG8_SCHED;
;             PG8_LDA(At, 1, 1); PG8_STAGE(PG8_SB(1, 0), b3, voffB); PG8_STAGE(PG8_SB(1, 1), b3 + hstep, voffB); PG8_STAGE(PG8_SA(1, 0), a3, voffA);
;             PG8_WAIT_V(8); PG8_WAIT_L(0); PG8_BAR; PG8_MMA(1, 0, At, B0); PG8_MMA(1, 1, At, B1); PG8_BAR; PG8_SCHED;
	v_mfma_f32_16x16x32_bf16 v[140:143], v[124:127], v[164:167], v[140:143]
	v_mfma_f32_16x16x32_bf16 v[140:143], v[128:131], v[168:171], v[140:143]
	v_mfma_f32_16x16x32_bf16 v[112:115], v[128:131], v[176:179], v[112:115]
	v_mfma_f32_16x16x32_bf16 v[112:115], v[124:127], v[172:175], v[112:115]
	v_mfma_f32_16x16x32_bf16 v[96:99], v[124:127], v[180:183], v[96:99]
	v_mfma_f32_16x16x32_bf16 v[96:99], v[128:131], v[184:187], v[96:99]
	v_mfma_f32_16x16x32_bf16 v[80:83], v[128:131], v[214:217], v[80:83]
	v_mfma_f32_16x16x32_bf16 v[80:83], v[124:127], v[188:191], v[80:83]
	v_mfma_f32_16x16x32_bf16 v[76:79], v[132:135], v[188:191], v[76:79]
	v_mfma_f32_16x16x32_bf16 v[76:79], v[144:147], v[214:217], v[76:79]
	v_mfma_f32_16x16x32_bf16 v[92:95], v[144:147], v[184:187], v[92:95]
	v_mfma_f32_16x16x32_bf16 v[92:95], v[132:135], v[180:183], v[92:95]
	v_mfma_f32_16x16x32_bf16 v[108:111], v[132:135], v[172:175], v[108:111]
	v_mfma_f32_16x16x32_bf16 v[108:111], v[144:147], v[176:179], v[108:111]
	v_mfma_f32_16x16x32_bf16 v[136:139], v[144:147], v[168:171], v[136:139]
	v_mfma_f32_16x16x32_bf16 v[136:139], v[132:135], v[164:167], v[136:139]
	v_mfma_f32_16x16x32_bf16 v[120:123], v[148:151], v[164:167], v[120:123]
	v_mfma_f32_16x16x32_bf16 v[120:123], v[152:155], v[168:171], v[120:123]
	v_mfma_f32_16x16x32_bf16 v[104:107], v[152:155], v[176:179], v[104:107]
	v_mfma_f32_16x16x32_bf16 v[104:107], v[148:151], v[172:175], v[104:107]
	v_mfma_f32_16x16x32_bf16 v[88:91], v[148:151], v[180:183], v[88:91]
	v_mfma_f32_16x16x32_bf16 v[88:91], v[152:155], v[184:187], v[88:91]
	v_mfma_f32_16x16x32_bf16 v[72:75], v[152:155], v[214:217], v[72:75]
	v_mfma_f32_16x16x32_bf16 v[72:75], v[148:151], v[188:191], v[72:75]
	v_mfma_f32_16x16x32_bf16 v[68:71], v[156:159], v[188:191], v[68:71]
	v_mfma_f32_16x16x32_bf16 v[68:71], v[160:163], v[214:217], v[68:71]
	v_mfma_f32_16x16x32_bf16 v[84:87], v[160:163], v[184:187], v[84:87]
	v_mfma_f32_16x16x32_bf16 v[84:87], v[156:159], v[180:183], v[84:87]
	v_mfma_f32_16x16x32_bf16 v[100:103], v[156:159], v[172:175], v[100:103]
	v_mfma_f32_16x16x32_bf16 v[100:103], v[160:163], v[176:179], v[100:103]
	v_mfma_f32_16x16x32_bf16 v[116:119], v[160:163], v[168:171], v[116:119]
	v_mfma_f32_16x16x32_bf16 v[116:119], v[156:159], v[164:167], v[116:119]
	s_barrier
	s_setprio 0
	s_add_i32 s36, s56, s40
	v_lshl_add_u64 v[218:219], v[218:219], 0, s[84:85]
	s_mov_b32 m0, s36
	ds_read_b128 v[164:167], v242 offset:49152
	ds_read_b128 v[168:171], v242 offset:50176
	ds_read_b128 v[172:175], v242 offset:51200
	ds_read_b128 v[176:179], v242 offset:52224
	ds_read_b128 v[180:183], v242 offset:53248
	ds_read_b128 v[184:187], v242 offset:54272
	ds_read_b128 v[188:191], v242 offset:55296
	ds_read_b128 v[214:217], v242 offset:56320
	global_load_lds_dwordx4 v[218:219], off
	s_add_i32 m0, s36, 0x2000
	s_add_u32 s26, s26, 0x100080
	v_lshl_add_u64 v[218:219], v[220:221], 0, s[84:85]
	s_addc_u32 s27, s27, 0
	s_add_i32 s36, s57, s40
	global_load_lds_dwordx4 v[218:219], off
	s_mov_b32 m0, s36
	s_nop 0
	global_load_lds_dwordx4 v2, s[26:27]
	s_add_i32 m0, s36, 0x2000
	s_nop 0
	global_load_lds_dwordx4 v204, s[26:27]
	s_cmp_eq_u32 s55, 60
	s_cbranch_scc0 .Ldefer_1456_body
	v_lshl_add_u64 v[218:219], v[222:223], 0, s[84:85]
	s_mov_b32 m0, s45
	s_nop 0
	global_load_lds_dwordx4 v[218:219], off
	v_lshl_add_u64 v[218:219], v[224:225], 0, s[84:85]
	s_mov_b32 m0, s46
	s_nop 0
	global_load_lds_dwordx4 v[218:219], off
.Ldefer_1456_body:
	s_waitcnt vmcnt(6) lgkmcnt(0)
	s_setprio 1
	s_barrier
	v_mfma_f32_16x16x32_bf16 v[64:67], v[124:127], v[164:167], v[64:67]
	v_mfma_f32_16x16x32_bf16 v[64:67], v[128:131], v[168:171], v[64:67]
	v_mfma_f32_16x16x32_bf16 v[48:51], v[128:131], v[176:179], v[48:51]
	v_mfma_f32_16x16x32_bf16 v[48:51], v[124:127], v[172:175], v[48:51]
	v_mfma_f32_16x16x32_bf16 v[32:35], v[124:127], v[180:183], v[32:35]
	v_mfma_f32_16x16x32_bf16 v[32:35], v[128:131], v[184:187], v[32:35]
	v_mfma_f32_16x16x32_bf16 v[16:19], v[128:131], v[214:217], v[16:19]
	v_mfma_f32_16x16x32_bf16 v[16:19], v[124:127], v[188:191], v[16:19]
	v_mfma_f32_16x16x32_bf16 v[12:15], v[132:135], v[188:191], v[12:15]
	v_mfma_f32_16x16x32_bf16 v[12:15], v[144:147], v[214:217], v[12:15]
	v_mfma_f32_16x16x32_bf16 v[28:31], v[144:147], v[184:187], v[28:31]
	v_mfma_f32_16x16x32_bf16 v[28:31], v[132:135], v[180:183], v[28:31]
	v_mfma_f32_16x16x32_bf16 v[44:47], v[132:135], v[172:175], v[44:47]
	v_mfma_f32_16x16x32_bf16 v[44:47], v[144:147], v[176:179], v[44:47]
	v_mfma_f32_16x16x32_bf16 v[60:63], v[144:147], v[168:171], v[60:63]
	v_mfma_f32_16x16x32_bf16 v[60:63], v[132:135], v[164:167], v[60:63]
	v_mfma_f32_16x16x32_bf16 v[56:59], v[148:151], v[164:167], v[56:59]
	v_mfma_f32_16x16x32_bf16 v[56:59], v[152:155], v[168:171], v[56:59]
	v_mfma_f32_16x16x32_bf16 v[40:43], v[152:155], v[176:179], v[40:43]
	v_mfma_f32_16x16x32_bf16 v[40:43], v[148:151], v[172:175], v[40:43]
	v_mfma_f32_16x16x32_bf16 v[24:27], v[148:151], v[180:183], v[24:27]
	v_mfma_f32_16x16x32_bf16 v[24:27], v[152:155], v[184:187], v[24:27]
	v_mfma_f32_16x16x32_bf16 v[8:11], v[152:155], v[214:217], v[8:11]
	v_mfma_f32_16x16x32_bf16 v[8:11], v[148:151], v[188:191], v[8:11]
	v_mfma_f32_16x16x32_bf16 v[4:7], v[156:159], v[188:191], v[4:7]
	v_mfma_f32_16x16x32_bf16 v[4:7], v[160:163], v[214:217], v[4:7]
	v_mfma_f32_16x16x32_bf16 v[20:23], v[160:163], v[184:187], v[20:23]
	v_mfma_f32_16x16x32_bf16 v[20:23], v[156:159], v[180:183], v[20:23]
	v_mfma_f32_16x16x32_bf16 v[36:39], v[156:159], v[172:175], v[36:39]
	v_mfma_f32_16x16x32_bf16 v[36:39], v[160:163], v[176:179], v[36:39]
	v_mfma_f32_16x16x32_bf16 v[52:55], v[160:163], v[168:171], v[52:55]
	v_mfma_f32_16x16x32_bf16 v[52:55], v[156:159], v[164:167], v[52:55]
	s_barrier
	s_setprio 0
	s_add_i32 s55, s55, 2
	s_add_u32 s24, s24, 0x100
	s_addc_u32 s25, s25, 0
	s_add_u32 s53, s53, 0x100
	s_addc_u32 s54, s54, 0
	s_cmp_gt_u32 s55, 61
	s_cbranch_scc0 .LBB0_1456

; #define PG8_STAGE(bufoff, gbase, voff) do { _Pragma("unroll") for (int _i = 0; _i < 2; ++_i) \
;         __builtin_amdgcn_global_load_lds((const unsigned*)((const char*)(gbase) + (voff)[_i]), (PG8_LAS unsigned*)(lds + (bufoff) + ldsw + _i * 8192), 16, 0, 0); } while (0)
; #define PG8_LDA(dst, b, h) do { _Pragma("unroll") for (int m = 0; m < 4; ++m) _Pragma("unroll") for (int k = 0; k < 2; ++k) dst[m][k] = *(const PG8_LAS bf16x8*)(lds + PG8_SA(b, h) + aoff + m * 2048 + k * 1024); } while (0)
; #define PG8_LDB(dst, b, h) do { _Pragma("unroll") for (int n = 0; n < 2; ++n) _Pragma("unroll") for (int k = 0; k < 2; ++k) dst[n][k] = *(const PG8_LAS bf16x8*)(lds + PG8_SB(b, h) + boff + n * 2048 + k * 1024); } while (0)
; #define PG8_WAIT_V(n) asm volatile("s_waitcnt vmcnt(" #n ")" ::: "memory")
; #define PG8_WAIT_L(n) asm volatile("s_waitcnt lgkmcnt(" #n ")" ::: "memory")
; #define PG8_BAR __builtin_amdgcn_s_barrier()
; #define PG8_SCHED __builtin_amdgcn_sched_barrier(0)
; template <class Epi, class Sched, bool ALIGN_EPI = false, bool SP2 = false, bool I8 = false>
; __device__ __forceinline__ void gemm_phase(PG8_LAS unsigned char* lds, const Gemm g, const Sched& S, const Epi& E) {
;     ...
;         const bool has_next = S.next(ui + 1, nxt);
;         const char* nA = has_next ? (const char*)g.A + (size_t)nxt.pm * tstep : cA; const char* nB = has_next ? (const char*)g.Bt + (size_t)nxt.pn * tstep : cB;
;         for (int t = 0; t < nt; t += 2) {
;             const bool last = (t == nt - 2);
;             const char* a1 = cA + (size_t)(t + 1) * kstep;
;             const char* a2 = last ? nA : cA + (size_t)(t + 2) * kstep; const char* b2 = last ? nB : cB + (size_t)(t + 2) * kstep;
;             const char* a3 = a2 + kstep; const char* b3 = b2 + kstep;
;             if (last && has_next) S.a_ready(nxt);
;             if constexpr (SP2) {
;             PG8_LDB(B0, 0, 0); PG8_LDB(B1, 0, 1); PG8_SCHED; PG8_LDA(At, 0, 0); PG8_STAGE(PG8_SA(1, 1), a1 + hstep, voffA);
;             PG8_WAIT_V(8); PG8_WAIT_L(0); PG8_BAR; PG8_MMA(0, 0, At, B0); PG8_MMA(0, 1, At, B1); PG8_BAR; PG8_SCHED;
;             PG8_LDA(At, 0, 1); PG8_STAGE(PG8_SB(0, 0), b2, voffB); PG8_STAGE(PG8_SB(0, 1), b2 + hstep, voffB); PG8_STAGE(PG8_SA(0, 0), a2, voffA);
;             PG8_WAIT_V(8); PG8_WAIT_L(0); PG8_BAR; PG8_MMA(1, 0, At, B0); PG8_MMA(1, 1, At, B1); PG8_BAR; PG8_SCHED;
.LBB0_1590:
	s_ashr_i32 s25, s24, 31
	s_lshl_b64 s[26:27], s[24:25], 20
	s_add_u32 s26, s28, s26
	s_addc_u32 s27, s42, s27
	s_and_b64 s[36:37], s[10:11], exec
	s_cselect_b32 s25, s27, s41
	s_cselect_b32 s57, s26, s40
	s_ashr_i32 s23, s22, 31
	s_lshl_b64 s[36:37], s[22:23], 20
	s_add_u32 s36, s43, s36
	s_addc_u32 s37, s46, s37
	s_and_b64 s[48:49], s[10:11], exec
	s_cselect_b32 s23, s37, s45
	s_cselect_b32 s58, s36, s44
	s_add_u32 s40, s40, 0x80080
	s_addc_u32 s41, s41, 0
	s_add_u32 s59, s44, 0x100
	s_addc_u32 s60, s45, 0
	s_mov_b32 s61, -2
	s_add_u32 s44, s40, 0xfff80080
	s_addc_u32 s45, s41, -1
	s_add_i32 s64, 0, 0x10000
	s_cmp_eq_u32 s61, 28
	s_cselect_b32 s49, s25, s45
	s_cselect_b32 s48, s57, s44
	s_cselect_b32 s45, s23, s60
	s_cselect_b32 s44, s58, s59
	s_add_i32 s67, 0, 0x14000
	v_add_u32_e32 v144, s64, v167
	v_add_u32_e32 v158, s67, v167
	ds_read_b128 v[36:39], v144
	ds_read_b128 v[44:47], v144 offset:1024
	ds_read_b128 v[140:143], v144 offset:2048
	ds_read_b128 v[144:147], v144 offset:3072
	ds_read_b128 v[160:163], v158
	ds_read_b128 v[172:175], v158 offset:1024
	ds_read_b128 v[176:179], v158 offset:2048
	ds_read_b128 v[180:183], v158 offset:3072
	s_add_i32 m0, s50, 0xc000
	ds_read_b128 v[184:187], v171
	ds_read_b128 v[188:191], v171 offset:1024
	ds_read_b128 v[204:207], v171 offset:2048
	ds_read_b128 v[208:211], v171 offset:3072
	ds_read_b128 v[212:215], v171 offset:4096
	ds_read_b128 v[216:219], v171 offset:5120
	ds_read_b128 v[220:223], v171 offset:6144
	ds_read_b128 v[224:227], v171 offset:7168
	global_load_lds_dwordx4 v154, s[40:41]
	s_add_i32 m0, s50, 0xe000
	s_nop 0
	global_load_lds_dwordx4 v156, s[40:41]
	s_waitcnt vmcnt(8) lgkmcnt(0)
	s_setprio 1
	s_barrier
	v_mfma_i32_16x16x64_i8 v[136:139], v[36:39], v[184:187], 0
	v_mfma_i32_16x16x64_i8 v[136:139], v[44:47], v[188:191], v[136:139]
	v_mfma_i32_16x16x64_i8 v[120:123], v[44:47], v[208:211], 0
	v_mfma_i32_16x16x64_i8 v[120:123], v[36:39], v[204:207], v[120:123]
	v_mfma_i32_16x16x64_i8 v[104:107], v[36:39], v[212:215], 0
	v_mfma_i32_16x16x64_i8 v[104:107], v[44:47], v[216:219], v[104:107]
	v_mfma_i32_16x16x64_i8 v[88:91], v[44:47], v[224:227], 0
	v_mfma_i32_16x16x64_i8 v[88:91], v[36:39], v[220:223], v[88:91]
	v_mfma_i32_16x16x64_i8 v[80:83], v[140:143], v[220:223], 0
	v_mfma_i32_16x16x64_i8 v[80:83], v[144:147], v[224:227], v[80:83]
	v_mfma_i32_16x16x64_i8 v[96:99], v[144:147], v[216:219], 0
	v_mfma_i32_16x16x64_i8 v[96:99], v[140:143], v[212:215], v[96:99]
	v_mfma_i32_16x16x64_i8 v[112:115], v[140:143], v[204:207], 0
	v_mfma_i32_16x16x64_i8 v[112:115], v[144:147], v[208:211], v[112:115]
	v_mfma_i32_16x16x64_i8 v[128:131], v[144:147], v[188:191], 0
	v_mfma_i32_16x16x64_i8 v[128:131], v[140:143], v[184:187], v[128:131]
	v_mfma_i32_16x16x64_i8 v[132:135], v[160:163], v[184:187], 0
	v_mfma_i32_16x16x64_i8 v[132:135], v[172:175], v[188:191], v[132:135]
	v_mfma_i32_16x16x64_i8 v[116:119], v[172:175], v[208:211], 0
	v_mfma_i32_16x16x64_i8 v[116:119], v[160:163], v[204:207], v[116:119]
	v_mfma_i32_16x16x64_i8 v[100:103], v[160:163], v[212:215], 0
	v_mfma_i32_16x16x64_i8 v[100:103], v[172:175], v[216:219], v[100:103]
	v_mfma_i32_16x16x64_i8 v[84:87], v[172:175], v[224:227], 0
	v_mfma_i32_16x16x64_i8 v[84:87], v[160:163], v[220:223], v[84:87]
	v_mfma_i32_16x16x64_i8 v[76:79], v[176:179], v[220:223], 0
	v_mfma_i32_16x16x64_i8 v[76:79], v[180:183], v[224:227], v[76:79]
	v_mfma_i32_16x16x64_i8 v[92:95], v[180:183], v[216:219], 0
	v_mfma_i32_16x16x64_i8 v[92:95], v[176:179], v[212:215], v[92:95]
	v_mfma_i32_16x16x64_i8 v[108:111], v[176:179], v[204:207], 0
	v_mfma_i32_16x16x64_i8 v[108:111], v[180:183], v[208:211], v[108:111]
	v_mfma_i32_16x16x64_i8 v[124:127], v[180:183], v[188:191], 0
	v_mfma_i32_16x16x64_i8 v[124:127], v[176:179], v[184:187], v[124:127]
	s_barrier
	s_setprio 0
	s_add_i32 s64, s64, s47
	v_lshl_add_u64 v[164:165], s[44:45], 0, v[2:3]
	s_mov_b32 m0, s64
	ds_read_b128 v[184:187], v171 offset:16384
	ds_read_b128 v[188:191], v171 offset:17408
	ds_read_b128 v[204:207], v171 offset:18432
	ds_read_b128 v[208:211], v171 offset:19456
	ds_read_b128 v[212:215], v171 offset:20480
	ds_read_b128 v[216:219], v171 offset:21504
	ds_read_b128 v[220:223], v171 offset:22528
	ds_read_b128 v[224:227], v171 offset:23552
	global_load_lds_dwordx4 v[164:165], off
	s_add_i32 m0, s64, 0x2000
	s_add_u32 s64, s44, 0x80000
	v_lshl_add_u64 v[228:229], s[44:45], 0, v[148:149]
	s_addc_u32 s65, s45, 0
	s_add_i32 s67, s67, s47
	global_load_lds_dwordx4 v[228:229], off
	s_mov_b32 m0, s67
	v_lshl_add_u64 v[242:243], s[48:49], 0, v[150:151]
	global_load_lds_dwordx4 v2, s[64:65]
	s_add_i32 m0, s67, 0x2000
	s_nop 0
	global_load_lds_dwordx4 v148, s[64:65]
	v_lshl_add_u64 v[240:241], s[48:49], 0, v[152:153]
	s_waitcnt vmcnt(6) lgkmcnt(0)
	s_setprio 1
	s_barrier
; #define PG8_STAGE(bufoff, gbase, voff) do { _Pragma("unroll") for (int _i = 0; _i < 2; ++_i) \
;         __builtin_amdgcn_global_load_lds((const unsigned*)((const char*)(gbase) + (voff)[_i]), (PG8_LAS unsigned*)(lds + (bufoff) + ldsw + _i * 8192), 16, 0, 0); } while (0)
; #define PG8_LDA(dst, b, h) do { _Pragma("unroll") for (int m = 0; m < 4; ++m) _Pragma("unroll") for (int k = 0; k < 2; ++k) dst[m][k] = *(const PG8_LAS bf16x8*)(lds + PG8_SA(b, h) + aoff + m * 2048 + k * 1024); } while (0)
; #define PG8_LDB(dst, b, h) do { _Pragma("unroll") for (int n = 0; n < 2; ++n) _Pragma("unroll") for (int k = 0; k < 2; ++k) dst[n][k] = *(const PG8_LAS bf16x8*)(lds + PG8_SB(b, h) + boff + n * 2048 + k * 1024); } while (0)
; #define PG8_WAIT_V(n) asm volatile("s_waitcnt vmcnt(" #n ")" ::: "memory")
; #define PG8_WAIT_L(n) asm volatile("s_waitcnt lgkmcnt(" #n ")" ::: "memory")
; #define PG8_BAR __builtin_amdgcn_s_barrier()
; #define PG8_SCHED __builtin_amdgcn_sched_barrier(0)
; template <class Epi, class Sched, bool ALIGN_EPI = false, bool SP2 = false, bool I8 = false>
; __device__ __forceinline__ void gemm_phase(PG8_LAS unsigned char* lds, const Gemm g, const Sched& S, const Epi& E) {
;     ...
;             PG8_LDB(B0, 0, 0); PG8_LDB(B1, 0, 1); PG8_SCHED; PG8_LDA(At, 0, 0); PG8_STAGE(PG8_SA(1, 1), a1 + hstep, voffA);
;             PG8_WAIT_V(8); PG8_WAIT_L(0); PG8_BAR; PG8_MMA(0, 0, At, B0); PG8_MMA(0, 1, At, B1); PG8_BAR; PG8_SCHED;
;             PG8_LDA(At, 0, 1); PG8_STAGE(PG8_SB(0, 0), b2, voffB); PG8_STAGE(PG8_SB(0, 1), b2 + hstep, voffB); PG8_STAGE(PG8_SA(0, 0), a2, voffA);
;             PG8_WAIT_V(8); PG8_WAIT_L(0); PG8_BAR; PG8_MMA(1, 0, At, B0); PG8_MMA(1, 1, At, B1); PG8_BAR; PG8_SCHED;
;             PG8_LDB(B0, 1, 0); PG8_LDB(B1, 1, 1); PG8_SCHED; PG8_LDA(At, 1, 0); PG8_STAGE(PG8_SA(0, 1), a2 + hstep, voffA);
;             PG8_WAIT_V(8); PG8_WAIT_L(0); PG8_BAR; PG8_MMA(0, 0, At, B0); PG8_MMA(0, 1, At, B1); PG8_BAR; PG8_SCHED;
;             PG8_LDA(At, 1, 1); PG8_STAGE(PG8_SB(1, 0), b3, voffB); PG8_STAGE(PG8_SB(1, 1), b3 + hstep, voffB); PG8_STAGE(PG8_SA(1, 0), a3, voffA);
;             PG8_WAIT_V(8); PG8_WAIT_L(0); PG8_BAR; PG8_MMA(1, 0, At, B0); PG8_MMA(1, 1, At, B1); PG8_BAR; PG8_SCHED;
	v_mfma_i32_16x16x64_i8 v[72:75], v[36:39], v[184:187], 0
	v_mfma_i32_16x16x64_i8 v[72:75], v[44:47], v[188:191], v[72:75]
	v_mfma_i32_16x16x64_i8 v[56:59], v[44:47], v[208:211], 0
	v_mfma_i32_16x16x64_i8 v[56:59], v[36:39], v[204:207], v[56:59]
	v_mfma_i32_16x16x64_i8 v[32:35], v[36:39], v[212:215], 0
	v_mfma_i32_16x16x64_i8 v[32:35], v[44:47], v[216:219], v[32:35]
	v_mfma_i32_16x16x64_i8 v[16:19], v[44:47], v[224:227], 0
	v_mfma_i32_16x16x64_i8 v[16:19], v[36:39], v[220:223], v[16:19]
	v_mfma_i32_16x16x64_i8 v[8:11], v[140:143], v[220:223], 0
	v_mfma_i32_16x16x64_i8 v[8:11], v[144:147], v[224:227], v[8:11]
	v_mfma_i32_16x16x64_i8 v[24:27], v[144:147], v[216:219], 0
	v_mfma_i32_16x16x64_i8 v[24:27], v[140:143], v[212:215], v[24:27]
	v_mfma_i32_16x16x64_i8 v[48:51], v[140:143], v[204:207], 0
	v_mfma_i32_16x16x64_i8 v[48:51], v[144:147], v[208:211], v[48:51]
	v_mfma_i32_16x16x64_i8 v[64:67], v[144:147], v[188:191], 0
	v_mfma_i32_16x16x64_i8 v[64:67], v[140:143], v[184:187], v[64:67]
	v_mfma_i32_16x16x64_i8 v[36:39], v[160:163], v[184:187], 0
	v_mfma_i32_16x16x64_i8 v[36:39], v[172:175], v[188:191], v[36:39]
	v_mfma_i32_16x16x64_i8 v[52:55], v[172:175], v[208:211], 0
	v_mfma_i32_16x16x64_i8 v[52:55], v[160:163], v[204:207], v[52:55]
	v_mfma_i32_16x16x64_i8 v[28:31], v[160:163], v[212:215], 0
	v_mfma_i32_16x16x64_i8 v[28:31], v[172:175], v[216:219], v[28:31]
	v_mfma_i32_16x16x64_i8 v[12:15], v[172:175], v[224:227], 0
	v_mfma_i32_16x16x64_i8 v[12:15], v[160:163], v[220:223], v[12:15]
	v_mfma_i32_16x16x64_i8 v[4:7], v[176:179], v[220:223], 0
	v_mfma_i32_16x16x64_i8 v[4:7], v[180:183], v[224:227], v[4:7]
	v_mfma_i32_16x16x64_i8 v[20:23], v[180:183], v[216:219], 0
	v_mfma_i32_16x16x64_i8 v[20:23], v[176:179], v[212:215], v[20:23]
	v_mfma_i32_16x16x64_i8 v[40:43], v[176:179], v[204:207], 0
	v_mfma_i32_16x16x64_i8 v[40:43], v[180:183], v[208:211], v[40:43]
	v_mfma_i32_16x16x64_i8 v[44:47], v[180:183], v[188:191], 0
	v_mfma_i32_16x16x64_i8 v[44:47], v[176:179], v[184:187], v[44:47]
	s_barrier
	s_setprio 0
	s_mov_b32 m0, s50
	s_nop 0
	global_load_lds_dwordx4 v[240:241], off
	s_mov_b32 m0, s51
	s_nop 0
	global_load_lds_dwordx4 v[242:243], off
	s_add_i32 s64, 0, 0x18000
	s_add_i32 s65, 0, 0x1c000
	v_add_u32_e32 v144, s64, v167
	v_add_u32_e32 v158, s65, v167
	ds_read_b128 v[60:63], v144
	ds_read_b128 v[68:71], v144 offset:1024
	ds_read_b128 v[140:143], v144 offset:2048
	ds_read_b128 v[144:147], v144 offset:3072
	ds_read_b128 v[160:163], v158
	ds_read_b128 v[172:175], v158 offset:1024
	ds_read_b128 v[176:179], v158 offset:2048
	ds_read_b128 v[180:183], v158 offset:3072
	s_add_u32 s48, s48, 0x80000
	s_addc_u32 s49, s49, 0
	s_mov_b32 m0, s52
	ds_read_b128 v[184:187], v171 offset:32768
	ds_read_b128 v[188:191], v171 offset:33792
	ds_read_b128 v[204:207], v171 offset:34816
	ds_read_b128 v[208:211], v171 offset:35840
	ds_read_b128 v[212:215], v171 offset:36864
	ds_read_b128 v[216:219], v171 offset:37888
	ds_read_b128 v[220:223], v171 offset:38912
	ds_read_b128 v[224:227], v171 offset:39936
	global_load_lds_dwordx4 v152, s[48:49]
	s_mov_b32 m0, s53
	s_nop 0
	global_load_lds_dwordx4 v150, s[48:49]
	s_waitcnt vmcnt(8) lgkmcnt(0)
	s_setprio 1
	s_barrier
	v_mfma_i32_16x16x64_i8 v[136:139], v[60:63], v[184:187], v[136:139]
	v_mfma_i32_16x16x64_i8 v[136:139], v[68:71], v[188:191], v[136:139]
	v_mfma_i32_16x16x64_i8 v[120:123], v[68:71], v[208:211], v[120:123]
	v_mfma_i32_16x16x64_i8 v[120:123], v[60:63], v[204:207], v[120:123]
	v_mfma_i32_16x16x64_i8 v[104:107], v[60:63], v[212:215], v[104:107]
	v_mfma_i32_16x16x64_i8 v[104:107], v[68:71], v[216:219], v[104:107]
	v_mfma_i32_16x16x64_i8 v[88:91], v[68:71], v[224:227], v[88:91]
	v_mfma_i32_16x16x64_i8 v[88:91], v[60:63], v[220:223], v[88:91]
	v_mfma_i32_16x16x64_i8 v[80:83], v[140:143], v[220:223], v[80:83]
	v_mfma_i32_16x16x64_i8 v[80:83], v[144:147], v[224:227], v[80:83]
	v_mfma_i32_16x16x64_i8 v[96:99], v[144:147], v[216:219], v[96:99]
	v_mfma_i32_16x16x64_i8 v[96:99], v[140:143], v[212:215], v[96:99]
	v_mfma_i32_16x16x64_i8 v[112:115], v[140:143], v[204:207], v[112:115]
	v_mfma_i32_16x16x64_i8 v[112:115], v[144:147], v[208:211], v[112:115]
	v_mfma_i32_16x16x64_i8 v[128:131], v[144:147], v[188:191], v[128:131]
	v_mfma_i32_16x16x64_i8 v[128:131], v[140:143], v[184:187], v[128:131]
	v_mfma_i32_16x16x64_i8 v[132:135], v[160:163], v[184:187], v[132:135]
	v_mfma_i32_16x16x64_i8 v[132:135], v[172:175], v[188:191], v[132:135]
	v_mfma_i32_16x16x64_i8 v[116:119], v[172:175], v[208:211], v[116:119]
	v_mfma_i32_16x16x64_i8 v[116:119], v[160:163], v[204:207], v[116:119]
	v_mfma_i32_16x16x64_i8 v[100:103], v[160:163], v[212:215], v[100:103]
	v_mfma_i32_16x16x64_i8 v[100:103], v[172:175], v[216:219], v[100:103]
	v_mfma_i32_16x16x64_i8 v[84:87], v[172:175], v[224:227], v[84:87]
	v_mfma_i32_16x16x64_i8 v[84:87], v[160:163], v[220:223], v[84:87]
	v_mfma_i32_16x16x64_i8 v[76:79], v[176:179], v[220:223], v[76:79]
	v_mfma_i32_16x16x64_i8 v[76:79], v[180:183], v[224:227], v[76:79]
	v_mfma_i32_16x16x64_i8 v[92:95], v[180:183], v[216:219], v[92:95]
	v_mfma_i32_16x16x64_i8 v[92:95], v[176:179], v[212:215], v[92:95]
	v_mfma_i32_16x16x64_i8 v[108:111], v[176:179], v[204:207], v[108:111]
	v_mfma_i32_16x16x64_i8 v[108:111], v[180:183], v[208:211], v[108:111]
	v_mfma_i32_16x16x64_i8 v[124:127], v[180:183], v[188:191], v[124:127]
	v_mfma_i32_16x16x64_i8 v[124:127], v[176:179], v[184:187], v[124:127]
	s_barrier
	s_setprio 0
	s_add_i32 s48, s64, s47
	v_lshl_add_u64 v[164:165], v[164:165], 0, s[84:85]
	s_mov_b32 m0, s48
	ds_read_b128 v[184:187], v171 offset:49152
	ds_read_b128 v[188:191], v171 offset:50176
	ds_read_b128 v[204:207], v171 offset:51200
	ds_read_b128 v[208:211], v171 offset:52224
	ds_read_b128 v[212:215], v171 offset:53248
	ds_read_b128 v[216:219], v171 offset:54272
	ds_read_b128 v[220:223], v171 offset:55296
	ds_read_b128 v[224:227], v171 offset:56320
	global_load_lds_dwordx4 v[164:165], off
	s_add_i32 m0, s48, 0x2000
	s_add_u32 s44, s44, 0x80080
	v_lshl_add_u64 v[164:165], v[228:229], 0, s[84:85]
	s_addc_u32 s45, s45, 0
	s_add_i32 s48, s65, s47
	global_load_lds_dwordx4 v[164:165], off
	s_mov_b32 m0, s48
	s_nop 0
	global_load_lds_dwordx4 v2, s[44:45]
	s_add_i32 m0, s48, 0x2000
	s_nop 0
	global_load_lds_dwordx4 v148, s[44:45]
	s_cmp_eq_u32 s61, 28
	s_cbranch_scc0 .Ldefer_1591_peel
	v_lshl_add_u64 v[164:165], v[240:241], 0, s[84:85]
	s_mov_b32 m0, s54
	s_nop 0
	global_load_lds_dwordx4 v[164:165], off
	v_lshl_add_u64 v[164:165], v[242:243], 0, s[84:85]
	s_mov_b32 m0, s55
	s_nop 0
	global_load_lds_dwordx4 v[164:165], off
; #define PG8_STAGE(bufoff, gbase, voff) do { _Pragma("unroll") for (int _i = 0; _i < 2; ++_i) \
;         __builtin_amdgcn_global_load_lds((const unsigned*)((const char*)(gbase) + (voff)[_i]), (PG8_LAS unsigned*)(lds + (bufoff) + ldsw + _i * 8192), 16, 0, 0); } while (0)
; #define PG8_LDA(dst, b, h) do { _Pragma("unroll") for (int m = 0; m < 4; ++m) _Pragma("unroll") for (int k = 0; k < 2; ++k) dst[m][k] = *(const PG8_LAS bf16x8*)(lds + PG8_SA(b, h) + aoff + m * 2048 + k * 1024); } while (0)
; #define PG8_WAIT_V(n) asm volatile("s_waitcnt vmcnt(" #n ")" ::: "memory")
; #define PG8_WAIT_L(n) asm volatile("s_waitcnt lgkmcnt(" #n ")" ::: "memory")
; #define PG8_BAR __builtin_amdgcn_s_barrier()
; template <class Epi, class Sched, bool ALIGN_EPI = false, bool SP2 = false, bool I8 = false>
; __device__ __forceinline__ void gemm_phase(PG8_LAS unsigned char* lds, const Gemm g, const Sched& S, const Epi& E) {
;     ...
;         for (int t = 0; t < nt; t += 2) {
;             const bool last = (t == nt - 2);
;             const char* a1 = cA + (size_t)(t + 1) * kstep;
;             const char* a2 = last ? nA : cA + (size_t)(t + 2) * kstep; const char* b2 = last ? nB : cB + (size_t)(t + 2) * kstep;
;             const char* a3 = a2 + kstep; const char* b3 = b2 + kstep;
;             if (last && has_next) S.a_ready(nxt);
;             if constexpr (SP2) {
;             PG8_LDB(B0, 0, 0); PG8_LDB(B1, 0, 1); PG8_SCHED; PG8_LDA(At, 0, 0); PG8_STAGE(PG8_SA(1, 1), a1 + hstep, voffA);
;             PG8_WAIT_V(8); PG8_WAIT_L(0); PG8_BAR; PG8_MMA(0, 0, At, B0); PG8_MMA(0, 1, At, B1); PG8_BAR; PG8_SCHED;
;             PG8_LDA(At, 0, 1); PG8_STAGE(PG8_SB(0, 0), b2, voffB); PG8_STAGE(PG8_SB(0, 1), b2 + hstep, voffB); PG8_STAGE(PG8_SA(0, 0), a2, voffA);
;             PG8_WAIT_V(8); PG8_WAIT_L(0); PG8_BAR; PG8_MMA(1, 0, At, B0); PG8_MMA(1, 1, At, B1); PG8_BAR; PG8_SCHED;
;             PG8_LDB(B0, 1, 0); PG8_LDB(B1, 1, 1); PG8_SCHED; PG8_LDA(At, 1, 0); PG8_STAGE(PG8_SA(0, 1), a2 + hstep, voffA);
;             PG8_WAIT_V(8); PG8_WAIT_L(0); PG8_BAR; PG8_MMA(0, 0, At, B0); PG8_MMA(0, 1, At, B1); PG8_BAR; PG8_SCHED;
;             PG8_LDA(At, 1, 1); PG8_STAGE(PG8_SB(1, 0), b3, voffB); PG8_STAGE(PG8_SB(1, 1), b3 + hstep, voffB); PG8_STAGE(PG8_SA(1, 0), a3, voffA);
;             PG8_WAIT_V(8); PG8_WAIT_L(0); PG8_BAR; PG8_MMA(1, 0, At, B0); PG8_MMA(1, 1, At, B1); PG8_BAR; PG8_SCHED;
.Ldefer_1591_peel:
	s_waitcnt vmcnt(6) lgkmcnt(0)
	s_setprio 1
	s_barrier
	v_mfma_i32_16x16x64_i8 v[72:75], v[60:63], v[184:187], v[72:75]
	v_mfma_i32_16x16x64_i8 v[72:75], v[68:71], v[188:191], v[72:75]
	v_mfma_i32_16x16x64_i8 v[56:59], v[68:71], v[208:211], v[56:59]
	v_mfma_i32_16x16x64_i8 v[56:59], v[60:63], v[204:207], v[56:59]
	v_mfma_i32_16x16x64_i8 v[32:35], v[60:63], v[212:215], v[32:35]
	v_mfma_i32_16x16x64_i8 v[32:35], v[68:71], v[216:219], v[32:35]
	v_mfma_i32_16x16x64_i8 v[16:19], v[68:71], v[224:227], v[16:19]
	v_mfma_i32_16x16x64_i8 v[16:19], v[60:63], v[220:223], v[16:19]
	v_mfma_i32_16x16x64_i8 v[8:11], v[140:143], v[220:223], v[8:11]
	v_mfma_i32_16x16x64_i8 v[8:11], v[144:147], v[224:227], v[8:11]
	v_mfma_i32_16x16x64_i8 v[24:27], v[144:147], v[216:219], v[24:27]
	v_mfma_i32_16x16x64_i8 v[24:27], v[140:143], v[212:215], v[24:27]
	v_mfma_i32_16x16x64_i8 v[48:51], v[140:143], v[204:207], v[48:51]
	v_mfma_i32_16x16x64_i8 v[48:51], v[144:147], v[208:211], v[48:51]
	v_mfma_i32_16x16x64_i8 v[64:67], v[144:147], v[188:191], v[64:67]
	v_mfma_i32_16x16x64_i8 v[64:67], v[140:143], v[184:187], v[64:67]
	v_mfma_i32_16x16x64_i8 v[36:39], v[160:163], v[184:187], v[36:39]
	v_mfma_i32_16x16x64_i8 v[68:71], v[172:175], v[188:191], v[36:39]
	v_mfma_i32_16x16x64_i8 v[36:39], v[172:175], v[208:211], v[52:55]
	v_mfma_i32_16x16x64_i8 v[52:55], v[160:163], v[204:207], v[36:39]
	v_mfma_i32_16x16x64_i8 v[28:31], v[160:163], v[212:215], v[28:31]
	v_mfma_i32_16x16x64_i8 v[28:31], v[172:175], v[216:219], v[28:31]
	v_mfma_i32_16x16x64_i8 v[12:15], v[172:175], v[224:227], v[12:15]
	v_mfma_i32_16x16x64_i8 v[12:15], v[160:163], v[220:223], v[12:15]
	v_mfma_i32_16x16x64_i8 v[4:7], v[176:179], v[220:223], v[4:7]
	v_mfma_i32_16x16x64_i8 v[4:7], v[180:183], v[224:227], v[4:7]
	v_mfma_i32_16x16x64_i8 v[20:23], v[180:183], v[216:219], v[20:23]
	v_mfma_i32_16x16x64_i8 v[20:23], v[176:179], v[212:215], v[20:23]
	v_mfma_i32_16x16x64_i8 v[36:39], v[176:179], v[204:207], v[40:43]
	v_mfma_i32_16x16x64_i8 v[40:43], v[180:183], v[208:211], v[36:39]
	v_mfma_i32_16x16x64_i8 v[36:39], v[180:183], v[188:191], v[44:47]
	v_mfma_i32_16x16x64_i8 v[60:63], v[176:179], v[184:187], v[36:39]
	s_barrier
	s_setprio 0
	s_add_i32 s61, s61, 2
	s_add_u32 s40, s40, 0x100
	s_addc_u32 s41, s41, 0
	s_add_u32 s59, s59, 0x100
	s_addc_u32 s60, s60, 0
	s_cmp_gt_u32 s61, 29
	s_cbranch_scc1 .Lkloop_exit_3
.LBB0_1591:
	s_add_u32 s44, s40, 0xfff80080
	s_addc_u32 s45, s41, -1
	s_add_i32 s64, 0, 0x10000
	s_cmp_eq_u32 s61, 28
	s_cselect_b32 s49, s25, s45
	s_cselect_b32 s48, s57, s44
	s_cselect_b32 s45, s23, s60
	s_cselect_b32 s44, s58, s59
	s_add_i32 s67, 0, 0x14000
	v_add_u32_e32 v144, s64, v167
	v_add_u32_e32 v158, s67, v167
	ds_read_b128 v[36:39], v144
	ds_read_b128 v[44:47], v144 offset:1024
	ds_read_b128 v[140:143], v144 offset:2048
	ds_read_b128 v[144:147], v144 offset:3072
	ds_read_b128 v[160:163], v158
	ds_read_b128 v[172:175], v158 offset:1024
	ds_read_b128 v[176:179], v158 offset:2048
	ds_read_b128 v[180:183], v158 offset:3072
	v_lshl_add_u64 v[164:165], v[240:241], 0, s[84:85]
	s_mov_b32 m0, s54
	s_nop 0
	global_load_lds_dwordx4 v[164:165], off
	v_lshl_add_u64 v[164:165], v[242:243], 0, s[84:85]
	s_mov_b32 m0, s55
	s_nop 0
	global_load_lds_dwordx4 v[164:165], off
	s_add_i32 m0, s50, 0xc000
	ds_read_b128 v[184:187], v171
	ds_read_b128 v[188:191], v171 offset:1024
	ds_read_b128 v[204:207], v171 offset:2048
	ds_read_b128 v[208:211], v171 offset:3072
	ds_read_b128 v[212:215], v171 offset:4096
	ds_read_b128 v[216:219], v171 offset:5120
	ds_read_b128 v[220:223], v171 offset:6144
	ds_read_b128 v[224:227], v171 offset:7168
	global_load_lds_dwordx4 v154, s[40:41]
	s_add_i32 m0, s50, 0xe000
	s_nop 0
	global_load_lds_dwordx4 v156, s[40:41]
	s_waitcnt vmcnt(8) lgkmcnt(0)
	s_setprio 1
	s_barrier
	v_mfma_i32_16x16x64_i8 v[136:139], v[36:39], v[184:187], v[136:139]
	v_mfma_i32_16x16x64_i8 v[136:139], v[44:47], v[188:191], v[136:139]
	v_mfma_i32_16x16x64_i8 v[120:123], v[44:47], v[208:211], v[120:123]
	v_mfma_i32_16x16x64_i8 v[120:123], v[36:39], v[204:207], v[120:123]
	v_mfma_i32_16x16x64_i8 v[104:107], v[36:39], v[212:215], v[104:107]
	v_mfma_i32_16x16x64_i8 v[104:107], v[44:47], v[216:219], v[104:107]
	v_mfma_i32_16x16x64_i8 v[88:91], v[44:47], v[224:227], v[88:91]
	v_mfma_i32_16x16x64_i8 v[88:91], v[36:39], v[220:223], v[88:91]
	v_mfma_i32_16x16x64_i8 v[80:83], v[140:143], v[220:223], v[80:83]
	v_mfma_i32_16x16x64_i8 v[80:83], v[144:147], v[224:227], v[80:83]
	v_mfma_i32_16x16x64_i8 v[96:99], v[144:147], v[216:219], v[96:99]
	v_mfma_i32_16x16x64_i8 v[96:99], v[140:143], v[212:215], v[96:99]
	v_mfma_i32_16x16x64_i8 v[112:115], v[140:143], v[204:207], v[112:115]
	v_mfma_i32_16x16x64_i8 v[112:115], v[144:147], v[208:211], v[112:115]
	v_mfma_i32_16x16x64_i8 v[128:131], v[144:147], v[188:191], v[128:131]
	v_mfma_i32_16x16x64_i8 v[128:131], v[140:143], v[184:187], v[128:131]
	v_mfma_i32_16x16x64_i8 v[132:135], v[160:163], v[184:187], v[132:135]
	v_mfma_i32_16x16x64_i8 v[132:135], v[172:175], v[188:191], v[132:135]
	v_mfma_i32_16x16x64_i8 v[116:119], v[172:175], v[208:211], v[116:119]
	v_mfma_i32_16x16x64_i8 v[116:119], v[160:163], v[204:207], v[116:119]
	v_mfma_i32_16x16x64_i8 v[100:103], v[160:163], v[212:215], v[100:103]
	v_mfma_i32_16x16x64_i8 v[100:103], v[172:175], v[216:219], v[100:103]
	v_mfma_i32_16x16x64_i8 v[84:87], v[172:175], v[224:227], v[84:87]
	v_mfma_i32_16x16x64_i8 v[84:87], v[160:163], v[220:223], v[84:87]
	v_mfma_i32_16x16x64_i8 v[76:79], v[176:179], v[220:223], v[76:79]
	v_mfma_i32_16x16x64_i8 v[76:79], v[180:183], v[224:227], v[76:79]
	v_mfma_i32_16x16x64_i8 v[92:95], v[180:183], v[216:219], v[92:95]
	v_mfma_i32_16x16x64_i8 v[92:95], v[176:179], v[212:215], v[92:95]
	v_mfma_i32_16x16x64_i8 v[108:111], v[176:179], v[204:207], v[108:111]
	v_mfma_i32_16x16x64_i8 v[108:111], v[180:183], v[208:211], v[108:111]
	v_mfma_i32_16x16x64_i8 v[124:127], v[180:183], v[188:191], v[124:127]
	v_mfma_i32_16x16x64_i8 v[124:127], v[176:179], v[184:187], v[124:127]
	s_barrier
; #define PG8_STAGE(bufoff, gbase, voff) do { _Pragma("unroll") for (int _i = 0; _i < 2; ++_i) \
;         __builtin_amdgcn_global_load_lds((const unsigned*)((const char*)(gbase) + (voff)[_i]), (PG8_LAS unsigned*)(lds + (bufoff) + ldsw + _i * 8192), 16, 0, 0); } while (0)
; #define PG8_LDA(dst, b, h) do { _Pragma("unroll") for (int m = 0; m < 4; ++m) _Pragma("unroll") for (int k = 0; k < 2; ++k) dst[m][k] = *(const PG8_LAS bf16x8*)(lds + PG8_SA(b, h) + aoff + m * 2048 + k * 1024); } while (0)
; #define PG8_LDB(dst, b, h) do { _Pragma("unroll") for (int n = 0; n < 2; ++n) _Pragma("unroll") for (int k = 0; k < 2; ++k) dst[n][k] = *(const PG8_LAS bf16x8*)(lds + PG8_SB(b, h) + boff + n * 2048 + k * 1024); } while (0)
; #define PG8_WAIT_V(n) asm volatile("s_waitcnt vmcnt(" #n ")" ::: "memory")
; #define PG8_WAIT_L(n) asm volatile("s_waitcnt lgkmcnt(" #n ")" ::: "memory")
; #define PG8_BAR __builtin_amdgcn_s_barrier()
; #define PG8_SCHED __builtin_amdgcn_sched_barrier(0)
; template <class Epi, class Sched, bool ALIGN_EPI = false, bool SP2 = false, bool I8 = false>
; __device__ __forceinline__ void gemm_phase(PG8_LAS unsigned char* lds, const Gemm g, const Sched& S, const Epi& E) {
;     ...
;             PG8_LDB(B0, 0, 0); PG8_LDB(B1, 0, 1); PG8_SCHED; PG8_LDA(At, 0, 0); PG8_STAGE(PG8_SA(1, 1), a1 + hstep, voffA);
;             PG8_WAIT_V(8); PG8_WAIT_L(0); PG8_BAR; PG8_MMA(0, 0, At, B0); PG8_MMA(0, 1, At, B1); PG8_BAR; PG8_SCHED;
;             PG8_LDA(At, 0, 1); PG8_STAGE(PG8_SB(0, 0), b2, voffB); PG8_STAGE(PG8_SB(0, 1), b2 + hstep, voffB); PG8_STAGE(PG8_SA(0, 0), a2, voffA);
;             PG8_WAIT_V(8); PG8_WAIT_L(0); PG8_BAR; PG8_MMA(1, 0, At, B0); PG8_MMA(1, 1, At, B1); PG8_BAR; PG8_SCHED;
;             PG8_LDB(B0, 1, 0); PG8_LDB(B1, 1, 1); PG8_SCHED; PG8_LDA(At, 1, 0); PG8_STAGE(PG8_SA(0, 1), a2 + hstep, voffA);
;             PG8_WAIT_V(8); PG8_WAIT_L(0); PG8_BAR; PG8_MMA(0, 0, At, B0); PG8_MMA(0, 1, At, B1); PG8_BAR; PG8_SCHED;
;             PG8_LDA(At, 1, 1); PG8_STAGE(PG8_SB(1, 0), b3, voffB); PG8_STAGE(PG8_SB(1, 1), b3 + hstep, voffB); PG8_STAGE(PG8_SA(1, 0), a3, voffA);
;             PG8_WAIT_V(8); PG8_WAIT_L(0); PG8_BAR; PG8_MMA(1, 0, At, B0); PG8_MMA(1, 1, At, B1); PG8_BAR; PG8_SCHED;
	s_setprio 0
	s_add_i32 s64, s64, s47
	v_lshl_add_u64 v[164:165], s[44:45], 0, v[2:3]
	s_mov_b32 m0, s64
	ds_read_b128 v[184:187], v171 offset:16384
	ds_read_b128 v[188:191], v171 offset:17408
	ds_read_b128 v[204:207], v171 offset:18432
	ds_read_b128 v[208:211], v171 offset:19456
	ds_read_b128 v[212:215], v171 offset:20480
	ds_read_b128 v[216:219], v171 offset:21504
	ds_read_b128 v[220:223], v171 offset:22528
	ds_read_b128 v[224:227], v171 offset:23552
	global_load_lds_dwordx4 v[164:165], off
	s_add_i32 m0, s64, 0x2000
	s_add_u32 s64, s44, 0x80000
	v_lshl_add_u64 v[228:229], s[44:45], 0, v[148:149]
	s_addc_u32 s65, s45, 0
	s_add_i32 s67, s67, s47
	global_load_lds_dwordx4 v[228:229], off
	s_mov_b32 m0, s67
	v_lshl_add_u64 v[242:243], s[48:49], 0, v[150:151]
	global_load_lds_dwordx4 v2, s[64:65]
	s_add_i32 m0, s67, 0x2000
	s_nop 0
	global_load_lds_dwordx4 v148, s[64:65]
	v_lshl_add_u64 v[240:241], s[48:49], 0, v[152:153]
	s_waitcnt vmcnt(6) lgkmcnt(0)
	s_setprio 1
	s_barrier
	v_mfma_i32_16x16x64_i8 v[72:75], v[36:39], v[184:187], v[72:75]
	v_mfma_i32_16x16x64_i8 v[72:75], v[44:47], v[188:191], v[72:75]
	v_mfma_i32_16x16x64_i8 v[56:59], v[44:47], v[208:211], v[56:59]
	v_mfma_i32_16x16x64_i8 v[56:59], v[36:39], v[204:207], v[56:59]
	v_mfma_i32_16x16x64_i8 v[32:35], v[36:39], v[212:215], v[32:35]
	v_mfma_i32_16x16x64_i8 v[32:35], v[44:47], v[216:219], v[32:35]
	v_mfma_i32_16x16x64_i8 v[16:19], v[44:47], v[224:227], v[16:19]
	v_mfma_i32_16x16x64_i8 v[16:19], v[36:39], v[220:223], v[16:19]
	v_mfma_i32_16x16x64_i8 v[8:11], v[140:143], v[220:223], v[8:11]
	v_mfma_i32_16x16x64_i8 v[8:11], v[144:147], v[224:227], v[8:11]
	v_mfma_i32_16x16x64_i8 v[24:27], v[144:147], v[216:219], v[24:27]
	v_mfma_i32_16x16x64_i8 v[24:27], v[140:143], v[212:215], v[24:27]
	v_mfma_i32_16x16x64_i8 v[48:51], v[140:143], v[204:207], v[48:51]
	v_mfma_i32_16x16x64_i8 v[48:51], v[144:147], v[208:211], v[48:51]
	v_mfma_i32_16x16x64_i8 v[64:67], v[144:147], v[188:191], v[64:67]
	v_mfma_i32_16x16x64_i8 v[64:67], v[140:143], v[184:187], v[64:67]
	v_mfma_i32_16x16x64_i8 v[36:39], v[160:163], v[184:187], v[68:71]
	v_mfma_i32_16x16x64_i8 v[36:39], v[172:175], v[188:191], v[36:39]
	v_mfma_i32_16x16x64_i8 v[52:55], v[172:175], v[208:211], v[52:55]
	v_mfma_i32_16x16x64_i8 v[52:55], v[160:163], v[204:207], v[52:55]
	v_mfma_i32_16x16x64_i8 v[28:31], v[160:163], v[212:215], v[28:31]
	v_mfma_i32_16x16x64_i8 v[28:31], v[172:175], v[216:219], v[28:31]
	v_mfma_i32_16x16x64_i8 v[12:15], v[172:175], v[224:227], v[12:15]
	v_mfma_i32_16x16x64_i8 v[12:15], v[160:163], v[220:223], v[12:15]
	v_mfma_i32_16x16x64_i8 v[4:7], v[176:179], v[220:223], v[4:7]
	v_mfma_i32_16x16x64_i8 v[4:7], v[180:183], v[224:227], v[4:7]
	v_mfma_i32_16x16x64_i8 v[20:23], v[180:183], v[216:219], v[20:23]
	v_mfma_i32_16x16x64_i8 v[20:23], v[176:179], v[212:215], v[20:23]
	v_mfma_i32_16x16x64_i8 v[40:43], v[176:179], v[204:207], v[40:43]
	v_mfma_i32_16x16x64_i8 v[40:43], v[180:183], v[208:211], v[40:43]
	v_mfma_i32_16x16x64_i8 v[44:47], v[180:183], v[188:191], v[60:63]
	v_mfma_i32_16x16x64_i8 v[44:47], v[176:179], v[184:187], v[44:47]
	s_barrier
	s_setprio 0
	s_mov_b32 m0, s50
	s_nop 0
	global_load_lds_dwordx4 v[240:241], off
	s_mov_b32 m0, s51
	s_nop 0
	global_load_lds_dwordx4 v[242:243], off
	s_add_i32 s64, 0, 0x18000
	s_add_i32 s65, 0, 0x1c000
	v_add_u32_e32 v144, s64, v167
	v_add_u32_e32 v158, s65, v167
	ds_read_b128 v[60:63], v144
	ds_read_b128 v[68:71], v144 offset:1024
	ds_read_b128 v[140:143], v144 offset:2048
	ds_read_b128 v[144:147], v144 offset:3072
	ds_read_b128 v[160:163], v158
	ds_read_b128 v[172:175], v158 offset:1024
	ds_read_b128 v[176:179], v158 offset:2048
	ds_read_b128 v[180:183], v158 offset:3072
	s_add_u32 s48, s48, 0x80000
	s_addc_u32 s49, s49, 0
	s_mov_b32 m0, s52
	ds_read_b128 v[184:187], v171 offset:32768
	ds_read_b128 v[188:191], v171 offset:33792
	ds_read_b128 v[204:207], v171 offset:34816
	ds_read_b128 v[208:211], v171 offset:35840
	ds_read_b128 v[212:215], v171 offset:36864
	ds_read_b128 v[216:219], v171 offset:37888
	ds_read_b128 v[220:223], v171 offset:38912
	ds_read_b128 v[224:227], v171 offset:39936
	global_load_lds_dwordx4 v152, s[48:49]
	s_mov_b32 m0, s53
	s_nop 0
	global_load_lds_dwordx4 v150, s[48:49]
	s_waitcnt vmcnt(8) lgkmcnt(0)
	s_setprio 1
	s_barrier
; #define PG8_STAGE(bufoff, gbase, voff) do { _Pragma("unroll") for (int _i = 0; _i < 2; ++_i) \
;         __builtin_amdgcn_global_load_lds((const unsigned*)((const char*)(gbase) + (voff)[_i]), (PG8_LAS unsigned*)(lds + (bufoff) + ldsw + _i * 8192), 16, 0, 0); } while (0)
; #define PG8_LDA(dst, b, h) do { _Pragma("unroll") for (int m = 0; m < 4; ++m) _Pragma("unroll") for (int k = 0; k < 2; ++k) dst[m][k] = *(const PG8_LAS bf16x8*)(lds + PG8_SA(b, h) + aoff + m * 2048 + k * 1024); } while (0)
; #define PG8_WAIT_V(n) asm volatile("s_waitcnt vmcnt(" #n ")" ::: "memory")
; #define PG8_WAIT_L(n) asm volatile("s_waitcnt lgkmcnt(" #n ")" ::: "memory")
; #define PG8_BAR __builtin_amdgcn_s_barrier()
; #define PG8_SCHED __builtin_amdgcn_sched_barrier(0)
; template <class Epi, class Sched, bool ALIGN_EPI = false, bool SP2 = false, bool I8 = false>
; __device__ __forceinline__ void gemm_phase(PG8_LAS unsigned char* lds, const Gemm g, const Sched& S, const Epi& E) {
;     ...
;             PG8_WAIT_V(8); PG8_WAIT_L(0); PG8_BAR; PG8_MMA(0, 0, At, B0); PG8_MMA(0, 1, At, B1); PG8_BAR; PG8_SCHED;
;             PG8_LDA(At, 1, 1); PG8_STAGE(PG8_SB(1, 0), b3, voffB); PG8_STAGE(PG8_SB(1, 1), b3 + hstep, voffB); PG8_STAGE(PG8_SA(1, 0), a3, voffA);
;             PG8_WAIT_V(8); PG8_WAIT_L(0); PG8_BAR; PG8_MMA(1, 0, At, B0); PG8_MMA(1, 1, At, B1); PG8_BAR; PG8_SCHED;
	v_mfma_i32_16x16x64_i8 v[136:139], v[60:63], v[184:187], v[136:139]
	v_mfma_i32_16x16x64_i8 v[136:139], v[68:71], v[188:191], v[136:139]
	v_mfma_i32_16x16x64_i8 v[120:123], v[68:71], v[208:211], v[120:123]
	v_mfma_i32_16x16x64_i8 v[120:123], v[60:63], v[204:207], v[120:123]
	v_mfma_i32_16x16x64_i8 v[104:107], v[60:63], v[212:215], v[104:107]
	v_mfma_i32_16x16x64_i8 v[104:107], v[68:71], v[216:219], v[104:107]
	v_mfma_i32_16x16x64_i8 v[88:91], v[68:71], v[224:227], v[88:91]
	v_mfma_i32_16x16x64_i8 v[88:91], v[60:63], v[220:223], v[88:91]
	v_mfma_i32_16x16x64_i8 v[80:83], v[140:143], v[220:223], v[80:83]
	v_mfma_i32_16x16x64_i8 v[80:83], v[144:147], v[224:227], v[80:83]
	v_mfma_i32_16x16x64_i8 v[96:99], v[144:147], v[216:219], v[96:99]
	v_mfma_i32_16x16x64_i8 v[96:99], v[140:143], v[212:215], v[96:99]
	v_mfma_i32_16x16x64_i8 v[112:115], v[140:143], v[204:207], v[112:115]
	v_mfma_i32_16x16x64_i8 v[112:115], v[144:147], v[208:211], v[112:115]
	v_mfma_i32_16x16x64_i8 v[128:131], v[144:147], v[188:191], v[128:131]
	v_mfma_i32_16x16x64_i8 v[128:131], v[140:143], v[184:187], v[128:131]
	v_mfma_i32_16x16x64_i8 v[132:135], v[160:163], v[184:187], v[132:135]
	v_mfma_i32_16x16x64_i8 v[132:135], v[172:175], v[188:191], v[132:135]
	v_mfma_i32_16x16x64_i8 v[116:119], v[172:175], v[208:211], v[116:119]
	v_mfma_i32_16x16x64_i8 v[116:119], v[160:163], v[204:207], v[116:119]
	v_mfma_i32_16x16x64_i8 v[100:103], v[160:163], v[212:215], v[100:103]
	v_mfma_i32_16x16x64_i8 v[100:103], v[172:175], v[216:219], v[100:103]
	v_mfma_i32_16x16x64_i8 v[84:87], v[172:175], v[224:227], v[84:87]
	v_mfma_i32_16x16x64_i8 v[84:87], v[160:163], v[220:223], v[84:87]
	v_mfma_i32_16x16x64_i8 v[76:79], v[176:179], v[220:223], v[76:79]
	v_mfma_i32_16x16x64_i8 v[76:79], v[180:183], v[224:227], v[76:79]
	v_mfma_i32_16x16x64_i8 v[92:95], v[180:183], v[216:219], v[92:95]
	v_mfma_i32_16x16x64_i8 v[92:95], v[176:179], v[212:215], v[92:95]
	v_mfma_i32_16x16x64_i8 v[108:111], v[176:179], v[204:207], v[108:111]
	v_mfma_i32_16x16x64_i8 v[108:111], v[180:183], v[208:211], v[108:111]
	v_mfma_i32_16x16x64_i8 v[124:127], v[180:183], v[188:191], v[124:127]
	v_mfma_i32_16x16x64_i8 v[124:127], v[176:179], v[184:187], v[124:127]
	s_barrier
	s_setprio 0
	s_add_i32 s48, s64, s47
	v_lshl_add_u64 v[164:165], v[164:165], 0, s[84:85]
	s_mov_b32 m0, s48
	ds_read_b128 v[184:187], v171 offset:49152
	ds_read_b128 v[188:191], v171 offset:50176
	ds_read_b128 v[204:207], v171 offset:51200
	ds_read_b128 v[208:211], v171 offset:52224
	ds_read_b128 v[212:215], v171 offset:53248
	ds_read_b128 v[216:219], v171 offset:54272
	ds_read_b128 v[220:223], v171 offset:55296
	ds_read_b128 v[224:227], v171 offset:56320
	global_load_lds_dwordx4 v[164:165], off
	s_add_i32 m0, s48, 0x2000
	s_add_u32 s44, s44, 0x80080
	v_lshl_add_u64 v[164:165], v[228:229], 0, s[84:85]
	s_addc_u32 s45, s45, 0
	s_add_i32 s48, s65, s47
	global_load_lds_dwordx4 v[164:165], off
	s_mov_b32 m0, s48
	s_nop 0
	global_load_lds_dwordx4 v2, s[44:45]
	s_add_i32 m0, s48, 0x2000
	s_nop 0
	global_load_lds_dwordx4 v148, s[44:45]
	s_cmp_eq_u32 s61, 28
	s_cbranch_scc0 .Ldefer_1591_body
	v_lshl_add_u64 v[164:165], v[240:241], 0, s[84:85]
	s_mov_b32 m0, s54
	s_nop 0
	global_load_lds_dwordx4 v[164:165], off
	v_lshl_add_u64 v[164:165], v[242:243], 0, s[84:85]
	s_mov_b32 m0, s55
	s_nop 0
	global_load_lds_dwordx4 v[164:165], off
.Ldefer_1591_body:
	s_waitcnt vmcnt(6) lgkmcnt(0)
	s_setprio 1
	s_barrier
	v_mfma_i32_16x16x64_i8 v[72:75], v[60:63], v[184:187], v[72:75]
	v_mfma_i32_16x16x64_i8 v[72:75], v[68:71], v[188:191], v[72:75]
	v_mfma_i32_16x16x64_i8 v[56:59], v[68:71], v[208:211], v[56:59]
	v_mfma_i32_16x16x64_i8 v[56:59], v[60:63], v[204:207], v[56:59]
	v_mfma_i32_16x16x64_i8 v[32:35], v[60:63], v[212:215], v[32:35]
	v_mfma_i32_16x16x64_i8 v[32:35], v[68:71], v[216:219], v[32:35]
	v_mfma_i32_16x16x64_i8 v[16:19], v[68:71], v[224:227], v[16:19]
	v_mfma_i32_16x16x64_i8 v[16:19], v[60:63], v[220:223], v[16:19]
	v_mfma_i32_16x16x64_i8 v[8:11], v[140:143], v[220:223], v[8:11]
	v_mfma_i32_16x16x64_i8 v[8:11], v[144:147], v[224:227], v[8:11]
	v_mfma_i32_16x16x64_i8 v[24:27], v[144:147], v[216:219], v[24:27]
	v_mfma_i32_16x16x64_i8 v[24:27], v[140:143], v[212:215], v[24:27]
	v_mfma_i32_16x16x64_i8 v[48:51], v[140:143], v[204:207], v[48:51]
	v_mfma_i32_16x16x64_i8 v[48:51], v[144:147], v[208:211], v[48:51]
	v_mfma_i32_16x16x64_i8 v[64:67], v[144:147], v[188:191], v[64:67]
	v_mfma_i32_16x16x64_i8 v[64:67], v[140:143], v[184:187], v[64:67]
	v_mfma_i32_16x16x64_i8 v[36:39], v[160:163], v[184:187], v[36:39]
	v_mfma_i32_16x16x64_i8 v[68:71], v[172:175], v[188:191], v[36:39]
	v_mfma_i32_16x16x64_i8 v[36:39], v[172:175], v[208:211], v[52:55]
	v_mfma_i32_16x16x64_i8 v[52:55], v[160:163], v[204:207], v[36:39]
	v_mfma_i32_16x16x64_i8 v[28:31], v[160:163], v[212:215], v[28:31]
	v_mfma_i32_16x16x64_i8 v[28:31], v[172:175], v[216:219], v[28:31]
	v_mfma_i32_16x16x64_i8 v[12:15], v[172:175], v[224:227], v[12:15]
	v_mfma_i32_16x16x64_i8 v[12:15], v[160:163], v[220:223], v[12:15]
	v_mfma_i32_16x16x64_i8 v[4:7], v[176:179], v[220:223], v[4:7]
	v_mfma_i32_16x16x64_i8 v[4:7], v[180:183], v[224:227], v[4:7]
	v_mfma_i32_16x16x64_i8 v[20:23], v[180:183], v[216:219], v[20:23]
	v_mfma_i32_16x16x64_i8 v[20:23], v[176:179], v[212:215], v[20:23]
	v_mfma_i32_16x16x64_i8 v[36:39], v[176:179], v[204:207], v[40:43]
	v_mfma_i32_16x16x64_i8 v[40:43], v[180:183], v[208:211], v[36:39]
	v_mfma_i32_16x16x64_i8 v[36:39], v[180:183], v[188:191], v[44:47]
	v_mfma_i32_16x16x64_i8 v[60:63], v[176:179], v[184:187], v[36:39]
	s_barrier
	s_setprio 0
	s_add_i32 s61, s61, 2
	s_add_u32 s40, s40, 0x100
	s_addc_u32 s41, s41, 0
	s_add_u32 s59, s59, 0x100
	s_addc_u32 s60, s60, 0
	s_cmp_gt_u32 s61, 29
	s_cbranch_scc0 .LBB0_1591

; #define PG8_STAGE(bufoff, gbase, voff) do { _Pragma("unroll") for (int _i = 0; _i < 2; ++_i) \
;         __builtin_amdgcn_global_load_lds((const unsigned*)((const char*)(gbase) + (voff)[_i]), (PG8_LAS unsigned*)(lds + (bufoff) + ldsw + _i * 8192), 16, 0, 0); } while (0)
; #define PG8_LDA(dst, b, h) do { _Pragma("unroll") for (int m = 0; m < 4; ++m) _Pragma("unroll") for (int k = 0; k < 2; ++k) dst[m][k] = *(const PG8_LAS bf16x8*)(lds + PG8_SA(b, h) + aoff + m * 2048 + k * 1024); } while (0)
; #define PG8_LDB(dst, b, h) do { _Pragma("unroll") for (int n = 0; n < 2; ++n) _Pragma("unroll") for (int k = 0; k < 2; ++k) dst[n][k] = *(const PG8_LAS bf16x8*)(lds + PG8_SB(b, h) + boff + n * 2048 + k * 1024); } while (0)
; #define PG8_WAIT_V(n) asm volatile("s_waitcnt vmcnt(" #n ")" ::: "memory")
; #define PG8_WAIT_L(n) asm volatile("s_waitcnt lgkmcnt(" #n ")" ::: "memory")
; #define PG8_BAR __builtin_amdgcn_s_barrier()
; #define PG8_SCHED __builtin_amdgcn_sched_barrier(0)
; template <class Epi, class Sched, bool ALIGN_EPI = false, bool SP2 = false, bool I8 = false>
; __device__ __forceinline__ void gemm_phase(PG8_LAS unsigned char* lds, const Gemm g, const Sched& S, const Epi& E) {
;     ...
;         const char* nA = has_next ? (const char*)g.A + (size_t)nxt.pm * tstep : cA; const char* nB = has_next ? (const char*)g.Bt + (size_t)nxt.pn * tstep : cB;
;         for (int t = 0; t < nt; t += 2) {
;             const bool last = (t == nt - 2);
;             const char* a1 = cA + (size_t)(t + 1) * kstep;
;             const char* a2 = last ? nA : cA + (size_t)(t + 2) * kstep; const char* b2 = last ? nB : cB + (size_t)(t + 2) * kstep;
;             const char* a3 = a2 + kstep; const char* b3 = b2 + kstep;
;             if (last && has_next) S.a_ready(nxt);
;             if constexpr (SP2) {
;             PG8_LDB(B0, 0, 0); PG8_LDB(B1, 0, 1); PG8_SCHED; PG8_LDA(At, 0, 0); PG8_STAGE(PG8_SA(1, 1), a1 + hstep, voffA);
;             PG8_WAIT_V(8); PG8_WAIT_L(0); PG8_BAR; PG8_MMA(0, 0, At, B0); PG8_MMA(0, 1, At, B1); PG8_BAR; PG8_SCHED;
;     ...
; #pragma unroll
;         for (int a = 0; a < 2; ++a)
; #pragma unroll
;             for (int b = 0; b < 2; ++b)
; #pragma unroll
;                 for (int m = 0; m < 4; ++m)
; #pragma unroll
;                     for (int n = 0; n < 2; ++n) acc[a][b][m][n] = (acc_t){0, 0, 0, 0};
.LBB0_1621:
	v_mov_b32_e32 v127, 0
	s_andn2_b64 vcc, exec, s[26:27]
	v_mov_b32_e32 v126, v127
	v_mov_b32_e32 v125, v127
	v_mov_b32_e32 v124, v127
	v_mov_b32_e32 v131, v127
	v_mov_b32_e32 v130, v127
	v_mov_b32_e32 v129, v127
	v_mov_b32_e32 v128, v127
	v_mov_b32_e32 v115, v127
	v_mov_b32_e32 v114, v127
	v_mov_b32_e32 v113, v127
	v_mov_b32_e32 v112, v127
	v_mov_b32_e32 v111, v127
	v_mov_b32_e32 v110, v127
	v_mov_b32_e32 v109, v127
	v_mov_b32_e32 v108, v127
	v_mov_b32_e32 v99, v127
	v_mov_b32_e32 v98, v127
	v_mov_b32_e32 v97, v127
	v_mov_b32_e32 v96, v127
	v_mov_b32_e32 v95, v127
	v_mov_b32_e32 v94, v127
	v_mov_b32_e32 v93, v127
	v_mov_b32_e32 v92, v127
	v_mov_b32_e32 v83, v127
	v_mov_b32_e32 v82, v127
	v_mov_b32_e32 v81, v127
	v_mov_b32_e32 v80, v127
	v_mov_b32_e32 v79, v127
	v_mov_b32_e32 v78, v127
	v_mov_b32_e32 v77, v127
	v_mov_b32_e32 v76, v127
	v_mov_b32_e32 v123, v127
	v_mov_b32_e32 v122, v127
	v_mov_b32_e32 v121, v127
	v_mov_b32_e32 v120, v127
	v_mov_b32_e32 v119, v127
	v_mov_b32_e32 v118, v127
	v_mov_b32_e32 v117, v127
	v_mov_b32_e32 v116, v127
	v_mov_b32_e32 v107, v127
	v_mov_b32_e32 v106, v127
	v_mov_b32_e32 v105, v127
	v_mov_b32_e32 v104, v127
	v_mov_b32_e32 v103, v127
	v_mov_b32_e32 v102, v127
	v_mov_b32_e32 v101, v127
	v_mov_b32_e32 v100, v127
	v_mov_b32_e32 v91, v127
	v_mov_b32_e32 v90, v127
	v_mov_b32_e32 v89, v127
	v_mov_b32_e32 v88, v127
	v_mov_b32_e32 v87, v127
	v_mov_b32_e32 v86, v127
	v_mov_b32_e32 v85, v127
	v_mov_b32_e32 v84, v127
	v_mov_b32_e32 v75, v127
	v_mov_b32_e32 v74, v127
	v_mov_b32_e32 v73, v127
	v_mov_b32_e32 v72, v127
	v_mov_b32_e32 v71, v127
	v_mov_b32_e32 v70, v127
	v_mov_b32_e32 v69, v127
	v_mov_b32_e32 v68, v127
	v_mov_b32_e32 v67, v127
	v_mov_b32_e32 v66, v127
	v_mov_b32_e32 v65, v127
	v_mov_b32_e32 v64, v127
	v_mov_b32_e32 v63, v127
	v_mov_b32_e32 v62, v127
	v_mov_b32_e32 v61, v127
	v_mov_b32_e32 v60, v127
	v_mov_b32_e32 v51, v127
	v_mov_b32_e32 v50, v127
	v_mov_b32_e32 v49, v127
	v_mov_b32_e32 v48, v127
	v_mov_b32_e32 v47, v127
	v_mov_b32_e32 v46, v127
	v_mov_b32_e32 v45, v127
	v_mov_b32_e32 v44, v127
	v_mov_b32_e32 v35, v127
	v_mov_b32_e32 v34, v127
	v_mov_b32_e32 v33, v127
	v_mov_b32_e32 v32, v127
	v_mov_b32_e32 v31, v127
	v_mov_b32_e32 v30, v127
	v_mov_b32_e32 v29, v127
	v_mov_b32_e32 v28, v127
	v_mov_b32_e32 v19, v127
	v_mov_b32_e32 v18, v127
	v_mov_b32_e32 v17, v127
	v_mov_b32_e32 v16, v127
	v_mov_b32_e32 v15, v127
	v_mov_b32_e32 v14, v127
	v_mov_b32_e32 v13, v127
	v_mov_b32_e32 v12, v127
	v_mov_b32_e32 v59, v127
	v_mov_b32_e32 v58, v127
	v_mov_b32_e32 v57, v127
	v_mov_b32_e32 v56, v127
	v_mov_b32_e32 v55, v127
	v_mov_b32_e32 v54, v127
	v_mov_b32_e32 v53, v127
	v_mov_b32_e32 v52, v127
	v_mov_b32_e32 v43, v127
	v_mov_b32_e32 v42, v127
	v_mov_b32_e32 v41, v127
	v_mov_b32_e32 v40, v127
	v_mov_b32_e32 v39, v127
	v_mov_b32_e32 v38, v127
	v_mov_b32_e32 v37, v127
	v_mov_b32_e32 v36, v127
	v_mov_b32_e32 v27, v127
	v_mov_b32_e32 v26, v127
	v_mov_b32_e32 v25, v127
	v_mov_b32_e32 v24, v127
	v_mov_b32_e32 v23, v127
	v_mov_b32_e32 v22, v127
	v_mov_b32_e32 v21, v127
	v_mov_b32_e32 v20, v127
	v_mov_b32_e32 v11, v127
	v_mov_b32_e32 v10, v127
	v_mov_b32_e32 v9, v127
	v_mov_b32_e32 v8, v127
	v_mov_b32_e32 v7, v127
	v_mov_b32_e32 v6, v127
	v_mov_b32_e32 v5, v127
	v_mov_b32_e32 v4, v127
	s_cbranch_vccnz .LBB0_1625
	s_add_u32 s44, s44, 0x80
	s_addc_u32 s45, s45, 0
	s_add_u32 s65, s48, 0x100
	s_addc_u32 s67, s49, 0
	s_mov_b32 s48, 0
	s_add_i32 s72, s48, 2
	s_add_u32 s73, s44, 0x80
	s_addc_u32 s49, s45, 0
	s_add_i32 s86, 0, 0x10000
	s_cmp_eq_u32 s57, s48
	s_cselect_b32 s49, s13, s49
	s_cselect_b32 s48, s12, s73
	s_cselect_b32 s77, s41, s67
	s_cselect_b32 s76, s40, s65
	s_add_i32 s73, 0, 0x14000
	v_add_u32_e32 v158, s86, v143
	v_add_u32_e32 v174, s73, v143
	ds_read_b128 v[146:149], v158
	ds_read_b128 v[150:153], v158 offset:1024
	ds_read_b128 v[154:157], v158 offset:2048
	ds_read_b128 v[158:161], v158 offset:3072
	ds_read_b128 v[162:165], v174
	ds_read_b128 v[166:169], v174 offset:1024
	ds_read_b128 v[170:173], v174 offset:2048
	ds_read_b128 v[174:177], v174 offset:3072
	v_lshl_add_u64 v[190:191], s[44:45], 0, v[138:139]
	s_add_i32 m0, s47, 0xc000
	ds_read_b128 v[178:181], v145
	ds_read_b128 v[182:185], v145 offset:1024
	ds_read_b128 v[186:189], v145 offset:2048
	ds_read_b128 v[204:207], v145 offset:3072
	ds_read_b128 v[208:211], v145 offset:4096
	ds_read_b128 v[212:215], v145 offset:5120
	ds_read_b128 v[216:219], v145 offset:6144
	ds_read_b128 v[220:223], v145 offset:7168
	global_load_lds_dwordx4 v[190:191], off
	v_lshl_add_u64 v[190:191], s[44:45], 0, v[140:141]
	s_add_i32 m0, s47, 0xe000
	s_nop 0
	global_load_lds_dwordx4 v[190:191], off
	s_waitcnt vmcnt(8) lgkmcnt(0)
	s_setprio 1
	s_barrier
; #define PG8_STAGE(bufoff, gbase, voff) do { _Pragma("unroll") for (int _i = 0; _i < 2; ++_i) \
;         __builtin_amdgcn_global_load_lds((const unsigned*)((const char*)(gbase) + (voff)[_i]), (PG8_LAS unsigned*)(lds + (bufoff) + ldsw + _i * 8192), 16, 0, 0); } while (0)
; #define PG8_LDA(dst, b, h) do { _Pragma("unroll") for (int m = 0; m < 4; ++m) _Pragma("unroll") for (int k = 0; k < 2; ++k) dst[m][k] = *(const PG8_LAS bf16x8*)(lds + PG8_SA(b, h) + aoff + m * 2048 + k * 1024); } while (0)
; #define PG8_WAIT_V(n) asm volatile("s_waitcnt vmcnt(" #n ")" ::: "memory")
; #define PG8_WAIT_L(n) asm volatile("s_waitcnt lgkmcnt(" #n ")" ::: "memory")
; #define PG8_BAR __builtin_amdgcn_s_barrier()
; #define PG8_SCHED __builtin_amdgcn_sched_barrier(0)
; template <class Epi, class Sched, bool ALIGN_EPI = false, bool SP2 = false, bool I8 = false>
; __device__ __forceinline__ void gemm_phase(PG8_LAS unsigned char* lds, const Gemm g, const Sched& S, const Epi& E) {
;     ...
;             PG8_WAIT_V(8); PG8_WAIT_L(0); PG8_BAR; PG8_MMA(0, 0, At, B0); PG8_MMA(0, 1, At, B1); PG8_BAR; PG8_SCHED;
;             PG8_LDA(At, 0, 1); PG8_STAGE(PG8_SB(0, 0), b2, voffB); PG8_STAGE(PG8_SB(0, 1), b2 + hstep, voffB); PG8_STAGE(PG8_SA(0, 0), a2, voffA);
;             PG8_WAIT_V(8); PG8_WAIT_L(0); PG8_BAR; PG8_MMA(1, 0, At, B0); PG8_MMA(1, 1, At, B1); PG8_BAR; PG8_SCHED;
	v_mfma_f32_16x16x32_bf16 v[124:127], v[146:149], v[178:181], 0
	v_mfma_f32_16x16x32_bf16 v[124:127], v[150:153], v[182:185], v[124:127]
	v_mfma_f32_16x16x32_bf16 v[112:115], v[150:153], v[204:207], 0
	v_mfma_f32_16x16x32_bf16 v[112:115], v[146:149], v[186:189], v[112:115]
	v_mfma_f32_16x16x32_bf16 v[96:99], v[146:149], v[208:211], 0
	v_mfma_f32_16x16x32_bf16 v[96:99], v[150:153], v[212:215], v[96:99]
	v_mfma_f32_16x16x32_bf16 v[80:83], v[150:153], v[220:223], 0
	v_mfma_f32_16x16x32_bf16 v[80:83], v[146:149], v[216:219], v[80:83]
	v_mfma_f32_16x16x32_bf16 v[76:79], v[154:157], v[216:219], 0
	v_mfma_f32_16x16x32_bf16 v[76:79], v[158:161], v[220:223], v[76:79]
	v_mfma_f32_16x16x32_bf16 v[92:95], v[158:161], v[212:215], 0
	v_mfma_f32_16x16x32_bf16 v[92:95], v[154:157], v[208:211], v[92:95]
	v_mfma_f32_16x16x32_bf16 v[108:111], v[154:157], v[186:189], 0
	v_mfma_f32_16x16x32_bf16 v[108:111], v[158:161], v[204:207], v[108:111]
	v_mfma_f32_16x16x32_bf16 v[128:131], v[158:161], v[182:185], 0
	v_mfma_f32_16x16x32_bf16 v[128:131], v[154:157], v[178:181], v[128:131]
	v_mfma_f32_16x16x32_bf16 v[120:123], v[162:165], v[178:181], 0
	v_mfma_f32_16x16x32_bf16 v[120:123], v[166:169], v[182:185], v[120:123]
	v_mfma_f32_16x16x32_bf16 v[104:107], v[166:169], v[204:207], 0
	v_mfma_f32_16x16x32_bf16 v[104:107], v[162:165], v[186:189], v[104:107]
	v_mfma_f32_16x16x32_bf16 v[88:91], v[162:165], v[208:211], 0
	v_mfma_f32_16x16x32_bf16 v[88:91], v[166:169], v[212:215], v[88:91]
	v_mfma_f32_16x16x32_bf16 v[72:75], v[166:169], v[220:223], 0
	v_mfma_f32_16x16x32_bf16 v[72:75], v[162:165], v[216:219], v[72:75]
	v_mfma_f32_16x16x32_bf16 v[68:71], v[170:173], v[216:219], 0
	v_mfma_f32_16x16x32_bf16 v[68:71], v[174:177], v[220:223], v[68:71]
	v_mfma_f32_16x16x32_bf16 v[84:87], v[174:177], v[212:215], 0
	v_mfma_f32_16x16x32_bf16 v[84:87], v[170:173], v[208:211], v[84:87]
	v_mfma_f32_16x16x32_bf16 v[100:103], v[170:173], v[186:189], 0
	v_mfma_f32_16x16x32_bf16 v[100:103], v[174:177], v[204:207], v[100:103]
	v_mfma_f32_16x16x32_bf16 v[116:119], v[174:177], v[182:185], 0
	v_mfma_f32_16x16x32_bf16 v[116:119], v[170:173], v[178:181], v[116:119]
	s_barrier
	s_setprio 0
	s_add_i32 s86, s86, s28
	v_lshl_add_u64 v[190:191], s[76:77], 0, v[2:3]
	s_mov_b32 m0, s86
	ds_read_b128 v[178:181], v145 offset:16384
	ds_read_b128 v[182:185], v145 offset:17408
	ds_read_b128 v[186:189], v145 offset:18432
	ds_read_b128 v[204:207], v145 offset:19456
	ds_read_b128 v[208:211], v145 offset:20480
	ds_read_b128 v[212:215], v145 offset:21504
	ds_read_b128 v[216:219], v145 offset:22528
	ds_read_b128 v[220:223], v145 offset:23552
	global_load_lds_dwordx4 v[190:191], off
	s_add_i32 m0, s86, 0x2000
	v_lshl_add_u64 v[224:225], s[76:77], 0, v[136:137]
	s_add_u32 s76, s76, s18
	s_addc_u32 s77, s77, s19
	s_add_i32 s73, s73, s28
	global_load_lds_dwordx4 v[224:225], off
	v_lshl_add_u64 v[226:227], s[76:77], 0, v[2:3]
	s_mov_b32 m0, s73
	v_lshl_add_u64 v[228:229], s[76:77], 0, v[136:137]
	global_load_lds_dwordx4 v[226:227], off
	s_add_i32 m0, s73, 0x2000
	v_lshl_add_u64 v[240:241], s[48:49], 0, v[132:133]
	global_load_lds_dwordx4 v[228:229], off
	v_lshl_add_u64 v[242:243], s[48:49], 0, v[134:135]
	s_waitcnt vmcnt(6) lgkmcnt(0)
	s_setprio 1
	s_barrier
	v_mfma_f32_16x16x32_bf16 v[64:67], v[146:149], v[178:181], 0
	v_mfma_f32_16x16x32_bf16 v[64:67], v[150:153], v[182:185], v[64:67]
	v_mfma_f32_16x16x32_bf16 v[48:51], v[150:153], v[204:207], 0
	v_mfma_f32_16x16x32_bf16 v[48:51], v[146:149], v[186:189], v[48:51]
	v_mfma_f32_16x16x32_bf16 v[32:35], v[146:149], v[208:211], 0
	v_mfma_f32_16x16x32_bf16 v[32:35], v[150:153], v[212:215], v[32:35]
	v_mfma_f32_16x16x32_bf16 v[16:19], v[150:153], v[220:223], 0
	v_mfma_f32_16x16x32_bf16 v[16:19], v[146:149], v[216:219], v[16:19]
	v_mfma_f32_16x16x32_bf16 v[12:15], v[154:157], v[216:219], 0
	v_mfma_f32_16x16x32_bf16 v[12:15], v[158:161], v[220:223], v[12:15]
	v_mfma_f32_16x16x32_bf16 v[28:31], v[158:161], v[212:215], 0
	v_mfma_f32_16x16x32_bf16 v[28:31], v[154:157], v[208:211], v[28:31]
	v_mfma_f32_16x16x32_bf16 v[44:47], v[154:157], v[186:189], 0
	v_mfma_f32_16x16x32_bf16 v[44:47], v[158:161], v[204:207], v[44:47]
	v_mfma_f32_16x16x32_bf16 v[60:63], v[158:161], v[182:185], 0
	v_mfma_f32_16x16x32_bf16 v[60:63], v[154:157], v[178:181], v[60:63]
	v_mfma_f32_16x16x32_bf16 v[56:59], v[162:165], v[178:181], 0
	v_mfma_f32_16x16x32_bf16 v[56:59], v[166:169], v[182:185], v[56:59]
	v_mfma_f32_16x16x32_bf16 v[40:43], v[166:169], v[204:207], 0
	v_mfma_f32_16x16x32_bf16 v[40:43], v[162:165], v[186:189], v[40:43]
	v_mfma_f32_16x16x32_bf16 v[24:27], v[162:165], v[208:211], 0
	v_mfma_f32_16x16x32_bf16 v[24:27], v[166:169], v[212:215], v[24:27]
	v_mfma_f32_16x16x32_bf16 v[8:11], v[166:169], v[220:223], 0
	v_mfma_f32_16x16x32_bf16 v[8:11], v[162:165], v[216:219], v[8:11]
	v_mfma_f32_16x16x32_bf16 v[4:7], v[170:173], v[216:219], 0
	v_mfma_f32_16x16x32_bf16 v[4:7], v[174:177], v[220:223], v[4:7]
	v_mfma_f32_16x16x32_bf16 v[20:23], v[174:177], v[212:215], 0
	v_mfma_f32_16x16x32_bf16 v[20:23], v[170:173], v[208:211], v[20:23]
	v_mfma_f32_16x16x32_bf16 v[36:39], v[170:173], v[186:189], 0
	v_mfma_f32_16x16x32_bf16 v[36:39], v[174:177], v[204:207], v[36:39]
	v_mfma_f32_16x16x32_bf16 v[52:55], v[174:177], v[182:185], 0
	v_mfma_f32_16x16x32_bf16 v[52:55], v[170:173], v[178:181], v[52:55]
	s_barrier
; #define PG8_STAGE(bufoff, gbase, voff) do { _Pragma("unroll") for (int _i = 0; _i < 2; ++_i) \
;         __builtin_amdgcn_global_load_lds((const unsigned*)((const char*)(gbase) + (voff)[_i]), (PG8_LAS unsigned*)(lds + (bufoff) + ldsw + _i * 8192), 16, 0, 0); } while (0)
; #define PG8_LDA(dst, b, h) do { _Pragma("unroll") for (int m = 0; m < 4; ++m) _Pragma("unroll") for (int k = 0; k < 2; ++k) dst[m][k] = *(const PG8_LAS bf16x8*)(lds + PG8_SA(b, h) + aoff + m * 2048 + k * 1024); } while (0)
; #define PG8_LDB(dst, b, h) do { _Pragma("unroll") for (int n = 0; n < 2; ++n) _Pragma("unroll") for (int k = 0; k < 2; ++k) dst[n][k] = *(const PG8_LAS bf16x8*)(lds + PG8_SB(b, h) + boff + n * 2048 + k * 1024); } while (0)
; #define PG8_WAIT_V(n) asm volatile("s_waitcnt vmcnt(" #n ")" ::: "memory")
; #define PG8_WAIT_L(n) asm volatile("s_waitcnt lgkmcnt(" #n ")" ::: "memory")
; #define PG8_BAR __builtin_amdgcn_s_barrier()
; #define PG8_SCHED __builtin_amdgcn_sched_barrier(0)
; template <class Epi, class Sched, bool ALIGN_EPI = false, bool SP2 = false, bool I8 = false>
; __device__ __forceinline__ void gemm_phase(PG8_LAS unsigned char* lds, const Gemm g, const Sched& S, const Epi& E) {
;     ...
;             PG8_WAIT_V(8); PG8_WAIT_L(0); PG8_BAR; PG8_MMA(1, 0, At, B0); PG8_MMA(1, 1, At, B1); PG8_BAR; PG8_SCHED;
;             PG8_LDB(B0, 1, 0); PG8_LDB(B1, 1, 1); PG8_SCHED; PG8_LDA(At, 1, 0); PG8_STAGE(PG8_SA(0, 1), a2 + hstep, voffA);
;             PG8_WAIT_V(8); PG8_WAIT_L(0); PG8_BAR; PG8_MMA(0, 0, At, B0); PG8_MMA(0, 1, At, B1); PG8_BAR; PG8_SCHED;
;             PG8_LDA(At, 1, 1); PG8_STAGE(PG8_SB(1, 0), b3, voffB); PG8_STAGE(PG8_SB(1, 1), b3 + hstep, voffB); PG8_STAGE(PG8_SA(1, 0), a3, voffA);
;             PG8_WAIT_V(8); PG8_WAIT_L(0); PG8_BAR; PG8_MMA(1, 0, At, B0); PG8_MMA(1, 1, At, B1); PG8_BAR; PG8_SCHED;
	s_setprio 0
	s_mov_b32 m0, s47
	s_nop 0
	global_load_lds_dwordx4 v[240:241], off
	s_mov_b32 m0, s50
	s_nop 0
	global_load_lds_dwordx4 v[242:243], off
	s_add_i32 s73, 0, 0x18000
	s_add_i32 s76, 0, 0x1c000
	v_add_u32_e32 v158, s73, v143
	v_add_u32_e32 v174, s76, v143
	ds_read_b128 v[146:149], v158
	ds_read_b128 v[150:153], v158 offset:1024
	ds_read_b128 v[154:157], v158 offset:2048
	ds_read_b128 v[158:161], v158 offset:3072
	ds_read_b128 v[162:165], v174
	ds_read_b128 v[166:169], v174 offset:1024
	ds_read_b128 v[170:173], v174 offset:2048
	ds_read_b128 v[174:177], v174 offset:3072
	s_add_u32 s48, s48, s18
	s_addc_u32 s49, s49, s19
	s_mov_b32 m0, s51
	ds_read_b128 v[178:181], v145 offset:32768
	ds_read_b128 v[182:185], v145 offset:33792
	ds_read_b128 v[186:189], v145 offset:34816
	ds_read_b128 v[204:207], v145 offset:35840
	ds_read_b128 v[208:211], v145 offset:36864
	ds_read_b128 v[212:215], v145 offset:37888
	ds_read_b128 v[216:219], v145 offset:38912
	ds_read_b128 v[220:223], v145 offset:39936
	global_load_lds_dwordx4 v132, s[48:49]
	s_mov_b32 m0, s52
	s_nop 0
	global_load_lds_dwordx4 v134, s[48:49]
	s_waitcnt vmcnt(8) lgkmcnt(0)
	s_setprio 1
	s_barrier
	v_mfma_f32_16x16x32_bf16 v[124:127], v[146:149], v[178:181], v[124:127]
	v_mfma_f32_16x16x32_bf16 v[124:127], v[150:153], v[182:185], v[124:127]
	v_mfma_f32_16x16x32_bf16 v[112:115], v[150:153], v[204:207], v[112:115]
	v_mfma_f32_16x16x32_bf16 v[112:115], v[146:149], v[186:189], v[112:115]
	v_mfma_f32_16x16x32_bf16 v[96:99], v[146:149], v[208:211], v[96:99]
	v_mfma_f32_16x16x32_bf16 v[96:99], v[150:153], v[212:215], v[96:99]
	v_mfma_f32_16x16x32_bf16 v[80:83], v[150:153], v[220:223], v[80:83]
	v_mfma_f32_16x16x32_bf16 v[80:83], v[146:149], v[216:219], v[80:83]
	v_mfma_f32_16x16x32_bf16 v[76:79], v[154:157], v[216:219], v[76:79]
	v_mfma_f32_16x16x32_bf16 v[76:79], v[158:161], v[220:223], v[76:79]
	v_mfma_f32_16x16x32_bf16 v[92:95], v[158:161], v[212:215], v[92:95]
	v_mfma_f32_16x16x32_bf16 v[92:95], v[154:157], v[208:211], v[92:95]
	v_mfma_f32_16x16x32_bf16 v[108:111], v[154:157], v[186:189], v[108:111]
	v_mfma_f32_16x16x32_bf16 v[108:111], v[158:161], v[204:207], v[108:111]
	v_mfma_f32_16x16x32_bf16 v[128:131], v[158:161], v[182:185], v[128:131]
	v_mfma_f32_16x16x32_bf16 v[128:131], v[154:157], v[178:181], v[128:131]
	v_mfma_f32_16x16x32_bf16 v[120:123], v[162:165], v[178:181], v[120:123]
	v_mfma_f32_16x16x32_bf16 v[120:123], v[166:169], v[182:185], v[120:123]
	v_mfma_f32_16x16x32_bf16 v[104:107], v[166:169], v[204:207], v[104:107]
	v_mfma_f32_16x16x32_bf16 v[104:107], v[162:165], v[186:189], v[104:107]
	v_mfma_f32_16x16x32_bf16 v[88:91], v[162:165], v[208:211], v[88:91]
	v_mfma_f32_16x16x32_bf16 v[88:91], v[166:169], v[212:215], v[88:91]
	v_mfma_f32_16x16x32_bf16 v[72:75], v[166:169], v[220:223], v[72:75]
	v_mfma_f32_16x16x32_bf16 v[72:75], v[162:165], v[216:219], v[72:75]
	v_mfma_f32_16x16x32_bf16 v[68:71], v[170:173], v[216:219], v[68:71]
	v_mfma_f32_16x16x32_bf16 v[68:71], v[174:177], v[220:223], v[68:71]
	v_mfma_f32_16x16x32_bf16 v[84:87], v[174:177], v[212:215], v[84:87]
	v_mfma_f32_16x16x32_bf16 v[84:87], v[170:173], v[208:211], v[84:87]
	v_mfma_f32_16x16x32_bf16 v[100:103], v[170:173], v[186:189], v[100:103]
	v_mfma_f32_16x16x32_bf16 v[100:103], v[174:177], v[204:207], v[100:103]
	v_mfma_f32_16x16x32_bf16 v[116:119], v[174:177], v[182:185], v[116:119]
	v_mfma_f32_16x16x32_bf16 v[116:119], v[170:173], v[178:181], v[116:119]
	s_barrier
	s_setprio 0
	s_add_i32 s48, s73, s28
	v_lshl_add_u64 v[190:191], v[190:191], 0, s[84:85]
	s_mov_b32 m0, s48
	ds_read_b128 v[178:181], v145 offset:49152
	ds_read_b128 v[182:185], v145 offset:50176
	ds_read_b128 v[186:189], v145 offset:51200
	ds_read_b128 v[204:207], v145 offset:52224
	ds_read_b128 v[208:211], v145 offset:53248
	ds_read_b128 v[212:215], v145 offset:54272
	ds_read_b128 v[216:219], v145 offset:55296
	ds_read_b128 v[220:223], v145 offset:56320
	global_load_lds_dwordx4 v[190:191], off
	v_lshl_add_u64 v[190:191], v[224:225], 0, s[84:85]
	s_add_i32 m0, s48, 0x2000
	s_add_i32 s48, s76, s28
	global_load_lds_dwordx4 v[190:191], off
	v_lshl_add_u64 v[190:191], v[226:227], 0, s[84:85]
	s_mov_b32 m0, s48
	s_nop 0
	global_load_lds_dwordx4 v[190:191], off
	v_lshl_add_u64 v[190:191], v[228:229], 0, s[84:85]
	s_add_i32 m0, s48, 0x2000
	s_nop 0
	global_load_lds_dwordx4 v[190:191], off
	v_lshl_add_u64 v[190:191], v[240:241], 0, s[84:85]
	s_mov_b32 m0, s55
	s_nop 0
	global_load_lds_dwordx4 v[190:191], off
	v_lshl_add_u64 v[190:191], v[242:243], 0, s[84:85]
	s_mov_b32 m0, s56
	s_nop 0
	global_load_lds_dwordx4 v[190:191], off
	s_waitcnt vmcnt(8) lgkmcnt(0)
	s_setprio 1
	s_barrier
	v_mfma_f32_16x16x32_bf16 v[64:67], v[146:149], v[178:181], v[64:67]
	v_mfma_f32_16x16x32_bf16 v[64:67], v[150:153], v[182:185], v[64:67]
	v_mfma_f32_16x16x32_bf16 v[48:51], v[150:153], v[204:207], v[48:51]
	v_mfma_f32_16x16x32_bf16 v[48:51], v[146:149], v[186:189], v[48:51]
	v_mfma_f32_16x16x32_bf16 v[32:35], v[146:149], v[208:211], v[32:35]
	v_mfma_f32_16x16x32_bf16 v[32:35], v[150:153], v[212:215], v[32:35]
	v_mfma_f32_16x16x32_bf16 v[16:19], v[150:153], v[220:223], v[16:19]
	v_mfma_f32_16x16x32_bf16 v[16:19], v[146:149], v[216:219], v[16:19]
	v_mfma_f32_16x16x32_bf16 v[12:15], v[154:157], v[216:219], v[12:15]
	v_mfma_f32_16x16x32_bf16 v[12:15], v[158:161], v[220:223], v[12:15]
	v_mfma_f32_16x16x32_bf16 v[28:31], v[158:161], v[212:215], v[28:31]
	v_mfma_f32_16x16x32_bf16 v[28:31], v[154:157], v[208:211], v[28:31]
	v_mfma_f32_16x16x32_bf16 v[44:47], v[154:157], v[186:189], v[44:47]
	v_mfma_f32_16x16x32_bf16 v[44:47], v[158:161], v[204:207], v[44:47]
	v_mfma_f32_16x16x32_bf16 v[60:63], v[158:161], v[182:185], v[60:63]
	v_mfma_f32_16x16x32_bf16 v[60:63], v[154:157], v[178:181], v[60:63]
	v_mfma_f32_16x16x32_bf16 v[56:59], v[162:165], v[178:181], v[56:59]
	v_mfma_f32_16x16x32_bf16 v[56:59], v[166:169], v[182:185], v[56:59]
	v_mfma_f32_16x16x32_bf16 v[40:43], v[166:169], v[204:207], v[40:43]
	v_mfma_f32_16x16x32_bf16 v[40:43], v[162:165], v[186:189], v[40:43]
	v_mfma_f32_16x16x32_bf16 v[24:27], v[162:165], v[208:211], v[24:27]
	v_mfma_f32_16x16x32_bf16 v[24:27], v[166:169], v[212:215], v[24:27]
	v_mfma_f32_16x16x32_bf16 v[8:11], v[166:169], v[220:223], v[8:11]
	v_mfma_f32_16x16x32_bf16 v[8:11], v[162:165], v[216:219], v[8:11]
	v_mfma_f32_16x16x32_bf16 v[4:7], v[170:173], v[216:219], v[4:7]
	v_mfma_f32_16x16x32_bf16 v[4:7], v[174:177], v[220:223], v[4:7]
	v_mfma_f32_16x16x32_bf16 v[20:23], v[174:177], v[212:215], v[20:23]
	v_mfma_f32_16x16x32_bf16 v[20:23], v[170:173], v[208:211], v[20:23]
	v_mfma_f32_16x16x32_bf16 v[36:39], v[170:173], v[186:189], v[36:39]
	v_mfma_f32_16x16x32_bf16 v[36:39], v[174:177], v[204:207], v[36:39]
	v_mfma_f32_16x16x32_bf16 v[52:55], v[174:177], v[182:185], v[52:55]
	v_mfma_f32_16x16x32_bf16 v[52:55], v[170:173], v[178:181], v[52:55]
	s_barrier
	s_setprio 0
	s_add_u32 s44, s44, 0x100
	s_addc_u32 s45, s45, 0
	s_add_u32 s65, s65, 0x100
	s_addc_u32 s67, s67, 0
	s_cmp_ge_i32 s72, s53
	s_mov_b32 s48, s72
	s_cbranch_scc1 .Lkloop_exit_4
; #define PG8_STAGE(bufoff, gbase, voff) do { _Pragma("unroll") for (int _i = 0; _i < 2; ++_i) \
;         __builtin_amdgcn_global_load_lds((const unsigned*)((const char*)(gbase) + (voff)[_i]), (PG8_LAS unsigned*)(lds + (bufoff) + ldsw + _i * 8192), 16, 0, 0); } while (0)
; #define PG8_LDA(dst, b, h) do { _Pragma("unroll") for (int m = 0; m < 4; ++m) _Pragma("unroll") for (int k = 0; k < 2; ++k) dst[m][k] = *(const PG8_LAS bf16x8*)(lds + PG8_SA(b, h) + aoff + m * 2048 + k * 1024); } while (0)
; #define PG8_LDB(dst, b, h) do { _Pragma("unroll") for (int n = 0; n < 2; ++n) _Pragma("unroll") for (int k = 0; k < 2; ++k) dst[n][k] = *(const PG8_LAS bf16x8*)(lds + PG8_SB(b, h) + boff + n * 2048 + k * 1024); } while (0)
; #define PG8_WAIT_V(n) asm volatile("s_waitcnt vmcnt(" #n ")" ::: "memory")
; #define PG8_WAIT_L(n) asm volatile("s_waitcnt lgkmcnt(" #n ")" ::: "memory")
; #define PG8_BAR __builtin_amdgcn_s_barrier()
; #define PG8_SCHED __builtin_amdgcn_sched_barrier(0)
; template <class Epi, class Sched, bool ALIGN_EPI = false, bool SP2 = false, bool I8 = false>
; __device__ __forceinline__ void gemm_phase(PG8_LAS unsigned char* lds, const Gemm g, const Sched& S, const Epi& E) {
;     ...
;         for (int t = 0; t < nt; t += 2) {
;             const bool last = (t == nt - 2);
;             const char* a1 = cA + (size_t)(t + 1) * kstep;
;             const char* a2 = last ? nA : cA + (size_t)(t + 2) * kstep; const char* b2 = last ? nB : cB + (size_t)(t + 2) * kstep;
;             const char* a3 = a2 + kstep; const char* b3 = b2 + kstep;
;             if (last && has_next) S.a_ready(nxt);
;             if constexpr (SP2) {
;             PG8_LDB(B0, 0, 0); PG8_LDB(B1, 0, 1); PG8_SCHED; PG8_LDA(At, 0, 0); PG8_STAGE(PG8_SA(1, 1), a1 + hstep, voffA);
;             PG8_WAIT_V(8); PG8_WAIT_L(0); PG8_BAR; PG8_MMA(0, 0, At, B0); PG8_MMA(0, 1, At, B1); PG8_BAR; PG8_SCHED;
;             PG8_LDA(At, 0, 1); PG8_STAGE(PG8_SB(0, 0), b2, voffB); PG8_STAGE(PG8_SB(0, 1), b2 + hstep, voffB); PG8_STAGE(PG8_SA(0, 0), a2, voffA);
;             PG8_WAIT_V(8); PG8_WAIT_L(0); PG8_BAR; PG8_MMA(1, 0, At, B0); PG8_MMA(1, 1, At, B1); PG8_BAR; PG8_SCHED;
.LBB0_1623:
	s_add_i32 s72, s48, 2
	s_add_u32 s73, s44, 0x80
	s_addc_u32 s49, s45, 0
	s_add_i32 s86, 0, 0x10000
	s_cmp_eq_u32 s57, s48
	s_cselect_b32 s49, s13, s49
	s_cselect_b32 s48, s12, s73
	s_cselect_b32 s77, s41, s67
	s_cselect_b32 s76, s40, s65
	s_add_i32 s73, 0, 0x14000
	v_add_u32_e32 v158, s86, v143
	v_add_u32_e32 v174, s73, v143
	ds_read_b128 v[146:149], v158
	ds_read_b128 v[150:153], v158 offset:1024
	ds_read_b128 v[154:157], v158 offset:2048
	ds_read_b128 v[158:161], v158 offset:3072
	ds_read_b128 v[162:165], v174
	ds_read_b128 v[166:169], v174 offset:1024
	ds_read_b128 v[170:173], v174 offset:2048
	ds_read_b128 v[174:177], v174 offset:3072
	v_lshl_add_u64 v[190:191], s[44:45], 0, v[138:139]
	s_add_i32 m0, s47, 0xc000
	ds_read_b128 v[178:181], v145
	ds_read_b128 v[182:185], v145 offset:1024
	ds_read_b128 v[186:189], v145 offset:2048
	ds_read_b128 v[204:207], v145 offset:3072
	ds_read_b128 v[208:211], v145 offset:4096
	ds_read_b128 v[212:215], v145 offset:5120
	ds_read_b128 v[216:219], v145 offset:6144
	ds_read_b128 v[220:223], v145 offset:7168
	global_load_lds_dwordx4 v[190:191], off
	v_lshl_add_u64 v[190:191], s[44:45], 0, v[140:141]
	s_add_i32 m0, s47, 0xe000
	s_nop 0
	global_load_lds_dwordx4 v[190:191], off
	s_waitcnt vmcnt(8) lgkmcnt(0)
	s_setprio 1
	s_barrier
	v_mfma_f32_16x16x32_bf16 v[124:127], v[146:149], v[178:181], v[124:127]
	v_mfma_f32_16x16x32_bf16 v[124:127], v[150:153], v[182:185], v[124:127]
	v_mfma_f32_16x16x32_bf16 v[112:115], v[150:153], v[204:207], v[112:115]
	v_mfma_f32_16x16x32_bf16 v[112:115], v[146:149], v[186:189], v[112:115]
	v_mfma_f32_16x16x32_bf16 v[96:99], v[146:149], v[208:211], v[96:99]
	v_mfma_f32_16x16x32_bf16 v[96:99], v[150:153], v[212:215], v[96:99]
	v_mfma_f32_16x16x32_bf16 v[80:83], v[150:153], v[220:223], v[80:83]
	v_mfma_f32_16x16x32_bf16 v[80:83], v[146:149], v[216:219], v[80:83]
	v_mfma_f32_16x16x32_bf16 v[76:79], v[154:157], v[216:219], v[76:79]
	v_mfma_f32_16x16x32_bf16 v[76:79], v[158:161], v[220:223], v[76:79]
	v_mfma_f32_16x16x32_bf16 v[92:95], v[158:161], v[212:215], v[92:95]
	v_mfma_f32_16x16x32_bf16 v[92:95], v[154:157], v[208:211], v[92:95]
	v_mfma_f32_16x16x32_bf16 v[108:111], v[154:157], v[186:189], v[108:111]
	v_mfma_f32_16x16x32_bf16 v[108:111], v[158:161], v[204:207], v[108:111]
	v_mfma_f32_16x16x32_bf16 v[128:131], v[158:161], v[182:185], v[128:131]
	v_mfma_f32_16x16x32_bf16 v[128:131], v[154:157], v[178:181], v[128:131]
	v_mfma_f32_16x16x32_bf16 v[120:123], v[162:165], v[178:181], v[120:123]
	v_mfma_f32_16x16x32_bf16 v[120:123], v[166:169], v[182:185], v[120:123]
	v_mfma_f32_16x16x32_bf16 v[104:107], v[166:169], v[204:207], v[104:107]
	v_mfma_f32_16x16x32_bf16 v[104:107], v[162:165], v[186:189], v[104:107]
	v_mfma_f32_16x16x32_bf16 v[88:91], v[162:165], v[208:211], v[88:91]
	v_mfma_f32_16x16x32_bf16 v[88:91], v[166:169], v[212:215], v[88:91]
	v_mfma_f32_16x16x32_bf16 v[72:75], v[166:169], v[220:223], v[72:75]
	v_mfma_f32_16x16x32_bf16 v[72:75], v[162:165], v[216:219], v[72:75]
	v_mfma_f32_16x16x32_bf16 v[68:71], v[170:173], v[216:219], v[68:71]
	v_mfma_f32_16x16x32_bf16 v[68:71], v[174:177], v[220:223], v[68:71]
	v_mfma_f32_16x16x32_bf16 v[84:87], v[174:177], v[212:215], v[84:87]
	v_mfma_f32_16x16x32_bf16 v[84:87], v[170:173], v[208:211], v[84:87]
	v_mfma_f32_16x16x32_bf16 v[100:103], v[170:173], v[186:189], v[100:103]
	v_mfma_f32_16x16x32_bf16 v[100:103], v[174:177], v[204:207], v[100:103]
	v_mfma_f32_16x16x32_bf16 v[116:119], v[174:177], v[182:185], v[116:119]
	v_mfma_f32_16x16x32_bf16 v[116:119], v[170:173], v[178:181], v[116:119]
	s_barrier
	s_setprio 0
	s_add_i32 s86, s86, s28
	v_lshl_add_u64 v[190:191], s[76:77], 0, v[2:3]
	s_mov_b32 m0, s86
	ds_read_b128 v[178:181], v145 offset:16384
	ds_read_b128 v[182:185], v145 offset:17408
	ds_read_b128 v[186:189], v145 offset:18432
	ds_read_b128 v[204:207], v145 offset:19456
	ds_read_b128 v[208:211], v145 offset:20480
	ds_read_b128 v[212:215], v145 offset:21504
	ds_read_b128 v[216:219], v145 offset:22528
	ds_read_b128 v[220:223], v145 offset:23552
	global_load_lds_dwordx4 v[190:191], off
	s_add_i32 m0, s86, 0x2000
	v_lshl_add_u64 v[224:225], s[76:77], 0, v[136:137]
	s_add_u32 s76, s76, s18
	s_addc_u32 s77, s77, s19
	s_add_i32 s73, s73, s28
	global_load_lds_dwordx4 v[224:225], off
	v_lshl_add_u64 v[226:227], s[76:77], 0, v[2:3]
	s_mov_b32 m0, s73
	v_lshl_add_u64 v[228:229], s[76:77], 0, v[136:137]
	global_load_lds_dwordx4 v[226:227], off
	s_add_i32 m0, s73, 0x2000
	v_lshl_add_u64 v[240:241], s[48:49], 0, v[132:133]
	global_load_lds_dwordx4 v[228:229], off
	v_lshl_add_u64 v[242:243], s[48:49], 0, v[134:135]
	s_waitcnt vmcnt(6) lgkmcnt(0)
	s_setprio 1
	s_barrier
; #define PG8_STAGE(bufoff, gbase, voff) do { _Pragma("unroll") for (int _i = 0; _i < 2; ++_i) \
;         __builtin_amdgcn_global_load_lds((const unsigned*)((const char*)(gbase) + (voff)[_i]), (PG8_LAS unsigned*)(lds + (bufoff) + ldsw + _i * 8192), 16, 0, 0); } while (0)
; #define PG8_LDA(dst, b, h) do { _Pragma("unroll") for (int m = 0; m < 4; ++m) _Pragma("unroll") for (int k = 0; k < 2; ++k) dst[m][k] = *(const PG8_LAS bf16x8*)(lds + PG8_SA(b, h) + aoff + m * 2048 + k * 1024); } while (0)
; #define PG8_LDB(dst, b, h) do { _Pragma("unroll") for (int n = 0; n < 2; ++n) _Pragma("unroll") for (int k = 0; k < 2; ++k) dst[n][k] = *(const PG8_LAS bf16x8*)(lds + PG8_SB(b, h) + boff + n * 2048 + k * 1024); } while (0)
; #define PG8_WAIT_V(n) asm volatile("s_waitcnt vmcnt(" #n ")" ::: "memory")
; #define PG8_WAIT_L(n) asm volatile("s_waitcnt lgkmcnt(" #n ")" ::: "memory")
; #define PG8_BAR __builtin_amdgcn_s_barrier()
; #define PG8_SCHED __builtin_amdgcn_sched_barrier(0)
; template <class Epi, class Sched, bool ALIGN_EPI = false, bool SP2 = false, bool I8 = false>
; __device__ __forceinline__ void gemm_phase(PG8_LAS unsigned char* lds, const Gemm g, const Sched& S, const Epi& E) {
;     ...
;             PG8_WAIT_V(8); PG8_WAIT_L(0); PG8_BAR; PG8_MMA(1, 0, At, B0); PG8_MMA(1, 1, At, B1); PG8_BAR; PG8_SCHED;
;             PG8_LDB(B0, 1, 0); PG8_LDB(B1, 1, 1); PG8_SCHED; PG8_LDA(At, 1, 0); PG8_STAGE(PG8_SA(0, 1), a2 + hstep, voffA);
;             PG8_WAIT_V(8); PG8_WAIT_L(0); PG8_BAR; PG8_MMA(0, 0, At, B0); PG8_MMA(0, 1, At, B1); PG8_BAR; PG8_SCHED;
	v_mfma_f32_16x16x32_bf16 v[64:67], v[146:149], v[178:181], v[64:67]
	v_mfma_f32_16x16x32_bf16 v[64:67], v[150:153], v[182:185], v[64:67]
	v_mfma_f32_16x16x32_bf16 v[48:51], v[150:153], v[204:207], v[48:51]
	v_mfma_f32_16x16x32_bf16 v[48:51], v[146:149], v[186:189], v[48:51]
	v_mfma_f32_16x16x32_bf16 v[32:35], v[146:149], v[208:211], v[32:35]
	v_mfma_f32_16x16x32_bf16 v[32:35], v[150:153], v[212:215], v[32:35]
	v_mfma_f32_16x16x32_bf16 v[16:19], v[150:153], v[220:223], v[16:19]
	v_mfma_f32_16x16x32_bf16 v[16:19], v[146:149], v[216:219], v[16:19]
	v_mfma_f32_16x16x32_bf16 v[12:15], v[154:157], v[216:219], v[12:15]
	v_mfma_f32_16x16x32_bf16 v[12:15], v[158:161], v[220:223], v[12:15]
	v_mfma_f32_16x16x32_bf16 v[28:31], v[158:161], v[212:215], v[28:31]
	v_mfma_f32_16x16x32_bf16 v[28:31], v[154:157], v[208:211], v[28:31]
	v_mfma_f32_16x16x32_bf16 v[44:47], v[154:157], v[186:189], v[44:47]
	v_mfma_f32_16x16x32_bf16 v[44:47], v[158:161], v[204:207], v[44:47]
	v_mfma_f32_16x16x32_bf16 v[60:63], v[158:161], v[182:185], v[60:63]
	v_mfma_f32_16x16x32_bf16 v[60:63], v[154:157], v[178:181], v[60:63]
	v_mfma_f32_16x16x32_bf16 v[56:59], v[162:165], v[178:181], v[56:59]
	v_mfma_f32_16x16x32_bf16 v[56:59], v[166:169], v[182:185], v[56:59]
	v_mfma_f32_16x16x32_bf16 v[40:43], v[166:169], v[204:207], v[40:43]
	v_mfma_f32_16x16x32_bf16 v[40:43], v[162:165], v[186:189], v[40:43]
	v_mfma_f32_16x16x32_bf16 v[24:27], v[162:165], v[208:211], v[24:27]
	v_mfma_f32_16x16x32_bf16 v[24:27], v[166:169], v[212:215], v[24:27]
	v_mfma_f32_16x16x32_bf16 v[8:11], v[166:169], v[220:223], v[8:11]
	v_mfma_f32_16x16x32_bf16 v[8:11], v[162:165], v[216:219], v[8:11]
	v_mfma_f32_16x16x32_bf16 v[4:7], v[170:173], v[216:219], v[4:7]
	v_mfma_f32_16x16x32_bf16 v[4:7], v[174:177], v[220:223], v[4:7]
	v_mfma_f32_16x16x32_bf16 v[20:23], v[174:177], v[212:215], v[20:23]
	v_mfma_f32_16x16x32_bf16 v[20:23], v[170:173], v[208:211], v[20:23]
	v_mfma_f32_16x16x32_bf16 v[36:39], v[170:173], v[186:189], v[36:39]
	v_mfma_f32_16x16x32_bf16 v[36:39], v[174:177], v[204:207], v[36:39]
	v_mfma_f32_16x16x32_bf16 v[52:55], v[174:177], v[182:185], v[52:55]
	v_mfma_f32_16x16x32_bf16 v[52:55], v[170:173], v[178:181], v[52:55]
	s_barrier
	s_setprio 0
	s_mov_b32 m0, s47
	s_nop 0
	global_load_lds_dwordx4 v[240:241], off
	s_mov_b32 m0, s50
	s_nop 0
	global_load_lds_dwordx4 v[242:243], off
	s_add_i32 s73, 0, 0x18000
	s_add_i32 s76, 0, 0x1c000
	v_add_u32_e32 v158, s73, v143
	v_add_u32_e32 v174, s76, v143
	ds_read_b128 v[146:149], v158
	ds_read_b128 v[150:153], v158 offset:1024
	ds_read_b128 v[154:157], v158 offset:2048
	ds_read_b128 v[158:161], v158 offset:3072
	ds_read_b128 v[162:165], v174
	ds_read_b128 v[166:169], v174 offset:1024
	ds_read_b128 v[170:173], v174 offset:2048
	ds_read_b128 v[174:177], v174 offset:3072
	s_add_u32 s48, s48, s18
	s_addc_u32 s49, s49, s19
	s_mov_b32 m0, s51
	ds_read_b128 v[178:181], v145 offset:32768
	ds_read_b128 v[182:185], v145 offset:33792
	ds_read_b128 v[186:189], v145 offset:34816
	ds_read_b128 v[204:207], v145 offset:35840
	ds_read_b128 v[208:211], v145 offset:36864
	ds_read_b128 v[212:215], v145 offset:37888
	ds_read_b128 v[216:219], v145 offset:38912
	ds_read_b128 v[220:223], v145 offset:39936
	global_load_lds_dwordx4 v132, s[48:49]
	s_mov_b32 m0, s52
	s_nop 0
	global_load_lds_dwordx4 v134, s[48:49]
	s_waitcnt vmcnt(8) lgkmcnt(0)
	s_setprio 1
	s_barrier
	v_mfma_f32_16x16x32_bf16 v[124:127], v[146:149], v[178:181], v[124:127]
	v_mfma_f32_16x16x32_bf16 v[124:127], v[150:153], v[182:185], v[124:127]
	v_mfma_f32_16x16x32_bf16 v[112:115], v[150:153], v[204:207], v[112:115]
	v_mfma_f32_16x16x32_bf16 v[112:115], v[146:149], v[186:189], v[112:115]
	v_mfma_f32_16x16x32_bf16 v[96:99], v[146:149], v[208:211], v[96:99]
	v_mfma_f32_16x16x32_bf16 v[96:99], v[150:153], v[212:215], v[96:99]
	v_mfma_f32_16x16x32_bf16 v[80:83], v[150:153], v[220:223], v[80:83]
	v_mfma_f32_16x16x32_bf16 v[80:83], v[146:149], v[216:219], v[80:83]
	v_mfma_f32_16x16x32_bf16 v[76:79], v[154:157], v[216:219], v[76:79]
	v_mfma_f32_16x16x32_bf16 v[76:79], v[158:161], v[220:223], v[76:79]
	v_mfma_f32_16x16x32_bf16 v[92:95], v[158:161], v[212:215], v[92:95]
	v_mfma_f32_16x16x32_bf16 v[92:95], v[154:157], v[208:211], v[92:95]
	v_mfma_f32_16x16x32_bf16 v[108:111], v[154:157], v[186:189], v[108:111]
	v_mfma_f32_16x16x32_bf16 v[108:111], v[158:161], v[204:207], v[108:111]
	v_mfma_f32_16x16x32_bf16 v[128:131], v[158:161], v[182:185], v[128:131]
	v_mfma_f32_16x16x32_bf16 v[128:131], v[154:157], v[178:181], v[128:131]
	v_mfma_f32_16x16x32_bf16 v[120:123], v[162:165], v[178:181], v[120:123]
	v_mfma_f32_16x16x32_bf16 v[120:123], v[166:169], v[182:185], v[120:123]
	v_mfma_f32_16x16x32_bf16 v[104:107], v[166:169], v[204:207], v[104:107]
	v_mfma_f32_16x16x32_bf16 v[104:107], v[162:165], v[186:189], v[104:107]
	v_mfma_f32_16x16x32_bf16 v[88:91], v[162:165], v[208:211], v[88:91]
	v_mfma_f32_16x16x32_bf16 v[88:91], v[166:169], v[212:215], v[88:91]
	v_mfma_f32_16x16x32_bf16 v[72:75], v[166:169], v[220:223], v[72:75]
	v_mfma_f32_16x16x32_bf16 v[72:75], v[162:165], v[216:219], v[72:75]
	v_mfma_f32_16x16x32_bf16 v[68:71], v[170:173], v[216:219], v[68:71]
	v_mfma_f32_16x16x32_bf16 v[68:71], v[174:177], v[220:223], v[68:71]
	v_mfma_f32_16x16x32_bf16 v[84:87], v[174:177], v[212:215], v[84:87]
	v_mfma_f32_16x16x32_bf16 v[84:87], v[170:173], v[208:211], v[84:87]
	v_mfma_f32_16x16x32_bf16 v[100:103], v[170:173], v[186:189], v[100:103]
	v_mfma_f32_16x16x32_bf16 v[100:103], v[174:177], v[204:207], v[100:103]
	v_mfma_f32_16x16x32_bf16 v[116:119], v[174:177], v[182:185], v[116:119]
	v_mfma_f32_16x16x32_bf16 v[116:119], v[170:173], v[178:181], v[116:119]
	s_barrier
; #define PG8_STAGE(bufoff, gbase, voff) do { _Pragma("unroll") for (int _i = 0; _i < 2; ++_i) \
;         __builtin_amdgcn_global_load_lds((const unsigned*)((const char*)(gbase) + (voff)[_i]), (PG8_LAS unsigned*)(lds + (bufoff) + ldsw + _i * 8192), 16, 0, 0); } while (0)
; #define PG8_LDA(dst, b, h) do { _Pragma("unroll") for (int m = 0; m < 4; ++m) _Pragma("unroll") for (int k = 0; k < 2; ++k) dst[m][k] = *(const PG8_LAS bf16x8*)(lds + PG8_SA(b, h) + aoff + m * 2048 + k * 1024); } while (0)
; #define PG8_WAIT_V(n) asm volatile("s_waitcnt vmcnt(" #n ")" ::: "memory")
; #define PG8_WAIT_L(n) asm volatile("s_waitcnt lgkmcnt(" #n ")" ::: "memory")
; #define PG8_BAR __builtin_amdgcn_s_barrier()
; #define PG8_SCHED __builtin_amdgcn_sched_barrier(0)
; template <class Epi, class Sched, bool ALIGN_EPI = false, bool SP2 = false, bool I8 = false>
; __device__ __forceinline__ void gemm_phase(PG8_LAS unsigned char* lds, const Gemm g, const Sched& S, const Epi& E) {
;     ...
;             PG8_WAIT_V(8); PG8_WAIT_L(0); PG8_BAR; PG8_MMA(0, 0, At, B0); PG8_MMA(0, 1, At, B1); PG8_BAR; PG8_SCHED;
;             PG8_LDA(At, 1, 1); PG8_STAGE(PG8_SB(1, 0), b3, voffB); PG8_STAGE(PG8_SB(1, 1), b3 + hstep, voffB); PG8_STAGE(PG8_SA(1, 0), a3, voffA);
;             PG8_WAIT_V(8); PG8_WAIT_L(0); PG8_BAR; PG8_MMA(1, 0, At, B0); PG8_MMA(1, 1, At, B1); PG8_BAR; PG8_SCHED;
	s_setprio 0
	s_add_i32 s48, s73, s28
	v_lshl_add_u64 v[190:191], v[190:191], 0, s[84:85]
	s_mov_b32 m0, s48
	ds_read_b128 v[178:181], v145 offset:49152
	ds_read_b128 v[182:185], v145 offset:50176
	ds_read_b128 v[186:189], v145 offset:51200
	ds_read_b128 v[204:207], v145 offset:52224
	ds_read_b128 v[208:211], v145 offset:53248
	ds_read_b128 v[212:215], v145 offset:54272
	ds_read_b128 v[216:219], v145 offset:55296
	ds_read_b128 v[220:223], v145 offset:56320
	global_load_lds_dwordx4 v[190:191], off
	v_lshl_add_u64 v[190:191], v[224:225], 0, s[84:85]
	s_add_i32 m0, s48, 0x2000
	s_add_i32 s48, s76, s28
	global_load_lds_dwordx4 v[190:191], off
	v_lshl_add_u64 v[190:191], v[226:227], 0, s[84:85]
	s_mov_b32 m0, s48
	s_nop 0
	global_load_lds_dwordx4 v[190:191], off
	v_lshl_add_u64 v[190:191], v[228:229], 0, s[84:85]
	s_add_i32 m0, s48, 0x2000
	s_nop 0
	global_load_lds_dwordx4 v[190:191], off
	v_lshl_add_u64 v[190:191], v[240:241], 0, s[84:85]
	s_mov_b32 m0, s55
	s_nop 0
	global_load_lds_dwordx4 v[190:191], off
	v_lshl_add_u64 v[190:191], v[242:243], 0, s[84:85]
	s_mov_b32 m0, s56
	s_nop 0
	global_load_lds_dwordx4 v[190:191], off
	s_waitcnt vmcnt(8) lgkmcnt(0)
	s_setprio 1
	s_barrier
	v_mfma_f32_16x16x32_bf16 v[64:67], v[146:149], v[178:181], v[64:67]
	v_mfma_f32_16x16x32_bf16 v[64:67], v[150:153], v[182:185], v[64:67]
	v_mfma_f32_16x16x32_bf16 v[48:51], v[150:153], v[204:207], v[48:51]
	v_mfma_f32_16x16x32_bf16 v[48:51], v[146:149], v[186:189], v[48:51]
	v_mfma_f32_16x16x32_bf16 v[32:35], v[146:149], v[208:211], v[32:35]
	v_mfma_f32_16x16x32_bf16 v[32:35], v[150:153], v[212:215], v[32:35]
	v_mfma_f32_16x16x32_bf16 v[16:19], v[150:153], v[220:223], v[16:19]
	v_mfma_f32_16x16x32_bf16 v[16:19], v[146:149], v[216:219], v[16:19]
	v_mfma_f32_16x16x32_bf16 v[12:15], v[154:157], v[216:219], v[12:15]
	v_mfma_f32_16x16x32_bf16 v[12:15], v[158:161], v[220:223], v[12:15]
	v_mfma_f32_16x16x32_bf16 v[28:31], v[158:161], v[212:215], v[28:31]
	v_mfma_f32_16x16x32_bf16 v[28:31], v[154:157], v[208:211], v[28:31]
	v_mfma_f32_16x16x32_bf16 v[44:47], v[154:157], v[186:189], v[44:47]
	v_mfma_f32_16x16x32_bf16 v[44:47], v[158:161], v[204:207], v[44:47]
	v_mfma_f32_16x16x32_bf16 v[60:63], v[158:161], v[182:185], v[60:63]
	v_mfma_f32_16x16x32_bf16 v[60:63], v[154:157], v[178:181], v[60:63]
	v_mfma_f32_16x16x32_bf16 v[56:59], v[162:165], v[178:181], v[56:59]
	v_mfma_f32_16x16x32_bf16 v[56:59], v[166:169], v[182:185], v[56:59]
	v_mfma_f32_16x16x32_bf16 v[40:43], v[166:169], v[204:207], v[40:43]
	v_mfma_f32_16x16x32_bf16 v[40:43], v[162:165], v[186:189], v[40:43]
	v_mfma_f32_16x16x32_bf16 v[24:27], v[162:165], v[208:211], v[24:27]
	v_mfma_f32_16x16x32_bf16 v[24:27], v[166:169], v[212:215], v[24:27]
	v_mfma_f32_16x16x32_bf16 v[8:11], v[166:169], v[220:223], v[8:11]
	v_mfma_f32_16x16x32_bf16 v[8:11], v[162:165], v[216:219], v[8:11]
	v_mfma_f32_16x16x32_bf16 v[4:7], v[170:173], v[216:219], v[4:7]
	v_mfma_f32_16x16x32_bf16 v[4:7], v[174:177], v[220:223], v[4:7]
	v_mfma_f32_16x16x32_bf16 v[20:23], v[174:177], v[212:215], v[20:23]
	v_mfma_f32_16x16x32_bf16 v[20:23], v[170:173], v[208:211], v[20:23]
	v_mfma_f32_16x16x32_bf16 v[36:39], v[170:173], v[186:189], v[36:39]
	v_mfma_f32_16x16x32_bf16 v[36:39], v[174:177], v[204:207], v[36:39]
	v_mfma_f32_16x16x32_bf16 v[52:55], v[174:177], v[182:185], v[52:55]
	v_mfma_f32_16x16x32_bf16 v[52:55], v[170:173], v[178:181], v[52:55]
	s_barrier
	s_setprio 0
	s_add_u32 s44, s44, 0x100
	s_addc_u32 s45, s45, 0
	s_add_u32 s65, s65, 0x100
	s_addc_u32 s67, s67, 0
	s_cmp_ge_i32 s72, s53
	s_mov_b32 s48, s72
	s_cbranch_scc0 .LBB0_1623

; #define PG8_STAGE(bufoff, gbase, voff) do { _Pragma("unroll") for (int _i = 0; _i < 2; ++_i) \
;         __builtin_amdgcn_global_load_lds((const unsigned*)((const char*)(gbase) + (voff)[_i]), (PG8_LAS unsigned*)(lds + (bufoff) + ldsw + _i * 8192), 16, 0, 0); } while (0)
; #define PG8_LDA(dst, b, h) do { _Pragma("unroll") for (int m = 0; m < 4; ++m) _Pragma("unroll") for (int k = 0; k < 2; ++k) dst[m][k] = *(const PG8_LAS bf16x8*)(lds + PG8_SA(b, h) + aoff + m * 2048 + k * 1024); } while (0)
; #define PG8_LDB(dst, b, h) do { _Pragma("unroll") for (int n = 0; n < 2; ++n) _Pragma("unroll") for (int k = 0; k < 2; ++k) dst[n][k] = *(const PG8_LAS bf16x8*)(lds + PG8_SB(b, h) + boff + n * 2048 + k * 1024); } while (0)
; #define PG8_WAIT_V(n) asm volatile("s_waitcnt vmcnt(" #n ")" ::: "memory")
; #define PG8_WAIT_L(n) asm volatile("s_waitcnt lgkmcnt(" #n ")" ::: "memory")
; #define PG8_BAR __builtin_amdgcn_s_barrier()
; #define PG8_SCHED __builtin_amdgcn_sched_barrier(0)
; template <class Epi, class Sched, bool ALIGN_EPI = false, bool SP2 = false, bool I8 = false>
; __device__ __forceinline__ void gemm_phase(PG8_LAS unsigned char* lds, const Gemm g, const Sched& S, const Epi& E) {
;     ...
;         const bool has_next = S.next(ui + 1, nxt);
;         const char* nA = has_next ? (const char*)g.A + (size_t)nxt.pm * tstep : cA; const char* nB = has_next ? (const char*)g.Bt + (size_t)nxt.pn * tstep : cB;
;         for (int t = 0; t < nt; t += 2) {
;             const bool last = (t == nt - 2);
;             const char* a1 = cA + (size_t)(t + 1) * kstep;
;             const char* a2 = last ? nA : cA + (size_t)(t + 2) * kstep; const char* b2 = last ? nB : cB + (size_t)(t + 2) * kstep;
;             const char* a3 = a2 + kstep; const char* b3 = b2 + kstep;
;             if (last && has_next) S.a_ready(nxt);
;             if constexpr (SP2) {
;             PG8_LDB(B0, 0, 0); PG8_LDB(B1, 0, 1); PG8_SCHED; PG8_LDA(At, 0, 0); PG8_STAGE(PG8_SA(1, 1), a1 + hstep, voffA);
;             PG8_WAIT_V(8); PG8_WAIT_L(0); PG8_BAR; PG8_MMA(0, 0, At, B0); PG8_MMA(0, 1, At, B1); PG8_BAR; PG8_SCHED;
;             PG8_LDA(At, 0, 1); PG8_STAGE(PG8_SB(0, 0), b2, voffB); PG8_STAGE(PG8_SB(0, 1), b2 + hstep, voffB); PG8_STAGE(PG8_SA(0, 0), a2, voffA);
;             PG8_WAIT_V(8); PG8_WAIT_L(0); PG8_BAR; PG8_MMA(1, 0, At, B0); PG8_MMA(1, 1, At, B1); PG8_BAR; PG8_SCHED;
.LBB0_1699:
	s_add_u32 s53, s24, 0x100
	s_addc_u32 s54, s25, 0
	s_mov_b32 s55, -2
	s_add_u32 s24, s22, 0x100
	s_addc_u32 s25, s23, 0
	s_add_i32 s56, 0, 0x10000
	s_cmpk_eq_i32 s55, 0xa8
	s_cselect_b32 s37, s13, s25
	s_cselect_b32 s36, s12, s24
	s_cselect_b32 s27, s21, s54
	s_cselect_b32 s26, s20, s53
	s_add_i32 s57, 0, 0x14000
	v_add_u32_e32 v144, s56, v240
	v_add_u32_e32 v160, s57, v240
	ds_read_b128 v[124:127], v144
	ds_read_b128 v[128:131], v144 offset:1024
	ds_read_b128 v[132:135], v144 offset:2048
	ds_read_b128 v[144:147], v144 offset:3072
	ds_read_b128 v[148:151], v160
	ds_read_b128 v[152:155], v160 offset:1024
	ds_read_b128 v[156:159], v160 offset:2048
	ds_read_b128 v[160:163], v160 offset:3072
	v_lshl_add_u64 v[218:219], s[22:23], 0, v[210:211]
	s_add_i32 m0, s42, 0xc000
	ds_read_b128 v[164:167], v242
	ds_read_b128 v[168:171], v242 offset:1024
	ds_read_b128 v[172:175], v242 offset:2048
	ds_read_b128 v[176:179], v242 offset:3072
	ds_read_b128 v[180:183], v242 offset:4096
	ds_read_b128 v[184:187], v242 offset:5120
	ds_read_b128 v[188:191], v242 offset:6144
	ds_read_b128 v[214:217], v242 offset:7168
	global_load_lds_dwordx4 v[218:219], off
	v_lshl_add_u64 v[218:219], s[22:23], 0, v[212:213]
	s_add_i32 m0, s42, 0xe000
	s_nop 0
	global_load_lds_dwordx4 v[218:219], off
	s_waitcnt vmcnt(8) lgkmcnt(0)
	s_setprio 1
	s_barrier
	v_mfma_f32_16x16x32_bf16 v[140:143], v[124:127], v[164:167], 0
	v_mfma_f32_16x16x32_bf16 v[140:143], v[128:131], v[168:171], v[140:143]
	v_mfma_f32_16x16x32_bf16 v[112:115], v[128:131], v[176:179], 0
	v_mfma_f32_16x16x32_bf16 v[112:115], v[124:127], v[172:175], v[112:115]
	v_mfma_f32_16x16x32_bf16 v[96:99], v[124:127], v[180:183], 0
	v_mfma_f32_16x16x32_bf16 v[96:99], v[128:131], v[184:187], v[96:99]
	v_mfma_f32_16x16x32_bf16 v[80:83], v[128:131], v[214:217], 0
	v_mfma_f32_16x16x32_bf16 v[80:83], v[124:127], v[188:191], v[80:83]
	v_mfma_f32_16x16x32_bf16 v[76:79], v[132:135], v[188:191], 0
	v_mfma_f32_16x16x32_bf16 v[76:79], v[144:147], v[214:217], v[76:79]
	v_mfma_f32_16x16x32_bf16 v[92:95], v[144:147], v[184:187], 0
	v_mfma_f32_16x16x32_bf16 v[92:95], v[132:135], v[180:183], v[92:95]
	v_mfma_f32_16x16x32_bf16 v[108:111], v[132:135], v[172:175], 0
	v_mfma_f32_16x16x32_bf16 v[108:111], v[144:147], v[176:179], v[108:111]
	v_mfma_f32_16x16x32_bf16 v[136:139], v[144:147], v[168:171], 0
	v_mfma_f32_16x16x32_bf16 v[136:139], v[132:135], v[164:167], v[136:139]
	v_mfma_f32_16x16x32_bf16 v[120:123], v[148:151], v[164:167], 0
	v_mfma_f32_16x16x32_bf16 v[120:123], v[152:155], v[168:171], v[120:123]
	v_mfma_f32_16x16x32_bf16 v[104:107], v[152:155], v[176:179], 0
	v_mfma_f32_16x16x32_bf16 v[104:107], v[148:151], v[172:175], v[104:107]
	v_mfma_f32_16x16x32_bf16 v[88:91], v[148:151], v[180:183], 0
	v_mfma_f32_16x16x32_bf16 v[88:91], v[152:155], v[184:187], v[88:91]
	v_mfma_f32_16x16x32_bf16 v[72:75], v[152:155], v[214:217], 0
	v_mfma_f32_16x16x32_bf16 v[72:75], v[148:151], v[188:191], v[72:75]
	v_mfma_f32_16x16x32_bf16 v[68:71], v[156:159], v[188:191], 0
	v_mfma_f32_16x16x32_bf16 v[68:71], v[160:163], v[214:217], v[68:71]
	v_mfma_f32_16x16x32_bf16 v[84:87], v[160:163], v[184:187], 0
	v_mfma_f32_16x16x32_bf16 v[84:87], v[156:159], v[180:183], v[84:87]
	v_mfma_f32_16x16x32_bf16 v[100:103], v[156:159], v[172:175], 0
	v_mfma_f32_16x16x32_bf16 v[100:103], v[160:163], v[176:179], v[100:103]
	v_mfma_f32_16x16x32_bf16 v[116:119], v[160:163], v[168:171], 0
	v_mfma_f32_16x16x32_bf16 v[116:119], v[156:159], v[164:167], v[116:119]
	s_barrier
	s_setprio 0
	s_add_i32 s22, s56, s41
	v_lshl_add_u64 v[218:219], s[26:27], 0, v[2:3]
	s_mov_b32 m0, s22
	ds_read_b128 v[164:167], v242 offset:16384
	ds_read_b128 v[168:171], v242 offset:17408
	ds_read_b128 v[172:175], v242 offset:18432
	ds_read_b128 v[176:179], v242 offset:19456
	ds_read_b128 v[180:183], v242 offset:20480
	ds_read_b128 v[184:187], v242 offset:21504
	ds_read_b128 v[188:191], v242 offset:22528
	ds_read_b128 v[214:217], v242 offset:23552
	global_load_lds_dwordx4 v[218:219], off
	s_add_i32 m0, s22, 0x2000
	s_add_u32 s22, s26, 0x2b0000
	v_lshl_add_u64 v[220:221], s[26:27], 0, v[204:205]
	s_addc_u32 s23, s27, 0
	s_add_i32 s56, s57, s41
	global_load_lds_dwordx4 v[220:221], off
	s_mov_b32 m0, s56
	v_lshl_add_u64 v[224:225], s[36:37], 0, v[206:207]
	global_load_lds_dwordx4 v2, s[22:23]
	s_add_i32 m0, s56, 0x2000
	s_nop 0
	global_load_lds_dwordx4 v204, s[22:23]
	v_lshl_add_u64 v[222:223], s[36:37], 0, v[208:209]
	s_waitcnt vmcnt(6) lgkmcnt(0)
	s_setprio 1
	s_barrier
	v_mfma_f32_16x16x32_bf16 v[64:67], v[124:127], v[164:167], 0
	v_mfma_f32_16x16x32_bf16 v[64:67], v[128:131], v[168:171], v[64:67]
	v_mfma_f32_16x16x32_bf16 v[48:51], v[128:131], v[176:179], 0
	v_mfma_f32_16x16x32_bf16 v[48:51], v[124:127], v[172:175], v[48:51]
	v_mfma_f32_16x16x32_bf16 v[32:35], v[124:127], v[180:183], 0
	v_mfma_f32_16x16x32_bf16 v[32:35], v[128:131], v[184:187], v[32:35]
	v_mfma_f32_16x16x32_bf16 v[16:19], v[128:131], v[214:217], 0
	v_mfma_f32_16x16x32_bf16 v[16:19], v[124:127], v[188:191], v[16:19]
	v_mfma_f32_16x16x32_bf16 v[12:15], v[132:135], v[188:191], 0
	v_mfma_f32_16x16x32_bf16 v[12:15], v[144:147], v[214:217], v[12:15]
	v_mfma_f32_16x16x32_bf16 v[28:31], v[144:147], v[184:187], 0
	v_mfma_f32_16x16x32_bf16 v[28:31], v[132:135], v[180:183], v[28:31]
	v_mfma_f32_16x16x32_bf16 v[44:47], v[132:135], v[172:175], 0
	v_mfma_f32_16x16x32_bf16 v[44:47], v[144:147], v[176:179], v[44:47]
	v_mfma_f32_16x16x32_bf16 v[60:63], v[144:147], v[168:171], 0
	v_mfma_f32_16x16x32_bf16 v[60:63], v[132:135], v[164:167], v[60:63]
	v_mfma_f32_16x16x32_bf16 v[56:59], v[148:151], v[164:167], 0
	v_mfma_f32_16x16x32_bf16 v[56:59], v[152:155], v[168:171], v[56:59]
	v_mfma_f32_16x16x32_bf16 v[40:43], v[152:155], v[176:179], 0
	v_mfma_f32_16x16x32_bf16 v[40:43], v[148:151], v[172:175], v[40:43]
	v_mfma_f32_16x16x32_bf16 v[24:27], v[148:151], v[180:183], 0
	v_mfma_f32_16x16x32_bf16 v[24:27], v[152:155], v[184:187], v[24:27]
	v_mfma_f32_16x16x32_bf16 v[8:11], v[152:155], v[214:217], 0
	v_mfma_f32_16x16x32_bf16 v[8:11], v[148:151], v[188:191], v[8:11]
	v_mfma_f32_16x16x32_bf16 v[4:7], v[156:159], v[188:191], 0
	v_mfma_f32_16x16x32_bf16 v[4:7], v[160:163], v[214:217], v[4:7]
	v_mfma_f32_16x16x32_bf16 v[20:23], v[160:163], v[184:187], 0
	v_mfma_f32_16x16x32_bf16 v[20:23], v[156:159], v[180:183], v[20:23]
	v_mfma_f32_16x16x32_bf16 v[36:39], v[156:159], v[172:175], 0
	v_mfma_f32_16x16x32_bf16 v[36:39], v[160:163], v[176:179], v[36:39]
	v_mfma_f32_16x16x32_bf16 v[52:55], v[160:163], v[168:171], 0
	v_mfma_f32_16x16x32_bf16 v[52:55], v[156:159], v[164:167], v[52:55]
	s_barrier
; #define PG8_STAGE(bufoff, gbase, voff) do { _Pragma("unroll") for (int _i = 0; _i < 2; ++_i) \
;         __builtin_amdgcn_global_load_lds((const unsigned*)((const char*)(gbase) + (voff)[_i]), (PG8_LAS unsigned*)(lds + (bufoff) + ldsw + _i * 8192), 16, 0, 0); } while (0)
; #define PG8_LDA(dst, b, h) do { _Pragma("unroll") for (int m = 0; m < 4; ++m) _Pragma("unroll") for (int k = 0; k < 2; ++k) dst[m][k] = *(const PG8_LAS bf16x8*)(lds + PG8_SA(b, h) + aoff + m * 2048 + k * 1024); } while (0)
; #define PG8_LDB(dst, b, h) do { _Pragma("unroll") for (int n = 0; n < 2; ++n) _Pragma("unroll") for (int k = 0; k < 2; ++k) dst[n][k] = *(const PG8_LAS bf16x8*)(lds + PG8_SB(b, h) + boff + n * 2048 + k * 1024); } while (0)
; #define PG8_WAIT_V(n) asm volatile("s_waitcnt vmcnt(" #n ")" ::: "memory")
; #define PG8_WAIT_L(n) asm volatile("s_waitcnt lgkmcnt(" #n ")" ::: "memory")
; #define PG8_BAR __builtin_amdgcn_s_barrier()
; #define PG8_SCHED __builtin_amdgcn_sched_barrier(0)
; template <class Epi, class Sched, bool ALIGN_EPI = false, bool SP2 = false, bool I8 = false>
; __device__ __forceinline__ void gemm_phase(PG8_LAS unsigned char* lds, const Gemm g, const Sched& S, const Epi& E) {
;     ...
;             PG8_LDB(B0, 1, 0); PG8_LDB(B1, 1, 1); PG8_SCHED; PG8_LDA(At, 1, 0); PG8_STAGE(PG8_SA(0, 1), a2 + hstep, voffA);
;             PG8_WAIT_V(8); PG8_WAIT_L(0); PG8_BAR; PG8_MMA(0, 0, At, B0); PG8_MMA(0, 1, At, B1); PG8_BAR; PG8_SCHED;
;             PG8_LDA(At, 1, 1); PG8_STAGE(PG8_SB(1, 0), b3, voffB); PG8_STAGE(PG8_SB(1, 1), b3 + hstep, voffB); PG8_STAGE(PG8_SA(1, 0), a3, voffA);
	s_setprio 0
	s_mov_b32 m0, s42
	s_nop 0
	global_load_lds_dwordx4 v[222:223], off
	s_mov_b32 m0, s43
	s_nop 0
	global_load_lds_dwordx4 v[224:225], off
	s_add_i32 s56, 0, 0x18000
	s_add_i32 s57, 0, 0x1c000
	v_add_u32_e32 v144, s56, v240
	v_add_u32_e32 v160, s57, v240
	ds_read_b128 v[124:127], v144
	ds_read_b128 v[128:131], v144 offset:1024
	ds_read_b128 v[132:135], v144 offset:2048
	ds_read_b128 v[144:147], v144 offset:3072
	ds_read_b128 v[148:151], v160
	ds_read_b128 v[152:155], v160 offset:1024
	ds_read_b128 v[156:159], v160 offset:2048
	ds_read_b128 v[160:163], v160 offset:3072
	s_add_u32 s22, s36, 0x2b0000
	s_addc_u32 s23, s37, 0
	s_mov_b32 m0, s44
	ds_read_b128 v[164:167], v242 offset:32768
	ds_read_b128 v[168:171], v242 offset:33792
	ds_read_b128 v[172:175], v242 offset:34816
	ds_read_b128 v[176:179], v242 offset:35840
	ds_read_b128 v[180:183], v242 offset:36864
	ds_read_b128 v[184:187], v242 offset:37888
	ds_read_b128 v[188:191], v242 offset:38912
	ds_read_b128 v[214:217], v242 offset:39936
	global_load_lds_dwordx4 v208, s[22:23]
	s_mov_b32 m0, s45
	s_nop 0
	global_load_lds_dwordx4 v206, s[22:23]
	s_waitcnt vmcnt(8) lgkmcnt(0)
	s_setprio 1
	s_barrier
	v_mfma_f32_16x16x32_bf16 v[140:143], v[124:127], v[164:167], v[140:143]
	v_mfma_f32_16x16x32_bf16 v[140:143], v[128:131], v[168:171], v[140:143]
	v_mfma_f32_16x16x32_bf16 v[112:115], v[128:131], v[176:179], v[112:115]
	v_mfma_f32_16x16x32_bf16 v[112:115], v[124:127], v[172:175], v[112:115]
	v_mfma_f32_16x16x32_bf16 v[96:99], v[124:127], v[180:183], v[96:99]
	v_mfma_f32_16x16x32_bf16 v[96:99], v[128:131], v[184:187], v[96:99]
	v_mfma_f32_16x16x32_bf16 v[80:83], v[128:131], v[214:217], v[80:83]
	v_mfma_f32_16x16x32_bf16 v[80:83], v[124:127], v[188:191], v[80:83]
	v_mfma_f32_16x16x32_bf16 v[76:79], v[132:135], v[188:191], v[76:79]
	v_mfma_f32_16x16x32_bf16 v[76:79], v[144:147], v[214:217], v[76:79]
	v_mfma_f32_16x16x32_bf16 v[92:95], v[144:147], v[184:187], v[92:95]
	v_mfma_f32_16x16x32_bf16 v[92:95], v[132:135], v[180:183], v[92:95]
	v_mfma_f32_16x16x32_bf16 v[108:111], v[132:135], v[172:175], v[108:111]
	v_mfma_f32_16x16x32_bf16 v[108:111], v[144:147], v[176:179], v[108:111]
	v_mfma_f32_16x16x32_bf16 v[136:139], v[144:147], v[168:171], v[136:139]
	v_mfma_f32_16x16x32_bf16 v[136:139], v[132:135], v[164:167], v[136:139]
	v_mfma_f32_16x16x32_bf16 v[120:123], v[148:151], v[164:167], v[120:123]
	v_mfma_f32_16x16x32_bf16 v[120:123], v[152:155], v[168:171], v[120:123]
	v_mfma_f32_16x16x32_bf16 v[104:107], v[152:155], v[176:179], v[104:107]
	v_mfma_f32_16x16x32_bf16 v[104:107], v[148:151], v[172:175], v[104:107]
	v_mfma_f32_16x16x32_bf16 v[88:91], v[148:151], v[180:183], v[88:91]
	v_mfma_f32_16x16x32_bf16 v[88:91], v[152:155], v[184:187], v[88:91]
	v_mfma_f32_16x16x32_bf16 v[72:75], v[152:155], v[214:217], v[72:75]
	v_mfma_f32_16x16x32_bf16 v[72:75], v[148:151], v[188:191], v[72:75]
	v_mfma_f32_16x16x32_bf16 v[68:71], v[156:159], v[188:191], v[68:71]
	v_mfma_f32_16x16x32_bf16 v[68:71], v[160:163], v[214:217], v[68:71]
	v_mfma_f32_16x16x32_bf16 v[84:87], v[160:163], v[184:187], v[84:87]
	v_mfma_f32_16x16x32_bf16 v[84:87], v[156:159], v[180:183], v[84:87]
	v_mfma_f32_16x16x32_bf16 v[100:103], v[156:159], v[172:175], v[100:103]
	v_mfma_f32_16x16x32_bf16 v[100:103], v[160:163], v[176:179], v[100:103]
	v_mfma_f32_16x16x32_bf16 v[116:119], v[160:163], v[168:171], v[116:119]
	v_mfma_f32_16x16x32_bf16 v[116:119], v[156:159], v[164:167], v[116:119]
	s_barrier
	s_setprio 0
	s_add_i32 s22, s56, s41
	v_lshl_add_u64 v[218:219], v[218:219], 0, s[84:85]
	s_mov_b32 m0, s22
	ds_read_b128 v[164:167], v242 offset:49152
	ds_read_b128 v[168:171], v242 offset:50176
	ds_read_b128 v[172:175], v242 offset:51200
	ds_read_b128 v[176:179], v242 offset:52224
	ds_read_b128 v[180:183], v242 offset:53248
	ds_read_b128 v[184:187], v242 offset:54272
	ds_read_b128 v[188:191], v242 offset:55296
	ds_read_b128 v[214:217], v242 offset:56320
	global_load_lds_dwordx4 v[218:219], off
	s_add_i32 m0, s22, 0x2000
	s_add_u32 s22, s26, 0x2b0080
	v_lshl_add_u64 v[218:219], v[220:221], 0, s[84:85]
	s_addc_u32 s23, s27, 0
	s_add_i32 s26, s57, s41
	global_load_lds_dwordx4 v[218:219], off
	s_mov_b32 m0, s26
	s_nop 0
	global_load_lds_dwordx4 v2, s[22:23]
	s_add_i32 m0, s26, 0x2000
	s_nop 0
	global_load_lds_dwordx4 v204, s[22:23]
	s_cmpk_eq_i32 s55, 0xa8
	s_cbranch_scc0 .Ldefer_1700_peel
	v_lshl_add_u64 v[218:219], v[222:223], 0, s[84:85]
	s_mov_b32 m0, s46
	s_nop 0
	global_load_lds_dwordx4 v[218:219], off
	v_lshl_add_u64 v[218:219], v[224:225], 0, s[84:85]
	s_mov_b32 m0, s47
	s_nop 0
	global_load_lds_dwordx4 v[218:219], off
; #define PG8_STAGE(bufoff, gbase, voff) do { _Pragma("unroll") for (int _i = 0; _i < 2; ++_i) \
;         __builtin_amdgcn_global_load_lds((const unsigned*)((const char*)(gbase) + (voff)[_i]), (PG8_LAS unsigned*)(lds + (bufoff) + ldsw + _i * 8192), 16, 0, 0); } while (0)
; #define PG8_LDA(dst, b, h) do { _Pragma("unroll") for (int m = 0; m < 4; ++m) _Pragma("unroll") for (int k = 0; k < 2; ++k) dst[m][k] = *(const PG8_LAS bf16x8*)(lds + PG8_SA(b, h) + aoff + m * 2048 + k * 1024); } while (0)
; #define PG8_LDB(dst, b, h) do { _Pragma("unroll") for (int n = 0; n < 2; ++n) _Pragma("unroll") for (int k = 0; k < 2; ++k) dst[n][k] = *(const PG8_LAS bf16x8*)(lds + PG8_SB(b, h) + boff + n * 2048 + k * 1024); } while (0)
; #define PG8_WAIT_V(n) asm volatile("s_waitcnt vmcnt(" #n ")" ::: "memory")
; #define PG8_WAIT_L(n) asm volatile("s_waitcnt lgkmcnt(" #n ")" ::: "memory")
; #define PG8_BAR __builtin_amdgcn_s_barrier()
; #define PG8_SCHED __builtin_amdgcn_sched_barrier(0)
; template <class Epi, class Sched, bool ALIGN_EPI = false, bool SP2 = false, bool I8 = false>
; __device__ __forceinline__ void gemm_phase(PG8_LAS unsigned char* lds, const Gemm g, const Sched& S, const Epi& E) {
;     ...
;         for (int t = 0; t < nt; t += 2) {
;             const bool last = (t == nt - 2);
;             const char* a1 = cA + (size_t)(t + 1) * kstep;
;             const char* a2 = last ? nA : cA + (size_t)(t + 2) * kstep; const char* b2 = last ? nB : cB + (size_t)(t + 2) * kstep;
;             const char* a3 = a2 + kstep; const char* b3 = b2 + kstep;
;             if (last && has_next) S.a_ready(nxt);
;             if constexpr (SP2) {
;             PG8_LDB(B0, 0, 0); PG8_LDB(B1, 0, 1); PG8_SCHED; PG8_LDA(At, 0, 0); PG8_STAGE(PG8_SA(1, 1), a1 + hstep, voffA);
;             PG8_WAIT_V(8); PG8_WAIT_L(0); PG8_BAR; PG8_MMA(0, 0, At, B0); PG8_MMA(0, 1, At, B1); PG8_BAR; PG8_SCHED;
;     ...
;             PG8_WAIT_V(8); PG8_WAIT_L(0); PG8_BAR; PG8_MMA(0, 0, At, B0); PG8_MMA(0, 1, At, B1); PG8_BAR; PG8_SCHED;
;             PG8_LDA(At, 1, 1); PG8_STAGE(PG8_SB(1, 0), b3, voffB); PG8_STAGE(PG8_SB(1, 1), b3 + hstep, voffB); PG8_STAGE(PG8_SA(1, 0), a3, voffA);
;             PG8_WAIT_V(8); PG8_WAIT_L(0); PG8_BAR; PG8_MMA(1, 0, At, B0); PG8_MMA(1, 1, At, B1); PG8_BAR; PG8_SCHED;
.Ldefer_1700_peel:
	s_waitcnt vmcnt(6) lgkmcnt(0)
	s_setprio 1
	s_barrier
	v_mfma_f32_16x16x32_bf16 v[64:67], v[124:127], v[164:167], v[64:67]
	v_mfma_f32_16x16x32_bf16 v[64:67], v[128:131], v[168:171], v[64:67]
	v_mfma_f32_16x16x32_bf16 v[48:51], v[128:131], v[176:179], v[48:51]
	v_mfma_f32_16x16x32_bf16 v[48:51], v[124:127], v[172:175], v[48:51]
	v_mfma_f32_16x16x32_bf16 v[32:35], v[124:127], v[180:183], v[32:35]
	v_mfma_f32_16x16x32_bf16 v[32:35], v[128:131], v[184:187], v[32:35]
	v_mfma_f32_16x16x32_bf16 v[16:19], v[128:131], v[214:217], v[16:19]
	v_mfma_f32_16x16x32_bf16 v[16:19], v[124:127], v[188:191], v[16:19]
	v_mfma_f32_16x16x32_bf16 v[12:15], v[132:135], v[188:191], v[12:15]
	v_mfma_f32_16x16x32_bf16 v[12:15], v[144:147], v[214:217], v[12:15]
	v_mfma_f32_16x16x32_bf16 v[28:31], v[144:147], v[184:187], v[28:31]
	v_mfma_f32_16x16x32_bf16 v[28:31], v[132:135], v[180:183], v[28:31]
	v_mfma_f32_16x16x32_bf16 v[44:47], v[132:135], v[172:175], v[44:47]
	v_mfma_f32_16x16x32_bf16 v[44:47], v[144:147], v[176:179], v[44:47]
	v_mfma_f32_16x16x32_bf16 v[60:63], v[144:147], v[168:171], v[60:63]
	v_mfma_f32_16x16x32_bf16 v[60:63], v[132:135], v[164:167], v[60:63]
	v_mfma_f32_16x16x32_bf16 v[56:59], v[148:151], v[164:167], v[56:59]
	v_mfma_f32_16x16x32_bf16 v[56:59], v[152:155], v[168:171], v[56:59]
	v_mfma_f32_16x16x32_bf16 v[40:43], v[152:155], v[176:179], v[40:43]
	v_mfma_f32_16x16x32_bf16 v[40:43], v[148:151], v[172:175], v[40:43]
	v_mfma_f32_16x16x32_bf16 v[24:27], v[148:151], v[180:183], v[24:27]
	v_mfma_f32_16x16x32_bf16 v[24:27], v[152:155], v[184:187], v[24:27]
	v_mfma_f32_16x16x32_bf16 v[8:11], v[152:155], v[214:217], v[8:11]
	v_mfma_f32_16x16x32_bf16 v[8:11], v[148:151], v[188:191], v[8:11]
	v_mfma_f32_16x16x32_bf16 v[4:7], v[156:159], v[188:191], v[4:7]
	v_mfma_f32_16x16x32_bf16 v[4:7], v[160:163], v[214:217], v[4:7]
	v_mfma_f32_16x16x32_bf16 v[20:23], v[160:163], v[184:187], v[20:23]
	v_mfma_f32_16x16x32_bf16 v[20:23], v[156:159], v[180:183], v[20:23]
	v_mfma_f32_16x16x32_bf16 v[36:39], v[156:159], v[172:175], v[36:39]
	v_mfma_f32_16x16x32_bf16 v[36:39], v[160:163], v[176:179], v[36:39]
	v_mfma_f32_16x16x32_bf16 v[52:55], v[160:163], v[168:171], v[52:55]
	v_mfma_f32_16x16x32_bf16 v[52:55], v[156:159], v[164:167], v[52:55]
	s_barrier
	s_setprio 0
	s_add_i32 s55, s55, 2
	s_add_u32 s53, s53, 0x100
	s_addc_u32 s54, s54, 0
	s_cmpk_gt_u32 s55, 0xa9
	s_mov_b64 s[22:23], s[24:25]
	s_cbranch_scc1 .Lkloop_exit_5
.LBB0_1700:
	s_add_u32 s24, s22, 0x100
	s_addc_u32 s25, s23, 0
	s_add_i32 s56, 0, 0x10000
	s_cmpk_eq_i32 s55, 0xa8
	s_cselect_b32 s37, s13, s25
	s_cselect_b32 s36, s12, s24
	s_cselect_b32 s27, s21, s54
	s_cselect_b32 s26, s20, s53
	s_add_i32 s57, 0, 0x14000
	v_add_u32_e32 v144, s56, v240
	v_add_u32_e32 v160, s57, v240
	ds_read_b128 v[124:127], v144
	ds_read_b128 v[128:131], v144 offset:1024
	ds_read_b128 v[132:135], v144 offset:2048
	ds_read_b128 v[144:147], v144 offset:3072
	ds_read_b128 v[148:151], v160
	ds_read_b128 v[152:155], v160 offset:1024
	ds_read_b128 v[156:159], v160 offset:2048
	ds_read_b128 v[160:163], v160 offset:3072
	v_lshl_add_u64 v[218:219], v[222:223], 0, s[84:85]
	s_mov_b32 m0, s46
	s_nop 0
	global_load_lds_dwordx4 v[218:219], off
	v_lshl_add_u64 v[218:219], v[224:225], 0, s[84:85]
	s_mov_b32 m0, s47
	s_nop 0
	global_load_lds_dwordx4 v[218:219], off
	v_lshl_add_u64 v[218:219], s[22:23], 0, v[210:211]
	s_add_i32 m0, s42, 0xc000
	ds_read_b128 v[164:167], v242
	ds_read_b128 v[168:171], v242 offset:1024
	ds_read_b128 v[172:175], v242 offset:2048
	ds_read_b128 v[176:179], v242 offset:3072
	ds_read_b128 v[180:183], v242 offset:4096
	ds_read_b128 v[184:187], v242 offset:5120
	ds_read_b128 v[188:191], v242 offset:6144
	ds_read_b128 v[214:217], v242 offset:7168
	global_load_lds_dwordx4 v[218:219], off
	v_lshl_add_u64 v[218:219], s[22:23], 0, v[212:213]
	s_add_i32 m0, s42, 0xe000
	s_nop 0
	global_load_lds_dwordx4 v[218:219], off
	s_waitcnt vmcnt(8) lgkmcnt(0)
	s_setprio 1
	s_barrier
	v_mfma_f32_16x16x32_bf16 v[140:143], v[124:127], v[164:167], v[140:143]
	v_mfma_f32_16x16x32_bf16 v[140:143], v[128:131], v[168:171], v[140:143]
	v_mfma_f32_16x16x32_bf16 v[112:115], v[128:131], v[176:179], v[112:115]
	v_mfma_f32_16x16x32_bf16 v[112:115], v[124:127], v[172:175], v[112:115]
	v_mfma_f32_16x16x32_bf16 v[96:99], v[124:127], v[180:183], v[96:99]
	v_mfma_f32_16x16x32_bf16 v[96:99], v[128:131], v[184:187], v[96:99]
	v_mfma_f32_16x16x32_bf16 v[80:83], v[128:131], v[214:217], v[80:83]
	v_mfma_f32_16x16x32_bf16 v[80:83], v[124:127], v[188:191], v[80:83]
	v_mfma_f32_16x16x32_bf16 v[76:79], v[132:135], v[188:191], v[76:79]
	v_mfma_f32_16x16x32_bf16 v[76:79], v[144:147], v[214:217], v[76:79]
	v_mfma_f32_16x16x32_bf16 v[92:95], v[144:147], v[184:187], v[92:95]
	v_mfma_f32_16x16x32_bf16 v[92:95], v[132:135], v[180:183], v[92:95]
	v_mfma_f32_16x16x32_bf16 v[108:111], v[132:135], v[172:175], v[108:111]
	v_mfma_f32_16x16x32_bf16 v[108:111], v[144:147], v[176:179], v[108:111]
	v_mfma_f32_16x16x32_bf16 v[136:139], v[144:147], v[168:171], v[136:139]
	v_mfma_f32_16x16x32_bf16 v[136:139], v[132:135], v[164:167], v[136:139]
	v_mfma_f32_16x16x32_bf16 v[120:123], v[148:151], v[164:167], v[120:123]
	v_mfma_f32_16x16x32_bf16 v[120:123], v[152:155], v[168:171], v[120:123]
	v_mfma_f32_16x16x32_bf16 v[104:107], v[152:155], v[176:179], v[104:107]
	v_mfma_f32_16x16x32_bf16 v[104:107], v[148:151], v[172:175], v[104:107]
	v_mfma_f32_16x16x32_bf16 v[88:91], v[148:151], v[180:183], v[88:91]
	v_mfma_f32_16x16x32_bf16 v[88:91], v[152:155], v[184:187], v[88:91]
	v_mfma_f32_16x16x32_bf16 v[72:75], v[152:155], v[214:217], v[72:75]
	v_mfma_f32_16x16x32_bf16 v[72:75], v[148:151], v[188:191], v[72:75]
	v_mfma_f32_16x16x32_bf16 v[68:71], v[156:159], v[188:191], v[68:71]
	v_mfma_f32_16x16x32_bf16 v[68:71], v[160:163], v[214:217], v[68:71]
	v_mfma_f32_16x16x32_bf16 v[84:87], v[160:163], v[184:187], v[84:87]
	v_mfma_f32_16x16x32_bf16 v[84:87], v[156:159], v[180:183], v[84:87]
	v_mfma_f32_16x16x32_bf16 v[100:103], v[156:159], v[172:175], v[100:103]
	v_mfma_f32_16x16x32_bf16 v[100:103], v[160:163], v[176:179], v[100:103]
	v_mfma_f32_16x16x32_bf16 v[116:119], v[160:163], v[168:171], v[116:119]
	v_mfma_f32_16x16x32_bf16 v[116:119], v[156:159], v[164:167], v[116:119]
	s_barrier
; #define PG8_STAGE(bufoff, gbase, voff) do { _Pragma("unroll") for (int _i = 0; _i < 2; ++_i) \
;         __builtin_amdgcn_global_load_lds((const unsigned*)((const char*)(gbase) + (voff)[_i]), (PG8_LAS unsigned*)(lds + (bufoff) + ldsw + _i * 8192), 16, 0, 0); } while (0)
; #define PG8_LDA(dst, b, h) do { _Pragma("unroll") for (int m = 0; m < 4; ++m) _Pragma("unroll") for (int k = 0; k < 2; ++k) dst[m][k] = *(const PG8_LAS bf16x8*)(lds + PG8_SA(b, h) + aoff + m * 2048 + k * 1024); } while (0)
; #define PG8_LDB(dst, b, h) do { _Pragma("unroll") for (int n = 0; n < 2; ++n) _Pragma("unroll") for (int k = 0; k < 2; ++k) dst[n][k] = *(const PG8_LAS bf16x8*)(lds + PG8_SB(b, h) + boff + n * 2048 + k * 1024); } while (0)
; #define PG8_WAIT_V(n) asm volatile("s_waitcnt vmcnt(" #n ")" ::: "memory")
; #define PG8_WAIT_L(n) asm volatile("s_waitcnt lgkmcnt(" #n ")" ::: "memory")
; #define PG8_BAR __builtin_amdgcn_s_barrier()
; #define PG8_SCHED __builtin_amdgcn_sched_barrier(0)
; template <class Epi, class Sched, bool ALIGN_EPI = false, bool SP2 = false, bool I8 = false>
; __device__ __forceinline__ void gemm_phase(PG8_LAS unsigned char* lds, const Gemm g, const Sched& S, const Epi& E) {
;     ...
;             PG8_LDA(At, 0, 1); PG8_STAGE(PG8_SB(0, 0), b2, voffB); PG8_STAGE(PG8_SB(0, 1), b2 + hstep, voffB); PG8_STAGE(PG8_SA(0, 0), a2, voffA);
;             PG8_WAIT_V(8); PG8_WAIT_L(0); PG8_BAR; PG8_MMA(1, 0, At, B0); PG8_MMA(1, 1, At, B1); PG8_BAR; PG8_SCHED;
;             PG8_LDB(B0, 1, 0); PG8_LDB(B1, 1, 1); PG8_SCHED; PG8_LDA(At, 1, 0); PG8_STAGE(PG8_SA(0, 1), a2 + hstep, voffA);
	s_setprio 0
	s_add_i32 s22, s56, s41
	v_lshl_add_u64 v[218:219], s[26:27], 0, v[2:3]
	s_mov_b32 m0, s22
	ds_read_b128 v[164:167], v242 offset:16384
	ds_read_b128 v[168:171], v242 offset:17408
	ds_read_b128 v[172:175], v242 offset:18432
	ds_read_b128 v[176:179], v242 offset:19456
	ds_read_b128 v[180:183], v242 offset:20480
	ds_read_b128 v[184:187], v242 offset:21504
	ds_read_b128 v[188:191], v242 offset:22528
	ds_read_b128 v[214:217], v242 offset:23552
	global_load_lds_dwordx4 v[218:219], off
	s_add_i32 m0, s22, 0x2000
	s_add_u32 s22, s26, 0x2b0000
	v_lshl_add_u64 v[220:221], s[26:27], 0, v[204:205]
	s_addc_u32 s23, s27, 0
	s_add_i32 s56, s57, s41
	global_load_lds_dwordx4 v[220:221], off
	s_mov_b32 m0, s56
	v_lshl_add_u64 v[224:225], s[36:37], 0, v[206:207]
	global_load_lds_dwordx4 v2, s[22:23]
	s_add_i32 m0, s56, 0x2000
	s_nop 0
	global_load_lds_dwordx4 v204, s[22:23]
	v_lshl_add_u64 v[222:223], s[36:37], 0, v[208:209]
	s_waitcnt vmcnt(6) lgkmcnt(0)
	s_setprio 1
	s_barrier
	v_mfma_f32_16x16x32_bf16 v[64:67], v[124:127], v[164:167], v[64:67]
	v_mfma_f32_16x16x32_bf16 v[64:67], v[128:131], v[168:171], v[64:67]
	v_mfma_f32_16x16x32_bf16 v[48:51], v[128:131], v[176:179], v[48:51]
	v_mfma_f32_16x16x32_bf16 v[48:51], v[124:127], v[172:175], v[48:51]
	v_mfma_f32_16x16x32_bf16 v[32:35], v[124:127], v[180:183], v[32:35]
	v_mfma_f32_16x16x32_bf16 v[32:35], v[128:131], v[184:187], v[32:35]
	v_mfma_f32_16x16x32_bf16 v[16:19], v[128:131], v[214:217], v[16:19]
	v_mfma_f32_16x16x32_bf16 v[16:19], v[124:127], v[188:191], v[16:19]
	v_mfma_f32_16x16x32_bf16 v[12:15], v[132:135], v[188:191], v[12:15]
	v_mfma_f32_16x16x32_bf16 v[12:15], v[144:147], v[214:217], v[12:15]
	v_mfma_f32_16x16x32_bf16 v[28:31], v[144:147], v[184:187], v[28:31]
	v_mfma_f32_16x16x32_bf16 v[28:31], v[132:135], v[180:183], v[28:31]
	v_mfma_f32_16x16x32_bf16 v[44:47], v[132:135], v[172:175], v[44:47]
	v_mfma_f32_16x16x32_bf16 v[44:47], v[144:147], v[176:179], v[44:47]
	v_mfma_f32_16x16x32_bf16 v[60:63], v[144:147], v[168:171], v[60:63]
	v_mfma_f32_16x16x32_bf16 v[60:63], v[132:135], v[164:167], v[60:63]
	v_mfma_f32_16x16x32_bf16 v[56:59], v[148:151], v[164:167], v[56:59]
	v_mfma_f32_16x16x32_bf16 v[56:59], v[152:155], v[168:171], v[56:59]
	v_mfma_f32_16x16x32_bf16 v[40:43], v[152:155], v[176:179], v[40:43]
	v_mfma_f32_16x16x32_bf16 v[40:43], v[148:151], v[172:175], v[40:43]
	v_mfma_f32_16x16x32_bf16 v[24:27], v[148:151], v[180:183], v[24:27]
	v_mfma_f32_16x16x32_bf16 v[24:27], v[152:155], v[184:187], v[24:27]
	v_mfma_f32_16x16x32_bf16 v[8:11], v[152:155], v[214:217], v[8:11]
	v_mfma_f32_16x16x32_bf16 v[8:11], v[148:151], v[188:191], v[8:11]
	v_mfma_f32_16x16x32_bf16 v[4:7], v[156:159], v[188:191], v[4:7]
	v_mfma_f32_16x16x32_bf16 v[4:7], v[160:163], v[214:217], v[4:7]
	v_mfma_f32_16x16x32_bf16 v[20:23], v[160:163], v[184:187], v[20:23]
	v_mfma_f32_16x16x32_bf16 v[20:23], v[156:159], v[180:183], v[20:23]
	v_mfma_f32_16x16x32_bf16 v[36:39], v[156:159], v[172:175], v[36:39]
	v_mfma_f32_16x16x32_bf16 v[36:39], v[160:163], v[176:179], v[36:39]
	v_mfma_f32_16x16x32_bf16 v[52:55], v[160:163], v[168:171], v[52:55]
	v_mfma_f32_16x16x32_bf16 v[52:55], v[156:159], v[164:167], v[52:55]
	s_barrier
	s_setprio 0
	s_mov_b32 m0, s42
	s_nop 0
	global_load_lds_dwordx4 v[222:223], off
	s_mov_b32 m0, s43
	s_nop 0
	global_load_lds_dwordx4 v[224:225], off
	s_add_i32 s56, 0, 0x18000
	s_add_i32 s57, 0, 0x1c000
	v_add_u32_e32 v144, s56, v240
	v_add_u32_e32 v160, s57, v240
	ds_read_b128 v[124:127], v144
	ds_read_b128 v[128:131], v144 offset:1024
	ds_read_b128 v[132:135], v144 offset:2048
	ds_read_b128 v[144:147], v144 offset:3072
	ds_read_b128 v[148:151], v160
	ds_read_b128 v[152:155], v160 offset:1024
	ds_read_b128 v[156:159], v160 offset:2048
	ds_read_b128 v[160:163], v160 offset:3072
	s_add_u32 s22, s36, 0x2b0000
	s_addc_u32 s23, s37, 0
	s_mov_b32 m0, s44
	ds_read_b128 v[164:167], v242 offset:32768
	ds_read_b128 v[168:171], v242 offset:33792
	ds_read_b128 v[172:175], v242 offset:34816
	ds_read_b128 v[176:179], v242 offset:35840
	ds_read_b128 v[180:183], v242 offset:36864
	ds_read_b128 v[184:187], v242 offset:37888
	ds_read_b128 v[188:191], v242 offset:38912
	ds_read_b128 v[214:217], v242 offset:39936
	global_load_lds_dwordx4 v208, s[22:23]
	s_mov_b32 m0, s45
	s_nop 0
	global_load_lds_dwordx4 v206, s[22:23]
	s_waitcnt vmcnt(8) lgkmcnt(0)
	s_setprio 1
	s_barrier
; #define PG8_STAGE(bufoff, gbase, voff) do { _Pragma("unroll") for (int _i = 0; _i < 2; ++_i) \
;         __builtin_amdgcn_global_load_lds((const unsigned*)((const char*)(gbase) + (voff)[_i]), (PG8_LAS unsigned*)(lds + (bufoff) + ldsw + _i * 8192), 16, 0, 0); } while (0)
; #define PG8_LDA(dst, b, h) do { _Pragma("unroll") for (int m = 0; m < 4; ++m) _Pragma("unroll") for (int k = 0; k < 2; ++k) dst[m][k] = *(const PG8_LAS bf16x8*)(lds + PG8_SA(b, h) + aoff + m * 2048 + k * 1024); } while (0)
; #define PG8_WAIT_V(n) asm volatile("s_waitcnt vmcnt(" #n ")" ::: "memory")
; #define PG8_WAIT_L(n) asm volatile("s_waitcnt lgkmcnt(" #n ")" ::: "memory")
; #define PG8_BAR __builtin_amdgcn_s_barrier()
; #define PG8_SCHED __builtin_amdgcn_sched_barrier(0)
; template <class Epi, class Sched, bool ALIGN_EPI = false, bool SP2 = false, bool I8 = false>
; __device__ __forceinline__ void gemm_phase(PG8_LAS unsigned char* lds, const Gemm g, const Sched& S, const Epi& E) {
;     ...
;             PG8_WAIT_V(8); PG8_WAIT_L(0); PG8_BAR; PG8_MMA(0, 0, At, B0); PG8_MMA(0, 1, At, B1); PG8_BAR; PG8_SCHED;
;             PG8_LDA(At, 1, 1); PG8_STAGE(PG8_SB(1, 0), b3, voffB); PG8_STAGE(PG8_SB(1, 1), b3 + hstep, voffB); PG8_STAGE(PG8_SA(1, 0), a3, voffA);
;             PG8_WAIT_V(8); PG8_WAIT_L(0); PG8_BAR; PG8_MMA(1, 0, At, B0); PG8_MMA(1, 1, At, B1); PG8_BAR; PG8_SCHED;
	v_mfma_f32_16x16x32_bf16 v[140:143], v[124:127], v[164:167], v[140:143]
	v_mfma_f32_16x16x32_bf16 v[140:143], v[128:131], v[168:171], v[140:143]
	v_mfma_f32_16x16x32_bf16 v[112:115], v[128:131], v[176:179], v[112:115]
	v_mfma_f32_16x16x32_bf16 v[112:115], v[124:127], v[172:175], v[112:115]
	v_mfma_f32_16x16x32_bf16 v[96:99], v[124:127], v[180:183], v[96:99]
	v_mfma_f32_16x16x32_bf16 v[96:99], v[128:131], v[184:187], v[96:99]
	v_mfma_f32_16x16x32_bf16 v[80:83], v[128:131], v[214:217], v[80:83]
	v_mfma_f32_16x16x32_bf16 v[80:83], v[124:127], v[188:191], v[80:83]
	v_mfma_f32_16x16x32_bf16 v[76:79], v[132:135], v[188:191], v[76:79]
	v_mfma_f32_16x16x32_bf16 v[76:79], v[144:147], v[214:217], v[76:79]
	v_mfma_f32_16x16x32_bf16 v[92:95], v[144:147], v[184:187], v[92:95]
	v_mfma_f32_16x16x32_bf16 v[92:95], v[132:135], v[180:183], v[92:95]
	v_mfma_f32_16x16x32_bf16 v[108:111], v[132:135], v[172:175], v[108:111]
	v_mfma_f32_16x16x32_bf16 v[108:111], v[144:147], v[176:179], v[108:111]
	v_mfma_f32_16x16x32_bf16 v[136:139], v[144:147], v[168:171], v[136:139]
	v_mfma_f32_16x16x32_bf16 v[136:139], v[132:135], v[164:167], v[136:139]
	v_mfma_f32_16x16x32_bf16 v[120:123], v[148:151], v[164:167], v[120:123]
	v_mfma_f32_16x16x32_bf16 v[120:123], v[152:155], v[168:171], v[120:123]
	v_mfma_f32_16x16x32_bf16 v[104:107], v[152:155], v[176:179], v[104:107]
	v_mfma_f32_16x16x32_bf16 v[104:107], v[148:151], v[172:175], v[104:107]
	v_mfma_f32_16x16x32_bf16 v[88:91], v[148:151], v[180:183], v[88:91]
	v_mfma_f32_16x16x32_bf16 v[88:91], v[152:155], v[184:187], v[88:91]
	v_mfma_f32_16x16x32_bf16 v[72:75], v[152:155], v[214:217], v[72:75]
	v_mfma_f32_16x16x32_bf16 v[72:75], v[148:151], v[188:191], v[72:75]
	v_mfma_f32_16x16x32_bf16 v[68:71], v[156:159], v[188:191], v[68:71]
	v_mfma_f32_16x16x32_bf16 v[68:71], v[160:163], v[214:217], v[68:71]
	v_mfma_f32_16x16x32_bf16 v[84:87], v[160:163], v[184:187], v[84:87]
	v_mfma_f32_16x16x32_bf16 v[84:87], v[156:159], v[180:183], v[84:87]
	v_mfma_f32_16x16x32_bf16 v[100:103], v[156:159], v[172:175], v[100:103]
	v_mfma_f32_16x16x32_bf16 v[100:103], v[160:163], v[176:179], v[100:103]
	v_mfma_f32_16x16x32_bf16 v[116:119], v[160:163], v[168:171], v[116:119]
	v_mfma_f32_16x16x32_bf16 v[116:119], v[156:159], v[164:167], v[116:119]
	s_barrier
	s_setprio 0
	s_add_i32 s22, s56, s41
	v_lshl_add_u64 v[218:219], v[218:219], 0, s[84:85]
	s_mov_b32 m0, s22
	ds_read_b128 v[164:167], v242 offset:49152
	ds_read_b128 v[168:171], v242 offset:50176
	ds_read_b128 v[172:175], v242 offset:51200
	ds_read_b128 v[176:179], v242 offset:52224
	ds_read_b128 v[180:183], v242 offset:53248
	ds_read_b128 v[184:187], v242 offset:54272
	ds_read_b128 v[188:191], v242 offset:55296
	ds_read_b128 v[214:217], v242 offset:56320
	global_load_lds_dwordx4 v[218:219], off
	s_add_i32 m0, s22, 0x2000
	s_add_u32 s22, s26, 0x2b0080
	v_lshl_add_u64 v[218:219], v[220:221], 0, s[84:85]
	s_addc_u32 s23, s27, 0
	s_add_i32 s26, s57, s41
	global_load_lds_dwordx4 v[218:219], off
	s_mov_b32 m0, s26
	s_nop 0
	global_load_lds_dwordx4 v2, s[22:23]
	s_add_i32 m0, s26, 0x2000
	s_nop 0
	global_load_lds_dwordx4 v204, s[22:23]
	s_cmpk_eq_i32 s55, 0xa8
	s_cbranch_scc0 .Ldefer_1700_body
	v_lshl_add_u64 v[218:219], v[222:223], 0, s[84:85]
	s_mov_b32 m0, s46
	s_nop 0
	global_load_lds_dwordx4 v[218:219], off
	v_lshl_add_u64 v[218:219], v[224:225], 0, s[84:85]
	s_mov_b32 m0, s47
	s_nop 0
	global_load_lds_dwordx4 v[218:219], off
.Ldefer_1700_body:
	s_waitcnt vmcnt(6) lgkmcnt(0)
	s_setprio 1
	s_barrier
	v_mfma_f32_16x16x32_bf16 v[64:67], v[124:127], v[164:167], v[64:67]
	v_mfma_f32_16x16x32_bf16 v[64:67], v[128:131], v[168:171], v[64:67]
	v_mfma_f32_16x16x32_bf16 v[48:51], v[128:131], v[176:179], v[48:51]
	v_mfma_f32_16x16x32_bf16 v[48:51], v[124:127], v[172:175], v[48:51]
	v_mfma_f32_16x16x32_bf16 v[32:35], v[124:127], v[180:183], v[32:35]
	v_mfma_f32_16x16x32_bf16 v[32:35], v[128:131], v[184:187], v[32:35]
	v_mfma_f32_16x16x32_bf16 v[16:19], v[128:131], v[214:217], v[16:19]
	v_mfma_f32_16x16x32_bf16 v[16:19], v[124:127], v[188:191], v[16:19]
	v_mfma_f32_16x16x32_bf16 v[12:15], v[132:135], v[188:191], v[12:15]
	v_mfma_f32_16x16x32_bf16 v[12:15], v[144:147], v[214:217], v[12:15]
	v_mfma_f32_16x16x32_bf16 v[28:31], v[144:147], v[184:187], v[28:31]
	v_mfma_f32_16x16x32_bf16 v[28:31], v[132:135], v[180:183], v[28:31]
	v_mfma_f32_16x16x32_bf16 v[44:47], v[132:135], v[172:175], v[44:47]
	v_mfma_f32_16x16x32_bf16 v[44:47], v[144:147], v[176:179], v[44:47]
	v_mfma_f32_16x16x32_bf16 v[60:63], v[144:147], v[168:171], v[60:63]
	v_mfma_f32_16x16x32_bf16 v[60:63], v[132:135], v[164:167], v[60:63]
	v_mfma_f32_16x16x32_bf16 v[56:59], v[148:151], v[164:167], v[56:59]
	v_mfma_f32_16x16x32_bf16 v[56:59], v[152:155], v[168:171], v[56:59]
	v_mfma_f32_16x16x32_bf16 v[40:43], v[152:155], v[176:179], v[40:43]
	v_mfma_f32_16x16x32_bf16 v[40:43], v[148:151], v[172:175], v[40:43]
	v_mfma_f32_16x16x32_bf16 v[24:27], v[148:151], v[180:183], v[24:27]
	v_mfma_f32_16x16x32_bf16 v[24:27], v[152:155], v[184:187], v[24:27]
	v_mfma_f32_16x16x32_bf16 v[8:11], v[152:155], v[214:217], v[8:11]
	v_mfma_f32_16x16x32_bf16 v[8:11], v[148:151], v[188:191], v[8:11]
	v_mfma_f32_16x16x32_bf16 v[4:7], v[156:159], v[188:191], v[4:7]
	v_mfma_f32_16x16x32_bf16 v[4:7], v[160:163], v[214:217], v[4:7]
	v_mfma_f32_16x16x32_bf16 v[20:23], v[160:163], v[184:187], v[20:23]
	v_mfma_f32_16x16x32_bf16 v[20:23], v[156:159], v[180:183], v[20:23]
	v_mfma_f32_16x16x32_bf16 v[36:39], v[156:159], v[172:175], v[36:39]
	v_mfma_f32_16x16x32_bf16 v[36:39], v[160:163], v[176:179], v[36:39]
	v_mfma_f32_16x16x32_bf16 v[52:55], v[160:163], v[168:171], v[52:55]
	v_mfma_f32_16x16x32_bf16 v[52:55], v[156:159], v[164:167], v[52:55]
	s_barrier
	s_setprio 0
	s_add_i32 s55, s55, 2
	s_add_u32 s53, s53, 0x100
	s_addc_u32 s54, s54, 0
	s_cmpk_gt_u32 s55, 0xa9
	s_mov_b64 s[22:23], s[24:25]
	s_cbranch_scc0 .LBB0_1700

; #define PG8_STAGE(bufoff, gbase, voff) do { _Pragma("unroll") for (int _i = 0; _i < 2; ++_i) \
;         __builtin_amdgcn_global_load_lds((const unsigned*)((const char*)(gbase) + (voff)[_i]), (PG8_LAS unsigned*)(lds + (bufoff) + ldsw + _i * 8192), 16, 0, 0); } while (0)
; #define PG8_LDA(dst, b, h) do { _Pragma("unroll") for (int m = 0; m < 4; ++m) _Pragma("unroll") for (int k = 0; k < 2; ++k) dst[m][k] = *(const PG8_LAS bf16x8*)(lds + PG8_SA(b, h) + aoff + m * 2048 + k * 1024); } while (0)
; #define PG8_LDB(dst, b, h) do { _Pragma("unroll") for (int n = 0; n < 2; ++n) _Pragma("unroll") for (int k = 0; k < 2; ++k) dst[n][k] = *(const PG8_LAS bf16x8*)(lds + PG8_SB(b, h) + boff + n * 2048 + k * 1024); } while (0)
; #define PG8_WAIT_V(n) asm volatile("s_waitcnt vmcnt(" #n ")" ::: "memory")
; #define PG8_WAIT_L(n) asm volatile("s_waitcnt lgkmcnt(" #n ")" ::: "memory")
; #define PG8_BAR __builtin_amdgcn_s_barrier()
; #define PG8_SCHED __builtin_amdgcn_sched_barrier(0)
; template <class Epi, class Sched, bool ALIGN_EPI = false, bool SP2 = false, bool I8 = false>
; __device__ __forceinline__ void gemm_phase(PG8_LAS unsigned char* lds, const Gemm g, const Sched& S, const Epi& E) {
;     ...
;         const char* nA = has_next ? (const char*)g.A + (size_t)nxt.pm * tstep : cA; const char* nB = has_next ? (const char*)g.Bt + (size_t)nxt.pn * tstep : cB;
;         for (int t = 0; t < nt; t += 2) {
;             const bool last = (t == nt - 2);
;             const char* a1 = cA + (size_t)(t + 1) * kstep;
;             const char* a2 = last ? nA : cA + (size_t)(t + 2) * kstep; const char* b2 = last ? nB : cB + (size_t)(t + 2) * kstep;
;             const char* a3 = a2 + kstep; const char* b3 = b2 + kstep;
;             if (last && has_next) S.a_ready(nxt);
;             if constexpr (SP2) {
;             PG8_LDB(B0, 0, 0); PG8_LDB(B1, 0, 1); PG8_SCHED; PG8_LDA(At, 0, 0); PG8_STAGE(PG8_SA(1, 1), a1 + hstep, voffA);
;             PG8_WAIT_V(8); PG8_WAIT_L(0); PG8_BAR; PG8_MMA(0, 0, At, B0); PG8_MMA(0, 1, At, B1); PG8_BAR; PG8_SCHED;
;             PG8_LDA(At, 0, 1); PG8_STAGE(PG8_SB(0, 0), b2, voffB); PG8_STAGE(PG8_SB(0, 1), b2 + hstep, voffB); PG8_STAGE(PG8_SA(0, 0), a2, voffA);
;             PG8_WAIT_V(8); PG8_WAIT_L(0); PG8_BAR; PG8_MMA(1, 0, At, B0); PG8_MMA(1, 1, At, B1); PG8_BAR; PG8_SCHED;
.LBB0_1842:
	s_ashr_i32 s45, s44, 31
	s_lshl_b64 s[34:35], s[44:45], 20
	s_add_u32 s50, s47, s34
	s_addc_u32 s51, s52, s35
	s_and_b64 s[34:35], s[8:9], exec
	s_cselect_b32 s11, s51, s55
	s_cselect_b32 s13, s50, s54
	s_ashr_i32 s49, s48, 31
	s_lshl_b64 s[34:35], s[48:49], 20
	s_add_u32 s56, s53, s34
	s_addc_u32 s57, s64, s35
	s_and_b64 s[34:35], s[8:9], exec
	s_cselect_b32 s34, s57, s59
	s_cselect_b32 s35, s56, s58
	s_add_u32 s54, s54, 0x80080
	s_addc_u32 s55, s55, 0
	s_add_u32 s45, s58, 0x100
	s_addc_u32 s49, s59, 0
	s_mov_b32 s86, -2
	s_waitcnt lgkmcnt(0)
	s_add_u32 s58, s54, 0xfff80080
	s_addc_u32 s59, s55, -1
	s_add_i32 s87, 0, 0x10000
	s_cmp_eq_u32 s86, 28
	s_cselect_b32 s61, s11, s59
	s_cselect_b32 s60, s13, s58
	s_cselect_b32 s59, s34, s49
	s_cselect_b32 s58, s35, s45
	s_add_i32 vcc_lo, 0, 0x14000
	v_add_u32_e32 v40, s87, v217
	v_add_u32_e32 v160, vcc_lo, v217
	ds_read_b128 v[28:31], v40
	ds_read_b128 v[32:35], v40 offset:1024
	ds_read_b128 v[36:39], v40 offset:2048
	ds_read_b128 v[40:43], v40 offset:3072
	ds_read_b128 v[140:143], v160
	ds_read_b128 v[144:147], v160 offset:1024
	ds_read_b128 v[156:159], v160 offset:2048
	ds_read_b128 v[160:163], v160 offset:3072
	s_add_i32 m0, s65, 0xc000
	ds_read_b128 v[164:167], v219
	ds_read_b128 v[168:171], v219 offset:1024
	ds_read_b128 v[172:175], v219 offset:2048
	ds_read_b128 v[176:179], v219 offset:3072
	ds_read_b128 v[204:207], v219 offset:4096
	ds_read_b128 v[208:211], v219 offset:5120
	ds_read_b128 v[212:215], v219 offset:6144
	ds_read_b128 v[220:223], v219 offset:7168
	global_load_lds_dwordx4 v186, s[54:55]
	s_add_i32 m0, s65, 0xe000
	s_nop 0
	global_load_lds_dwordx4 v188, s[54:55]
	s_waitcnt vmcnt(8) lgkmcnt(0)
	s_setprio 1
	s_barrier
	v_mfma_i32_16x16x64_i8 v[152:155], v[28:31], v[164:167], 0
	v_mfma_i32_16x16x64_i8 v[152:155], v[32:35], v[168:171], v[152:155]
	v_mfma_i32_16x16x64_i8 v[128:131], v[32:35], v[176:179], 0
	v_mfma_i32_16x16x64_i8 v[128:131], v[28:31], v[172:175], v[128:131]
	v_mfma_i32_16x16x64_i8 v[112:115], v[28:31], v[204:207], 0
	v_mfma_i32_16x16x64_i8 v[112:115], v[32:35], v[208:211], v[112:115]
	v_mfma_i32_16x16x64_i8 v[96:99], v[32:35], v[220:223], 0
	v_mfma_i32_16x16x64_i8 v[96:99], v[28:31], v[212:215], v[96:99]
	v_mfma_i32_16x16x64_i8 v[92:95], v[36:39], v[212:215], 0
	v_mfma_i32_16x16x64_i8 v[92:95], v[40:43], v[220:223], v[92:95]
	v_mfma_i32_16x16x64_i8 v[108:111], v[40:43], v[208:211], 0
	v_mfma_i32_16x16x64_i8 v[108:111], v[36:39], v[204:207], v[108:111]
	v_mfma_i32_16x16x64_i8 v[124:127], v[36:39], v[172:175], 0
	v_mfma_i32_16x16x64_i8 v[124:127], v[40:43], v[176:179], v[124:127]
	v_mfma_i32_16x16x64_i8 v[148:151], v[40:43], v[168:171], 0
	v_mfma_i32_16x16x64_i8 v[148:151], v[36:39], v[164:167], v[148:151]
	v_mfma_i32_16x16x64_i8 v[136:139], v[140:143], v[164:167], 0
	v_mfma_i32_16x16x64_i8 v[136:139], v[144:147], v[168:171], v[136:139]
	v_mfma_i32_16x16x64_i8 v[120:123], v[144:147], v[176:179], 0
	v_mfma_i32_16x16x64_i8 v[120:123], v[140:143], v[172:175], v[120:123]
	v_mfma_i32_16x16x64_i8 v[104:107], v[140:143], v[204:207], 0
	v_mfma_i32_16x16x64_i8 v[104:107], v[144:147], v[208:211], v[104:107]
	v_mfma_i32_16x16x64_i8 v[88:91], v[144:147], v[220:223], 0
	v_mfma_i32_16x16x64_i8 v[88:91], v[140:143], v[212:215], v[88:91]
	v_mfma_i32_16x16x64_i8 v[84:87], v[156:159], v[212:215], 0
	v_mfma_i32_16x16x64_i8 v[84:87], v[160:163], v[220:223], v[84:87]
	v_mfma_i32_16x16x64_i8 v[100:103], v[160:163], v[208:211], 0
	v_mfma_i32_16x16x64_i8 v[100:103], v[156:159], v[204:207], v[100:103]
	v_mfma_i32_16x16x64_i8 v[116:119], v[156:159], v[172:175], 0
	v_mfma_i32_16x16x64_i8 v[116:119], v[160:163], v[176:179], v[116:119]
	v_mfma_i32_16x16x64_i8 v[132:135], v[160:163], v[168:171], 0
	v_mfma_i32_16x16x64_i8 v[132:135], v[156:159], v[164:167], v[132:135]
	s_barrier
	s_setprio 0
	s_add_i32 s87, s87, s46
	v_lshl_add_u64 v[190:191], s[58:59], 0, v[2:3]
	s_mov_b32 m0, s87
	ds_read_b128 v[164:167], v219 offset:16384
	ds_read_b128 v[168:171], v219 offset:17408
	ds_read_b128 v[172:175], v219 offset:18432
	ds_read_b128 v[176:179], v219 offset:19456
	ds_read_b128 v[204:207], v219 offset:20480
	ds_read_b128 v[208:211], v219 offset:21504
	ds_read_b128 v[212:215], v219 offset:22528
	ds_read_b128 v[220:223], v219 offset:23552
	global_load_lds_dwordx4 v[190:191], off
	s_add_i32 m0, s87, 0x2000
	s_add_u32 s96, s58, 0x80000
	v_lshl_add_u64 v[224:225], s[58:59], 0, v[184:185]
	s_addc_u32 s97, s59, 0
	s_add_i32 s87, vcc_lo, s46
	global_load_lds_dwordx4 v[224:225], off
	s_mov_b32 m0, s87
	v_lshl_add_u64 v[228:229], s[60:61], 0, v[182:183]
	global_load_lds_dwordx4 v2, s[96:97]
	s_add_i32 m0, s87, 0x2000
	s_nop 0
	global_load_lds_dwordx4 v184, s[96:97]
	v_lshl_add_u64 v[226:227], s[60:61], 0, v[180:181]
	s_waitcnt vmcnt(6) lgkmcnt(0)
	s_setprio 1
	s_barrier
; #define PG8_STAGE(bufoff, gbase, voff) do { _Pragma("unroll") for (int _i = 0; _i < 2; ++_i) \
;         __builtin_amdgcn_global_load_lds((const unsigned*)((const char*)(gbase) + (voff)[_i]), (PG8_LAS unsigned*)(lds + (bufoff) + ldsw + _i * 8192), 16, 0, 0); } while (0)
; #define PG8_LDA(dst, b, h) do { _Pragma("unroll") for (int m = 0; m < 4; ++m) _Pragma("unroll") for (int k = 0; k < 2; ++k) dst[m][k] = *(const PG8_LAS bf16x8*)(lds + PG8_SA(b, h) + aoff + m * 2048 + k * 1024); } while (0)
; #define PG8_LDB(dst, b, h) do { _Pragma("unroll") for (int n = 0; n < 2; ++n) _Pragma("unroll") for (int k = 0; k < 2; ++k) dst[n][k] = *(const PG8_LAS bf16x8*)(lds + PG8_SB(b, h) + boff + n * 2048 + k * 1024); } while (0)
; #define PG8_WAIT_V(n) asm volatile("s_waitcnt vmcnt(" #n ")" ::: "memory")
; #define PG8_WAIT_L(n) asm volatile("s_waitcnt lgkmcnt(" #n ")" ::: "memory")
; #define PG8_BAR __builtin_amdgcn_s_barrier()
; #define PG8_SCHED __builtin_amdgcn_sched_barrier(0)
; template <class Epi, class Sched, bool ALIGN_EPI = false, bool SP2 = false, bool I8 = false>
; __device__ __forceinline__ void gemm_phase(PG8_LAS unsigned char* lds, const Gemm g, const Sched& S, const Epi& E) {
;     ...
;             PG8_WAIT_V(8); PG8_WAIT_L(0); PG8_BAR; PG8_MMA(1, 0, At, B0); PG8_MMA(1, 1, At, B1); PG8_BAR; PG8_SCHED;
;             PG8_LDB(B0, 1, 0); PG8_LDB(B1, 1, 1); PG8_SCHED; PG8_LDA(At, 1, 0); PG8_STAGE(PG8_SA(0, 1), a2 + hstep, voffA);
;             PG8_WAIT_V(8); PG8_WAIT_L(0); PG8_BAR; PG8_MMA(0, 0, At, B0); PG8_MMA(0, 1, At, B1); PG8_BAR; PG8_SCHED;
;             PG8_LDA(At, 1, 1); PG8_STAGE(PG8_SB(1, 0), b3, voffB); PG8_STAGE(PG8_SB(1, 1), b3 + hstep, voffB); PG8_STAGE(PG8_SA(1, 0), a3, voffA);
	v_mfma_i32_16x16x64_i8 v[80:83], v[28:31], v[164:167], 0
	v_mfma_i32_16x16x64_i8 v[80:83], v[32:35], v[168:171], v[80:83]
	v_mfma_i32_16x16x64_i8 v[64:67], v[32:35], v[176:179], 0
	v_mfma_i32_16x16x64_i8 v[64:67], v[28:31], v[172:175], v[64:67]
	v_mfma_i32_16x16x64_i8 v[48:51], v[28:31], v[204:207], 0
	v_mfma_i32_16x16x64_i8 v[48:51], v[32:35], v[208:211], v[48:51]
	v_mfma_i32_16x16x64_i8 v[16:19], v[32:35], v[220:223], 0
	v_mfma_i32_16x16x64_i8 v[16:19], v[28:31], v[212:215], v[16:19]
	v_mfma_i32_16x16x64_i8 v[12:15], v[36:39], v[212:215], 0
	v_mfma_i32_16x16x64_i8 v[12:15], v[40:43], v[220:223], v[12:15]
	v_mfma_i32_16x16x64_i8 v[44:47], v[40:43], v[208:211], 0
	v_mfma_i32_16x16x64_i8 v[44:47], v[36:39], v[204:207], v[44:47]
	v_mfma_i32_16x16x64_i8 v[60:63], v[36:39], v[172:175], 0
	v_mfma_i32_16x16x64_i8 v[60:63], v[40:43], v[176:179], v[60:63]
	v_mfma_i32_16x16x64_i8 v[76:79], v[40:43], v[168:171], 0
	v_mfma_i32_16x16x64_i8 v[76:79], v[36:39], v[164:167], v[76:79]
	v_mfma_i32_16x16x64_i8 v[28:31], v[140:143], v[164:167], 0
	v_mfma_i32_16x16x64_i8 v[28:31], v[144:147], v[168:171], v[28:31]
	v_mfma_i32_16x16x64_i8 v[36:39], v[144:147], v[176:179], 0
	v_mfma_i32_16x16x64_i8 v[36:39], v[140:143], v[172:175], v[36:39]
	v_mfma_i32_16x16x64_i8 v[24:27], v[140:143], v[204:207], 0
	v_mfma_i32_16x16x64_i8 v[24:27], v[144:147], v[208:211], v[24:27]
	v_mfma_i32_16x16x64_i8 v[8:11], v[144:147], v[220:223], 0
	v_mfma_i32_16x16x64_i8 v[8:11], v[140:143], v[212:215], v[8:11]
	v_mfma_i32_16x16x64_i8 v[4:7], v[156:159], v[212:215], 0
	v_mfma_i32_16x16x64_i8 v[4:7], v[160:163], v[220:223], v[4:7]
	v_mfma_i32_16x16x64_i8 v[20:23], v[160:163], v[208:211], 0
	v_mfma_i32_16x16x64_i8 v[20:23], v[156:159], v[204:207], v[20:23]
	v_mfma_i32_16x16x64_i8 v[40:43], v[156:159], v[172:175], 0
	v_mfma_i32_16x16x64_i8 v[40:43], v[160:163], v[176:179], v[40:43]
	v_mfma_i32_16x16x64_i8 v[32:35], v[160:163], v[168:171], 0
	v_mfma_i32_16x16x64_i8 v[32:35], v[156:159], v[164:167], v[32:35]
	s_barrier
	s_setprio 0
	s_mov_b32 m0, s65
	s_nop 0
	global_load_lds_dwordx4 v[226:227], off
	s_mov_b32 m0, s67
	s_nop 0
	global_load_lds_dwordx4 v[228:229], off
	s_add_i32 s87, 0, 0x18000
	s_add_i32 s96, 0, 0x1c000
	v_add_u32_e32 v72, s87, v217
	v_add_u32_e32 v160, s96, v217
	ds_read_b128 v[52:55], v72
	ds_read_b128 v[56:59], v72 offset:1024
	ds_read_b128 v[68:71], v72 offset:2048
	ds_read_b128 v[72:75], v72 offset:3072
	ds_read_b128 v[140:143], v160
	ds_read_b128 v[144:147], v160 offset:1024
	ds_read_b128 v[156:159], v160 offset:2048
	ds_read_b128 v[160:163], v160 offset:3072
	s_add_u32 s60, s60, 0x80000
	s_addc_u32 s61, s61, 0
	s_mov_b32 m0, s72
	ds_read_b128 v[164:167], v219 offset:32768
	ds_read_b128 v[168:171], v219 offset:33792
	ds_read_b128 v[172:175], v219 offset:34816
	ds_read_b128 v[176:179], v219 offset:35840
	ds_read_b128 v[204:207], v219 offset:36864
	ds_read_b128 v[208:211], v219 offset:37888
	ds_read_b128 v[212:215], v219 offset:38912
	ds_read_b128 v[220:223], v219 offset:39936
	global_load_lds_dwordx4 v180, s[60:61]
	s_mov_b32 m0, s73
	s_nop 0
	global_load_lds_dwordx4 v182, s[60:61]
	s_waitcnt vmcnt(8) lgkmcnt(0)
	s_setprio 1
	s_barrier
	v_mfma_i32_16x16x64_i8 v[152:155], v[52:55], v[164:167], v[152:155]
	v_mfma_i32_16x16x64_i8 v[152:155], v[56:59], v[168:171], v[152:155]
	v_mfma_i32_16x16x64_i8 v[128:131], v[56:59], v[176:179], v[128:131]
	v_mfma_i32_16x16x64_i8 v[128:131], v[52:55], v[172:175], v[128:131]
	v_mfma_i32_16x16x64_i8 v[112:115], v[52:55], v[204:207], v[112:115]
	v_mfma_i32_16x16x64_i8 v[112:115], v[56:59], v[208:211], v[112:115]
	v_mfma_i32_16x16x64_i8 v[96:99], v[56:59], v[220:223], v[96:99]
	v_mfma_i32_16x16x64_i8 v[96:99], v[52:55], v[212:215], v[96:99]
	v_mfma_i32_16x16x64_i8 v[92:95], v[68:71], v[212:215], v[92:95]
	v_mfma_i32_16x16x64_i8 v[92:95], v[72:75], v[220:223], v[92:95]
	v_mfma_i32_16x16x64_i8 v[108:111], v[72:75], v[208:211], v[108:111]
	v_mfma_i32_16x16x64_i8 v[108:111], v[68:71], v[204:207], v[108:111]
	v_mfma_i32_16x16x64_i8 v[124:127], v[68:71], v[172:175], v[124:127]
	v_mfma_i32_16x16x64_i8 v[124:127], v[72:75], v[176:179], v[124:127]
	v_mfma_i32_16x16x64_i8 v[148:151], v[72:75], v[168:171], v[148:151]
	v_mfma_i32_16x16x64_i8 v[148:151], v[68:71], v[164:167], v[148:151]
	v_mfma_i32_16x16x64_i8 v[136:139], v[140:143], v[164:167], v[136:139]
	v_mfma_i32_16x16x64_i8 v[136:139], v[144:147], v[168:171], v[136:139]
	v_mfma_i32_16x16x64_i8 v[120:123], v[144:147], v[176:179], v[120:123]
	v_mfma_i32_16x16x64_i8 v[120:123], v[140:143], v[172:175], v[120:123]
	v_mfma_i32_16x16x64_i8 v[104:107], v[140:143], v[204:207], v[104:107]
	v_mfma_i32_16x16x64_i8 v[104:107], v[144:147], v[208:211], v[104:107]
	v_mfma_i32_16x16x64_i8 v[88:91], v[144:147], v[220:223], v[88:91]
	v_mfma_i32_16x16x64_i8 v[88:91], v[140:143], v[212:215], v[88:91]
	v_mfma_i32_16x16x64_i8 v[84:87], v[156:159], v[212:215], v[84:87]
	v_mfma_i32_16x16x64_i8 v[84:87], v[160:163], v[220:223], v[84:87]
	v_mfma_i32_16x16x64_i8 v[100:103], v[160:163], v[208:211], v[100:103]
	v_mfma_i32_16x16x64_i8 v[100:103], v[156:159], v[204:207], v[100:103]
	v_mfma_i32_16x16x64_i8 v[116:119], v[156:159], v[172:175], v[116:119]
	v_mfma_i32_16x16x64_i8 v[116:119], v[160:163], v[176:179], v[116:119]
	v_mfma_i32_16x16x64_i8 v[132:135], v[160:163], v[168:171], v[132:135]
	v_mfma_i32_16x16x64_i8 v[132:135], v[156:159], v[164:167], v[132:135]
	s_barrier
	s_setprio 0
	s_add_i32 s60, s87, s46
	v_lshl_add_u64 v[190:191], v[190:191], 0, s[84:85]
	s_mov_b32 m0, s60
	ds_read_b128 v[164:167], v219 offset:49152
	ds_read_b128 v[168:171], v219 offset:50176
	ds_read_b128 v[172:175], v219 offset:51200
	ds_read_b128 v[176:179], v219 offset:52224
	ds_read_b128 v[204:207], v219 offset:53248
	ds_read_b128 v[208:211], v219 offset:54272
	ds_read_b128 v[212:215], v219 offset:55296
	ds_read_b128 v[220:223], v219 offset:56320
	global_load_lds_dwordx4 v[190:191], off
	s_add_i32 m0, s60, 0x2000
	s_add_u32 s58, s58, 0x80080
	v_lshl_add_u64 v[190:191], v[224:225], 0, s[84:85]
	s_addc_u32 s59, s59, 0
	s_add_i32 s60, s96, s46
	global_load_lds_dwordx4 v[190:191], off
	s_mov_b32 m0, s60
	s_nop 0
	global_load_lds_dwordx4 v2, s[58:59]
	s_add_i32 m0, s60, 0x2000
	s_nop 0
	global_load_lds_dwordx4 v184, s[58:59]
	s_cmp_eq_u32 s86, 28
	s_cbranch_scc0 .Ldefer_1843_peel
	v_lshl_add_u64 v[190:191], v[226:227], 0, s[84:85]
	s_mov_b32 m0, s28
	s_nop 0
	global_load_lds_dwordx4 v[190:191], off
	v_lshl_add_u64 v[190:191], v[228:229], 0, s[84:85]
	s_mov_b32 m0, s77
	s_nop 0
	global_load_lds_dwordx4 v[190:191], off
; #define PG8_STAGE(bufoff, gbase, voff) do { _Pragma("unroll") for (int _i = 0; _i < 2; ++_i) \
;         __builtin_amdgcn_global_load_lds((const unsigned*)((const char*)(gbase) + (voff)[_i]), (PG8_LAS unsigned*)(lds + (bufoff) + ldsw + _i * 8192), 16, 0, 0); } while (0)
; #define PG8_LDA(dst, b, h) do { _Pragma("unroll") for (int m = 0; m < 4; ++m) _Pragma("unroll") for (int k = 0; k < 2; ++k) dst[m][k] = *(const PG8_LAS bf16x8*)(lds + PG8_SA(b, h) + aoff + m * 2048 + k * 1024); } while (0)
; #define PG8_LDB(dst, b, h) do { _Pragma("unroll") for (int n = 0; n < 2; ++n) _Pragma("unroll") for (int k = 0; k < 2; ++k) dst[n][k] = *(const PG8_LAS bf16x8*)(lds + PG8_SB(b, h) + boff + n * 2048 + k * 1024); } while (0)
; #define PG8_WAIT_V(n) asm volatile("s_waitcnt vmcnt(" #n ")" ::: "memory")
; #define PG8_WAIT_L(n) asm volatile("s_waitcnt lgkmcnt(" #n ")" ::: "memory")
; #define PG8_BAR __builtin_amdgcn_s_barrier()
; #define PG8_SCHED __builtin_amdgcn_sched_barrier(0)
; template <class Epi, class Sched, bool ALIGN_EPI = false, bool SP2 = false, bool I8 = false>
; __device__ __forceinline__ void gemm_phase(PG8_LAS unsigned char* lds, const Gemm g, const Sched& S, const Epi& E) {
;     ...
;         for (int t = 0; t < nt; t += 2) {
;             const bool last = (t == nt - 2);
;             const char* a1 = cA + (size_t)(t + 1) * kstep;
;             const char* a2 = last ? nA : cA + (size_t)(t + 2) * kstep; const char* b2 = last ? nB : cB + (size_t)(t + 2) * kstep;
;             const char* a3 = a2 + kstep; const char* b3 = b2 + kstep;
;             if (last && has_next) S.a_ready(nxt);
;             if constexpr (SP2) {
;             PG8_LDB(B0, 0, 0); PG8_LDB(B1, 0, 1); PG8_SCHED; PG8_LDA(At, 0, 0); PG8_STAGE(PG8_SA(1, 1), a1 + hstep, voffA);
;             PG8_WAIT_V(8); PG8_WAIT_L(0); PG8_BAR; PG8_MMA(0, 0, At, B0); PG8_MMA(0, 1, At, B1); PG8_BAR; PG8_SCHED;
;     ...
;             PG8_WAIT_V(8); PG8_WAIT_L(0); PG8_BAR; PG8_MMA(0, 0, At, B0); PG8_MMA(0, 1, At, B1); PG8_BAR; PG8_SCHED;
;             PG8_LDA(At, 1, 1); PG8_STAGE(PG8_SB(1, 0), b3, voffB); PG8_STAGE(PG8_SB(1, 1), b3 + hstep, voffB); PG8_STAGE(PG8_SA(1, 0), a3, voffA);
;             PG8_WAIT_V(8); PG8_WAIT_L(0); PG8_BAR; PG8_MMA(1, 0, At, B0); PG8_MMA(1, 1, At, B1); PG8_BAR; PG8_SCHED;
.Ldefer_1843_peel:
	s_waitcnt vmcnt(6) lgkmcnt(0)
	s_setprio 1
	s_barrier
	v_mfma_i32_16x16x64_i8 v[80:83], v[52:55], v[164:167], v[80:83]
	v_mfma_i32_16x16x64_i8 v[80:83], v[56:59], v[168:171], v[80:83]
	v_mfma_i32_16x16x64_i8 v[64:67], v[56:59], v[176:179], v[64:67]
	v_mfma_i32_16x16x64_i8 v[64:67], v[52:55], v[172:175], v[64:67]
	v_mfma_i32_16x16x64_i8 v[48:51], v[52:55], v[204:207], v[48:51]
	v_mfma_i32_16x16x64_i8 v[48:51], v[56:59], v[208:211], v[48:51]
	v_mfma_i32_16x16x64_i8 v[16:19], v[56:59], v[220:223], v[16:19]
	v_mfma_i32_16x16x64_i8 v[16:19], v[52:55], v[212:215], v[16:19]
	v_mfma_i32_16x16x64_i8 v[12:15], v[68:71], v[212:215], v[12:15]
	v_mfma_i32_16x16x64_i8 v[12:15], v[72:75], v[220:223], v[12:15]
	v_mfma_i32_16x16x64_i8 v[44:47], v[72:75], v[208:211], v[44:47]
	v_mfma_i32_16x16x64_i8 v[44:47], v[68:71], v[204:207], v[44:47]
	v_mfma_i32_16x16x64_i8 v[60:63], v[68:71], v[172:175], v[60:63]
	v_mfma_i32_16x16x64_i8 v[60:63], v[72:75], v[176:179], v[60:63]
	v_mfma_i32_16x16x64_i8 v[76:79], v[72:75], v[168:171], v[76:79]
	v_mfma_i32_16x16x64_i8 v[76:79], v[68:71], v[164:167], v[76:79]
	v_mfma_i32_16x16x64_i8 v[28:31], v[140:143], v[164:167], v[28:31]
	v_mfma_i32_16x16x64_i8 v[72:75], v[144:147], v[168:171], v[28:31]
	v_mfma_i32_16x16x64_i8 v[28:31], v[144:147], v[176:179], v[36:39]
	v_mfma_i32_16x16x64_i8 v[56:59], v[140:143], v[172:175], v[28:31]
	v_mfma_i32_16x16x64_i8 v[24:27], v[140:143], v[204:207], v[24:27]
	v_mfma_i32_16x16x64_i8 v[24:27], v[144:147], v[208:211], v[24:27]
	v_mfma_i32_16x16x64_i8 v[8:11], v[144:147], v[220:223], v[8:11]
	v_mfma_i32_16x16x64_i8 v[8:11], v[140:143], v[212:215], v[8:11]
	v_mfma_i32_16x16x64_i8 v[4:7], v[156:159], v[212:215], v[4:7]
	v_mfma_i32_16x16x64_i8 v[4:7], v[160:163], v[220:223], v[4:7]
	v_mfma_i32_16x16x64_i8 v[20:23], v[160:163], v[208:211], v[20:23]
	v_mfma_i32_16x16x64_i8 v[20:23], v[156:159], v[204:207], v[20:23]
	v_mfma_i32_16x16x64_i8 v[28:31], v[156:159], v[172:175], v[40:43]
	v_mfma_i32_16x16x64_i8 v[52:55], v[160:163], v[176:179], v[28:31]
	v_mfma_i32_16x16x64_i8 v[28:31], v[160:163], v[168:171], v[32:35]
	v_mfma_i32_16x16x64_i8 v[68:71], v[156:159], v[164:167], v[28:31]
	s_barrier
	s_setprio 0
	s_add_i32 s86, s86, 2
	s_add_u32 s54, s54, 0x100
	s_addc_u32 s55, s55, 0
	s_add_u32 s45, s45, 0x100
	s_addc_u32 s49, s49, 0
	s_cmp_gt_u32 s86, 29
	s_cbranch_scc1 .Lkloop_exit_6
.LBB0_1843:
	s_add_u32 s58, s54, 0xfff80080
	s_addc_u32 s59, s55, -1
	s_add_i32 s87, 0, 0x10000
	s_cmp_eq_u32 s86, 28
	s_cselect_b32 s61, s11, s59
	s_cselect_b32 s60, s13, s58
	s_cselect_b32 s59, s34, s49
	s_cselect_b32 s58, s35, s45
	s_add_i32 vcc_lo, 0, 0x14000
	v_add_u32_e32 v40, s87, v217
	v_add_u32_e32 v160, vcc_lo, v217
	ds_read_b128 v[28:31], v40
	ds_read_b128 v[32:35], v40 offset:1024
	ds_read_b128 v[36:39], v40 offset:2048
	ds_read_b128 v[40:43], v40 offset:3072
	ds_read_b128 v[140:143], v160
	ds_read_b128 v[144:147], v160 offset:1024
	ds_read_b128 v[156:159], v160 offset:2048
	ds_read_b128 v[160:163], v160 offset:3072
	v_lshl_add_u64 v[190:191], v[226:227], 0, s[84:85]
	s_mov_b32 m0, s28
	s_nop 0
	global_load_lds_dwordx4 v[190:191], off
	v_lshl_add_u64 v[190:191], v[228:229], 0, s[84:85]
	s_mov_b32 m0, s77
	s_nop 0
	global_load_lds_dwordx4 v[190:191], off
	s_add_i32 m0, s65, 0xc000
	ds_read_b128 v[164:167], v219
	ds_read_b128 v[168:171], v219 offset:1024
	ds_read_b128 v[172:175], v219 offset:2048
	ds_read_b128 v[176:179], v219 offset:3072
	ds_read_b128 v[204:207], v219 offset:4096
	ds_read_b128 v[208:211], v219 offset:5120
	ds_read_b128 v[212:215], v219 offset:6144
	ds_read_b128 v[220:223], v219 offset:7168
	global_load_lds_dwordx4 v186, s[54:55]
	s_add_i32 m0, s65, 0xe000
	s_nop 0
	global_load_lds_dwordx4 v188, s[54:55]
	s_waitcnt vmcnt(8) lgkmcnt(0)
	s_setprio 1
	s_barrier
	v_mfma_i32_16x16x64_i8 v[152:155], v[28:31], v[164:167], v[152:155]
	v_mfma_i32_16x16x64_i8 v[152:155], v[32:35], v[168:171], v[152:155]
	v_mfma_i32_16x16x64_i8 v[128:131], v[32:35], v[176:179], v[128:131]
	v_mfma_i32_16x16x64_i8 v[128:131], v[28:31], v[172:175], v[128:131]
	v_mfma_i32_16x16x64_i8 v[112:115], v[28:31], v[204:207], v[112:115]
	v_mfma_i32_16x16x64_i8 v[112:115], v[32:35], v[208:211], v[112:115]
	v_mfma_i32_16x16x64_i8 v[96:99], v[32:35], v[220:223], v[96:99]
	v_mfma_i32_16x16x64_i8 v[96:99], v[28:31], v[212:215], v[96:99]
	v_mfma_i32_16x16x64_i8 v[92:95], v[36:39], v[212:215], v[92:95]
	v_mfma_i32_16x16x64_i8 v[92:95], v[40:43], v[220:223], v[92:95]
	v_mfma_i32_16x16x64_i8 v[108:111], v[40:43], v[208:211], v[108:111]
	v_mfma_i32_16x16x64_i8 v[108:111], v[36:39], v[204:207], v[108:111]
	v_mfma_i32_16x16x64_i8 v[124:127], v[36:39], v[172:175], v[124:127]
	v_mfma_i32_16x16x64_i8 v[124:127], v[40:43], v[176:179], v[124:127]
	v_mfma_i32_16x16x64_i8 v[148:151], v[40:43], v[168:171], v[148:151]
	v_mfma_i32_16x16x64_i8 v[148:151], v[36:39], v[164:167], v[148:151]
	v_mfma_i32_16x16x64_i8 v[136:139], v[140:143], v[164:167], v[136:139]
	v_mfma_i32_16x16x64_i8 v[136:139], v[144:147], v[168:171], v[136:139]
	v_mfma_i32_16x16x64_i8 v[120:123], v[144:147], v[176:179], v[120:123]
	v_mfma_i32_16x16x64_i8 v[120:123], v[140:143], v[172:175], v[120:123]
	v_mfma_i32_16x16x64_i8 v[104:107], v[140:143], v[204:207], v[104:107]
	v_mfma_i32_16x16x64_i8 v[104:107], v[144:147], v[208:211], v[104:107]
	v_mfma_i32_16x16x64_i8 v[88:91], v[144:147], v[220:223], v[88:91]
	v_mfma_i32_16x16x64_i8 v[88:91], v[140:143], v[212:215], v[88:91]
	v_mfma_i32_16x16x64_i8 v[84:87], v[156:159], v[212:215], v[84:87]
	v_mfma_i32_16x16x64_i8 v[84:87], v[160:163], v[220:223], v[84:87]
	v_mfma_i32_16x16x64_i8 v[100:103], v[160:163], v[208:211], v[100:103]
	v_mfma_i32_16x16x64_i8 v[100:103], v[156:159], v[204:207], v[100:103]
	v_mfma_i32_16x16x64_i8 v[116:119], v[156:159], v[172:175], v[116:119]
	v_mfma_i32_16x16x64_i8 v[116:119], v[160:163], v[176:179], v[116:119]
	v_mfma_i32_16x16x64_i8 v[132:135], v[160:163], v[168:171], v[132:135]
	v_mfma_i32_16x16x64_i8 v[132:135], v[156:159], v[164:167], v[132:135]
	s_barrier
; #define PG8_STAGE(bufoff, gbase, voff) do { _Pragma("unroll") for (int _i = 0; _i < 2; ++_i) \
;         __builtin_amdgcn_global_load_lds((const unsigned*)((const char*)(gbase) + (voff)[_i]), (PG8_LAS unsigned*)(lds + (bufoff) + ldsw + _i * 8192), 16, 0, 0); } while (0)
; #define PG8_LDA(dst, b, h) do { _Pragma("unroll") for (int m = 0; m < 4; ++m) _Pragma("unroll") for (int k = 0; k < 2; ++k) dst[m][k] = *(const PG8_LAS bf16x8*)(lds + PG8_SA(b, h) + aoff + m * 2048 + k * 1024); } while (0)
; #define PG8_LDB(dst, b, h) do { _Pragma("unroll") for (int n = 0; n < 2; ++n) _Pragma("unroll") for (int k = 0; k < 2; ++k) dst[n][k] = *(const PG8_LAS bf16x8*)(lds + PG8_SB(b, h) + boff + n * 2048 + k * 1024); } while (0)
; #define PG8_WAIT_V(n) asm volatile("s_waitcnt vmcnt(" #n ")" ::: "memory")
; #define PG8_WAIT_L(n) asm volatile("s_waitcnt lgkmcnt(" #n ")" ::: "memory")
; #define PG8_BAR __builtin_amdgcn_s_barrier()
; #define PG8_SCHED __builtin_amdgcn_sched_barrier(0)
; template <class Epi, class Sched, bool ALIGN_EPI = false, bool SP2 = false, bool I8 = false>
; __device__ __forceinline__ void gemm_phase(PG8_LAS unsigned char* lds, const Gemm g, const Sched& S, const Epi& E) {
;     ...
;             PG8_LDA(At, 0, 1); PG8_STAGE(PG8_SB(0, 0), b2, voffB); PG8_STAGE(PG8_SB(0, 1), b2 + hstep, voffB); PG8_STAGE(PG8_SA(0, 0), a2, voffA);
;             PG8_WAIT_V(8); PG8_WAIT_L(0); PG8_BAR; PG8_MMA(1, 0, At, B0); PG8_MMA(1, 1, At, B1); PG8_BAR; PG8_SCHED;
;             PG8_LDB(B0, 1, 0); PG8_LDB(B1, 1, 1); PG8_SCHED; PG8_LDA(At, 1, 0); PG8_STAGE(PG8_SA(0, 1), a2 + hstep, voffA);
;             PG8_WAIT_V(8); PG8_WAIT_L(0); PG8_BAR; PG8_MMA(0, 0, At, B0); PG8_MMA(0, 1, At, B1); PG8_BAR; PG8_SCHED;
	s_setprio 0
	s_add_i32 s87, s87, s46
	v_lshl_add_u64 v[190:191], s[58:59], 0, v[2:3]
	s_mov_b32 m0, s87
	ds_read_b128 v[164:167], v219 offset:16384
	ds_read_b128 v[168:171], v219 offset:17408
	ds_read_b128 v[172:175], v219 offset:18432
	ds_read_b128 v[176:179], v219 offset:19456
	ds_read_b128 v[204:207], v219 offset:20480
	ds_read_b128 v[208:211], v219 offset:21504
	ds_read_b128 v[212:215], v219 offset:22528
	ds_read_b128 v[220:223], v219 offset:23552
	global_load_lds_dwordx4 v[190:191], off
	s_add_i32 m0, s87, 0x2000
	s_add_u32 s96, s58, 0x80000
	v_lshl_add_u64 v[224:225], s[58:59], 0, v[184:185]
	s_addc_u32 s97, s59, 0
	s_add_i32 s87, vcc_lo, s46
	global_load_lds_dwordx4 v[224:225], off
	s_mov_b32 m0, s87
	v_lshl_add_u64 v[228:229], s[60:61], 0, v[182:183]
	global_load_lds_dwordx4 v2, s[96:97]
	s_add_i32 m0, s87, 0x2000
	s_nop 0
	global_load_lds_dwordx4 v184, s[96:97]
	v_lshl_add_u64 v[226:227], s[60:61], 0, v[180:181]
	s_waitcnt vmcnt(6) lgkmcnt(0)
	s_setprio 1
	s_barrier
	v_mfma_i32_16x16x64_i8 v[80:83], v[28:31], v[164:167], v[80:83]
	v_mfma_i32_16x16x64_i8 v[80:83], v[32:35], v[168:171], v[80:83]
	v_mfma_i32_16x16x64_i8 v[64:67], v[32:35], v[176:179], v[64:67]
	v_mfma_i32_16x16x64_i8 v[64:67], v[28:31], v[172:175], v[64:67]
	v_mfma_i32_16x16x64_i8 v[48:51], v[28:31], v[204:207], v[48:51]
	v_mfma_i32_16x16x64_i8 v[48:51], v[32:35], v[208:211], v[48:51]
	v_mfma_i32_16x16x64_i8 v[16:19], v[32:35], v[220:223], v[16:19]
	v_mfma_i32_16x16x64_i8 v[16:19], v[28:31], v[212:215], v[16:19]
	v_mfma_i32_16x16x64_i8 v[12:15], v[36:39], v[212:215], v[12:15]
	v_mfma_i32_16x16x64_i8 v[12:15], v[40:43], v[220:223], v[12:15]
	v_mfma_i32_16x16x64_i8 v[44:47], v[40:43], v[208:211], v[44:47]
	v_mfma_i32_16x16x64_i8 v[44:47], v[36:39], v[204:207], v[44:47]
	v_mfma_i32_16x16x64_i8 v[60:63], v[36:39], v[172:175], v[60:63]
	v_mfma_i32_16x16x64_i8 v[60:63], v[40:43], v[176:179], v[60:63]
	v_mfma_i32_16x16x64_i8 v[76:79], v[40:43], v[168:171], v[76:79]
	v_mfma_i32_16x16x64_i8 v[76:79], v[36:39], v[164:167], v[76:79]
	v_mfma_i32_16x16x64_i8 v[28:31], v[140:143], v[164:167], v[72:75]
	v_mfma_i32_16x16x64_i8 v[28:31], v[144:147], v[168:171], v[28:31]
	v_mfma_i32_16x16x64_i8 v[36:39], v[144:147], v[176:179], v[56:59]
	v_mfma_i32_16x16x64_i8 v[36:39], v[140:143], v[172:175], v[36:39]
	v_mfma_i32_16x16x64_i8 v[24:27], v[140:143], v[204:207], v[24:27]
	v_mfma_i32_16x16x64_i8 v[24:27], v[144:147], v[208:211], v[24:27]
	v_mfma_i32_16x16x64_i8 v[8:11], v[144:147], v[220:223], v[8:11]
	v_mfma_i32_16x16x64_i8 v[8:11], v[140:143], v[212:215], v[8:11]
	v_mfma_i32_16x16x64_i8 v[4:7], v[156:159], v[212:215], v[4:7]
	v_mfma_i32_16x16x64_i8 v[4:7], v[160:163], v[220:223], v[4:7]
	v_mfma_i32_16x16x64_i8 v[20:23], v[160:163], v[208:211], v[20:23]
	v_mfma_i32_16x16x64_i8 v[20:23], v[156:159], v[204:207], v[20:23]
	v_mfma_i32_16x16x64_i8 v[40:43], v[156:159], v[172:175], v[52:55]
	v_mfma_i32_16x16x64_i8 v[40:43], v[160:163], v[176:179], v[40:43]
	v_mfma_i32_16x16x64_i8 v[32:35], v[160:163], v[168:171], v[68:71]
	v_mfma_i32_16x16x64_i8 v[32:35], v[156:159], v[164:167], v[32:35]
	s_barrier
	s_setprio 0
	s_mov_b32 m0, s65
	s_nop 0
	global_load_lds_dwordx4 v[226:227], off
	s_mov_b32 m0, s67
	s_nop 0
	global_load_lds_dwordx4 v[228:229], off
	s_add_i32 s87, 0, 0x18000
	s_add_i32 s96, 0, 0x1c000
	v_add_u32_e32 v72, s87, v217
	v_add_u32_e32 v160, s96, v217
	ds_read_b128 v[52:55], v72
	ds_read_b128 v[56:59], v72 offset:1024
	ds_read_b128 v[68:71], v72 offset:2048
	ds_read_b128 v[72:75], v72 offset:3072
	ds_read_b128 v[140:143], v160
	ds_read_b128 v[144:147], v160 offset:1024
	ds_read_b128 v[156:159], v160 offset:2048
	ds_read_b128 v[160:163], v160 offset:3072
	s_add_u32 s60, s60, 0x80000
	s_addc_u32 s61, s61, 0
	s_mov_b32 m0, s72
	ds_read_b128 v[164:167], v219 offset:32768
	ds_read_b128 v[168:171], v219 offset:33792
	ds_read_b128 v[172:175], v219 offset:34816
	ds_read_b128 v[176:179], v219 offset:35840
	ds_read_b128 v[204:207], v219 offset:36864
	ds_read_b128 v[208:211], v219 offset:37888
	ds_read_b128 v[212:215], v219 offset:38912
	ds_read_b128 v[220:223], v219 offset:39936
	global_load_lds_dwordx4 v180, s[60:61]
	s_mov_b32 m0, s73
	s_nop 0
	global_load_lds_dwordx4 v182, s[60:61]
	s_waitcnt vmcnt(8) lgkmcnt(0)
	s_setprio 1
	s_barrier
; #define PG8_STAGE(bufoff, gbase, voff) do { _Pragma("unroll") for (int _i = 0; _i < 2; ++_i) \
;         __builtin_amdgcn_global_load_lds((const unsigned*)((const char*)(gbase) + (voff)[_i]), (PG8_LAS unsigned*)(lds + (bufoff) + ldsw + _i * 8192), 16, 0, 0); } while (0)
; #define PG8_LDA(dst, b, h) do { _Pragma("unroll") for (int m = 0; m < 4; ++m) _Pragma("unroll") for (int k = 0; k < 2; ++k) dst[m][k] = *(const PG8_LAS bf16x8*)(lds + PG8_SA(b, h) + aoff + m * 2048 + k * 1024); } while (0)
; #define PG8_WAIT_V(n) asm volatile("s_waitcnt vmcnt(" #n ")" ::: "memory")
; #define PG8_WAIT_L(n) asm volatile("s_waitcnt lgkmcnt(" #n ")" ::: "memory")
; #define PG8_BAR __builtin_amdgcn_s_barrier()
; #define PG8_SCHED __builtin_amdgcn_sched_barrier(0)
; template <class Epi, class Sched, bool ALIGN_EPI = false, bool SP2 = false, bool I8 = false>
; __device__ __forceinline__ void gemm_phase(PG8_LAS unsigned char* lds, const Gemm g, const Sched& S, const Epi& E) {
;     ...
;             PG8_WAIT_V(8); PG8_WAIT_L(0); PG8_BAR; PG8_MMA(0, 0, At, B0); PG8_MMA(0, 1, At, B1); PG8_BAR; PG8_SCHED;
;             PG8_LDA(At, 1, 1); PG8_STAGE(PG8_SB(1, 0), b3, voffB); PG8_STAGE(PG8_SB(1, 1), b3 + hstep, voffB); PG8_STAGE(PG8_SA(1, 0), a3, voffA);
;             PG8_WAIT_V(8); PG8_WAIT_L(0); PG8_BAR; PG8_MMA(1, 0, At, B0); PG8_MMA(1, 1, At, B1); PG8_BAR; PG8_SCHED;
	v_mfma_i32_16x16x64_i8 v[152:155], v[52:55], v[164:167], v[152:155]
	v_mfma_i32_16x16x64_i8 v[152:155], v[56:59], v[168:171], v[152:155]
	v_mfma_i32_16x16x64_i8 v[128:131], v[56:59], v[176:179], v[128:131]
	v_mfma_i32_16x16x64_i8 v[128:131], v[52:55], v[172:175], v[128:131]
	v_mfma_i32_16x16x64_i8 v[112:115], v[52:55], v[204:207], v[112:115]
	v_mfma_i32_16x16x64_i8 v[112:115], v[56:59], v[208:211], v[112:115]
	v_mfma_i32_16x16x64_i8 v[96:99], v[56:59], v[220:223], v[96:99]
	v_mfma_i32_16x16x64_i8 v[96:99], v[52:55], v[212:215], v[96:99]
	v_mfma_i32_16x16x64_i8 v[92:95], v[68:71], v[212:215], v[92:95]
	v_mfma_i32_16x16x64_i8 v[92:95], v[72:75], v[220:223], v[92:95]
	v_mfma_i32_16x16x64_i8 v[108:111], v[72:75], v[208:211], v[108:111]
	v_mfma_i32_16x16x64_i8 v[108:111], v[68:71], v[204:207], v[108:111]
	v_mfma_i32_16x16x64_i8 v[124:127], v[68:71], v[172:175], v[124:127]
	v_mfma_i32_16x16x64_i8 v[124:127], v[72:75], v[176:179], v[124:127]
	v_mfma_i32_16x16x64_i8 v[148:151], v[72:75], v[168:171], v[148:151]
	v_mfma_i32_16x16x64_i8 v[148:151], v[68:71], v[164:167], v[148:151]
	v_mfma_i32_16x16x64_i8 v[136:139], v[140:143], v[164:167], v[136:139]
	v_mfma_i32_16x16x64_i8 v[136:139], v[144:147], v[168:171], v[136:139]
	v_mfma_i32_16x16x64_i8 v[120:123], v[144:147], v[176:179], v[120:123]
	v_mfma_i32_16x16x64_i8 v[120:123], v[140:143], v[172:175], v[120:123]
	v_mfma_i32_16x16x64_i8 v[104:107], v[140:143], v[204:207], v[104:107]
	v_mfma_i32_16x16x64_i8 v[104:107], v[144:147], v[208:211], v[104:107]
	v_mfma_i32_16x16x64_i8 v[88:91], v[144:147], v[220:223], v[88:91]
	v_mfma_i32_16x16x64_i8 v[88:91], v[140:143], v[212:215], v[88:91]
	v_mfma_i32_16x16x64_i8 v[84:87], v[156:159], v[212:215], v[84:87]
	v_mfma_i32_16x16x64_i8 v[84:87], v[160:163], v[220:223], v[84:87]
	v_mfma_i32_16x16x64_i8 v[100:103], v[160:163], v[208:211], v[100:103]
	v_mfma_i32_16x16x64_i8 v[100:103], v[156:159], v[204:207], v[100:103]
	v_mfma_i32_16x16x64_i8 v[116:119], v[156:159], v[172:175], v[116:119]
	v_mfma_i32_16x16x64_i8 v[116:119], v[160:163], v[176:179], v[116:119]
	v_mfma_i32_16x16x64_i8 v[132:135], v[160:163], v[168:171], v[132:135]
	v_mfma_i32_16x16x64_i8 v[132:135], v[156:159], v[164:167], v[132:135]
	s_barrier
	s_setprio 0
	s_add_i32 s60, s87, s46
	v_lshl_add_u64 v[190:191], v[190:191], 0, s[84:85]
	s_mov_b32 m0, s60
	ds_read_b128 v[164:167], v219 offset:49152
	ds_read_b128 v[168:171], v219 offset:50176
	ds_read_b128 v[172:175], v219 offset:51200
	ds_read_b128 v[176:179], v219 offset:52224
	ds_read_b128 v[204:207], v219 offset:53248
	ds_read_b128 v[208:211], v219 offset:54272
	ds_read_b128 v[212:215], v219 offset:55296
	ds_read_b128 v[220:223], v219 offset:56320
	global_load_lds_dwordx4 v[190:191], off
	s_add_i32 m0, s60, 0x2000
	s_add_u32 s58, s58, 0x80080
	v_lshl_add_u64 v[190:191], v[224:225], 0, s[84:85]
	s_addc_u32 s59, s59, 0
	s_add_i32 s60, s96, s46
	global_load_lds_dwordx4 v[190:191], off
	s_mov_b32 m0, s60
	s_nop 0
	global_load_lds_dwordx4 v2, s[58:59]
	s_add_i32 m0, s60, 0x2000
	s_nop 0
	global_load_lds_dwordx4 v184, s[58:59]
	s_cmp_eq_u32 s86, 28
	s_cbranch_scc0 .Ldefer_1843_body
	v_lshl_add_u64 v[190:191], v[226:227], 0, s[84:85]
	s_mov_b32 m0, s28
	s_nop 0
	global_load_lds_dwordx4 v[190:191], off
	v_lshl_add_u64 v[190:191], v[228:229], 0, s[84:85]
	s_mov_b32 m0, s77
	s_nop 0
	global_load_lds_dwordx4 v[190:191], off
.Ldefer_1843_body:
	s_waitcnt vmcnt(6) lgkmcnt(0)
	s_setprio 1
	s_barrier
	v_mfma_i32_16x16x64_i8 v[80:83], v[52:55], v[164:167], v[80:83]
	v_mfma_i32_16x16x64_i8 v[80:83], v[56:59], v[168:171], v[80:83]
	v_mfma_i32_16x16x64_i8 v[64:67], v[56:59], v[176:179], v[64:67]
	v_mfma_i32_16x16x64_i8 v[64:67], v[52:55], v[172:175], v[64:67]
	v_mfma_i32_16x16x64_i8 v[48:51], v[52:55], v[204:207], v[48:51]
	v_mfma_i32_16x16x64_i8 v[48:51], v[56:59], v[208:211], v[48:51]
	v_mfma_i32_16x16x64_i8 v[16:19], v[56:59], v[220:223], v[16:19]
	v_mfma_i32_16x16x64_i8 v[16:19], v[52:55], v[212:215], v[16:19]
	v_mfma_i32_16x16x64_i8 v[12:15], v[68:71], v[212:215], v[12:15]
	v_mfma_i32_16x16x64_i8 v[12:15], v[72:75], v[220:223], v[12:15]
	v_mfma_i32_16x16x64_i8 v[44:47], v[72:75], v[208:211], v[44:47]
	v_mfma_i32_16x16x64_i8 v[44:47], v[68:71], v[204:207], v[44:47]
	v_mfma_i32_16x16x64_i8 v[60:63], v[68:71], v[172:175], v[60:63]
	v_mfma_i32_16x16x64_i8 v[60:63], v[72:75], v[176:179], v[60:63]
	v_mfma_i32_16x16x64_i8 v[76:79], v[72:75], v[168:171], v[76:79]
	v_mfma_i32_16x16x64_i8 v[76:79], v[68:71], v[164:167], v[76:79]
	v_mfma_i32_16x16x64_i8 v[28:31], v[140:143], v[164:167], v[28:31]
	v_mfma_i32_16x16x64_i8 v[72:75], v[144:147], v[168:171], v[28:31]
	v_mfma_i32_16x16x64_i8 v[28:31], v[144:147], v[176:179], v[36:39]
	v_mfma_i32_16x16x64_i8 v[56:59], v[140:143], v[172:175], v[28:31]
	v_mfma_i32_16x16x64_i8 v[24:27], v[140:143], v[204:207], v[24:27]
	v_mfma_i32_16x16x64_i8 v[24:27], v[144:147], v[208:211], v[24:27]
	v_mfma_i32_16x16x64_i8 v[8:11], v[144:147], v[220:223], v[8:11]
	v_mfma_i32_16x16x64_i8 v[8:11], v[140:143], v[212:215], v[8:11]
	v_mfma_i32_16x16x64_i8 v[4:7], v[156:159], v[212:215], v[4:7]
	v_mfma_i32_16x16x64_i8 v[4:7], v[160:163], v[220:223], v[4:7]
	v_mfma_i32_16x16x64_i8 v[20:23], v[160:163], v[208:211], v[20:23]
	v_mfma_i32_16x16x64_i8 v[20:23], v[156:159], v[204:207], v[20:23]
	v_mfma_i32_16x16x64_i8 v[28:31], v[156:159], v[172:175], v[40:43]
	v_mfma_i32_16x16x64_i8 v[52:55], v[160:163], v[176:179], v[28:31]
	v_mfma_i32_16x16x64_i8 v[28:31], v[160:163], v[168:171], v[32:35]
	v_mfma_i32_16x16x64_i8 v[68:71], v[156:159], v[164:167], v[28:31]
	s_barrier
	s_setprio 0
	s_add_i32 s86, s86, 2
	s_add_u32 s54, s54, 0x100
	s_addc_u32 s55, s55, 0
	s_add_u32 s45, s45, 0x100
	s_addc_u32 s49, s49, 0
	s_cmp_gt_u32 s86, 29
	s_cbranch_scc0 .LBB0_1843
